# K-loop LDS-DMA loads use scalar base + 32-bit lane offset (no 64-bit VALU address adds); K loops 64B-aligned; hand-written ml_scan; serialized load chains un-serialized
# speedup vs baseline: 1.0079x; 1.0079x over previous
; #define PG8_STAGE(bufoff, gbase, voff) do { _Pragma("unroll") for (int _i = 0; _i < 2; ++_i) \
;         __builtin_amdgcn_global_load_lds((const unsigned*)((const char*)(gbase) + (voff)[_i]), (PG8_LAS unsigned*)(lds + (bufoff) + ldsw + _i * 8192), 16, 0, 0); } while (0)
; #define PG8_LDA(dst, b, h) do { _Pragma("unroll") for (int m = 0; m < 4; ++m) _Pragma("unroll") for (int k = 0; k < 2; ++k) dst[m][k] = *(const PG8_LAS bf16x8*)(lds + PG8_SA(b, h) + aoff + m * 2048 + k * 1024); } while (0)
; #define PG8_LDB(dst, b, h) do { _Pragma("unroll") for (int n = 0; n < 2; ++n) _Pragma("unroll") for (int k = 0; k < 2; ++k) dst[n][k] = *(const PG8_LAS bf16x8*)(lds + PG8_SB(b, h) + boff + n * 2048 + k * 1024); } while (0)
; #define PG8_MMA(ai, bj, At, Bt) do { __builtin_amdgcn_s_setprio(1); _Pragma("unroll") for (int m = 0; m < 4; ++m) _Pragma("unroll") for (int n = 0; n < 2; ++n) _Pragma("unroll") for (int k = 0; k < 2; ++k) \
;         acc[ai][bj][m][n] = __builtin_amdgcn_mfma_f32_16x16x32_bf16(Bt[n][k], At[m][k], acc[ai][bj][m][n], 0, 0, 0); __builtin_amdgcn_s_setprio(0); } while (0)
; template <class Epi, class Sched, bool ALIGN_EPI = false, bool SP2 = false>
; __device__ __forceinline__ void gemm_phase(PG8_LAS unsigned char* lds, const Gemm g, const Sched& S, const Epi& E) {
;     ...
;         for (int t = 0; t < nt; t += 2) {
;             const bool last = (t == nt - 2);
;             const char* a1 = cA + (size_t)(t + 1) * kstep;
;             const char* a2 = last ? nA : cA + (size_t)(t + 2) * kstep; const char* b2 = last ? nB : cB + (size_t)(t + 2) * kstep;
;             const char* a3 = a2 + kstep; const char* b3 = b2 + kstep;
;             if (last && has_next) S.a_ready(nxt);
;             if constexpr (SP2) {
;             PG8_LDB(B0, 0, 0); PG8_LDB(B1, 0, 1); PG8_SCHED; PG8_LDA(At, 0, 0); PG8_STAGE(PG8_SA(1, 1), a1 + hstep, voffA);
;             PG8_WAIT_V(8); PG8_WAIT_L(0); PG8_BAR; PG8_MMA(0, 0, At, B0); PG8_MMA(0, 1, At, B1); PG8_BAR; PG8_SCHED;
;     ...
;         if (zero_acc) {
; #pragma unroll
;         for (int a = 0; a < 2; ++a)
; #pragma unroll
;             for (int b = 0; b < 2; ++b)
; #pragma unroll
;                 for (int m = 0; m < 4; ++m)
; #pragma unroll
;                     for (int n = 0; n < 2; ++n) acc[a][b][m][n] = (f32x4){0.f, 0.f, 0.f, 0.f};
;         }
;         cur = nxt; cA = nA; cB = nB; ++ui;
.LBB0_300:
	s_ashr_i32 s13, s12, 31
	s_lshl_b64 s[28:29], s[12:13], 20
	s_add_u32 s28, s43, s28
	s_addc_u32 s29, s44, s29
	s_ashr_i32 s11, s10, 31
	s_lshl_b64 s[30:31], s[10:11], 20
	s_add_u32 s30, s45, s30
	s_addc_u32 s31, s46, s31
	s_and_b64 s[40:41], s[0:1], exec
	s_cselect_b32 s11, s29, s37
	s_cselect_b32 s13, s28, s36
	s_cselect_b32 s56, s31, s39
	s_cselect_b32 s57, s30, s38
	s_add_u32 s36, s36, 0x80080
	s_addc_u32 s37, s37, 0
	s_add_u32 s58, s38, 0x100
	v_mov_b32_e32 v4, 0
	s_addc_u32 s59, s39, 0
	s_mov_b32 s60, -2
	v_mov_b32_e32 v5, v4
	v_mov_b32_e32 v6, v4
	v_mov_b32_e32 v7, v4
	v_mov_b32_e32 v12, v4
	v_mov_b32_e32 v13, v4
	v_mov_b32_e32 v14, v4
	v_mov_b32_e32 v15, v4
	v_mov_b32_e32 v20, v4
	v_mov_b32_e32 v21, v4
	v_mov_b32_e32 v22, v4
	v_mov_b32_e32 v23, v4
	v_mov_b32_e32 v28, v4
	v_mov_b32_e32 v29, v4
	v_mov_b32_e32 v30, v4
	v_mov_b32_e32 v31, v4
	v_mov_b32_e32 v36, v4
	v_mov_b32_e32 v37, v4
	v_mov_b32_e32 v38, v4
	v_mov_b32_e32 v39, v4
	v_mov_b32_e32 v44, v4
	v_mov_b32_e32 v45, v4
	v_mov_b32_e32 v46, v4
	v_mov_b32_e32 v47, v4
	v_mov_b32_e32 v52, v4
	v_mov_b32_e32 v53, v4
	v_mov_b32_e32 v54, v4
	v_mov_b32_e32 v55, v4
	v_mov_b32_e32 v60, v4
	v_mov_b32_e32 v61, v4
	v_mov_b32_e32 v62, v4
	v_mov_b32_e32 v63, v4
	v_mov_b32_e32 v8, v4
	v_mov_b32_e32 v9, v4
	v_mov_b32_e32 v10, v4
	v_mov_b32_e32 v11, v4
	v_mov_b32_e32 v16, v4
	v_mov_b32_e32 v17, v4
	v_mov_b32_e32 v18, v4
	v_mov_b32_e32 v19, v4
	v_mov_b32_e32 v24, v4
	v_mov_b32_e32 v25, v4
	v_mov_b32_e32 v26, v4
	v_mov_b32_e32 v27, v4
	v_mov_b32_e32 v32, v4
	v_mov_b32_e32 v33, v4
	v_mov_b32_e32 v34, v4
	v_mov_b32_e32 v35, v4
	v_mov_b32_e32 v40, v4
	v_mov_b32_e32 v41, v4
	v_mov_b32_e32 v42, v4
	v_mov_b32_e32 v43, v4
	v_mov_b32_e32 v48, v4
	v_mov_b32_e32 v49, v4
	v_mov_b32_e32 v50, v4
	v_mov_b32_e32 v51, v4
	v_mov_b32_e32 v56, v4
	v_mov_b32_e32 v57, v4
	v_mov_b32_e32 v58, v4
	v_mov_b32_e32 v59, v4
	v_mov_b32_e32 v64, v4
	v_mov_b32_e32 v65, v4
	v_mov_b32_e32 v66, v4
	v_mov_b32_e32 v67, v4
	v_mov_b32_e32 v68, v4
	v_mov_b32_e32 v69, v4
	v_mov_b32_e32 v70, v4
	v_mov_b32_e32 v71, v4
	v_mov_b32_e32 v76, v4
	v_mov_b32_e32 v77, v4
	v_mov_b32_e32 v78, v4
	v_mov_b32_e32 v79, v4
	v_mov_b32_e32 v84, v4
	v_mov_b32_e32 v85, v4
	v_mov_b32_e32 v86, v4
	v_mov_b32_e32 v87, v4
	v_mov_b32_e32 v92, v4
	v_mov_b32_e32 v93, v4
	v_mov_b32_e32 v94, v4
	v_mov_b32_e32 v95, v4
	v_mov_b32_e32 v100, v4
	v_mov_b32_e32 v101, v4
	v_mov_b32_e32 v102, v4
	v_mov_b32_e32 v103, v4
	v_mov_b32_e32 v108, v4
	v_mov_b32_e32 v109, v4
	v_mov_b32_e32 v110, v4
	v_mov_b32_e32 v111, v4
	v_mov_b32_e32 v116, v4
	v_mov_b32_e32 v117, v4
	v_mov_b32_e32 v118, v4
	v_mov_b32_e32 v119, v4
	v_mov_b32_e32 v124, v4
	v_mov_b32_e32 v125, v4
	v_mov_b32_e32 v126, v4
	v_mov_b32_e32 v127, v4
	v_mov_b32_e32 v72, v4
	v_mov_b32_e32 v73, v4
	v_mov_b32_e32 v74, v4
	v_mov_b32_e32 v75, v4
	v_mov_b32_e32 v80, v4
	v_mov_b32_e32 v81, v4
	v_mov_b32_e32 v82, v4
	v_mov_b32_e32 v83, v4
	v_mov_b32_e32 v88, v4
	v_mov_b32_e32 v89, v4
	v_mov_b32_e32 v90, v4
	v_mov_b32_e32 v91, v4
	v_mov_b32_e32 v96, v4
	v_mov_b32_e32 v97, v4
	v_mov_b32_e32 v98, v4
	v_mov_b32_e32 v99, v4
	v_mov_b32_e32 v104, v4
	v_mov_b32_e32 v105, v4
	v_mov_b32_e32 v106, v4
	v_mov_b32_e32 v107, v4
	v_mov_b32_e32 v112, v4
	v_mov_b32_e32 v113, v4
	v_mov_b32_e32 v114, v4
	v_mov_b32_e32 v115, v4
	v_mov_b32_e32 v120, v4
	v_mov_b32_e32 v121, v4
	v_mov_b32_e32 v122, v4
	v_mov_b32_e32 v123, v4
	v_mov_b32_e32 v128, v4
	v_mov_b32_e32 v129, v4
	v_mov_b32_e32 v130, v4
	v_mov_b32_e32 v131, v4
	.p2align 6
	s_nop 0
.LBB0_301:
	s_add_u32 s38, s36, 0xfff80080
	s_addc_u32 s39, s37, -1
	s_add_i32 s61, 0, 0x10000
	s_cmp_eq_u32 s60, 28
	s_cselect_b32 s41, s11, s39
	s_cselect_b32 s40, s13, s38
	s_cselect_b32 s39, s56, s59
	s_cselect_b32 s38, s57, s58
	s_add_i32 s64, 0, 0x14000
	v_add_u32_e32 v158, s61, v150
	v_add_u32_e32 v162, s64, v150
	ds_read_b128 v[142:145], v158
	ds_read_b128 v[146:149], v158 offset:1024
	ds_read_b128 v[154:157], v158 offset:2048
	ds_read_b128 v[158:161], v158 offset:3072
	ds_read_b128 v[174:177], v162
	ds_read_b128 v[178:181], v162 offset:1024
	ds_read_b128 v[204:207], v162 offset:2048
	ds_read_b128 v[208:211], v162 offset:3072
	s_add_i32 m0, s47, 0xc000
	ds_read_b128 v[212:215], v153
	ds_read_b128 v[216:219], v153 offset:1024
	ds_read_b128 v[220:223], v153 offset:2048
	ds_read_b128 v[224:227], v153 offset:3072
	ds_read_b128 v[228:231], v153 offset:4096
	ds_read_b128 v[232:235], v153 offset:5120
	ds_read_b128 v[236:239], v153 offset:6144
	ds_read_b128 v[240:243], v153 offset:7168
	global_load_lds_dwordx4 v138, s[36:37]
	s_add_i32 m0, s47, 0xe000
	s_nop 0
	global_load_lds_dwordx4 v140, s[36:37]
	s_waitcnt vmcnt(8)
	s_waitcnt lgkmcnt(0)
	s_barrier
; #define PG8_STAGE(bufoff, gbase, voff) do { _Pragma("unroll") for (int _i = 0; _i < 2; ++_i) \
;         __builtin_amdgcn_global_load_lds((const unsigned*)((const char*)(gbase) + (voff)[_i]), (PG8_LAS unsigned*)(lds + (bufoff) + ldsw + _i * 8192), 16, 0, 0); } while (0)
; #define PG8_LDA(dst, b, h) do { _Pragma("unroll") for (int m = 0; m < 4; ++m) _Pragma("unroll") for (int k = 0; k < 2; ++k) dst[m][k] = *(const PG8_LAS bf16x8*)(lds + PG8_SA(b, h) + aoff + m * 2048 + k * 1024); } while (0)
; #define PG8_MMA(ai, bj, At, Bt) do { __builtin_amdgcn_s_setprio(1); _Pragma("unroll") for (int m = 0; m < 4; ++m) _Pragma("unroll") for (int n = 0; n < 2; ++n) _Pragma("unroll") for (int k = 0; k < 2; ++k) \
;         acc[ai][bj][m][n] = __builtin_amdgcn_mfma_f32_16x16x32_bf16(Bt[n][k], At[m][k], acc[ai][bj][m][n], 0, 0, 0); __builtin_amdgcn_s_setprio(0); } while (0)
; #define PG8_WAIT_V(n) asm volatile("s_waitcnt vmcnt(" #n ")" ::: "memory")
; #define PG8_WAIT_L(n) asm volatile("s_waitcnt lgkmcnt(" #n ")" ::: "memory")
; #define PG8_BAR __builtin_amdgcn_s_barrier()
; #define PG8_SCHED __builtin_amdgcn_sched_barrier(0)
; template <class Epi, class Sched, bool ALIGN_EPI = false, bool SP2 = false>
; __device__ __forceinline__ void gemm_phase(PG8_LAS unsigned char* lds, const Gemm g, const Sched& S, const Epi& E) {
;     ...
;             PG8_WAIT_V(8); PG8_WAIT_L(0); PG8_BAR; PG8_MMA(0, 0, At, B0); PG8_MMA(0, 1, At, B1); PG8_BAR; PG8_SCHED;
;             PG8_LDA(At, 0, 1); PG8_STAGE(PG8_SB(0, 0), b2, voffB); PG8_STAGE(PG8_SB(0, 1), b2 + hstep, voffB); PG8_STAGE(PG8_SA(0, 0), a2, voffA);
;             PG8_WAIT_V(8); PG8_WAIT_L(0); PG8_BAR; PG8_MMA(1, 0, At, B0); PG8_MMA(1, 1, At, B1); PG8_BAR; PG8_SCHED;
	s_setprio 1
	s_waitcnt lgkmcnt(0)
	v_mfma_f32_16x16x32_bf16 v[128:131], v[142:145], v[212:215], v[128:131]
	v_mfma_f32_16x16x32_bf16 v[120:123], v[154:157], v[212:215], v[120:123]
	v_mfma_f32_16x16x32_bf16 v[112:115], v[142:145], v[220:223], v[112:115]
	v_mfma_f32_16x16x32_bf16 v[104:107], v[154:157], v[220:223], v[104:107]
	v_mfma_f32_16x16x32_bf16 v[96:99], v[142:145], v[228:231], v[96:99]
	v_mfma_f32_16x16x32_bf16 v[88:91], v[154:157], v[228:231], v[88:91]
	v_mfma_f32_16x16x32_bf16 v[80:83], v[142:145], v[236:239], v[80:83]
	v_mfma_f32_16x16x32_bf16 v[72:75], v[154:157], v[236:239], v[72:75]
	v_mfma_f32_16x16x32_bf16 v[128:131], v[146:149], v[216:219], v[128:131]
	v_mfma_f32_16x16x32_bf16 v[120:123], v[158:161], v[216:219], v[120:123]
	v_mfma_f32_16x16x32_bf16 v[112:115], v[146:149], v[224:227], v[112:115]
	v_mfma_f32_16x16x32_bf16 v[104:107], v[158:161], v[224:227], v[104:107]
	v_mfma_f32_16x16x32_bf16 v[96:99], v[146:149], v[232:235], v[96:99]
	v_mfma_f32_16x16x32_bf16 v[88:91], v[158:161], v[232:235], v[88:91]
	v_mfma_f32_16x16x32_bf16 v[80:83], v[146:149], v[240:243], v[80:83]
	v_mfma_f32_16x16x32_bf16 v[72:75], v[158:161], v[240:243], v[72:75]
	s_setprio 0
	s_setprio 1
	v_mfma_f32_16x16x32_bf16 v[124:127], v[174:177], v[212:215], v[124:127]
	v_mfma_f32_16x16x32_bf16 v[116:119], v[204:207], v[212:215], v[116:119]
	v_mfma_f32_16x16x32_bf16 v[108:111], v[174:177], v[220:223], v[108:111]
	v_mfma_f32_16x16x32_bf16 v[100:103], v[204:207], v[220:223], v[100:103]
	v_mfma_f32_16x16x32_bf16 v[92:95], v[174:177], v[228:231], v[92:95]
	v_mfma_f32_16x16x32_bf16 v[84:87], v[204:207], v[228:231], v[84:87]
	v_mfma_f32_16x16x32_bf16 v[76:79], v[174:177], v[236:239], v[76:79]
	v_mfma_f32_16x16x32_bf16 v[68:71], v[204:207], v[236:239], v[68:71]
	v_mfma_f32_16x16x32_bf16 v[124:127], v[178:181], v[216:219], v[124:127]
	v_mfma_f32_16x16x32_bf16 v[116:119], v[208:211], v[216:219], v[116:119]
	v_mfma_f32_16x16x32_bf16 v[108:111], v[178:181], v[224:227], v[108:111]
	v_mfma_f32_16x16x32_bf16 v[100:103], v[208:211], v[224:227], v[100:103]
	v_mfma_f32_16x16x32_bf16 v[92:95], v[178:181], v[232:235], v[92:95]
	v_mfma_f32_16x16x32_bf16 v[84:87], v[208:211], v[232:235], v[84:87]
	v_mfma_f32_16x16x32_bf16 v[76:79], v[178:181], v[240:243], v[76:79]
	v_mfma_f32_16x16x32_bf16 v[68:71], v[208:211], v[240:243], v[68:71]
	s_setprio 0
	s_barrier
	s_add_i32 s61, s61, s42
	s_mov_b32 m0, s61
	ds_read_b128 v[212:215], v153 offset:16384
	ds_read_b128 v[216:219], v153 offset:17408
	ds_read_b128 v[220:223], v153 offset:18432
	ds_read_b128 v[224:227], v153 offset:19456
	ds_read_b128 v[228:231], v153 offset:20480
	ds_read_b128 v[232:235], v153 offset:21504
	ds_read_b128 v[236:239], v153 offset:22528
	ds_read_b128 v[240:243], v153 offset:23552
	global_load_lds_dwordx4 v2, s[38:39]
	s_add_i32 m0, s61, 0x2000
	s_add_u32 s62, s38, 0x80000
	s_addc_u32 s63, s39, 0
	s_add_i32 s61, s64, s42
	global_load_lds_dwordx4 v132, s[38:39]
	s_mov_b32 m0, s61
	s_nop 0
	global_load_lds_dwordx4 v2, s[62:63]
	s_add_i32 m0, s61, 0x2000
	s_nop 0
	global_load_lds_dwordx4 v132, s[62:63]
	s_mov_b32 m0, s47
	s_nop 0
	global_load_lds_dwordx4 v136, s[40:41]
	s_mov_b32 m0, s48
	s_nop 0
	global_load_lds_dwordx4 v134, s[40:41]
	s_waitcnt vmcnt(8)
	s_waitcnt lgkmcnt(0)
	s_barrier
	s_setprio 1
	s_waitcnt lgkmcnt(0)
	v_mfma_f32_16x16x32_bf16 v[64:67], v[142:145], v[212:215], v[64:67]
	v_mfma_f32_16x16x32_bf16 v[56:59], v[154:157], v[212:215], v[56:59]
	v_mfma_f32_16x16x32_bf16 v[48:51], v[142:145], v[220:223], v[48:51]
	v_mfma_f32_16x16x32_bf16 v[40:43], v[154:157], v[220:223], v[40:43]
	v_mfma_f32_16x16x32_bf16 v[32:35], v[142:145], v[228:231], v[32:35]
	v_mfma_f32_16x16x32_bf16 v[24:27], v[154:157], v[228:231], v[24:27]
	v_mfma_f32_16x16x32_bf16 v[16:19], v[142:145], v[236:239], v[16:19]
	v_mfma_f32_16x16x32_bf16 v[8:11], v[154:157], v[236:239], v[8:11]
	v_mfma_f32_16x16x32_bf16 v[64:67], v[146:149], v[216:219], v[64:67]
	v_mfma_f32_16x16x32_bf16 v[56:59], v[158:161], v[216:219], v[56:59]
	v_mfma_f32_16x16x32_bf16 v[48:51], v[146:149], v[224:227], v[48:51]
	v_mfma_f32_16x16x32_bf16 v[40:43], v[158:161], v[224:227], v[40:43]
	v_mfma_f32_16x16x32_bf16 v[32:35], v[146:149], v[232:235], v[32:35]
	v_mfma_f32_16x16x32_bf16 v[24:27], v[158:161], v[232:235], v[24:27]
	v_mfma_f32_16x16x32_bf16 v[16:19], v[146:149], v[240:243], v[16:19]
	v_mfma_f32_16x16x32_bf16 v[8:11], v[158:161], v[240:243], v[8:11]
	s_setprio 0
	s_setprio 1
	v_mfma_f32_16x16x32_bf16 v[60:63], v[174:177], v[212:215], v[60:63]
	v_mfma_f32_16x16x32_bf16 v[52:55], v[204:207], v[212:215], v[52:55]
	v_mfma_f32_16x16x32_bf16 v[44:47], v[174:177], v[220:223], v[44:47]
	v_mfma_f32_16x16x32_bf16 v[36:39], v[204:207], v[220:223], v[36:39]
	v_mfma_f32_16x16x32_bf16 v[28:31], v[174:177], v[228:231], v[28:31]
	v_mfma_f32_16x16x32_bf16 v[20:23], v[204:207], v[228:231], v[20:23]
	v_mfma_f32_16x16x32_bf16 v[12:15], v[174:177], v[236:239], v[12:15]
	v_mfma_f32_16x16x32_bf16 v[4:7], v[204:207], v[236:239], v[4:7]
	v_mfma_f32_16x16x32_bf16 v[60:63], v[178:181], v[216:219], v[60:63]
	v_mfma_f32_16x16x32_bf16 v[52:55], v[208:211], v[216:219], v[52:55]
	v_mfma_f32_16x16x32_bf16 v[44:47], v[178:181], v[224:227], v[44:47]
	v_mfma_f32_16x16x32_bf16 v[36:39], v[208:211], v[224:227], v[36:39]
	v_mfma_f32_16x16x32_bf16 v[28:31], v[178:181], v[232:235], v[28:31]
	v_mfma_f32_16x16x32_bf16 v[20:23], v[208:211], v[232:235], v[20:23]
	v_mfma_f32_16x16x32_bf16 v[12:15], v[178:181], v[240:243], v[12:15]
	v_mfma_f32_16x16x32_bf16 v[4:7], v[208:211], v[240:243], v[4:7]
	s_setprio 0
	s_barrier
; #define PG8_STAGE(bufoff, gbase, voff) do { _Pragma("unroll") for (int _i = 0; _i < 2; ++_i) \
;         __builtin_amdgcn_global_load_lds((const unsigned*)((const char*)(gbase) + (voff)[_i]), (PG8_LAS unsigned*)(lds + (bufoff) + ldsw + _i * 8192), 16, 0, 0); } while (0)
; #define PG8_LDA(dst, b, h) do { _Pragma("unroll") for (int m = 0; m < 4; ++m) _Pragma("unroll") for (int k = 0; k < 2; ++k) dst[m][k] = *(const PG8_LAS bf16x8*)(lds + PG8_SA(b, h) + aoff + m * 2048 + k * 1024); } while (0)
; #define PG8_LDB(dst, b, h) do { _Pragma("unroll") for (int n = 0; n < 2; ++n) _Pragma("unroll") for (int k = 0; k < 2; ++k) dst[n][k] = *(const PG8_LAS bf16x8*)(lds + PG8_SB(b, h) + boff + n * 2048 + k * 1024); } while (0)
; #define PG8_MMA(ai, bj, At, Bt) do { __builtin_amdgcn_s_setprio(1); _Pragma("unroll") for (int m = 0; m < 4; ++m) _Pragma("unroll") for (int n = 0; n < 2; ++n) _Pragma("unroll") for (int k = 0; k < 2; ++k) \
;         acc[ai][bj][m][n] = __builtin_amdgcn_mfma_f32_16x16x32_bf16(Bt[n][k], At[m][k], acc[ai][bj][m][n], 0, 0, 0); __builtin_amdgcn_s_setprio(0); } while (0)
; #define PG8_WAIT_V(n) asm volatile("s_waitcnt vmcnt(" #n ")" ::: "memory")
; #define PG8_WAIT_L(n) asm volatile("s_waitcnt lgkmcnt(" #n ")" ::: "memory")
; #define PG8_BAR __builtin_amdgcn_s_barrier()
; #define PG8_SCHED __builtin_amdgcn_sched_barrier(0)
; template <class Epi, class Sched, bool ALIGN_EPI = false, bool SP2 = false>
; __device__ __forceinline__ void gemm_phase(PG8_LAS unsigned char* lds, const Gemm g, const Sched& S, const Epi& E) {
;     ...
;             PG8_LDB(B0, 1, 0); PG8_LDB(B1, 1, 1); PG8_SCHED; PG8_LDA(At, 1, 0); PG8_STAGE(PG8_SA(0, 1), a2 + hstep, voffA);
;             PG8_WAIT_V(8); PG8_WAIT_L(0); PG8_BAR; PG8_MMA(0, 0, At, B0); PG8_MMA(0, 1, At, B1); PG8_BAR; PG8_SCHED;
;             PG8_LDA(At, 1, 1); PG8_STAGE(PG8_SB(1, 0), b3, voffB); PG8_STAGE(PG8_SB(1, 1), b3 + hstep, voffB); PG8_STAGE(PG8_SA(1, 0), a3, voffA);
;             PG8_WAIT_V(8); PG8_WAIT_L(0); PG8_BAR; PG8_MMA(1, 0, At, B0); PG8_MMA(1, 1, At, B1); PG8_BAR; PG8_SCHED;
	s_add_i32 s61, 0, 0x18000
	s_add_i32 s62, 0, 0x1c000
	v_add_u32_e32 v158, s61, v150
	v_add_u32_e32 v164, s62, v150
	ds_read_b128 v[142:145], v158
	ds_read_b128 v[146:149], v158 offset:1024
	ds_read_b128 v[154:157], v158 offset:2048
	ds_read_b128 v[158:161], v158 offset:3072
	ds_read_b128 v[174:177], v164
	ds_read_b128 v[178:181], v164 offset:1024
	ds_read_b128 v[204:207], v164 offset:2048
	ds_read_b128 v[208:211], v164 offset:3072
	s_add_u32 s100, s40, 0x80
	s_addc_u32 s101, s41, 0
	s_add_u32 s40, s40, 0x80000
	s_addc_u32 s41, s41, 0
	s_mov_b32 m0, s49
	ds_read_b128 v[212:215], v153 offset:32768
	ds_read_b128 v[216:219], v153 offset:33792
	ds_read_b128 v[220:223], v153 offset:34816
	ds_read_b128 v[224:227], v153 offset:35840
	ds_read_b128 v[228:231], v153 offset:36864
	ds_read_b128 v[232:235], v153 offset:37888
	ds_read_b128 v[236:239], v153 offset:38912
	ds_read_b128 v[240:243], v153 offset:39936
	global_load_lds_dwordx4 v136, s[40:41]
	s_mov_b32 m0, s50
	s_nop 0
	global_load_lds_dwordx4 v134, s[40:41]
	s_waitcnt vmcnt(8)
	s_waitcnt lgkmcnt(0)
	s_barrier
	s_setprio 1
	s_waitcnt lgkmcnt(0)
	v_mfma_f32_16x16x32_bf16 v[128:131], v[142:145], v[212:215], v[128:131]
	v_mfma_f32_16x16x32_bf16 v[120:123], v[154:157], v[212:215], v[120:123]
	v_mfma_f32_16x16x32_bf16 v[112:115], v[142:145], v[220:223], v[112:115]
	v_mfma_f32_16x16x32_bf16 v[104:107], v[154:157], v[220:223], v[104:107]
	v_mfma_f32_16x16x32_bf16 v[96:99], v[142:145], v[228:231], v[96:99]
	v_mfma_f32_16x16x32_bf16 v[88:91], v[154:157], v[228:231], v[88:91]
	v_mfma_f32_16x16x32_bf16 v[80:83], v[142:145], v[236:239], v[80:83]
	v_mfma_f32_16x16x32_bf16 v[72:75], v[154:157], v[236:239], v[72:75]
	v_mfma_f32_16x16x32_bf16 v[128:131], v[146:149], v[216:219], v[128:131]
	v_mfma_f32_16x16x32_bf16 v[120:123], v[158:161], v[216:219], v[120:123]
	v_mfma_f32_16x16x32_bf16 v[112:115], v[146:149], v[224:227], v[112:115]
	v_mfma_f32_16x16x32_bf16 v[104:107], v[158:161], v[224:227], v[104:107]
	v_mfma_f32_16x16x32_bf16 v[96:99], v[146:149], v[232:235], v[96:99]
	v_mfma_f32_16x16x32_bf16 v[88:91], v[158:161], v[232:235], v[88:91]
	v_mfma_f32_16x16x32_bf16 v[80:83], v[146:149], v[240:243], v[80:83]
	v_mfma_f32_16x16x32_bf16 v[72:75], v[158:161], v[240:243], v[72:75]
	s_setprio 0
	s_setprio 1
	v_mfma_f32_16x16x32_bf16 v[124:127], v[174:177], v[212:215], v[124:127]
	v_mfma_f32_16x16x32_bf16 v[116:119], v[204:207], v[212:215], v[116:119]
	v_mfma_f32_16x16x32_bf16 v[108:111], v[174:177], v[220:223], v[108:111]
	v_mfma_f32_16x16x32_bf16 v[100:103], v[204:207], v[220:223], v[100:103]
	v_mfma_f32_16x16x32_bf16 v[92:95], v[174:177], v[228:231], v[92:95]
	v_mfma_f32_16x16x32_bf16 v[84:87], v[204:207], v[228:231], v[84:87]
	v_mfma_f32_16x16x32_bf16 v[76:79], v[174:177], v[236:239], v[76:79]
	v_mfma_f32_16x16x32_bf16 v[68:71], v[204:207], v[236:239], v[68:71]
	v_mfma_f32_16x16x32_bf16 v[124:127], v[178:181], v[216:219], v[124:127]
	v_mfma_f32_16x16x32_bf16 v[116:119], v[208:211], v[216:219], v[116:119]
	v_mfma_f32_16x16x32_bf16 v[108:111], v[178:181], v[224:227], v[108:111]
	v_mfma_f32_16x16x32_bf16 v[100:103], v[208:211], v[224:227], v[100:103]
	v_mfma_f32_16x16x32_bf16 v[92:95], v[178:181], v[232:235], v[92:95]
	v_mfma_f32_16x16x32_bf16 v[84:87], v[208:211], v[232:235], v[84:87]
	v_mfma_f32_16x16x32_bf16 v[76:79], v[178:181], v[240:243], v[76:79]
	v_mfma_f32_16x16x32_bf16 v[68:71], v[208:211], v[240:243], v[68:71]
	s_setprio 0
	s_barrier
	s_add_i32 s40, s61, s42
	s_add_i32 m0, s40, 0xffffff80
	ds_read_b128 v[212:215], v153 offset:49152
	ds_read_b128 v[216:219], v153 offset:50176
	ds_read_b128 v[220:223], v153 offset:51200
	ds_read_b128 v[224:227], v153 offset:52224
	ds_read_b128 v[228:231], v153 offset:53248
	ds_read_b128 v[232:235], v153 offset:54272
	ds_read_b128 v[236:239], v153 offset:55296
	ds_read_b128 v[240:243], v153 offset:56320
	global_load_lds_dwordx4 v2, s[38:39] offset:128
	s_add_i32 m0, s40, 0x1f80
	s_add_i32 s40, s62, s42
	global_load_lds_dwordx4 v132, s[38:39] offset:128
	s_add_u32 s38, s38, 0x80080
	s_addc_u32 s39, s39, 0
	s_mov_b32 m0, s40
	s_nop 0
	global_load_lds_dwordx4 v2, s[38:39]
	s_add_i32 m0, s40, 0x2000
	s_nop 0
	global_load_lds_dwordx4 v132, s[38:39]
	s_mov_b32 m0, s51
	s_nop 0
	global_load_lds_dwordx4 v136, s[100:101]
	s_mov_b32 m0, s53
	s_nop 0
	global_load_lds_dwordx4 v134, s[100:101]
	s_nop 0
	s_waitcnt vmcnt(8)
	s_waitcnt lgkmcnt(0)
	s_barrier
	s_setprio 1
	s_waitcnt lgkmcnt(0)
	v_mfma_f32_16x16x32_bf16 v[64:67], v[142:145], v[212:215], v[64:67]
	v_mfma_f32_16x16x32_bf16 v[56:59], v[154:157], v[212:215], v[56:59]
	v_mfma_f32_16x16x32_bf16 v[48:51], v[142:145], v[220:223], v[48:51]
	v_mfma_f32_16x16x32_bf16 v[40:43], v[154:157], v[220:223], v[40:43]
	v_mfma_f32_16x16x32_bf16 v[32:35], v[142:145], v[228:231], v[32:35]
	v_mfma_f32_16x16x32_bf16 v[24:27], v[154:157], v[228:231], v[24:27]
	v_mfma_f32_16x16x32_bf16 v[16:19], v[142:145], v[236:239], v[16:19]
	v_mfma_f32_16x16x32_bf16 v[8:11], v[154:157], v[236:239], v[8:11]
	v_mfma_f32_16x16x32_bf16 v[64:67], v[146:149], v[216:219], v[64:67]
	v_mfma_f32_16x16x32_bf16 v[56:59], v[158:161], v[216:219], v[56:59]
	v_mfma_f32_16x16x32_bf16 v[48:51], v[146:149], v[224:227], v[48:51]
	v_mfma_f32_16x16x32_bf16 v[40:43], v[158:161], v[224:227], v[40:43]
	v_mfma_f32_16x16x32_bf16 v[32:35], v[146:149], v[232:235], v[32:35]
	v_mfma_f32_16x16x32_bf16 v[24:27], v[158:161], v[232:235], v[24:27]
	v_mfma_f32_16x16x32_bf16 v[16:19], v[146:149], v[240:243], v[16:19]
	v_mfma_f32_16x16x32_bf16 v[8:11], v[158:161], v[240:243], v[8:11]
	s_setprio 0
	s_setprio 1
	v_mfma_f32_16x16x32_bf16 v[60:63], v[174:177], v[212:215], v[60:63]
	v_mfma_f32_16x16x32_bf16 v[52:55], v[204:207], v[212:215], v[52:55]
	v_mfma_f32_16x16x32_bf16 v[44:47], v[174:177], v[220:223], v[44:47]
	v_mfma_f32_16x16x32_bf16 v[36:39], v[204:207], v[220:223], v[36:39]
	v_mfma_f32_16x16x32_bf16 v[28:31], v[174:177], v[228:231], v[28:31]
	v_mfma_f32_16x16x32_bf16 v[20:23], v[204:207], v[228:231], v[20:23]
	v_mfma_f32_16x16x32_bf16 v[12:15], v[174:177], v[236:239], v[12:15]
	v_mfma_f32_16x16x32_bf16 v[4:7], v[204:207], v[236:239], v[4:7]
	v_mfma_f32_16x16x32_bf16 v[60:63], v[178:181], v[216:219], v[60:63]
	v_mfma_f32_16x16x32_bf16 v[52:55], v[208:211], v[216:219], v[52:55]
	v_mfma_f32_16x16x32_bf16 v[44:47], v[178:181], v[224:227], v[44:47]
	v_mfma_f32_16x16x32_bf16 v[36:39], v[208:211], v[224:227], v[36:39]
	v_mfma_f32_16x16x32_bf16 v[28:31], v[178:181], v[232:235], v[28:31]
	v_mfma_f32_16x16x32_bf16 v[20:23], v[208:211], v[232:235], v[20:23]
	v_mfma_f32_16x16x32_bf16 v[12:15], v[178:181], v[240:243], v[12:15]
	v_mfma_f32_16x16x32_bf16 v[4:7], v[208:211], v[240:243], v[4:7]
	s_setprio 0
	s_barrier
	s_add_i32 s60, s60, 2
	s_add_u32 s36, s36, 0x100
	s_addc_u32 s37, s37, 0
	s_add_u32 s58, s58, 0x100
	s_addc_u32 s59, s59, 0
	s_cmp_gt_u32 s60, 29
	s_cbranch_scc0 .LBB0_301
	s_and_b64 vcc, exec, s[8:9]
	s_cbranch_vccz .LBB0_304
	s_barrier

; #define PG8_STAGE(bufoff, gbase, voff) do { _Pragma("unroll") for (int _i = 0; _i < 2; ++_i) \
;         __builtin_amdgcn_global_load_lds((const unsigned*)((const char*)(gbase) + (voff)[_i]), (PG8_LAS unsigned*)(lds + (bufoff) + ldsw + _i * 8192), 16, 0, 0); } while (0)
; #define PG8_LDA(dst, b, h) do { _Pragma("unroll") for (int m = 0; m < 4; ++m) _Pragma("unroll") for (int k = 0; k < 2; ++k) dst[m][k] = *(const PG8_LAS bf16x8*)(lds + PG8_SA(b, h) + aoff + m * 2048 + k * 1024); } while (0)
; #define PG8_LDB(dst, b, h) do { _Pragma("unroll") for (int n = 0; n < 2; ++n) _Pragma("unroll") for (int k = 0; k < 2; ++k) dst[n][k] = *(const PG8_LAS bf16x8*)(lds + PG8_SB(b, h) + boff + n * 2048 + k * 1024); } while (0)
; #define PG8_MMA(ai, bj, At, Bt) do { __builtin_amdgcn_s_setprio(1); _Pragma("unroll") for (int m = 0; m < 4; ++m) _Pragma("unroll") for (int n = 0; n < 2; ++n) _Pragma("unroll") for (int k = 0; k < 2; ++k) \
;         acc[ai][bj][m][n] = __builtin_amdgcn_mfma_f32_16x16x32_bf16(Bt[n][k], At[m][k], acc[ai][bj][m][n], 0, 0, 0); __builtin_amdgcn_s_setprio(0); } while (0)
; #define PG8_WAIT_V(n) asm volatile("s_waitcnt vmcnt(" #n ")" ::: "memory")
; template <class Epi, class Sched, bool ALIGN_EPI = false, bool SP2 = false>
; __device__ __forceinline__ void gemm_phase(PG8_LAS unsigned char* lds, const Gemm g, const Sched& S, const Epi& E) {
;     ...
;         for (int t = 0; t < nt; t += 2) {
;             const bool last = (t == nt - 2);
;             const char* a1 = cA + (size_t)(t + 1) * kstep;
;             const char* a2 = last ? nA : cA + (size_t)(t + 2) * kstep; const char* b2 = last ? nB : cB + (size_t)(t + 2) * kstep;
;             const char* a3 = a2 + kstep; const char* b3 = b2 + kstep;
;             if (last && has_next) S.a_ready(nxt);
;             if constexpr (SP2) {
;             PG8_LDB(B0, 0, 0); PG8_LDB(B1, 0, 1); PG8_SCHED; PG8_LDA(At, 0, 0); PG8_STAGE(PG8_SA(1, 1), a1 + hstep, voffA);
;             PG8_WAIT_V(8); PG8_WAIT_L(0); PG8_BAR; PG8_MMA(0, 0, At, B0); PG8_MMA(0, 1, At, B1); PG8_BAR; PG8_SCHED;
;     ...
;         if (zero_acc) {
; #pragma unroll
;         for (int a = 0; a < 2; ++a)
; #pragma unroll
;             for (int b = 0; b < 2; ++b)
; #pragma unroll
;                 for (int m = 0; m < 4; ++m)
; #pragma unroll
;                     for (int n = 0; n < 2; ++n) acc[a][b][m][n] = (f32x4){0.f, 0.f, 0.f, 0.f};
.LBB0_574:
	s_add_u32 s61, s36, 0x100
	v_mov_b32_e32 v4, 0
	s_addc_u32 s62, s37, 0
	s_mov_b32 s63, -2
	s_waitcnt lgkmcnt(0)
	v_mov_b32_e32 v5, v4
	v_mov_b32_e32 v6, v4
	v_mov_b32_e32 v7, v4
	v_mov_b32_e32 v8, v4
	v_mov_b32_e32 v9, v4
	v_mov_b32_e32 v10, v4
	v_mov_b32_e32 v11, v4
	v_mov_b32_e32 v20, v4
	v_mov_b32_e32 v21, v4
	s_waitcnt vmcnt(0)
	v_mov_b32_e32 v22, v4
	v_mov_b32_e32 v23, v4
	v_mov_b32_e32 v24, v4
	v_mov_b32_e32 v25, v4
	v_mov_b32_e32 v26, v4
	v_mov_b32_e32 v27, v4
	v_mov_b32_e32 v36, v4
	v_mov_b32_e32 v37, v4
	v_mov_b32_e32 v38, v4
	v_mov_b32_e32 v39, v4
	v_mov_b32_e32 v40, v4
	v_mov_b32_e32 v41, v4
	v_mov_b32_e32 v42, v4
	v_mov_b32_e32 v43, v4
	v_mov_b32_e32 v52, v4
	v_mov_b32_e32 v53, v4
	v_mov_b32_e32 v54, v4
	v_mov_b32_e32 v55, v4
	v_mov_b32_e32 v56, v4
	v_mov_b32_e32 v57, v4
	v_mov_b32_e32 v58, v4
	v_mov_b32_e32 v59, v4
	v_mov_b32_e32 v12, v4
	v_mov_b32_e32 v13, v4
	v_mov_b32_e32 v14, v4
	v_mov_b32_e32 v15, v4
	v_mov_b32_e32 v16, v4
	v_mov_b32_e32 v17, v4
	v_mov_b32_e32 v18, v4
	v_mov_b32_e32 v19, v4
	v_mov_b32_e32 v28, v4
	v_mov_b32_e32 v29, v4
	v_mov_b32_e32 v30, v4
	v_mov_b32_e32 v31, v4
	v_mov_b32_e32 v32, v4
	v_mov_b32_e32 v33, v4
	v_mov_b32_e32 v34, v4
	v_mov_b32_e32 v35, v4
	v_mov_b32_e32 v44, v4
	v_mov_b32_e32 v45, v4
	v_mov_b32_e32 v46, v4
	v_mov_b32_e32 v47, v4
	v_mov_b32_e32 v48, v4
	v_mov_b32_e32 v49, v4
	v_mov_b32_e32 v50, v4
	v_mov_b32_e32 v51, v4
	v_mov_b32_e32 v60, v4
	v_mov_b32_e32 v61, v4
	v_mov_b32_e32 v62, v4
	v_mov_b32_e32 v63, v4
	v_mov_b32_e32 v64, v4
	v_mov_b32_e32 v65, v4
	v_mov_b32_e32 v66, v4
	v_mov_b32_e32 v67, v4
	v_mov_b32_e32 v68, v4
	v_mov_b32_e32 v69, v4
	v_mov_b32_e32 v70, v4
	v_mov_b32_e32 v71, v4
	v_mov_b32_e32 v72, v4
	v_mov_b32_e32 v73, v4
	v_mov_b32_e32 v74, v4
	v_mov_b32_e32 v75, v4
	v_mov_b32_e32 v84, v4
	v_mov_b32_e32 v85, v4
	v_mov_b32_e32 v86, v4
	v_mov_b32_e32 v87, v4
	v_mov_b32_e32 v88, v4
	v_mov_b32_e32 v89, v4
	v_mov_b32_e32 v90, v4
	v_mov_b32_e32 v91, v4
	v_mov_b32_e32 v100, v4
	v_mov_b32_e32 v101, v4
	v_mov_b32_e32 v102, v4
	v_mov_b32_e32 v103, v4
	v_mov_b32_e32 v104, v4
	v_mov_b32_e32 v105, v4
	v_mov_b32_e32 v106, v4
	v_mov_b32_e32 v107, v4
	v_mov_b32_e32 v116, v4
	v_mov_b32_e32 v117, v4
	v_mov_b32_e32 v118, v4
	v_mov_b32_e32 v119, v4
	v_mov_b32_e32 v120, v4
	v_mov_b32_e32 v121, v4
	v_mov_b32_e32 v122, v4
	v_mov_b32_e32 v123, v4
	v_mov_b32_e32 v76, v4
	v_mov_b32_e32 v77, v4
	v_mov_b32_e32 v78, v4
	v_mov_b32_e32 v79, v4
	v_mov_b32_e32 v80, v4
	v_mov_b32_e32 v81, v4
	v_mov_b32_e32 v82, v4
	v_mov_b32_e32 v83, v4
	v_mov_b32_e32 v92, v4
	v_mov_b32_e32 v93, v4
	v_mov_b32_e32 v94, v4
	v_mov_b32_e32 v95, v4
	v_mov_b32_e32 v96, v4
	v_mov_b32_e32 v97, v4
	v_mov_b32_e32 v98, v4
	v_mov_b32_e32 v99, v4
	v_mov_b32_e32 v108, v4
	v_mov_b32_e32 v109, v4
	v_mov_b32_e32 v110, v4
	v_mov_b32_e32 v111, v4
	v_mov_b32_e32 v112, v4
	v_mov_b32_e32 v113, v4
	v_mov_b32_e32 v114, v4
	v_mov_b32_e32 v115, v4
	v_mov_b32_e32 v124, v4
	v_mov_b32_e32 v125, v4
	v_mov_b32_e32 v126, v4
	v_mov_b32_e32 v127, v4
	v_mov_b32_e32 v128, v4
	v_mov_b32_e32 v129, v4
	v_mov_b32_e32 v130, v4
	v_mov_b32_e32 v131, v4
	.p2align 6
	s_nop 0
.LBB0_575:
	s_add_u32 s36, s34, 0x100
	s_addc_u32 s37, s35, 0
	s_add_i32 s64, 0, 0x10000
	s_cmpk_eq_i32 s63, 0x52
	s_cselect_b32 s41, s5, s37
	s_cselect_b32 s40, s4, s36
	v_add_u32_e32 v135, s64, v173
	s_cselect_b32 s39, s31, s62
	s_cselect_b32 s38, s30, s61
	s_add_i32 s65, 0, 0x14000
	ds_read_b128 v[142:145], v135
	ds_read_b128 v[146:149], v135 offset:1024
	ds_read_b128 v[150:153], v135 offset:2048
	ds_read_b128 v[154:157], v135 offset:3072
	v_add_u32_e32 v135, s65, v173
	ds_read_b128 v[158:161], v135
	ds_read_b128 v[174:177], v135 offset:1024
	ds_read_b128 v[180:183], v135 offset:2048
	ds_read_b128 v[204:207], v135 offset:3072
	v_lshl_add_u64 v[162:163], s[34:35], 0, v[138:139]
	s_add_i32 m0, s47, 0xc000
	ds_read_b128 v[208:211], v179
	ds_read_b128 v[212:215], v179 offset:1024
	ds_read_b128 v[216:219], v179 offset:2048
	ds_read_b128 v[220:223], v179 offset:3072
	ds_read_b128 v[224:227], v179 offset:4096
	ds_read_b128 v[228:231], v179 offset:5120
	ds_read_b128 v[232:235], v179 offset:6144
	ds_read_b128 v[236:239], v179 offset:7168
	global_load_lds_dwordx4 v[162:163], off
	v_lshl_add_u64 v[162:163], s[34:35], 0, v[140:141]
	s_add_i32 m0, s47, 0xe000
	s_nop 0
	global_load_lds_dwordx4 v[162:163], off
	s_waitcnt vmcnt(8)
	s_waitcnt lgkmcnt(0)
	s_barrier
	s_setprio 1
	s_waitcnt lgkmcnt(0)
	v_mfma_f32_16x16x32_bf16 v[128:131], v[142:145], v[208:211], v[128:131]
	v_mfma_f32_16x16x32_bf16 v[124:127], v[150:153], v[208:211], v[124:127]
	v_mfma_f32_16x16x32_bf16 v[112:115], v[142:145], v[216:219], v[112:115]
	v_mfma_f32_16x16x32_bf16 v[108:111], v[150:153], v[216:219], v[108:111]
	v_mfma_f32_16x16x32_bf16 v[96:99], v[142:145], v[224:227], v[96:99]
	v_mfma_f32_16x16x32_bf16 v[92:95], v[150:153], v[224:227], v[92:95]
	v_mfma_f32_16x16x32_bf16 v[80:83], v[142:145], v[232:235], v[80:83]
	v_mfma_f32_16x16x32_bf16 v[76:79], v[150:153], v[232:235], v[76:79]
	v_mfma_f32_16x16x32_bf16 v[128:131], v[146:149], v[212:215], v[128:131]
	v_mfma_f32_16x16x32_bf16 v[124:127], v[154:157], v[212:215], v[124:127]
	v_mfma_f32_16x16x32_bf16 v[112:115], v[146:149], v[220:223], v[112:115]
	v_mfma_f32_16x16x32_bf16 v[108:111], v[154:157], v[220:223], v[108:111]
	v_mfma_f32_16x16x32_bf16 v[96:99], v[146:149], v[228:231], v[96:99]
	v_mfma_f32_16x16x32_bf16 v[92:95], v[154:157], v[228:231], v[92:95]
	v_mfma_f32_16x16x32_bf16 v[80:83], v[146:149], v[236:239], v[80:83]
	v_mfma_f32_16x16x32_bf16 v[76:79], v[154:157], v[236:239], v[76:79]
	s_setprio 0
	s_setprio 1
	v_mfma_f32_16x16x32_bf16 v[120:123], v[158:161], v[208:211], v[120:123]
	v_mfma_f32_16x16x32_bf16 v[116:119], v[180:183], v[208:211], v[116:119]
	v_mfma_f32_16x16x32_bf16 v[104:107], v[158:161], v[216:219], v[104:107]
	v_mfma_f32_16x16x32_bf16 v[100:103], v[180:183], v[216:219], v[100:103]
	v_mfma_f32_16x16x32_bf16 v[88:91], v[158:161], v[224:227], v[88:91]
	v_mfma_f32_16x16x32_bf16 v[84:87], v[180:183], v[224:227], v[84:87]
	v_mfma_f32_16x16x32_bf16 v[72:75], v[158:161], v[232:235], v[72:75]
	v_mfma_f32_16x16x32_bf16 v[68:71], v[180:183], v[232:235], v[68:71]
	v_mfma_f32_16x16x32_bf16 v[120:123], v[174:177], v[212:215], v[120:123]
	v_mfma_f32_16x16x32_bf16 v[116:119], v[204:207], v[212:215], v[116:119]
	v_mfma_f32_16x16x32_bf16 v[104:107], v[174:177], v[220:223], v[104:107]
	v_mfma_f32_16x16x32_bf16 v[100:103], v[204:207], v[220:223], v[100:103]
	v_mfma_f32_16x16x32_bf16 v[88:91], v[174:177], v[228:231], v[88:91]
	v_mfma_f32_16x16x32_bf16 v[84:87], v[204:207], v[228:231], v[84:87]
	v_mfma_f32_16x16x32_bf16 v[72:75], v[174:177], v[236:239], v[72:75]
	v_mfma_f32_16x16x32_bf16 v[68:71], v[204:207], v[236:239], v[68:71]
	s_setprio 0
	s_barrier
; #define PG8_STAGE(bufoff, gbase, voff) do { _Pragma("unroll") for (int _i = 0; _i < 2; ++_i) \
;         __builtin_amdgcn_global_load_lds((const unsigned*)((const char*)(gbase) + (voff)[_i]), (PG8_LAS unsigned*)(lds + (bufoff) + ldsw + _i * 8192), 16, 0, 0); } while (0)
; #define PG8_LDA(dst, b, h) do { _Pragma("unroll") for (int m = 0; m < 4; ++m) _Pragma("unroll") for (int k = 0; k < 2; ++k) dst[m][k] = *(const PG8_LAS bf16x8*)(lds + PG8_SA(b, h) + aoff + m * 2048 + k * 1024); } while (0)
; #define PG8_LDB(dst, b, h) do { _Pragma("unroll") for (int n = 0; n < 2; ++n) _Pragma("unroll") for (int k = 0; k < 2; ++k) dst[n][k] = *(const PG8_LAS bf16x8*)(lds + PG8_SB(b, h) + boff + n * 2048 + k * 1024); } while (0)
; #define PG8_MMA(ai, bj, At, Bt) do { __builtin_amdgcn_s_setprio(1); _Pragma("unroll") for (int m = 0; m < 4; ++m) _Pragma("unroll") for (int n = 0; n < 2; ++n) _Pragma("unroll") for (int k = 0; k < 2; ++k) \
;         acc[ai][bj][m][n] = __builtin_amdgcn_mfma_f32_16x16x32_bf16(Bt[n][k], At[m][k], acc[ai][bj][m][n], 0, 0, 0); __builtin_amdgcn_s_setprio(0); } while (0)
; #define PG8_WAIT_V(n) asm volatile("s_waitcnt vmcnt(" #n ")" ::: "memory")
; #define PG8_WAIT_L(n) asm volatile("s_waitcnt lgkmcnt(" #n ")" ::: "memory")
; #define PG8_BAR __builtin_amdgcn_s_barrier()
; #define PG8_SCHED __builtin_amdgcn_sched_barrier(0)
; template <class Epi, class Sched, bool ALIGN_EPI = false, bool SP2 = false>
; __device__ __forceinline__ void gemm_phase(PG8_LAS unsigned char* lds, const Gemm g, const Sched& S, const Epi& E) {
;     ...
;             PG8_WAIT_V(8); PG8_WAIT_L(0); PG8_BAR; PG8_MMA(0, 0, At, B0); PG8_MMA(0, 1, At, B1); PG8_BAR; PG8_SCHED;
;             PG8_LDA(At, 0, 1); PG8_STAGE(PG8_SB(0, 0), b2, voffB); PG8_STAGE(PG8_SB(0, 1), b2 + hstep, voffB); PG8_STAGE(PG8_SA(0, 0), a2, voffA);
;             PG8_WAIT_V(8); PG8_WAIT_L(0); PG8_BAR; PG8_MMA(1, 0, At, B0); PG8_MMA(1, 1, At, B1); PG8_BAR; PG8_SCHED;
;             PG8_LDB(B0, 1, 0); PG8_LDB(B1, 1, 1); PG8_SCHED; PG8_LDA(At, 1, 0); PG8_STAGE(PG8_SA(0, 1), a2 + hstep, voffA);
;             PG8_WAIT_V(8); PG8_WAIT_L(0); PG8_BAR; PG8_MMA(0, 0, At, B0); PG8_MMA(0, 1, At, B1); PG8_BAR; PG8_SCHED;
	s_add_i32 s34, s64, s46
	s_mov_b32 m0, s34
	ds_read_b128 v[208:211], v179 offset:16384
	ds_read_b128 v[212:215], v179 offset:17408
	ds_read_b128 v[216:219], v179 offset:18432
	ds_read_b128 v[220:223], v179 offset:19456
	ds_read_b128 v[224:227], v179 offset:20480
	ds_read_b128 v[228:231], v179 offset:21504
	ds_read_b128 v[232:235], v179 offset:22528
	ds_read_b128 v[236:239], v179 offset:23552
	global_load_lds_dwordx4 v2, s[38:39]
	s_add_i32 m0, s34, 0x2000
	s_add_u32 s34, s38, 0x158000
	s_addc_u32 s35, s39, 0
	s_add_i32 s64, s65, s46
	global_load_lds_dwordx4 v132, s[38:39]
	s_mov_b32 m0, s64
	s_nop 0
	global_load_lds_dwordx4 v2, s[34:35]
	s_add_i32 m0, s64, 0x2000
	s_nop 0
	global_load_lds_dwordx4 v132, s[34:35]
	s_mov_b32 m0, s47
	s_nop 0
	global_load_lds_dwordx4 v2, s[40:41]
	s_mov_b32 m0, s48
	s_nop 0
	global_load_lds_dwordx4 v132, s[40:41]
	s_waitcnt vmcnt(8)
	s_waitcnt lgkmcnt(0)
	s_barrier
	s_setprio 1
	s_waitcnt lgkmcnt(0)
	v_mfma_f32_16x16x32_bf16 v[64:67], v[142:145], v[208:211], v[64:67]
	v_mfma_f32_16x16x32_bf16 v[60:63], v[150:153], v[208:211], v[60:63]
	v_mfma_f32_16x16x32_bf16 v[48:51], v[142:145], v[216:219], v[48:51]
	v_mfma_f32_16x16x32_bf16 v[44:47], v[150:153], v[216:219], v[44:47]
	v_mfma_f32_16x16x32_bf16 v[32:35], v[142:145], v[224:227], v[32:35]
	v_mfma_f32_16x16x32_bf16 v[28:31], v[150:153], v[224:227], v[28:31]
	v_mfma_f32_16x16x32_bf16 v[16:19], v[142:145], v[232:235], v[16:19]
	v_mfma_f32_16x16x32_bf16 v[12:15], v[150:153], v[232:235], v[12:15]
	v_mfma_f32_16x16x32_bf16 v[64:67], v[146:149], v[212:215], v[64:67]
	v_mfma_f32_16x16x32_bf16 v[60:63], v[154:157], v[212:215], v[60:63]
	v_mfma_f32_16x16x32_bf16 v[48:51], v[146:149], v[220:223], v[48:51]
	v_mfma_f32_16x16x32_bf16 v[44:47], v[154:157], v[220:223], v[44:47]
	v_mfma_f32_16x16x32_bf16 v[32:35], v[146:149], v[228:231], v[32:35]
	v_mfma_f32_16x16x32_bf16 v[28:31], v[154:157], v[228:231], v[28:31]
	v_mfma_f32_16x16x32_bf16 v[16:19], v[146:149], v[236:239], v[16:19]
	v_mfma_f32_16x16x32_bf16 v[12:15], v[154:157], v[236:239], v[12:15]
	s_setprio 0
	s_setprio 1
	v_mfma_f32_16x16x32_bf16 v[56:59], v[158:161], v[208:211], v[56:59]
	v_mfma_f32_16x16x32_bf16 v[52:55], v[180:183], v[208:211], v[52:55]
	v_mfma_f32_16x16x32_bf16 v[40:43], v[158:161], v[216:219], v[40:43]
	v_mfma_f32_16x16x32_bf16 v[36:39], v[180:183], v[216:219], v[36:39]
	v_mfma_f32_16x16x32_bf16 v[24:27], v[158:161], v[224:227], v[24:27]
	v_mfma_f32_16x16x32_bf16 v[20:23], v[180:183], v[224:227], v[20:23]
	v_mfma_f32_16x16x32_bf16 v[8:11], v[158:161], v[232:235], v[8:11]
	v_mfma_f32_16x16x32_bf16 v[4:7], v[180:183], v[232:235], v[4:7]
	v_mfma_f32_16x16x32_bf16 v[56:59], v[174:177], v[212:215], v[56:59]
	v_mfma_f32_16x16x32_bf16 v[52:55], v[204:207], v[212:215], v[52:55]
	v_mfma_f32_16x16x32_bf16 v[40:43], v[174:177], v[220:223], v[40:43]
	v_mfma_f32_16x16x32_bf16 v[36:39], v[204:207], v[220:223], v[36:39]
	v_mfma_f32_16x16x32_bf16 v[24:27], v[174:177], v[228:231], v[24:27]
	v_mfma_f32_16x16x32_bf16 v[20:23], v[204:207], v[228:231], v[20:23]
	v_mfma_f32_16x16x32_bf16 v[8:11], v[174:177], v[236:239], v[8:11]
	v_mfma_f32_16x16x32_bf16 v[4:7], v[204:207], v[236:239], v[4:7]
	s_setprio 0
	s_barrier
	s_add_i32 s64, 0, 0x18000
	v_add_u32_e32 v135, s64, v173
	s_add_i32 s65, 0, 0x1c000
	ds_read_b128 v[142:145], v135
	ds_read_b128 v[146:149], v135 offset:1024
	ds_read_b128 v[150:153], v135 offset:2048
	ds_read_b128 v[154:157], v135 offset:3072
	v_add_u32_e32 v135, s65, v173
	ds_read_b128 v[158:161], v135
	ds_read_b128 v[174:177], v135 offset:1024
	ds_read_b128 v[180:183], v135 offset:2048
	ds_read_b128 v[204:207], v135 offset:3072
	s_add_u32 s34, s40, 0x158000
	s_addc_u32 s35, s41, 0
	s_mov_b32 m0, s49
	ds_read_b128 v[208:211], v179 offset:32768
	ds_read_b128 v[212:215], v179 offset:33792
	ds_read_b128 v[216:219], v179 offset:34816
	ds_read_b128 v[220:223], v179 offset:35840
	ds_read_b128 v[224:227], v179 offset:36864
	ds_read_b128 v[228:231], v179 offset:37888
	ds_read_b128 v[232:235], v179 offset:38912
	ds_read_b128 v[236:239], v179 offset:39936
	global_load_lds_dwordx4 v2, s[34:35]
	s_mov_b32 m0, s50
	s_nop 0
	global_load_lds_dwordx4 v132, s[34:35]
	s_nop 0
	s_waitcnt vmcnt(8)
	s_waitcnt lgkmcnt(0)
	s_barrier
; #define PG8_STAGE(bufoff, gbase, voff) do { _Pragma("unroll") for (int _i = 0; _i < 2; ++_i) \
;         __builtin_amdgcn_global_load_lds((const unsigned*)((const char*)(gbase) + (voff)[_i]), (PG8_LAS unsigned*)(lds + (bufoff) + ldsw + _i * 8192), 16, 0, 0); } while (0)
; #define PG8_LDA(dst, b, h) do { _Pragma("unroll") for (int m = 0; m < 4; ++m) _Pragma("unroll") for (int k = 0; k < 2; ++k) dst[m][k] = *(const PG8_LAS bf16x8*)(lds + PG8_SA(b, h) + aoff + m * 2048 + k * 1024); } while (0)
; #define PG8_MMA(ai, bj, At, Bt) do { __builtin_amdgcn_s_setprio(1); _Pragma("unroll") for (int m = 0; m < 4; ++m) _Pragma("unroll") for (int n = 0; n < 2; ++n) _Pragma("unroll") for (int k = 0; k < 2; ++k) \
;         acc[ai][bj][m][n] = __builtin_amdgcn_mfma_f32_16x16x32_bf16(Bt[n][k], At[m][k], acc[ai][bj][m][n], 0, 0, 0); __builtin_amdgcn_s_setprio(0); } while (0)
; #define PG8_WAIT_V(n) asm volatile("s_waitcnt vmcnt(" #n ")" ::: "memory")
; #define PG8_WAIT_L(n) asm volatile("s_waitcnt lgkmcnt(" #n ")" ::: "memory")
; #define PG8_BAR __builtin_amdgcn_s_barrier()
; #define PG8_SCHED __builtin_amdgcn_sched_barrier(0)
; template <class Epi, class Sched, bool ALIGN_EPI = false, bool SP2 = false>
; __device__ __forceinline__ void gemm_phase(PG8_LAS unsigned char* lds, const Gemm g, const Sched& S, const Epi& E) {
;     ...
;             PG8_WAIT_V(8); PG8_WAIT_L(0); PG8_BAR; PG8_MMA(0, 0, At, B0); PG8_MMA(0, 1, At, B1); PG8_BAR; PG8_SCHED;
;             PG8_LDA(At, 1, 1); PG8_STAGE(PG8_SB(1, 0), b3, voffB); PG8_STAGE(PG8_SB(1, 1), b3 + hstep, voffB); PG8_STAGE(PG8_SA(1, 0), a3, voffA);
;             PG8_WAIT_V(8); PG8_WAIT_L(0); PG8_BAR; PG8_MMA(1, 0, At, B0); PG8_MMA(1, 1, At, B1); PG8_BAR; PG8_SCHED;
	s_setprio 1
	s_waitcnt lgkmcnt(0)
	v_mfma_f32_16x16x32_bf16 v[128:131], v[142:145], v[208:211], v[128:131]
	v_mfma_f32_16x16x32_bf16 v[124:127], v[150:153], v[208:211], v[124:127]
	v_mfma_f32_16x16x32_bf16 v[112:115], v[142:145], v[216:219], v[112:115]
	v_mfma_f32_16x16x32_bf16 v[108:111], v[150:153], v[216:219], v[108:111]
	v_mfma_f32_16x16x32_bf16 v[96:99], v[142:145], v[224:227], v[96:99]
	v_mfma_f32_16x16x32_bf16 v[92:95], v[150:153], v[224:227], v[92:95]
	v_mfma_f32_16x16x32_bf16 v[80:83], v[142:145], v[232:235], v[80:83]
	v_mfma_f32_16x16x32_bf16 v[76:79], v[150:153], v[232:235], v[76:79]
	v_mfma_f32_16x16x32_bf16 v[128:131], v[146:149], v[212:215], v[128:131]
	v_mfma_f32_16x16x32_bf16 v[124:127], v[154:157], v[212:215], v[124:127]
	v_mfma_f32_16x16x32_bf16 v[112:115], v[146:149], v[220:223], v[112:115]
	v_mfma_f32_16x16x32_bf16 v[108:111], v[154:157], v[220:223], v[108:111]
	v_mfma_f32_16x16x32_bf16 v[96:99], v[146:149], v[228:231], v[96:99]
	v_mfma_f32_16x16x32_bf16 v[92:95], v[154:157], v[228:231], v[92:95]
	v_mfma_f32_16x16x32_bf16 v[80:83], v[146:149], v[236:239], v[80:83]
	v_mfma_f32_16x16x32_bf16 v[76:79], v[154:157], v[236:239], v[76:79]
	s_setprio 0
	s_setprio 1
	v_mfma_f32_16x16x32_bf16 v[120:123], v[158:161], v[208:211], v[120:123]
	v_mfma_f32_16x16x32_bf16 v[116:119], v[180:183], v[208:211], v[116:119]
	v_mfma_f32_16x16x32_bf16 v[104:107], v[158:161], v[216:219], v[104:107]
	v_mfma_f32_16x16x32_bf16 v[100:103], v[180:183], v[216:219], v[100:103]
	v_mfma_f32_16x16x32_bf16 v[88:91], v[158:161], v[224:227], v[88:91]
	v_mfma_f32_16x16x32_bf16 v[84:87], v[180:183], v[224:227], v[84:87]
	v_mfma_f32_16x16x32_bf16 v[72:75], v[158:161], v[232:235], v[72:75]
	v_mfma_f32_16x16x32_bf16 v[68:71], v[180:183], v[232:235], v[68:71]
	v_mfma_f32_16x16x32_bf16 v[120:123], v[174:177], v[212:215], v[120:123]
	v_mfma_f32_16x16x32_bf16 v[116:119], v[204:207], v[212:215], v[116:119]
	v_mfma_f32_16x16x32_bf16 v[104:107], v[174:177], v[220:223], v[104:107]
	v_mfma_f32_16x16x32_bf16 v[100:103], v[204:207], v[220:223], v[100:103]
	v_mfma_f32_16x16x32_bf16 v[88:91], v[174:177], v[228:231], v[88:91]
	v_mfma_f32_16x16x32_bf16 v[84:87], v[204:207], v[228:231], v[84:87]
	v_mfma_f32_16x16x32_bf16 v[72:75], v[174:177], v[236:239], v[72:75]
	v_mfma_f32_16x16x32_bf16 v[68:71], v[204:207], v[236:239], v[68:71]
	s_setprio 0
	s_barrier
	s_add_i32 s34, s64, s46
	s_add_i32 m0, s34, 0xffffff80
	ds_read_b128 v[208:211], v179 offset:49152
	ds_read_b128 v[212:215], v179 offset:50176
	ds_read_b128 v[216:219], v179 offset:51200
	ds_read_b128 v[220:223], v179 offset:52224
	ds_read_b128 v[224:227], v179 offset:53248
	ds_read_b128 v[228:231], v179 offset:54272
	ds_read_b128 v[232:235], v179 offset:55296
	ds_read_b128 v[236:239], v179 offset:56320
	global_load_lds_dwordx4 v2, s[38:39] offset:128
	s_add_i32 m0, s34, 0x1f80
	s_add_u32 s34, s38, 0x158080
	s_addc_u32 s35, s39, 0
	global_load_lds_dwordx4 v132, s[38:39] offset:128
	s_add_i32 s38, s65, s46
	s_mov_b32 m0, s38
	s_nop 0
	global_load_lds_dwordx4 v2, s[34:35]
	s_add_i32 m0, s38, 0x2000
	s_nop 0
	global_load_lds_dwordx4 v132, s[34:35]
	s_add_i32 m0, s53, 0xffffff80
	s_nop 0
	global_load_lds_dwordx4 v2, s[40:41] offset:128
	s_add_i32 m0, s54, 0xffffff80
	s_nop 0
	global_load_lds_dwordx4 v132, s[40:41] offset:128
	s_nop 0
	s_waitcnt vmcnt(8)
	s_waitcnt lgkmcnt(0)
	s_barrier
	s_setprio 1
	s_waitcnt lgkmcnt(0)
	v_mfma_f32_16x16x32_bf16 v[64:67], v[142:145], v[208:211], v[64:67]
	v_mfma_f32_16x16x32_bf16 v[60:63], v[150:153], v[208:211], v[60:63]
	v_mfma_f32_16x16x32_bf16 v[48:51], v[142:145], v[216:219], v[48:51]
	v_mfma_f32_16x16x32_bf16 v[44:47], v[150:153], v[216:219], v[44:47]
	v_mfma_f32_16x16x32_bf16 v[32:35], v[142:145], v[224:227], v[32:35]
	v_mfma_f32_16x16x32_bf16 v[28:31], v[150:153], v[224:227], v[28:31]
	v_mfma_f32_16x16x32_bf16 v[16:19], v[142:145], v[232:235], v[16:19]
	v_mfma_f32_16x16x32_bf16 v[12:15], v[150:153], v[232:235], v[12:15]
	v_mfma_f32_16x16x32_bf16 v[64:67], v[146:149], v[212:215], v[64:67]
	v_mfma_f32_16x16x32_bf16 v[60:63], v[154:157], v[212:215], v[60:63]
	v_mfma_f32_16x16x32_bf16 v[48:51], v[146:149], v[220:223], v[48:51]
	v_mfma_f32_16x16x32_bf16 v[44:47], v[154:157], v[220:223], v[44:47]
	v_mfma_f32_16x16x32_bf16 v[32:35], v[146:149], v[228:231], v[32:35]
	v_mfma_f32_16x16x32_bf16 v[28:31], v[154:157], v[228:231], v[28:31]
	v_mfma_f32_16x16x32_bf16 v[16:19], v[146:149], v[236:239], v[16:19]
	v_mfma_f32_16x16x32_bf16 v[12:15], v[154:157], v[236:239], v[12:15]
	s_setprio 0
	s_setprio 1
	v_mfma_f32_16x16x32_bf16 v[56:59], v[158:161], v[208:211], v[56:59]
	v_mfma_f32_16x16x32_bf16 v[52:55], v[180:183], v[208:211], v[52:55]
	v_mfma_f32_16x16x32_bf16 v[40:43], v[158:161], v[216:219], v[40:43]
	v_mfma_f32_16x16x32_bf16 v[36:39], v[180:183], v[216:219], v[36:39]
	v_mfma_f32_16x16x32_bf16 v[24:27], v[158:161], v[224:227], v[24:27]
	v_mfma_f32_16x16x32_bf16 v[20:23], v[180:183], v[224:227], v[20:23]
	v_mfma_f32_16x16x32_bf16 v[8:11], v[158:161], v[232:235], v[8:11]
	v_mfma_f32_16x16x32_bf16 v[4:7], v[180:183], v[232:235], v[4:7]
	v_mfma_f32_16x16x32_bf16 v[56:59], v[174:177], v[212:215], v[56:59]
	v_mfma_f32_16x16x32_bf16 v[52:55], v[204:207], v[212:215], v[52:55]
	v_mfma_f32_16x16x32_bf16 v[40:43], v[174:177], v[220:223], v[40:43]
	v_mfma_f32_16x16x32_bf16 v[36:39], v[204:207], v[220:223], v[36:39]
	v_mfma_f32_16x16x32_bf16 v[24:27], v[174:177], v[228:231], v[24:27]
	v_mfma_f32_16x16x32_bf16 v[20:23], v[204:207], v[228:231], v[20:23]
	v_mfma_f32_16x16x32_bf16 v[8:11], v[174:177], v[236:239], v[8:11]
	v_mfma_f32_16x16x32_bf16 v[4:7], v[204:207], v[236:239], v[4:7]
	s_setprio 0
	s_barrier
	s_add_i32 s63, s63, 2
	s_add_u32 s61, s61, 0x100
	s_addc_u32 s62, s62, 0
	s_cmpk_gt_u32 s63, 0x53
	s_mov_b64 s[34:35], s[36:37]
	s_cbranch_scc0 .LBB0_575
	s_and_b64 vcc, exec, s[28:29]
	s_cbranch_vccz .LBB0_578
	s_barrier

; #define PG8_STAGE(bufoff, gbase, voff) do { _Pragma("unroll") for (int _i = 0; _i < 2; ++_i) \
;         __builtin_amdgcn_global_load_lds((const unsigned*)((const char*)(gbase) + (voff)[_i]), (PG8_LAS unsigned*)(lds + (bufoff) + ldsw + _i * 8192), 16, 0, 0); } while (0)
; #define PG8_LDA(dst, b, h) do { _Pragma("unroll") for (int m = 0; m < 4; ++m) _Pragma("unroll") for (int k = 0; k < 2; ++k) dst[m][k] = *(const PG8_LAS bf16x8*)(lds + PG8_SA(b, h) + aoff + m * 2048 + k * 1024); } while (0)
; #define PG8_LDB(dst, b, h) do { _Pragma("unroll") for (int n = 0; n < 2; ++n) _Pragma("unroll") for (int k = 0; k < 2; ++k) dst[n][k] = *(const PG8_LAS bf16x8*)(lds + PG8_SB(b, h) + boff + n * 2048 + k * 1024); } while (0)
; #define PG8_MMA(ai, bj, At, Bt) do { __builtin_amdgcn_s_setprio(1); _Pragma("unroll") for (int m = 0; m < 4; ++m) _Pragma("unroll") for (int n = 0; n < 2; ++n) _Pragma("unroll") for (int k = 0; k < 2; ++k) \
;         acc[ai][bj][m][n] = __builtin_amdgcn_mfma_f32_16x16x32_bf16(Bt[n][k], At[m][k], acc[ai][bj][m][n], 0, 0, 0); __builtin_amdgcn_s_setprio(0); } while (0)
; #define PG8_WAIT_V(n) asm volatile("s_waitcnt vmcnt(" #n ")" ::: "memory")
; template <class Epi, class Sched, bool ALIGN_EPI = false, bool SP2 = false>
; __device__ __forceinline__ void gemm_phase(PG8_LAS unsigned char* lds, const Gemm g, const Sched& S, const Epi& E) {
;     ...
;         for (int t = 0; t < nt; t += 2) {
;             const bool last = (t == nt - 2);
;             const char* a1 = cA + (size_t)(t + 1) * kstep;
;             const char* a2 = last ? nA : cA + (size_t)(t + 2) * kstep; const char* b2 = last ? nB : cB + (size_t)(t + 2) * kstep;
;             const char* a3 = a2 + kstep; const char* b3 = b2 + kstep;
;             if (last && has_next) S.a_ready(nxt);
;             if constexpr (SP2) {
;             PG8_LDB(B0, 0, 0); PG8_LDB(B1, 0, 1); PG8_SCHED; PG8_LDA(At, 0, 0); PG8_STAGE(PG8_SA(1, 1), a1 + hstep, voffA);
;             PG8_WAIT_V(8); PG8_WAIT_L(0); PG8_BAR; PG8_MMA(0, 0, At, B0); PG8_MMA(0, 1, At, B1); PG8_BAR; PG8_SCHED;
;     ...
;         if (zero_acc) {
; #pragma unroll
;         for (int a = 0; a < 2; ++a)
; #pragma unroll
;             for (int b = 0; b < 2; ++b)
; #pragma unroll
;                 for (int m = 0; m < 4; ++m)
; #pragma unroll
;                     for (int n = 0; n < 2; ++n) acc[a][b][m][n] = (f32x4){0.f, 0.f, 0.f, 0.f};
.LBB0_673:
	s_add_u32 s40, s40, 0x80080
	s_addc_u32 s41, s41, 0
	s_add_u32 s35, s42, 0x100
	v_mov_b32_e32 v4, 0
	s_addc_u32 s62, s43, 0
	s_mov_b32 s63, -2
	v_mov_b32_e32 v5, v4
	v_mov_b32_e32 v6, v4
	v_mov_b32_e32 v7, v4
	v_mov_b32_e32 v8, v4
	v_mov_b32_e32 v9, v4
	v_mov_b32_e32 v10, v4
	v_mov_b32_e32 v11, v4
	v_mov_b32_e32 v16, v4
	v_mov_b32_e32 v17, v4
	v_mov_b32_e32 v18, v4
	v_mov_b32_e32 v19, v4
	v_mov_b32_e32 v24, v4
	v_mov_b32_e32 v25, v4
	v_mov_b32_e32 v26, v4
	v_mov_b32_e32 v27, v4
	v_mov_b32_e32 v32, v4
	v_mov_b32_e32 v33, v4
	v_mov_b32_e32 v34, v4
	v_mov_b32_e32 v35, v4
	v_mov_b32_e32 v40, v4
	v_mov_b32_e32 v41, v4
	v_mov_b32_e32 v42, v4
	v_mov_b32_e32 v43, v4
	v_mov_b32_e32 v48, v4
	v_mov_b32_e32 v49, v4
	v_mov_b32_e32 v50, v4
	v_mov_b32_e32 v51, v4
	v_mov_b32_e32 v56, v4
	v_mov_b32_e32 v57, v4
	v_mov_b32_e32 v58, v4
	v_mov_b32_e32 v59, v4
	v_mov_b32_e32 v12, v4
	v_mov_b32_e32 v13, v4
	v_mov_b32_e32 v14, v4
	v_mov_b32_e32 v15, v4
	v_mov_b32_e32 v20, v4
	v_mov_b32_e32 v21, v4
	v_mov_b32_e32 v22, v4
	v_mov_b32_e32 v23, v4
	v_mov_b32_e32 v28, v4
	v_mov_b32_e32 v29, v4
	v_mov_b32_e32 v30, v4
	v_mov_b32_e32 v31, v4
	v_mov_b32_e32 v36, v4
	v_mov_b32_e32 v37, v4
	v_mov_b32_e32 v38, v4
	v_mov_b32_e32 v39, v4
	v_mov_b32_e32 v44, v4
	v_mov_b32_e32 v45, v4
	v_mov_b32_e32 v46, v4
	v_mov_b32_e32 v47, v4
	v_mov_b32_e32 v52, v4
	v_mov_b32_e32 v53, v4
	v_mov_b32_e32 v54, v4
	v_mov_b32_e32 v55, v4
	v_mov_b32_e32 v60, v4
	v_mov_b32_e32 v61, v4
	v_mov_b32_e32 v62, v4
	v_mov_b32_e32 v63, v4
	v_mov_b32_e32 v64, v4
	v_mov_b32_e32 v65, v4
	v_mov_b32_e32 v66, v4
	v_mov_b32_e32 v67, v4
	v_mov_b32_e32 v68, v4
	v_mov_b32_e32 v69, v4
	v_mov_b32_e32 v70, v4
	v_mov_b32_e32 v71, v4
	v_mov_b32_e32 v72, v4
	v_mov_b32_e32 v73, v4
	v_mov_b32_e32 v74, v4
	v_mov_b32_e32 v75, v4
	v_mov_b32_e32 v80, v4
	v_mov_b32_e32 v81, v4
	v_mov_b32_e32 v82, v4
	v_mov_b32_e32 v83, v4
	v_mov_b32_e32 v88, v4
	v_mov_b32_e32 v89, v4
	v_mov_b32_e32 v90, v4
	v_mov_b32_e32 v91, v4
	v_mov_b32_e32 v96, v4
	v_mov_b32_e32 v97, v4
	v_mov_b32_e32 v98, v4
	v_mov_b32_e32 v99, v4
	v_mov_b32_e32 v104, v4
	v_mov_b32_e32 v105, v4
	v_mov_b32_e32 v106, v4
	v_mov_b32_e32 v107, v4
	v_mov_b32_e32 v112, v4
	v_mov_b32_e32 v113, v4
	v_mov_b32_e32 v114, v4
	v_mov_b32_e32 v115, v4
	v_mov_b32_e32 v120, v4
	v_mov_b32_e32 v121, v4
	v_mov_b32_e32 v122, v4
	v_mov_b32_e32 v123, v4
	v_mov_b32_e32 v76, v4
	v_mov_b32_e32 v77, v4
	v_mov_b32_e32 v78, v4
	v_mov_b32_e32 v79, v4
	v_mov_b32_e32 v84, v4
	v_mov_b32_e32 v85, v4
	v_mov_b32_e32 v86, v4
	v_mov_b32_e32 v87, v4
	v_mov_b32_e32 v92, v4
	v_mov_b32_e32 v93, v4
	v_mov_b32_e32 v94, v4
	v_mov_b32_e32 v95, v4
	v_mov_b32_e32 v100, v4
	v_mov_b32_e32 v101, v4
	v_mov_b32_e32 v102, v4
	v_mov_b32_e32 v103, v4
	v_mov_b32_e32 v108, v4
	v_mov_b32_e32 v109, v4
	v_mov_b32_e32 v110, v4
	v_mov_b32_e32 v111, v4
	v_mov_b32_e32 v116, v4
	v_mov_b32_e32 v117, v4
	v_mov_b32_e32 v118, v4
	v_mov_b32_e32 v119, v4
	v_mov_b32_e32 v124, v4
	v_mov_b32_e32 v125, v4
	v_mov_b32_e32 v126, v4
	v_mov_b32_e32 v127, v4
	v_mov_b32_e32 v128, v4
	v_mov_b32_e32 v129, v4
	v_mov_b32_e32 v130, v4
	v_mov_b32_e32 v131, v4
	.p2align 6
	s_nop 0
.LBB0_674:
	s_add_u32 s42, s40, 0xfff80080
	s_addc_u32 s43, s41, -1
	s_add_i32 s64, 0, 0x10000
	s_cmp_eq_u32 s63, 28
	s_cselect_b32 s45, s5, s43
	s_cselect_b32 s44, s4, s42
	s_cselect_b32 s43, s37, s62
	s_cselect_b32 s42, s36, s35
	s_add_i32 s66, 0, 0x14000
	v_add_u32_e32 v144, s64, v173
	v_add_u32_e32 v162, s66, v173
	ds_read_b128 v[132:135], v144
	ds_read_b128 v[136:139], v144 offset:1024
	ds_read_b128 v[140:143], v144 offset:2048
	ds_read_b128 v[144:147], v144 offset:3072
	ds_read_b128 v[158:161], v162
	ds_read_b128 v[174:177], v162 offset:1024
	ds_read_b128 v[206:209], v162 offset:2048
	ds_read_b128 v[210:213], v162 offset:3072
	s_add_i32 m0, s39, 0xc000
	ds_read_b128 v[214:217], v204
	ds_read_b128 v[218:221], v204 offset:1024
	ds_read_b128 v[222:225], v204 offset:2048
	ds_read_b128 v[226:229], v204 offset:3072
	ds_read_b128 v[230:233], v204 offset:4096
	ds_read_b128 v[234:237], v204 offset:5120
	ds_read_b128 v[238:241], v204 offset:6144
	ds_read_b128 v[242:245], v204 offset:7168
	global_load_lds_dwordx4 v154, s[40:41]
	s_add_i32 m0, s39, 0xe000
	s_nop 0
	global_load_lds_dwordx4 v156, s[40:41]
	s_waitcnt vmcnt(8)
	s_waitcnt lgkmcnt(0)
	s_barrier
	s_setprio 1
	s_waitcnt lgkmcnt(0)
	v_mfma_f32_16x16x32_bf16 v[128:131], v[132:135], v[214:217], v[128:131]
	v_mfma_f32_16x16x32_bf16 v[124:127], v[140:143], v[214:217], v[124:127]
	v_mfma_f32_16x16x32_bf16 v[116:119], v[132:135], v[222:225], v[116:119]
	v_mfma_f32_16x16x32_bf16 v[108:111], v[140:143], v[222:225], v[108:111]
	v_mfma_f32_16x16x32_bf16 v[100:103], v[132:135], v[230:233], v[100:103]
	v_mfma_f32_16x16x32_bf16 v[92:95], v[140:143], v[230:233], v[92:95]
	v_mfma_f32_16x16x32_bf16 v[84:87], v[132:135], v[238:241], v[84:87]
	v_mfma_f32_16x16x32_bf16 v[76:79], v[140:143], v[238:241], v[76:79]
	v_mfma_f32_16x16x32_bf16 v[128:131], v[136:139], v[218:221], v[128:131]
	v_mfma_f32_16x16x32_bf16 v[124:127], v[144:147], v[218:221], v[124:127]
	v_mfma_f32_16x16x32_bf16 v[116:119], v[136:139], v[226:229], v[116:119]
	v_mfma_f32_16x16x32_bf16 v[108:111], v[144:147], v[226:229], v[108:111]
	v_mfma_f32_16x16x32_bf16 v[100:103], v[136:139], v[234:237], v[100:103]
	v_mfma_f32_16x16x32_bf16 v[92:95], v[144:147], v[234:237], v[92:95]
	v_mfma_f32_16x16x32_bf16 v[84:87], v[136:139], v[242:245], v[84:87]
	v_mfma_f32_16x16x32_bf16 v[76:79], v[144:147], v[242:245], v[76:79]
	s_setprio 0
	s_setprio 1
	v_mfma_f32_16x16x32_bf16 v[120:123], v[158:161], v[214:217], v[120:123]
	v_mfma_f32_16x16x32_bf16 v[112:115], v[206:209], v[214:217], v[112:115]
	v_mfma_f32_16x16x32_bf16 v[104:107], v[158:161], v[222:225], v[104:107]
	v_mfma_f32_16x16x32_bf16 v[96:99], v[206:209], v[222:225], v[96:99]
	v_mfma_f32_16x16x32_bf16 v[88:91], v[158:161], v[230:233], v[88:91]
	v_mfma_f32_16x16x32_bf16 v[80:83], v[206:209], v[230:233], v[80:83]
	v_mfma_f32_16x16x32_bf16 v[72:75], v[158:161], v[238:241], v[72:75]
	v_mfma_f32_16x16x32_bf16 v[68:71], v[206:209], v[238:241], v[68:71]
	v_mfma_f32_16x16x32_bf16 v[120:123], v[174:177], v[218:221], v[120:123]
	v_mfma_f32_16x16x32_bf16 v[112:115], v[210:213], v[218:221], v[112:115]
	v_mfma_f32_16x16x32_bf16 v[104:107], v[174:177], v[226:229], v[104:107]
	v_mfma_f32_16x16x32_bf16 v[96:99], v[210:213], v[226:229], v[96:99]
	v_mfma_f32_16x16x32_bf16 v[88:91], v[174:177], v[234:237], v[88:91]
	v_mfma_f32_16x16x32_bf16 v[80:83], v[210:213], v[234:237], v[80:83]
	v_mfma_f32_16x16x32_bf16 v[72:75], v[174:177], v[242:245], v[72:75]
	v_mfma_f32_16x16x32_bf16 v[68:71], v[210:213], v[242:245], v[68:71]
	s_setprio 0
	s_barrier
; #define PG8_STAGE(bufoff, gbase, voff) do { _Pragma("unroll") for (int _i = 0; _i < 2; ++_i) \
;         __builtin_amdgcn_global_load_lds((const unsigned*)((const char*)(gbase) + (voff)[_i]), (PG8_LAS unsigned*)(lds + (bufoff) + ldsw + _i * 8192), 16, 0, 0); } while (0)
; #define PG8_LDA(dst, b, h) do { _Pragma("unroll") for (int m = 0; m < 4; ++m) _Pragma("unroll") for (int k = 0; k < 2; ++k) dst[m][k] = *(const PG8_LAS bf16x8*)(lds + PG8_SA(b, h) + aoff + m * 2048 + k * 1024); } while (0)
; #define PG8_LDB(dst, b, h) do { _Pragma("unroll") for (int n = 0; n < 2; ++n) _Pragma("unroll") for (int k = 0; k < 2; ++k) dst[n][k] = *(const PG8_LAS bf16x8*)(lds + PG8_SB(b, h) + boff + n * 2048 + k * 1024); } while (0)
; #define PG8_MMA(ai, bj, At, Bt) do { __builtin_amdgcn_s_setprio(1); _Pragma("unroll") for (int m = 0; m < 4; ++m) _Pragma("unroll") for (int n = 0; n < 2; ++n) _Pragma("unroll") for (int k = 0; k < 2; ++k) \
;         acc[ai][bj][m][n] = __builtin_amdgcn_mfma_f32_16x16x32_bf16(Bt[n][k], At[m][k], acc[ai][bj][m][n], 0, 0, 0); __builtin_amdgcn_s_setprio(0); } while (0)
; #define PG8_WAIT_V(n) asm volatile("s_waitcnt vmcnt(" #n ")" ::: "memory")
; #define PG8_WAIT_L(n) asm volatile("s_waitcnt lgkmcnt(" #n ")" ::: "memory")
; #define PG8_BAR __builtin_amdgcn_s_barrier()
; #define PG8_SCHED __builtin_amdgcn_sched_barrier(0)
; template <class Epi, class Sched, bool ALIGN_EPI = false, bool SP2 = false>
; __device__ __forceinline__ void gemm_phase(PG8_LAS unsigned char* lds, const Gemm g, const Sched& S, const Epi& E) {
;     ...
;             PG8_WAIT_V(8); PG8_WAIT_L(0); PG8_BAR; PG8_MMA(0, 0, At, B0); PG8_MMA(0, 1, At, B1); PG8_BAR; PG8_SCHED;
;             PG8_LDA(At, 0, 1); PG8_STAGE(PG8_SB(0, 0), b2, voffB); PG8_STAGE(PG8_SB(0, 1), b2 + hstep, voffB); PG8_STAGE(PG8_SA(0, 0), a2, voffA);
;             PG8_WAIT_V(8); PG8_WAIT_L(0); PG8_BAR; PG8_MMA(1, 0, At, B0); PG8_MMA(1, 1, At, B1); PG8_BAR; PG8_SCHED;
;             PG8_LDB(B0, 1, 0); PG8_LDB(B1, 1, 1); PG8_SCHED; PG8_LDA(At, 1, 0); PG8_STAGE(PG8_SA(0, 1), a2 + hstep, voffA);
	s_add_i32 s64, s64, s46
	s_mov_b32 m0, s64
	ds_read_b128 v[214:217], v204 offset:16384
	ds_read_b128 v[218:221], v204 offset:17408
	ds_read_b128 v[222:225], v204 offset:18432
	ds_read_b128 v[226:229], v204 offset:19456
	ds_read_b128 v[230:233], v204 offset:20480
	ds_read_b128 v[234:237], v204 offset:21504
	ds_read_b128 v[238:241], v204 offset:22528
	ds_read_b128 v[242:245], v204 offset:23552
	global_load_lds_dwordx4 v2, s[42:43]
	s_add_i32 m0, s64, 0x2000
	s_add_u32 s64, s42, 0x80000
	s_addc_u32 s65, s43, 0
	s_add_i32 s66, s66, s46
	global_load_lds_dwordx4 v148, s[42:43]
	s_mov_b32 m0, s66
	s_nop 0
	global_load_lds_dwordx4 v2, s[64:65]
	s_add_i32 m0, s66, 0x2000
	s_nop 0
	global_load_lds_dwordx4 v148, s[64:65]
	s_mov_b32 m0, s39
	s_nop 0
	global_load_lds_dwordx4 v152, s[44:45]
	s_mov_b32 m0, s51
	s_nop 0
	global_load_lds_dwordx4 v150, s[44:45]
	s_waitcnt vmcnt(8)
	s_waitcnt lgkmcnt(0)
	s_barrier
	s_setprio 1
	s_waitcnt lgkmcnt(0)
	v_mfma_f32_16x16x32_bf16 v[64:67], v[132:135], v[214:217], v[64:67]
	v_mfma_f32_16x16x32_bf16 v[60:63], v[140:143], v[214:217], v[60:63]
	v_mfma_f32_16x16x32_bf16 v[52:55], v[132:135], v[222:225], v[52:55]
	v_mfma_f32_16x16x32_bf16 v[44:47], v[140:143], v[222:225], v[44:47]
	v_mfma_f32_16x16x32_bf16 v[36:39], v[132:135], v[230:233], v[36:39]
	v_mfma_f32_16x16x32_bf16 v[28:31], v[140:143], v[230:233], v[28:31]
	v_mfma_f32_16x16x32_bf16 v[20:23], v[132:135], v[238:241], v[20:23]
	v_mfma_f32_16x16x32_bf16 v[12:15], v[140:143], v[238:241], v[12:15]
	v_mfma_f32_16x16x32_bf16 v[64:67], v[136:139], v[218:221], v[64:67]
	v_mfma_f32_16x16x32_bf16 v[60:63], v[144:147], v[218:221], v[60:63]
	v_mfma_f32_16x16x32_bf16 v[52:55], v[136:139], v[226:229], v[52:55]
	v_mfma_f32_16x16x32_bf16 v[44:47], v[144:147], v[226:229], v[44:47]
	v_mfma_f32_16x16x32_bf16 v[36:39], v[136:139], v[234:237], v[36:39]
	v_mfma_f32_16x16x32_bf16 v[28:31], v[144:147], v[234:237], v[28:31]
	v_mfma_f32_16x16x32_bf16 v[20:23], v[136:139], v[242:245], v[20:23]
	v_mfma_f32_16x16x32_bf16 v[12:15], v[144:147], v[242:245], v[12:15]
	s_setprio 0
	s_setprio 1
	v_mfma_f32_16x16x32_bf16 v[56:59], v[158:161], v[214:217], v[56:59]
	v_mfma_f32_16x16x32_bf16 v[48:51], v[206:209], v[214:217], v[48:51]
	v_mfma_f32_16x16x32_bf16 v[40:43], v[158:161], v[222:225], v[40:43]
	v_mfma_f32_16x16x32_bf16 v[32:35], v[206:209], v[222:225], v[32:35]
	v_mfma_f32_16x16x32_bf16 v[24:27], v[158:161], v[230:233], v[24:27]
	v_mfma_f32_16x16x32_bf16 v[16:19], v[206:209], v[230:233], v[16:19]
	v_mfma_f32_16x16x32_bf16 v[8:11], v[158:161], v[238:241], v[8:11]
	v_mfma_f32_16x16x32_bf16 v[4:7], v[206:209], v[238:241], v[4:7]
	v_mfma_f32_16x16x32_bf16 v[56:59], v[174:177], v[218:221], v[56:59]
	v_mfma_f32_16x16x32_bf16 v[48:51], v[210:213], v[218:221], v[48:51]
	v_mfma_f32_16x16x32_bf16 v[40:43], v[174:177], v[226:229], v[40:43]
	v_mfma_f32_16x16x32_bf16 v[32:35], v[210:213], v[226:229], v[32:35]
	v_mfma_f32_16x16x32_bf16 v[24:27], v[174:177], v[234:237], v[24:27]
	v_mfma_f32_16x16x32_bf16 v[16:19], v[210:213], v[234:237], v[16:19]
	v_mfma_f32_16x16x32_bf16 v[8:11], v[174:177], v[242:245], v[8:11]
	v_mfma_f32_16x16x32_bf16 v[4:7], v[210:213], v[242:245], v[4:7]
	s_setprio 0
	s_barrier
	s_add_i32 s64, 0, 0x18000
	s_add_i32 s65, 0, 0x1c000
	v_add_u32_e32 v144, s64, v173
	v_add_u32_e32 v164, s65, v173
	ds_read_b128 v[132:135], v144
	ds_read_b128 v[136:139], v144 offset:1024
	ds_read_b128 v[140:143], v144 offset:2048
	ds_read_b128 v[144:147], v144 offset:3072
	ds_read_b128 v[158:161], v164
	ds_read_b128 v[174:177], v164 offset:1024
	ds_read_b128 v[206:209], v164 offset:2048
	ds_read_b128 v[210:213], v164 offset:3072
	s_add_u32 s100, s44, 0x80
	s_addc_u32 s101, s45, 0
	s_add_u32 s44, s44, 0x80000
	s_addc_u32 s45, s45, 0
	s_mov_b32 m0, s52
	ds_read_b128 v[214:217], v204 offset:32768
	ds_read_b128 v[218:221], v204 offset:33792
	ds_read_b128 v[222:225], v204 offset:34816
	ds_read_b128 v[226:229], v204 offset:35840
	ds_read_b128 v[230:233], v204 offset:36864
	ds_read_b128 v[234:237], v204 offset:37888
	ds_read_b128 v[238:241], v204 offset:38912
	ds_read_b128 v[242:245], v204 offset:39936
	global_load_lds_dwordx4 v152, s[44:45]
	s_mov_b32 m0, s53
	s_nop 0
	global_load_lds_dwordx4 v150, s[44:45]
	s_waitcnt vmcnt(8)
	s_waitcnt lgkmcnt(0)
	s_barrier
; #define PG8_STAGE(bufoff, gbase, voff) do { _Pragma("unroll") for (int _i = 0; _i < 2; ++_i) \
;         __builtin_amdgcn_global_load_lds((const unsigned*)((const char*)(gbase) + (voff)[_i]), (PG8_LAS unsigned*)(lds + (bufoff) + ldsw + _i * 8192), 16, 0, 0); } while (0)
; #define PG8_LDA(dst, b, h) do { _Pragma("unroll") for (int m = 0; m < 4; ++m) _Pragma("unroll") for (int k = 0; k < 2; ++k) dst[m][k] = *(const PG8_LAS bf16x8*)(lds + PG8_SA(b, h) + aoff + m * 2048 + k * 1024); } while (0)
; #define PG8_MMA(ai, bj, At, Bt) do { __builtin_amdgcn_s_setprio(1); _Pragma("unroll") for (int m = 0; m < 4; ++m) _Pragma("unroll") for (int n = 0; n < 2; ++n) _Pragma("unroll") for (int k = 0; k < 2; ++k) \
;         acc[ai][bj][m][n] = __builtin_amdgcn_mfma_f32_16x16x32_bf16(Bt[n][k], At[m][k], acc[ai][bj][m][n], 0, 0, 0); __builtin_amdgcn_s_setprio(0); } while (0)
; #define PG8_WAIT_V(n) asm volatile("s_waitcnt vmcnt(" #n ")" ::: "memory")
; #define PG8_WAIT_L(n) asm volatile("s_waitcnt lgkmcnt(" #n ")" ::: "memory")
; #define PG8_BAR __builtin_amdgcn_s_barrier()
; #define PG8_SCHED __builtin_amdgcn_sched_barrier(0)
; template <class Epi, class Sched, bool ALIGN_EPI = false, bool SP2 = false>
; __device__ __forceinline__ void gemm_phase(PG8_LAS unsigned char* lds, const Gemm g, const Sched& S, const Epi& E) {
;     ...
;             PG8_WAIT_V(8); PG8_WAIT_L(0); PG8_BAR; PG8_MMA(0, 0, At, B0); PG8_MMA(0, 1, At, B1); PG8_BAR; PG8_SCHED;
;             PG8_LDA(At, 1, 1); PG8_STAGE(PG8_SB(1, 0), b3, voffB); PG8_STAGE(PG8_SB(1, 1), b3 + hstep, voffB); PG8_STAGE(PG8_SA(1, 0), a3, voffA);
;             PG8_WAIT_V(8); PG8_WAIT_L(0); PG8_BAR; PG8_MMA(1, 0, At, B0); PG8_MMA(1, 1, At, B1); PG8_BAR; PG8_SCHED;
	s_setprio 1
	s_waitcnt lgkmcnt(0)
	v_mfma_f32_16x16x32_bf16 v[128:131], v[132:135], v[214:217], v[128:131]
	v_mfma_f32_16x16x32_bf16 v[124:127], v[140:143], v[214:217], v[124:127]
	v_mfma_f32_16x16x32_bf16 v[116:119], v[132:135], v[222:225], v[116:119]
	v_mfma_f32_16x16x32_bf16 v[108:111], v[140:143], v[222:225], v[108:111]
	v_mfma_f32_16x16x32_bf16 v[100:103], v[132:135], v[230:233], v[100:103]
	v_mfma_f32_16x16x32_bf16 v[92:95], v[140:143], v[230:233], v[92:95]
	v_mfma_f32_16x16x32_bf16 v[84:87], v[132:135], v[238:241], v[84:87]
	v_mfma_f32_16x16x32_bf16 v[76:79], v[140:143], v[238:241], v[76:79]
	v_mfma_f32_16x16x32_bf16 v[128:131], v[136:139], v[218:221], v[128:131]
	v_mfma_f32_16x16x32_bf16 v[124:127], v[144:147], v[218:221], v[124:127]
	v_mfma_f32_16x16x32_bf16 v[116:119], v[136:139], v[226:229], v[116:119]
	v_mfma_f32_16x16x32_bf16 v[108:111], v[144:147], v[226:229], v[108:111]
	v_mfma_f32_16x16x32_bf16 v[100:103], v[136:139], v[234:237], v[100:103]
	v_mfma_f32_16x16x32_bf16 v[92:95], v[144:147], v[234:237], v[92:95]
	v_mfma_f32_16x16x32_bf16 v[84:87], v[136:139], v[242:245], v[84:87]
	v_mfma_f32_16x16x32_bf16 v[76:79], v[144:147], v[242:245], v[76:79]
	s_setprio 0
	s_setprio 1
	v_mfma_f32_16x16x32_bf16 v[120:123], v[158:161], v[214:217], v[120:123]
	v_mfma_f32_16x16x32_bf16 v[112:115], v[206:209], v[214:217], v[112:115]
	v_mfma_f32_16x16x32_bf16 v[104:107], v[158:161], v[222:225], v[104:107]
	v_mfma_f32_16x16x32_bf16 v[96:99], v[206:209], v[222:225], v[96:99]
	v_mfma_f32_16x16x32_bf16 v[88:91], v[158:161], v[230:233], v[88:91]
	v_mfma_f32_16x16x32_bf16 v[80:83], v[206:209], v[230:233], v[80:83]
	v_mfma_f32_16x16x32_bf16 v[72:75], v[158:161], v[238:241], v[72:75]
	v_mfma_f32_16x16x32_bf16 v[68:71], v[206:209], v[238:241], v[68:71]
	v_mfma_f32_16x16x32_bf16 v[120:123], v[174:177], v[218:221], v[120:123]
	v_mfma_f32_16x16x32_bf16 v[112:115], v[210:213], v[218:221], v[112:115]
	v_mfma_f32_16x16x32_bf16 v[104:107], v[174:177], v[226:229], v[104:107]
	v_mfma_f32_16x16x32_bf16 v[96:99], v[210:213], v[226:229], v[96:99]
	v_mfma_f32_16x16x32_bf16 v[88:91], v[174:177], v[234:237], v[88:91]
	v_mfma_f32_16x16x32_bf16 v[80:83], v[210:213], v[234:237], v[80:83]
	v_mfma_f32_16x16x32_bf16 v[72:75], v[174:177], v[242:245], v[72:75]
	v_mfma_f32_16x16x32_bf16 v[68:71], v[210:213], v[242:245], v[68:71]
	s_setprio 0
	s_barrier
	s_add_i32 s44, s64, s46
	s_add_i32 m0, s44, 0xffffff80
	ds_read_b128 v[214:217], v204 offset:49152
	ds_read_b128 v[218:221], v204 offset:50176
	ds_read_b128 v[222:225], v204 offset:51200
	ds_read_b128 v[226:229], v204 offset:52224
	ds_read_b128 v[230:233], v204 offset:53248
	ds_read_b128 v[234:237], v204 offset:54272
	ds_read_b128 v[238:241], v204 offset:55296
	ds_read_b128 v[242:245], v204 offset:56320
	global_load_lds_dwordx4 v2, s[42:43] offset:128
	s_add_i32 m0, s44, 0x1f80
	s_add_i32 s44, s65, s46
	global_load_lds_dwordx4 v148, s[42:43] offset:128
	s_add_u32 s42, s42, 0x80080
	s_addc_u32 s43, s43, 0
	s_mov_b32 m0, s44
	s_nop 0
	global_load_lds_dwordx4 v2, s[42:43]
	s_add_i32 m0, s44, 0x2000
	s_nop 0
	global_load_lds_dwordx4 v148, s[42:43]
	s_mov_b32 m0, s54
	s_nop 0
	global_load_lds_dwordx4 v152, s[100:101]
	s_mov_b32 m0, s55
	s_nop 0
	global_load_lds_dwordx4 v150, s[100:101]
	s_nop 0
	s_waitcnt vmcnt(8)
	s_waitcnt lgkmcnt(0)
	s_barrier
	s_setprio 1
	s_waitcnt lgkmcnt(0)
	v_mfma_f32_16x16x32_bf16 v[64:67], v[132:135], v[214:217], v[64:67]
	v_mfma_f32_16x16x32_bf16 v[60:63], v[140:143], v[214:217], v[60:63]
	v_mfma_f32_16x16x32_bf16 v[52:55], v[132:135], v[222:225], v[52:55]
	v_mfma_f32_16x16x32_bf16 v[44:47], v[140:143], v[222:225], v[44:47]
	v_mfma_f32_16x16x32_bf16 v[36:39], v[132:135], v[230:233], v[36:39]
	v_mfma_f32_16x16x32_bf16 v[28:31], v[140:143], v[230:233], v[28:31]
	v_mfma_f32_16x16x32_bf16 v[20:23], v[132:135], v[238:241], v[20:23]
	v_mfma_f32_16x16x32_bf16 v[12:15], v[140:143], v[238:241], v[12:15]
	v_mfma_f32_16x16x32_bf16 v[64:67], v[136:139], v[218:221], v[64:67]
	v_mfma_f32_16x16x32_bf16 v[60:63], v[144:147], v[218:221], v[60:63]
	v_mfma_f32_16x16x32_bf16 v[52:55], v[136:139], v[226:229], v[52:55]
	v_mfma_f32_16x16x32_bf16 v[44:47], v[144:147], v[226:229], v[44:47]
	v_mfma_f32_16x16x32_bf16 v[36:39], v[136:139], v[234:237], v[36:39]
	v_mfma_f32_16x16x32_bf16 v[28:31], v[144:147], v[234:237], v[28:31]
	v_mfma_f32_16x16x32_bf16 v[20:23], v[136:139], v[242:245], v[20:23]
	v_mfma_f32_16x16x32_bf16 v[12:15], v[144:147], v[242:245], v[12:15]
	s_setprio 0
	s_setprio 1
	v_mfma_f32_16x16x32_bf16 v[56:59], v[158:161], v[214:217], v[56:59]
	v_mfma_f32_16x16x32_bf16 v[48:51], v[206:209], v[214:217], v[48:51]
	v_mfma_f32_16x16x32_bf16 v[40:43], v[158:161], v[222:225], v[40:43]
	v_mfma_f32_16x16x32_bf16 v[32:35], v[206:209], v[222:225], v[32:35]
	v_mfma_f32_16x16x32_bf16 v[24:27], v[158:161], v[230:233], v[24:27]
	v_mfma_f32_16x16x32_bf16 v[16:19], v[206:209], v[230:233], v[16:19]
	v_mfma_f32_16x16x32_bf16 v[8:11], v[158:161], v[238:241], v[8:11]
	v_mfma_f32_16x16x32_bf16 v[4:7], v[206:209], v[238:241], v[4:7]
	v_mfma_f32_16x16x32_bf16 v[56:59], v[174:177], v[218:221], v[56:59]
	v_mfma_f32_16x16x32_bf16 v[48:51], v[210:213], v[218:221], v[48:51]
	v_mfma_f32_16x16x32_bf16 v[40:43], v[174:177], v[226:229], v[40:43]
	v_mfma_f32_16x16x32_bf16 v[32:35], v[210:213], v[226:229], v[32:35]
	v_mfma_f32_16x16x32_bf16 v[24:27], v[174:177], v[234:237], v[24:27]
	v_mfma_f32_16x16x32_bf16 v[16:19], v[210:213], v[234:237], v[16:19]
	v_mfma_f32_16x16x32_bf16 v[8:11], v[174:177], v[242:245], v[8:11]
	v_mfma_f32_16x16x32_bf16 v[4:7], v[210:213], v[242:245], v[4:7]
	s_setprio 0
	s_barrier
	s_add_i32 s63, s63, 2
	s_add_u32 s40, s40, 0x100
	s_addc_u32 s41, s41, 0
	s_add_u32 s35, s35, 0x100
	s_addc_u32 s62, s62, 0
	s_cmp_gt_u32 s63, 29
	s_cbranch_scc0 .LBB0_674
	s_and_b64 vcc, exec, s[30:31]
	s_cbranch_vccz .LBB0_677
	s_barrier

; #define LAS __attribute__((address_space(3)))
; __device__ __forceinline__ void ml_ktrans(const bf16* __restrict__ Z, bf16* __restrict__ AKT, LAS unsigned char* lds) {
;     ...
;     for (int u = gw; u < 2048; u += nw) { const int tok0 = (u >> 4) * 64, ch0 = (u & 15) * 64;
; #pragma unroll
;         for (int i = 0; i < 8; ++i) { const int tk = 8 * i + (lane >> 3), cc = (lane & 7) * 8;
;             *(LAS u32x4v*)(tl + tk * 72 + cc) = *(const u32x4v*)(Z + (size_t)(tok0 + tk) * NZ + Z_AK + ch0 + cc); }
;         asm volatile("s_waitcnt lgkmcnt(0)" ::: "memory");
; #pragma unroll
;         for (int i = 0; i < 8; ++i) { const int ch = 8 * i + (lane >> 3), tc = (lane & 7) * 8; unsigned w[4];
; #pragma unroll
;             for (int e = 0; e < 4; ++e) w[e] = (unsigned)tl[(tc + 2 * e) * 72 + ch] | ((unsigned)tl[(tc + 2 * e + 1) * 72 + ch] << 16);
;             *(uint4*)(AKT + (size_t)(ch0 + ch) * T_SEQ + tok0 + tc) = make_uint4(w[0], w[1], w[2], w[3]); }
;         asm volatile("s_waitcnt lgkmcnt(0)" ::: "memory");
.LBB0_946:
	s_and_b32 s12, s8, 0xffffffc0
	s_and_b32 s10, s6, 0x3c0
	v_mov_b64_e32 v[10:11], s[0:1]
	s_lshl_b32 s2, s10, 1
	v_or_b32_e32 v4, s12, v1
	v_mad_i64_i32 v[4:5], s[26:27], v4, s25, v[10:11]
	v_lshl_add_u64 v[4:5], v[4:5], 0, s[2:3]
	v_lshl_add_u64 v[4:5], v[4:5], 0, v[2:3]
	global_load_dwordx4 v[4:7], v[4:5], off offset:2048
	v_or_b32_e32 v24, s12, v16
	v_mad_i64_i32 v[24:25], s[26:27], v24, s25, v[10:11]
	v_lshl_add_u64 v[24:25], v[24:25], 0, s[2:3]
	v_lshl_add_u64 v[24:25], v[24:25], 0, v[2:3]
	global_load_dwordx4 v[24:27], v[24:25], off offset:2048
	v_or_b32_e32 v28, s12, v17
	v_mad_i64_i32 v[28:29], s[26:27], v28, s25, v[10:11]
	v_lshl_add_u64 v[28:29], v[28:29], 0, s[2:3]
	v_lshl_add_u64 v[28:29], v[28:29], 0, v[2:3]
	global_load_dwordx4 v[28:31], v[28:29], off offset:2048
	v_or_b32_e32 v32, s12, v18
	v_mad_i64_i32 v[32:33], s[26:27], v32, s25, v[10:11]
	v_lshl_add_u64 v[32:33], v[32:33], 0, s[2:3]
	v_lshl_add_u64 v[32:33], v[32:33], 0, v[2:3]
	global_load_dwordx4 v[32:35], v[32:33], off offset:2048
	v_or_b32_e32 v36, s12, v19
	v_mad_i64_i32 v[36:37], s[26:27], v36, s25, v[10:11]
	v_lshl_add_u64 v[36:37], v[36:37], 0, s[2:3]
	v_lshl_add_u64 v[36:37], v[36:37], 0, v[2:3]
	global_load_dwordx4 v[36:39], v[36:37], off offset:2048
	v_or_b32_e32 v40, s12, v20
	v_mad_i64_i32 v[40:41], s[26:27], v40, s25, v[10:11]
	v_lshl_add_u64 v[40:41], v[40:41], 0, s[2:3]
	v_lshl_add_u64 v[40:41], v[40:41], 0, v[2:3]
	global_load_dwordx4 v[40:43], v[40:41], off offset:2048
	v_or_b32_e32 v44, s12, v21
	v_mad_i64_i32 v[44:45], s[26:27], v44, s25, v[10:11]
	v_lshl_add_u64 v[44:45], v[44:45], 0, s[2:3]
	v_lshl_add_u64 v[44:45], v[44:45], 0, v[2:3]
	global_load_dwordx4 v[44:47], v[44:45], off offset:2048
	v_or_b32_e32 v48, s12, v14
	v_mad_i64_i32 v[48:49], s[26:27], v48, s25, v[10:11]
	v_lshl_add_u64 v[48:49], v[48:49], 0, s[2:3]
	v_lshl_add_u64 v[48:49], v[48:49], 0, v[2:3]
	global_load_dwordx4 v[48:51], v[48:49], off offset:2048
	s_ashr_i32 s13, s12, 31
	v_mov_b32_e32 v13, v3
	s_add_i32 s5, s5, s4
	s_add_i32 s6, s6, s7
	s_add_i32 s8, s8, s9
	s_cmpk_lt_i32 s5, 0x800
	v_lshl_add_u64 v[10:11], s[12:13], 1, v[8:9]
	s_waitcnt vmcnt(0)
	ds_write_b128 v22, v[4:7]
	ds_write_b128 v22, v[24:27] offset:1152
	ds_write_b128 v22, v[28:31] offset:2304
	ds_write_b128 v22, v[32:35] offset:3456
	ds_write_b128 v22, v[36:39] offset:4608
	ds_write_b128 v22, v[40:43] offset:5760
	ds_write_b128 v22, v[44:47] offset:6912
	ds_write_b128 v22, v[48:51] offset:8064
	s_waitcnt lgkmcnt(0)
	ds_read_u16 v4, v15 offset:144
	ds_read_u16 v5, v15
	ds_read_u16 v23, v15 offset:16
	s_waitcnt lgkmcnt(1)
	v_lshl_or_b32 v4, v4, 16, v5
	ds_read_u16 v5, v15 offset:288
	ds_read_u16 v6, v15 offset:432
	s_waitcnt lgkmcnt(0)
	v_lshl_or_b32 v5, v6, 16, v5
	ds_read_u16 v6, v15 offset:576
	ds_read_u16 v7, v15 offset:720
	s_waitcnt lgkmcnt(0)
	v_lshl_or_b32 v6, v7, 16, v6
	ds_read_u16 v7, v15 offset:864
	ds_read_u16 v12, v15 offset:1008
	s_waitcnt lgkmcnt(0)
	v_lshl_or_b32 v7, v12, 16, v7
	v_or_b32_e32 v12, s10, v1
	v_lshlrev_b32_e32 v12, 14, v12
	v_lshl_add_u64 v[12:13], v[10:11], 0, v[12:13]
	global_store_dwordx4 v[12:13], v[4:7], off
	ds_read_u16 v4, v15 offset:160
	ds_read_u16 v5, v15 offset:304
	ds_read_u16 v6, v15 offset:448
	v_mov_b32_e32 v13, v3
	s_waitcnt lgkmcnt(2)
	v_lshl_or_b32 v4, v4, 16, v23
	s_waitcnt lgkmcnt(0)
	v_lshl_or_b32 v5, v6, 16, v5
	ds_read_u16 v6, v15 offset:592
	ds_read_u16 v7, v15 offset:736
	s_waitcnt lgkmcnt(0)
	v_lshl_or_b32 v6, v7, 16, v6
	ds_read_u16 v7, v15 offset:880
	ds_read_u16 v12, v15 offset:1024
	s_waitcnt lgkmcnt(0)
	v_lshl_or_b32 v7, v12, 16, v7
	v_or_b32_e32 v12, s10, v16
	v_lshlrev_b32_e32 v12, 14, v12
	v_lshl_add_u64 v[12:13], v[10:11], 0, v[12:13]
	global_store_dwordx4 v[12:13], v[4:7], off
	ds_read_u16 v4, v15 offset:176
	ds_read_u16 v5, v15 offset:32
	ds_read_u16 v23, v15 offset:48
	v_mov_b32_e32 v13, v3
	s_waitcnt lgkmcnt(1)
; __device__ __forceinline__ void ml_ktrans(const bf16* __restrict__ Z, bf16* __restrict__ AKT, LAS unsigned char* lds) {
;     ...
;         for (int i = 0; i < 8; ++i) { const int ch = 8 * i + (lane >> 3), tc = (lane & 7) * 8; unsigned w[4];
; #pragma unroll
;             for (int e = 0; e < 4; ++e) w[e] = (unsigned)tl[(tc + 2 * e) * 72 + ch] | ((unsigned)tl[(tc + 2 * e + 1) * 72 + ch] << 16);
;             *(uint4*)(AKT + (size_t)(ch0 + ch) * T_SEQ + tok0 + tc) = make_uint4(w[0], w[1], w[2], w[3]); }
;         asm volatile("s_waitcnt lgkmcnt(0)" ::: "memory");
	v_lshl_or_b32 v4, v4, 16, v5
	ds_read_u16 v5, v15 offset:320
	ds_read_u16 v6, v15 offset:464
	s_waitcnt lgkmcnt(0)
	v_lshl_or_b32 v5, v6, 16, v5
	ds_read_u16 v6, v15 offset:608
	ds_read_u16 v7, v15 offset:752
	s_waitcnt lgkmcnt(0)
	v_lshl_or_b32 v6, v7, 16, v6
	ds_read_u16 v7, v15 offset:896
	ds_read_u16 v12, v15 offset:1040
	s_waitcnt lgkmcnt(0)
	v_lshl_or_b32 v7, v12, 16, v7
	v_or_b32_e32 v12, s10, v17
	v_lshlrev_b32_e32 v12, 14, v12
	v_lshl_add_u64 v[12:13], v[10:11], 0, v[12:13]
	global_store_dwordx4 v[12:13], v[4:7], off
	ds_read_u16 v4, v15 offset:192
	ds_read_u16 v5, v15 offset:336
	ds_read_u16 v6, v15 offset:480
	v_mov_b32_e32 v13, v3
	s_waitcnt lgkmcnt(2)
	v_lshl_or_b32 v4, v4, 16, v23
	s_waitcnt lgkmcnt(0)
	v_lshl_or_b32 v5, v6, 16, v5
	ds_read_u16 v6, v15 offset:624
	ds_read_u16 v7, v15 offset:768
	s_waitcnt lgkmcnt(0)
	v_lshl_or_b32 v6, v7, 16, v6
	ds_read_u16 v7, v15 offset:912
	ds_read_u16 v12, v15 offset:1056
	s_waitcnt lgkmcnt(0)
	v_lshl_or_b32 v7, v12, 16, v7
	v_or_b32_e32 v12, s10, v18
	v_lshlrev_b32_e32 v12, 14, v12
	v_lshl_add_u64 v[12:13], v[10:11], 0, v[12:13]
	global_store_dwordx4 v[12:13], v[4:7], off
	ds_read_u16 v4, v15 offset:64
	ds_read_u16 v5, v15 offset:208
	v_mov_b32_e32 v13, v3
	s_waitcnt lgkmcnt(0)
	v_lshl_or_b32 v4, v5, 16, v4
	ds_read_u16 v5, v15 offset:352
	ds_read_u16 v6, v15 offset:496
	s_waitcnt lgkmcnt(0)
	v_lshl_or_b32 v5, v6, 16, v5
	ds_read_u16 v6, v15 offset:640
	ds_read_u16 v7, v15 offset:784
	s_waitcnt lgkmcnt(0)
	v_lshl_or_b32 v6, v7, 16, v6
	ds_read_u16 v7, v15 offset:928
	ds_read_u16 v12, v15 offset:1072
	s_waitcnt lgkmcnt(0)
	v_lshl_or_b32 v7, v12, 16, v7
	v_or_b32_e32 v12, s10, v19
	v_lshlrev_b32_e32 v12, 14, v12
	v_lshl_add_u64 v[12:13], v[10:11], 0, v[12:13]
	global_store_dwordx4 v[12:13], v[4:7], off
	ds_read_u16 v4, v15 offset:80
	ds_read_u16 v5, v15 offset:224
	v_mov_b32_e32 v13, v3
	s_waitcnt lgkmcnt(0)
	v_lshl_or_b32 v4, v5, 16, v4
	ds_read_u16 v5, v15 offset:368
	ds_read_u16 v6, v15 offset:512
	s_waitcnt lgkmcnt(0)
	v_lshl_or_b32 v5, v6, 16, v5
	ds_read_u16 v6, v15 offset:656
	ds_read_u16 v7, v15 offset:800
	s_waitcnt lgkmcnt(0)
	v_lshl_or_b32 v6, v7, 16, v6
	ds_read_u16 v7, v15 offset:944
	ds_read_u16 v12, v15 offset:1088
	s_waitcnt lgkmcnt(0)
	v_lshl_or_b32 v7, v12, 16, v7
	v_or_b32_e32 v12, s10, v20
	v_lshlrev_b32_e32 v12, 14, v12
	v_lshl_add_u64 v[12:13], v[10:11], 0, v[12:13]
	global_store_dwordx4 v[12:13], v[4:7], off
	ds_read_u16 v4, v15 offset:96
	ds_read_u16 v5, v15 offset:240
	v_mov_b32_e32 v13, v3
	s_waitcnt lgkmcnt(0)
	v_lshl_or_b32 v4, v5, 16, v4
	ds_read_u16 v5, v15 offset:384
	ds_read_u16 v6, v15 offset:528
	s_waitcnt lgkmcnt(0)
	v_lshl_or_b32 v5, v6, 16, v5
	ds_read_u16 v6, v15 offset:672
	ds_read_u16 v7, v15 offset:816
	s_waitcnt lgkmcnt(0)
	v_lshl_or_b32 v6, v7, 16, v6
	ds_read_u16 v7, v15 offset:960
	ds_read_u16 v12, v15 offset:1104
	s_waitcnt lgkmcnt(0)
	v_lshl_or_b32 v7, v12, 16, v7
	v_or_b32_e32 v12, s10, v21
	v_lshlrev_b32_e32 v12, 14, v12
	v_lshl_add_u64 v[12:13], v[10:11], 0, v[12:13]
	global_store_dwordx4 v[12:13], v[4:7], off
	ds_read_u16 v4, v15 offset:112
	ds_read_u16 v5, v15 offset:256
	v_mov_b32_e32 v13, v3
	s_waitcnt lgkmcnt(0)
	v_lshl_or_b32 v4, v5, 16, v4
	ds_read_u16 v5, v15 offset:400
	ds_read_u16 v6, v15 offset:544
	s_waitcnt lgkmcnt(0)
	v_lshl_or_b32 v5, v6, 16, v5
	ds_read_u16 v6, v15 offset:688
	ds_read_u16 v7, v15 offset:832
	s_waitcnt lgkmcnt(0)
	v_lshl_or_b32 v6, v7, 16, v6
	ds_read_u16 v7, v15 offset:976
	ds_read_u16 v12, v15 offset:1120
	s_waitcnt lgkmcnt(0)
	v_lshl_or_b32 v7, v12, 16, v7
	v_or_b32_e32 v12, s10, v14
	v_lshlrev_b32_e32 v12, 14, v12
	v_lshl_add_u64 v[10:11], v[10:11], 0, v[12:13]
	global_store_dwordx4 v[10:11], v[4:7], off
	s_waitcnt lgkmcnt(0)
	s_cbranch_scc1 .LBB0_946

; #define LAS __attribute__((address_space(3)))
; template <int PASS> __device__ __forceinline__ void lru_pass(const bf16* __restrict__ Z, const bf16* __restrict__ LW, const float* __restrict__ cw_g, const float* __restrict__ cb_g, const float* __restrict__ b_a, const float* __restrict__ b_x, const float* __restrict__ lam, ...
;     ...
;             { int t_ = tid; asm volatile("" : "+v"(t_));
; #pragma unroll
;               for (int i = 0; i < 5; ++i) { const int idx = t_ + 512 * i; if (idx < 131 * 16) { const int row = idx >> 4, c = idx & 15, t = tok0 - 3 + row; u32x4v v = (u32x4v){0u, 0u, 0u, 0u};
;                   if (t >= 0) v = *(const u32x4v*)(Z + (size_t)t * NZ + Z_CX + blk * 128 + c * 8); *(LAS u32x4v*)(RAW + row * 128 + c * 8) = v; } } }
.LBB0_950:
	s_ashr_i32 s46, s54, 3
	s_waitcnt vmcnt(0) lgkmcnt(0)
	s_barrier
	v_mov_b32_e32 v10, v1
	s_and_b32 s56, s54, 7
	s_lshl_b32 s47, s46, 7
	s_movk_i32 s2, 0x830
	v_and_b32_e32 v204, 15, v10
	s_lshl_b32 s55, s56, 7
	s_add_i32 s57, s47, -3
	v_lshlrev_b32_e32 v9, 3, v204
	v_lshl_add_u32 v8, v204, 4, 0
	v_cmp_gt_i32_e32 vcc, s2, v10
	s_and_saveexec_b64 s[4:5], vcc
	s_cbranch_execz .LBB0_954
	v_ashrrev_i32_e32 v11, 4, v10
	v_add_u32_e32 v12, s57, v11
	v_cmp_lt_i32_e32 vcc, -1, v12
	v_mov_b32_e32 v204, 0
	v_mov_b32_e32 v205, 0
	v_mov_b32_e32 v206, 0
	v_mov_b32_e32 v207, 0
	s_and_saveexec_b64 s[48:49], vcc
	s_cbranch_execz .LBB0_953
	v_mov_b64_e32 v[204:205], s[6:7]
	v_mad_u64_u32 v[204:205], s[58:59], v12, s25, v[204:205]
	s_lshl_b32 s2, s55, 1
	v_lshl_add_u64 v[204:205], v[204:205], 0, s[2:3]
	v_lshlrev_b32_e32 v206, 1, v9
	v_mov_b32_e32 v207, v3
	v_lshl_add_u64 v[204:205], v[204:205], 0, v[206:207]
	v_add_co_u32_e32 v204, vcc, 0x2000, v204
	s_nop 1
	v_addc_co_u32_e32 v205, vcc, 0, v205, vcc
	global_load_dwordx4 v[204:207], v[204:205], off offset:2048
.LBB0_953:
	s_or_b64 exec, exec, s[48:49]
	v_lshl_add_u32 v224, v11, 8, v8
.LBB0_954:
	s_or_b64 exec, exec, s[4:5]
	s_movk_i32 s2, 0x630
	v_cmp_gt_i32_e32 vcc, s2, v10
	s_and_saveexec_b64 s[4:5], vcc
	s_cbranch_execz .LBB0_958
	v_add_u32_e32 v208, 0x200, v10
	v_ashrrev_i32_e32 v11, 4, v208
	v_add_u32_e32 v12, s57, v11
	v_cmp_lt_i32_e32 vcc, -1, v12
	v_mov_b32_e32 v208, 0
	v_mov_b32_e32 v209, 0
	v_mov_b32_e32 v210, 0
	v_mov_b32_e32 v211, 0
	s_and_saveexec_b64 s[48:49], vcc
	s_cbranch_execz .LBB0_957
	v_mov_b64_e32 v[208:209], s[6:7]
	v_mad_u64_u32 v[208:209], s[58:59], v12, s25, v[208:209]
	s_lshl_b32 s2, s55, 1
	v_lshl_add_u64 v[208:209], v[208:209], 0, s[2:3]
	v_lshlrev_b32_e32 v210, 1, v9
	v_mov_b32_e32 v211, v3
	v_lshl_add_u64 v[208:209], v[208:209], 0, v[210:211]
	v_add_co_u32_e32 v208, vcc, 0x2000, v208
	s_nop 1
	v_addc_co_u32_e32 v209, vcc, 0, v209, vcc
	global_load_dwordx4 v[208:211], v[208:209], off offset:2048
.LBB0_957:
	s_or_b64 exec, exec, s[48:49]
	v_lshl_add_u32 v225, v11, 8, v8
.LBB0_958:
	s_or_b64 exec, exec, s[4:5]
	s_movk_i32 s2, 0x430
	v_cmp_gt_i32_e32 vcc, s2, v10
	s_and_saveexec_b64 s[4:5], vcc
	s_cbranch_execz .LBB0_962
	v_add_u32_e32 v212, 0x400, v10
	v_ashrrev_i32_e32 v11, 4, v212
	v_add_u32_e32 v12, s57, v11
	v_cmp_lt_i32_e32 vcc, -1, v12
	v_mov_b32_e32 v212, 0
	v_mov_b32_e32 v213, 0
	v_mov_b32_e32 v214, 0
	v_mov_b32_e32 v215, 0
	s_and_saveexec_b64 s[48:49], vcc
	s_cbranch_execz .LBB0_961
	v_mov_b64_e32 v[212:213], s[6:7]
	v_mad_u64_u32 v[212:213], s[58:59], v12, s25, v[212:213]
	s_lshl_b32 s2, s55, 1
	v_lshl_add_u64 v[212:213], v[212:213], 0, s[2:3]
	v_lshlrev_b32_e32 v214, 1, v9
	v_mov_b32_e32 v215, v3
	v_lshl_add_u64 v[212:213], v[212:213], 0, v[214:215]
	v_add_co_u32_e32 v212, vcc, 0x2000, v212
	s_nop 1
	v_addc_co_u32_e32 v213, vcc, 0, v213, vcc
	global_load_dwordx4 v[212:215], v[212:213], off offset:2048
.LBB0_961:
	s_or_b64 exec, exec, s[48:49]
	v_lshl_add_u32 v226, v11, 8, v8
.LBB0_962:
	s_or_b64 exec, exec, s[4:5]
	s_movk_i32 s2, 0x230
	v_cmp_gt_i32_e32 vcc, s2, v10
	s_and_saveexec_b64 s[4:5], vcc
	s_cbranch_execz .LBB0_966
	v_add_u32_e32 v216, 0x600, v10
	v_ashrrev_i32_e32 v11, 4, v216
	v_add_u32_e32 v12, s57, v11
	v_cmp_lt_i32_e32 vcc, -1, v12
	v_mov_b32_e32 v216, 0
	v_mov_b32_e32 v217, 0
	v_mov_b32_e32 v218, 0
	v_mov_b32_e32 v219, 0
	s_and_saveexec_b64 s[48:49], vcc
	s_cbranch_execz .LBB0_965
	v_mov_b64_e32 v[216:217], s[6:7]
	v_mad_u64_u32 v[216:217], s[58:59], v12, s25, v[216:217]
	s_lshl_b32 s2, s55, 1
	v_lshl_add_u64 v[216:217], v[216:217], 0, s[2:3]
	v_lshlrev_b32_e32 v218, 1, v9
	v_mov_b32_e32 v219, v3
	v_lshl_add_u64 v[216:217], v[216:217], 0, v[218:219]
	v_add_co_u32_e32 v216, vcc, 0x2000, v216
	s_nop 1
	v_addc_co_u32_e32 v217, vcc, 0, v217, vcc
	global_load_dwordx4 v[216:219], v[216:217], off offset:2048
.LBB0_965:
	s_or_b64 exec, exec, s[48:49]
	v_lshl_add_u32 v227, v11, 8, v8
.LBB0_966:
	s_or_b64 exec, exec, s[4:5]
	v_cmp_gt_i32_e32 vcc, 48, v10
	s_and_saveexec_b64 s[4:5], vcc
	s_cbranch_execz .LBB0_970
	v_add_u32_e32 v220, 0x800, v10
	v_ashrrev_i32_e32 v10, 4, v220
	v_add_u32_e32 v11, s57, v10
	v_cmp_lt_i32_e32 vcc, -1, v11
	v_mov_b32_e32 v220, 0
	v_mov_b32_e32 v221, 0
	v_mov_b32_e32 v222, 0
	v_mov_b32_e32 v223, 0
	s_and_saveexec_b64 s[48:49], vcc
	s_cbranch_execz .LBB0_969
	v_mov_b64_e32 v[220:221], s[6:7]
	v_mad_u64_u32 v[220:221], s[58:59], v11, s25, v[220:221]
	s_lshl_b32 s2, s55, 1
	v_lshl_add_u64 v[220:221], v[220:221], 0, s[2:3]
	v_lshlrev_b32_e32 v222, 1, v9
	v_mov_b32_e32 v223, v3
	v_lshl_add_u64 v[220:221], v[220:221], 0, v[222:223]
	v_add_co_u32_e32 v220, vcc, 0x2000, v220
	s_nop 1
	v_addc_co_u32_e32 v221, vcc, 0, v221, vcc
	global_load_dwordx4 v[220:223], v[220:221], off offset:2048
.LBB0_969:
	s_or_b64 exec, exec, s[48:49]
	v_lshl_add_u32 v228, v10, 8, v8
; #define LAS __attribute__((address_space(3)))
; template <int PASS> __device__ __forceinline__ void lru_pass(const bf16* __restrict__ Z, const bf16* __restrict__ LW, const float* __restrict__ cw_g, const float* __restrict__ cb_g, const float* __restrict__ b_a, const float* __restrict__ b_x, const float* __restrict__ lam, ...
;     ...
;                   if (t >= 0) v = *(const u32x4v*)(Z + (size_t)t * NZ + Z_CX + blk * 128 + c * 8); *(LAS u32x4v*)(RAW + row * 128 + c * 8) = v; } } }
;             const bf16* wt = LW + (size_t)blk * 256 * 128;
;             bf16x8 ba[8], bx[8];
; #pragma unroll
;             for (int s = 0; s < 8; ++s) { ba[s] = *(const bf16x8*)(wt + (size_t)dd * 128 + 16 * s + 8 * hh); bx[s] = *(const bf16x8*)(wt + (size_t)(128 + dd) * 128 + 16 * s + 8 * hh); }
;             const float bav = b_a[d], bxv = b_x[d], sp8 = 8.f * log1pf(expf(-lam[d]));
;             const float w0 = cw_g[d], w1 = cw_g[1024 + d], w2 = cw_g[2048 + d], w3 = cw_g[3072 + d], wb = cb_g[d];
;             LRU_BAR();
;             { const int c8 = tid & 15; const float* cwp = cw_g + blk * 128 + c8 * 8; float cw[4][8], cbv[8];
; #pragma unroll
;               for (int jj = 0; jj < 4; ++jj) { const float4 q0 = *(const float4*)(cwp + jj * 1024), q1 = *(const float4*)(cwp + jj * 1024 + 4); cw[jj][0] = q0.x; cw[jj][1] = q0.y; cw[jj][2] = q0.z; cw[jj][3] = q0.w; cw[jj][4] = q1.x; cw[jj][5] = q1.y; cw[jj][6] = q1.z; cw[jj][7] = q1.w; }
;               { const float4 q0 = *(const float4*)(cb_g + blk * 128 + c8 * 8), q1 = *(const float4*)(cb_g + blk * 128 + c8 * 8 + 4); cbv[0] = q0.x; cbv[1] = q0.y; cbv[2] = q0.z; cbv[3] = q0.w; cbv[4] = q1.x; cbv[5] = q1.y; cbv[6] = q1.z; cbv[7] = q1.w; }
; #pragma unroll
;               for (int i = 0; i < 4; ++i) { const int t = (tid >> 4) + 32 * i; float xv[8];
; #pragma unroll
;                   for (int e = 0; e < 8; ++e) xv[e] = cbv[e];
; #pragma unroll
;                   for (int jj = 0; jj < 4; ++jj) { const u32x4v raw = *(const LAS u32x4v*)(RAW + (t + jj) * 128 + c8 * 8);
;                       xv[0] += cw[jj][0] * lo_bf(raw[0]); xv[1] += cw[jj][1] * hi_bf(raw[0]); xv[2] += cw[jj][2] * lo_bf(raw[1]); xv[3] += cw[jj][3] * hi_bf(raw[1]);
;                       xv[4] += cw[jj][4] * lo_bf(raw[2]); xv[5] += cw[jj][5] * hi_bf(raw[2]); xv[6] += cw[jj][6] * lo_bf(raw[3]); xv[7] += cw[jj][7] * hi_bf(raw[3]); }
.LBB0_970:
	s_or_b64 exec, exec, s[4:5]
	s_waitcnt vmcnt(0)
	ds_write_b128 v224, v[204:207]
	ds_write_b128 v225, v[208:211]
	ds_write_b128 v226, v[212:215]
	ds_write_b128 v227, v[216:219]
	v_cmp_gt_i32_e32 vcc, 48, v0
	s_and_saveexec_b64 s[4:5], vcc
	ds_write_b128 v228, v[220:223]
	s_or_b64 exec, exec, s[4:5]
	s_lshl_b32 s2, s56, 16
	v_lshl_add_u64 v[4:5], v[120:121], 0, s[2:3]
	v_lshl_add_u64 v[4:5], v[4:5], 0, v[2:3]
	v_or_b32_e32 v152, s55, v131
	s_mov_b64 s[4:5], 0x8000
	v_add_co_u32_e32 v8, vcc, 0x8000, v4
	s_waitcnt vmcnt(12)
	v_lshlrev_b32_e32 v48, 2, v152
	v_lshl_add_u64 v[6:7], v[4:5], 0, s[4:5]
	v_addc_co_u32_e32 v9, vcc, 0, v5, vcc
	global_load_dwordx4 v[40:43], v[4:5], off
	global_load_dwordx4 v[36:39], v[4:5], off offset:32
	global_load_dwordx4 v[116:119], v[6:7], off offset:32
	global_load_dwordx4 v[108:111], v[6:7], off offset:64
	global_load_dwordx4 v[112:115], v[4:5], off offset:64
	global_load_dwordx4 v[104:107], v[4:5], off offset:96
	global_load_dwordx4 v[100:103], v[6:7], off offset:96
	global_load_dwordx4 v[92:95], v[6:7], off offset:128
	global_load_dwordx4 v[96:99], v[4:5], off offset:128
	global_load_dwordx4 v[88:91], v[4:5], off offset:160
	global_load_dwordx4 v[80:83], v[6:7], off offset:160
	global_load_dwordx4 v[72:75], v[6:7], off offset:192
	global_load_dword v28, v48, s[36:37]
	global_load_dwordx4 v[84:87], v[4:5], off offset:192
	global_load_dwordx4 v[76:79], v[4:5], off offset:224
	global_load_dwordx4 v[44:47], v[8:9], off
	global_load_dwordx4 v[68:71], v[6:7], off offset:224
	v_mov_b32_e32 v49, v3
	v_lshl_add_u64 v[4:5], s[8:9], 0, v[48:49]
	v_add_co_u32_e32 v6, vcc, s88, v4
	s_movk_i32 s48, 0x3000
	s_nop 0
	v_addc_co_u32_e32 v7, vcc, 0, v5, vcc
	v_add_co_u32_e32 v4, vcc, s48, v4
	s_lshl_b32 s2, s55, 2
	s_nop 0
	v_addc_co_u32_e32 v5, vcc, 0, v5, vcc
	global_load_dword v129, v[6:7], off offset:-4096
	global_load_dword v126, v[6:7], off
	global_load_dword v154, v48, s[12:13]
	global_load_dword v153, v48, s[28:29]
	global_load_dword v128, v48, s[8:9]
	global_load_dword v130, v48, s[10:11]
	global_load_dword v127, v[4:5], off
	v_lshl_add_u64 v[4:5], v[122:123], 0, s[2:3]
	v_add_co_u32_e32 v6, vcc, s88, v4
	s_waitcnt vmcnt(0) lgkmcnt(0)
	s_barrier
	s_nop 0
	v_addc_co_u32_e32 v7, vcc, 0, v5, vcc
	global_load_dwordx4 v[30:33], v[4:5], off
	global_load_dwordx4 v[8:11], v[6:7], off offset:-4096
	v_lshl_add_u64 v[16:17], v[124:125], 0, s[2:3]
	global_load_dwordx4 v[24:27], v[16:17], off
	global_load_dwordx4 v[50:53], v[4:5], off offset:16
	s_mov_b64 s[4:5], 0x1000
	v_lshl_add_u64 v[12:13], v[4:5], 0, s[4:5]
	global_load_dwordx4 v[12:15], v[12:13], off offset:16
	s_nop 0
	global_load_dwordx4 v[16:19], v[16:17], off offset:16
	s_mov_b64 s[4:5], 0x2000
	v_lshl_add_u64 v[20:21], v[4:5], 0, s[4:5]
	s_mov_b64 s[4:5], 0x3000
	v_lshl_add_u64 v[22:23], v[4:5], 0, s[4:5]
	v_add_co_u32_e32 v4, vcc, s48, v4
	s_mov_b32 s2, 0x42ce8ed0
	s_nop 0
	v_addc_co_u32_e32 v5, vcc, 0, v5, vcc
	global_load_dwordx4 v[54:57], v[6:7], off
	s_nop 0
	global_load_dwordx4 v[4:7], v[4:5], off
	s_nop 0
	global_load_dwordx4 v[60:63], v[20:21], off offset:16
	s_waitcnt vmcnt(41)
	ds_read_b128 v[64:67], v148
	ds_read_b128 v[132:135], v148 offset:256
	s_mov_b32 s49, 0x13000
	s_mov_b32 s55, 0x19000
	s_mov_b32 s56, 0x21000
	s_mov_b32 s57, 0x23000
	s_waitcnt lgkmcnt(0)
	v_lshlrev_b32_e32 v35, 16, v132
	s_mov_b32 s58, 0x29000
	s_mov_b32 s59, 0x2b000
	s_mov_b32 s60, 0x31000
	s_mov_b32 s61, 0x33000
	s_mov_b32 s62, 0x39000
	s_mov_b32 s63, 0x3b000
	s_waitcnt vmcnt(20)
	v_mul_f32_e32 v20, 0xbfb8aa3b, v28
	v_fma_f32 v21, v28, s18, -v20
	v_rndne_f32_e32 v29, v20
	v_fmac_f32_e32 v21, 0xb2a5705f, v28
	v_sub_f32_e32 v20, v20, v29
	v_add_f32_e32 v20, v20, v21
	v_cvt_i32_f32_e32 v29, v29
	v_exp_f32_e32 v20, v20
	v_cmp_nlt_f32_e32 vcc, s2, v28
	s_mov_b32 s2, 0xc2b17218
	v_cmp_ngt_f32_e64 s[4:5], s2, v28
	v_ldexp_f32 v20, v20, v29
	v_cndmask_b32_e32 v20, 0, v20, vcc
	v_cndmask_b32_e64 v58, v194, v20, s[4:5]
	v_add_f32_e32 v155, 1.0, v58
	v_add_f32_e32 v28, -1.0, v155
	v_frexp_mant_f32_e32 v29, v155
	v_cvt_f64_f32_e32 v[20:21], v155
	v_sub_f32_e32 v34, v28, v155
	s_mov_b32 s2, 0x3f2aaaab
	v_sub_f32_e32 v28, v58, v28
	v_frexp_exp_i32_f64_e32 v20, v[20:21]
	v_cmp_gt_f32_e32 vcc, s2, v29
	v_add_f32_e32 v21, 1.0, v34
	v_add_f32_e32 v156, v28, v21
	v_subbrev_co_u32_e32 v59, vcc, 0, v20, vcc
	global_load_dwordx4 v[20:23], v[22:23], off offset:16
	v_lshlrev_b32_e32 v34, 16, v64
	s_waitcnt vmcnt(9)
	v_mov_b32_e32 v28, v30
	s_waitcnt vmcnt(8)
	v_mov_b32_e32 v29, v8
	v_pk_mul_f32 v[34:35], v[28:29], v[34:35]
	s_mov_b32 s2, 0x3f317218
	s_waitcnt vmcnt(7)
	v_add_f32_e32 v8, v24, v34
	v_add_f32_e32 v157, v8, v35
	v_and_b32_e32 v35, 0xffff0000, v132
	v_and_b32_e32 v34, 0xffff0000, v64
	v_mov_b32_e32 v8, v31
	v_pk_mul_f32 v[30:31], v[8:9], v[34:35]
	v_lshlrev_b32_e32 v35, 16, v133
	v_add_f32_e32 v30, v25, v30
	v_add_f32_e32 v158, v30, v31
	v_lshlrev_b32_e32 v34, 16, v65
	v_mov_b32_e32 v30, v32
	v_mov_b32_e32 v31, v10
	v_pk_mul_f32 v[34:35], v[30:31], v[34:35]
	v_cmp_neq_f32_e32 vcc, s19, v58
	v_add_f32_e32 v10, v26, v34
	v_add_f32_e32 v159, v10, v35
	v_and_b32_e32 v35, 0xffff0000, v133
	v_and_b32_e32 v34, 0xffff0000, v65
	v_mov_b32_e32 v10, v33
	v_pk_mul_f32 v[32:33], v[10:11], v[34:35]
	v_lshlrev_b32_e32 v35, 16, v134
	v_add_f32_e32 v32, v27, v32
	v_add_f32_e32 v160, v32, v33
	v_lshlrev_b32_e32 v34, 16, v66
	s_waitcnt vmcnt(6)
	v_mov_b32_e32 v32, v50
	s_waitcnt vmcnt(5)
	v_mov_b32_e32 v33, v12
	v_pk_mul_f32 v[34:35], v[32:33], v[34:35]
	v_lshlrev_b32_e32 v50, 16, v67
	s_waitcnt vmcnt(4)
; #define LAS __attribute__((address_space(3)))
; __device__ __forceinline__ float lo_bf(unsigned w) { return __uint_as_float(w << 16); }
; __device__ __forceinline__ float hi_bf(unsigned w) { return __uint_as_float(w & 0xffff0000u); }
; __device__ __forceinline__ bf16x8 pack8(const float* v) { typedef unsigned u32x4_ __attribute__((ext_vector_type(4))); u32x4_ w; w.x = pk_bf16(v[0], v[1]); w.y = pk_bf16(v[2], v[3]); w.z = pk_bf16(v[4], v[5]); w.w = pk_bf16(v[6], v[7]); return __builtin_bit_cast(bf16x8, w); }
; template <int PASS> __device__ __forceinline__ void lru_pass(const bf16* __restrict__ Z, const bf16* __restrict__ LW, const float* __restrict__ cw_g, const float* __restrict__ cb_g, const float* __restrict__ b_a, const float* __restrict__ b_x, const float* __restrict__ lam, ...
;     ...
;               for (int i = 0; i < 4; ++i) { const int t = (tid >> 4) + 32 * i; float xv[8];
; #pragma unroll
;                   for (int e = 0; e < 8; ++e) xv[e] = cbv[e];
; #pragma unroll
;                   for (int jj = 0; jj < 4; ++jj) { const u32x4v raw = *(const LAS u32x4v*)(RAW + (t + jj) * 128 + c8 * 8);
;                       xv[0] += cw[jj][0] * lo_bf(raw[0]); xv[1] += cw[jj][1] * hi_bf(raw[0]); xv[2] += cw[jj][2] * lo_bf(raw[1]); xv[3] += cw[jj][3] * hi_bf(raw[1]);
;                       xv[4] += cw[jj][4] * lo_bf(raw[2]); xv[5] += cw[jj][5] * hi_bf(raw[2]); xv[6] += cw[jj][6] * lo_bf(raw[3]); xv[7] += cw[jj][7] * hi_bf(raw[3]); }
;                   *(LAS bf16x8*)(XC + t * 256 + ((c8 ^ (t & 15)) << 4)) = pack8(xv); } }
	v_add_f32_e32 v12, v16, v34
	v_add_f32_e32 v161, v12, v35
	v_and_b32_e32 v35, 0xffff0000, v134
	v_and_b32_e32 v34, 0xffff0000, v66
	v_mov_b32_e32 v12, v51
	v_pk_mul_f32 v[34:35], v[12:13], v[34:35]
	v_lshlrev_b32_e32 v51, 16, v135
	v_add_f32_e32 v34, v17, v34
	v_add_f32_e32 v162, v34, v35
	v_mov_b32_e32 v34, v52
	v_mov_b32_e32 v35, v14
	v_pk_mul_f32 v[50:51], v[34:35], v[50:51]
	s_mov_b32 s4, 0x9000
	v_add_f32_e32 v14, v18, v50
	v_add_f32_e32 v163, v14, v51
	v_and_b32_e32 v51, 0xffff0000, v135
	v_and_b32_e32 v50, 0xffff0000, v67
	ds_read_b128 v[64:67], v148 offset:512
	ds_read_b128 v[132:135], v148 offset:768
	v_mov_b32_e32 v14, v53
	v_pk_mul_f32 v[50:51], v[14:15], v[50:51]
	s_mov_b32 s5, 0xb000
	v_add_f32_e32 v50, v19, v50
	v_add_f32_e32 v164, v50, v51
	s_waitcnt lgkmcnt(0)
	v_lshlrev_b32_e32 v53, 16, v132
	v_lshlrev_b32_e32 v52, 16, v64
	s_waitcnt vmcnt(3)
	v_mov_b32_e32 v50, v54
	s_waitcnt vmcnt(2)
	v_mov_b32_e32 v51, v4
	v_pk_mul_f32 v[52:53], v[50:51], v[52:53]
	v_lshlrev_b32_e32 v54, 16, v65
	v_add_f32_e32 v4, v157, v52
	v_add_f32_e32 v157, v4, v53
	v_and_b32_e32 v53, 0xffff0000, v132
	v_and_b32_e32 v52, 0xffff0000, v64
	v_mov_b32_e32 v4, v55
	v_pk_mul_f32 v[52:53], v[4:5], v[52:53]
	v_lshlrev_b32_e32 v55, 16, v133
	v_add_f32_e32 v52, v158, v52
	v_add_f32_e32 v64, v52, v53
	v_mov_b32_e32 v52, v56
	v_mov_b32_e32 v53, v6
	v_pk_mul_f32 v[54:55], v[52:53], v[54:55]
	v_lshlrev_b32_e32 v56, 16, v66
	v_add_f32_e32 v6, v159, v54
	v_add_f32_e32 v132, v6, v55
	v_and_b32_e32 v55, 0xffff0000, v133
	v_and_b32_e32 v54, 0xffff0000, v65
	v_mov_b32_e32 v6, v57
	v_pk_mul_f32 v[54:55], v[6:7], v[54:55]
	v_lshlrev_b32_e32 v57, 16, v134
	v_add_f32_e32 v54, v160, v54
	v_add_f32_e32 v65, v54, v55
	s_waitcnt vmcnt(1)
	v_mov_b32_e32 v54, v60
	s_waitcnt vmcnt(0)
	v_mov_b32_e32 v55, v20
	v_pk_mul_f32 v[56:57], v[54:55], v[56:57]
	v_lshlrev_b32_e32 v60, 16, v67
	v_add_f32_e32 v20, v161, v56
	v_add_f32_e32 v133, v20, v57
	v_and_b32_e32 v57, 0xffff0000, v134
	v_and_b32_e32 v56, 0xffff0000, v66
	v_mov_b32_e32 v20, v61
	v_pk_mul_f32 v[56:57], v[20:21], v[56:57]
	v_lshlrev_b32_e32 v61, 16, v135
	v_add_f32_e32 v56, v162, v56
	v_add_f32_e32 v66, v56, v57
	v_mov_b32_e32 v56, v62
	v_mov_b32_e32 v57, v22
	v_pk_mul_f32 v[60:61], v[56:57], v[60:61]
	s_nop 0
	v_add_f32_e32 v22, v163, v60
	v_add_f32_e32 v134, v22, v61
	v_and_b32_e32 v61, 0xffff0000, v135
	v_and_b32_e32 v60, 0xffff0000, v67
	v_mov_b32_e32 v22, v63
	v_pk_mul_f32 v[60:61], v[22:23], v[60:61]
	s_nop 0
	v_add_f32_e32 v60, v164, v60
	v_add_f32_e32 v63, v60, v61
	v_cvt_pk_bf16_f32 v60, v157, v64
	v_cvt_pk_bf16_f32 v61, v132, v65
	v_cvt_pk_bf16_f32 v62, v133, v66
	v_cvt_pk_bf16_f32 v63, v134, v63
	ds_read_b128 v[64:67], v148 offset:8192
	ds_read_b128 v[132:135], v148 offset:8448
	ds_write_b128 v149, v[60:63] offset:36864
	v_sub_u32_e32 v157, 0, v59
	v_ldexp_f32 v155, v155, v157
	s_waitcnt lgkmcnt(2)
	v_lshlrev_b32_e32 v60, 16, v64
	s_waitcnt lgkmcnt(1)
	v_lshlrev_b32_e32 v61, 16, v132
	v_pk_mul_f32 v[60:61], v[28:29], v[60:61]
	v_ldexp_f32 v156, v156, v157
	v_add_f32_e32 v60, v24, v60
	v_add_f32_e32 v157, v60, v61
	v_and_b32_e32 v61, 0xffff0000, v132
	v_and_b32_e32 v60, 0xffff0000, v64
	v_pk_mul_f32 v[60:61], v[8:9], v[60:61]
	v_and_b32_e32 v64, 0xffff0000, v67
	v_add_f32_e32 v60, v25, v60
	v_add_f32_e32 v158, v60, v61
	v_lshlrev_b32_e32 v61, 16, v133
	v_lshlrev_b32_e32 v60, 16, v65
	v_pk_mul_f32 v[60:61], v[30:31], v[60:61]
	s_nop 0
	v_add_f32_e32 v60, v26, v60
	v_add_f32_e32 v159, v60, v61
	v_and_b32_e32 v61, 0xffff0000, v133
	v_and_b32_e32 v60, 0xffff0000, v65
	v_pk_mul_f32 v[60:61], v[10:11], v[60:61]
	v_and_b32_e32 v65, 0xffff0000, v135
	v_add_f32_e32 v60, v27, v60
	v_add_f32_e32 v160, v60, v61
	v_lshlrev_b32_e32 v61, 16, v134
	v_lshlrev_b32_e32 v60, 16, v66
	v_pk_mul_f32 v[60:61], v[32:33], v[60:61]
	v_pk_mul_f32 v[64:65], v[14:15], v[64:65]
	v_add_f32_e32 v60, v16, v60
	v_add_f32_e32 v161, v60, v61
	v_and_b32_e32 v61, 0xffff0000, v134
	v_and_b32_e32 v60, 0xffff0000, v66
	v_pk_mul_f32 v[60:61], v[12:13], v[60:61]
	v_add_f32_e32 v64, v19, v64
	v_add_f32_e32 v60, v17, v60
	v_add_f32_e32 v66, v60, v61
	v_lshlrev_b32_e32 v61, 16, v135
	v_lshlrev_b32_e32 v60, 16, v67
	v_pk_mul_f32 v[60:61], v[34:35], v[60:61]
	v_add_f32_e32 v67, v64, v65
	v_add_f32_e32 v60, v18, v60
	v_add_f32_e32 v162, v60, v61
	ds_read_b128 v[60:63], v148 offset:8704
	ds_read_b128 v[132:135], v148 offset:8960
	s_waitcnt lgkmcnt(1)
	v_lshlrev_b32_e32 v64, 16, v60
	s_waitcnt lgkmcnt(0)
	v_lshlrev_b32_e32 v65, 16, v132
	v_pk_mul_f32 v[64:65], v[50:51], v[64:65]
	s_nop 0
	v_add_f32_e32 v64, v157, v64
	v_add_f32_e32 v157, v64, v65
	v_and_b32_e32 v65, 0xffff0000, v132
	v_and_b32_e32 v64, 0xffff0000, v60
	v_pk_mul_f32 v[64:65], v[4:5], v[64:65]
	s_nop 0
	v_add_f32_e32 v60, v158, v64
	v_add_f32_e32 v132, v60, v65
	v_lshlrev_b32_e32 v65, 16, v133
	v_lshlrev_b32_e32 v64, 16, v61
	v_pk_mul_f32 v[64:65], v[52:53], v[64:65]
	s_nop 0
	v_add_f32_e32 v60, v159, v64
	v_add_f32_e32 v158, v60, v65
	v_and_b32_e32 v65, 0xffff0000, v133
	v_and_b32_e32 v64, 0xffff0000, v61
	v_pk_mul_f32 v[60:61], v[6:7], v[64:65]
	s_nop 0
	v_add_f32_e32 v60, v160, v60
	v_add_f32_e32 v64, v60, v61
	v_lshlrev_b32_e32 v61, 16, v134
	v_lshlrev_b32_e32 v60, 16, v62
	v_pk_mul_f32 v[60:61], v[54:55], v[60:61]
	s_nop 0
	v_add_f32_e32 v60, v161, v60
	v_add_f32_e32 v65, v60, v61
	v_and_b32_e32 v61, 0xffff0000, v134
	v_and_b32_e32 v60, 0xffff0000, v62
	v_pk_mul_f32 v[60:61], v[20:21], v[60:61]
	s_nop 0
	v_add_f32_e32 v60, v66, v60
	v_add_f32_e32 v62, v60, v61
	v_lshlrev_b32_e32 v61, 16, v135
	v_lshlrev_b32_e32 v60, 16, v63
	v_pk_mul_f32 v[60:61], v[56:57], v[60:61]
	s_nop 0
	v_add_f32_e32 v60, v162, v60
	v_add_f32_e32 v66, v60, v61
	v_and_b32_e32 v61, 0xffff0000, v135
	v_and_b32_e32 v60, 0xffff0000, v63
	v_pk_mul_f32 v[60:61], v[22:23], v[60:61]
	s_nop 0
	v_add_f32_e32 v60, v67, v60
	v_add_f32_e32 v63, v60, v61
	v_cvt_pk_bf16_f32 v60, v157, v132
	v_cvt_pk_bf16_f32 v61, v158, v64
	v_cvt_pk_bf16_f32 v62, v65, v62
	v_cvt_pk_bf16_f32 v63, v66, v63
	ds_read_b128 v[64:67], v148 offset:16384
	ds_read_b128 v[132:135], v148 offset:16640
	ds_write_b128 v149, v[60:63] offset:45056
	v_add_f32_e32 v157, -1.0, v155
	v_add_f32_e32 v158, 1.0, v157
	s_waitcnt lgkmcnt(2)
; #define LAS __attribute__((address_space(3)))
; __device__ __forceinline__ float lo_bf(unsigned w) { return __uint_as_float(w << 16); }
; __device__ __forceinline__ float hi_bf(unsigned w) { return __uint_as_float(w & 0xffff0000u); }
; __device__ __forceinline__ bf16x8 pack8(const float* v) { typedef unsigned u32x4_ __attribute__((ext_vector_type(4))); u32x4_ w; w.x = pk_bf16(v[0], v[1]); w.y = pk_bf16(v[2], v[3]); w.z = pk_bf16(v[4], v[5]); w.w = pk_bf16(v[6], v[7]); return __builtin_bit_cast(bf16x8, w); }
; #define LRU_BAR() do { asm volatile("s_waitcnt vmcnt(0) lgkmcnt(0)" ::: "memory"); __builtin_amdgcn_s_barrier(); asm volatile("" ::: "memory"); } while (0)
; template <int PASS> __device__ __forceinline__ void lru_pass(const bf16* __restrict__ Z, const bf16* __restrict__ LW, const float* __restrict__ cw_g, const float* __restrict__ cb_g, const float* __restrict__ b_a, const float* __restrict__ b_x, const float* __restrict__ lam, ...
;     ...
;               for (int i = 0; i < 4; ++i) { const int t = (tid >> 4) + 32 * i; float xv[8];
; #pragma unroll
;                   for (int e = 0; e < 8; ++e) xv[e] = cbv[e];
; #pragma unroll
;                   for (int jj = 0; jj < 4; ++jj) { const u32x4v raw = *(const LAS u32x4v*)(RAW + (t + jj) * 128 + c8 * 8);
;                       xv[0] += cw[jj][0] * lo_bf(raw[0]); xv[1] += cw[jj][1] * hi_bf(raw[0]); xv[2] += cw[jj][2] * lo_bf(raw[1]); xv[3] += cw[jj][3] * hi_bf(raw[1]);
;                       xv[4] += cw[jj][4] * lo_bf(raw[2]); xv[5] += cw[jj][5] * hi_bf(raw[2]); xv[6] += cw[jj][6] * lo_bf(raw[3]); xv[7] += cw[jj][7] * hi_bf(raw[3]); }
;                   *(LAS bf16x8*)(XC + t * 256 + ((c8 ^ (t & 15)) << 4)) = pack8(xv); } }
;             LRU_BAR();
	v_lshlrev_b32_e32 v60, 16, v64
	s_waitcnt lgkmcnt(1)
	v_lshlrev_b32_e32 v61, 16, v132
	v_pk_mul_f32 v[60:61], v[28:29], v[60:61]
	v_sub_f32_e32 v158, v155, v158
	v_add_f32_e32 v60, v24, v60
	v_add_f32_e32 v159, v60, v61
	v_and_b32_e32 v61, 0xffff0000, v132
	v_and_b32_e32 v60, 0xffff0000, v64
	v_pk_mul_f32 v[60:61], v[8:9], v[60:61]
	v_and_b32_e32 v64, 0xffff0000, v67
	v_add_f32_e32 v60, v25, v60
	v_add_f32_e32 v160, v60, v61
	v_lshlrev_b32_e32 v61, 16, v133
	v_lshlrev_b32_e32 v60, 16, v65
	v_pk_mul_f32 v[60:61], v[30:31], v[60:61]
	v_add_f32_e32 v158, v156, v158
	v_add_f32_e32 v60, v26, v60
	v_add_f32_e32 v161, v60, v61
	v_and_b32_e32 v61, 0xffff0000, v133
	v_and_b32_e32 v60, 0xffff0000, v65
	v_pk_mul_f32 v[60:61], v[10:11], v[60:61]
	v_and_b32_e32 v65, 0xffff0000, v135
	v_add_f32_e32 v60, v27, v60
	v_add_f32_e32 v162, v60, v61
	v_lshlrev_b32_e32 v61, 16, v134
	v_lshlrev_b32_e32 v60, 16, v66
	v_pk_mul_f32 v[60:61], v[32:33], v[60:61]
	v_pk_mul_f32 v[64:65], v[14:15], v[64:65]
	v_add_f32_e32 v60, v16, v60
	v_add_f32_e32 v163, v60, v61
	v_and_b32_e32 v61, 0xffff0000, v134
	v_and_b32_e32 v60, 0xffff0000, v66
	v_pk_mul_f32 v[60:61], v[12:13], v[60:61]
	v_add_f32_e32 v64, v19, v64
	v_add_f32_e32 v60, v17, v60
	v_add_f32_e32 v66, v60, v61
	v_lshlrev_b32_e32 v61, 16, v135
	v_lshlrev_b32_e32 v60, 16, v67
	v_pk_mul_f32 v[60:61], v[34:35], v[60:61]
	v_add_f32_e32 v67, v64, v65
	v_add_f32_e32 v60, v18, v60
	v_add_f32_e32 v164, v60, v61
	ds_read_b128 v[60:63], v148 offset:16896
	ds_read_b128 v[132:135], v148 offset:17152
	s_waitcnt lgkmcnt(1)
	v_lshlrev_b32_e32 v64, 16, v60
	s_waitcnt lgkmcnt(0)
	v_lshlrev_b32_e32 v65, 16, v132
	v_pk_mul_f32 v[64:65], v[50:51], v[64:65]
	s_nop 0
	v_add_f32_e32 v64, v159, v64
	v_add_f32_e32 v159, v64, v65
	v_and_b32_e32 v65, 0xffff0000, v132
	v_and_b32_e32 v64, 0xffff0000, v60
	v_pk_mul_f32 v[64:65], v[4:5], v[64:65]
	s_nop 0
	v_add_f32_e32 v60, v160, v64
	v_add_f32_e32 v132, v60, v65
	v_lshlrev_b32_e32 v65, 16, v133
	v_lshlrev_b32_e32 v64, 16, v61
	v_pk_mul_f32 v[64:65], v[52:53], v[64:65]
	s_nop 0
	v_add_f32_e32 v60, v161, v64
	v_add_f32_e32 v160, v60, v65
	v_and_b32_e32 v65, 0xffff0000, v133
	v_and_b32_e32 v64, 0xffff0000, v61
	v_pk_mul_f32 v[60:61], v[6:7], v[64:65]
	s_nop 0
	v_add_f32_e32 v60, v162, v60
	v_add_f32_e32 v64, v60, v61
	v_lshlrev_b32_e32 v61, 16, v134
	v_lshlrev_b32_e32 v60, 16, v62
	v_pk_mul_f32 v[60:61], v[54:55], v[60:61]
	s_nop 0
	v_add_f32_e32 v60, v163, v60
	v_add_f32_e32 v65, v60, v61
	v_and_b32_e32 v61, 0xffff0000, v134
	v_and_b32_e32 v60, 0xffff0000, v62
	v_pk_mul_f32 v[60:61], v[20:21], v[60:61]
	s_nop 0
	v_add_f32_e32 v60, v66, v60
	v_add_f32_e32 v62, v60, v61
	v_lshlrev_b32_e32 v61, 16, v135
	v_lshlrev_b32_e32 v60, 16, v63
	v_pk_mul_f32 v[60:61], v[56:57], v[60:61]
	s_nop 0
	v_add_f32_e32 v60, v164, v60
	v_add_f32_e32 v66, v60, v61
	v_and_b32_e32 v61, 0xffff0000, v135
	v_and_b32_e32 v60, 0xffff0000, v63
	v_pk_mul_f32 v[60:61], v[22:23], v[60:61]
	s_nop 0
	v_add_f32_e32 v60, v67, v60
	v_add_f32_e32 v63, v60, v61
	v_cvt_pk_bf16_f32 v60, v159, v132
	v_cvt_pk_bf16_f32 v61, v160, v64
	v_cvt_pk_bf16_f32 v62, v65, v62
	v_cvt_pk_bf16_f32 v63, v66, v63
	ds_read_b128 v[64:67], v148 offset:24576
	ds_read_b128 v[132:135], v148 offset:24832
	ds_write_b128 v149, v[60:63] offset:53248
	v_add_f32_e32 v159, 1.0, v155
	v_add_f32_e32 v160, -1.0, v159
	s_waitcnt lgkmcnt(2)
	v_lshlrev_b32_e32 v60, 16, v64
	s_waitcnt lgkmcnt(1)
	v_lshlrev_b32_e32 v61, 16, v132
	v_pk_mul_f32 v[28:29], v[28:29], v[60:61]
	s_nop 0
	v_add_f32_e32 v24, v24, v28
	v_add_f32_e32 v60, v24, v29
	v_and_b32_e32 v29, 0xffff0000, v132
	v_and_b32_e32 v28, 0xffff0000, v64
	v_pk_mul_f32 v[8:9], v[8:9], v[28:29]
	s_nop 0
	v_add_f32_e32 v8, v25, v8
	v_add_f32_e32 v28, v8, v9
	v_lshlrev_b32_e32 v9, 16, v133
	v_lshlrev_b32_e32 v8, 16, v65
	v_pk_mul_f32 v[8:9], v[30:31], v[8:9]
	s_nop 0
	v_add_f32_e32 v8, v26, v8
	v_add_f32_e32 v29, v8, v9
	v_and_b32_e32 v9, 0xffff0000, v133
	v_and_b32_e32 v8, 0xffff0000, v65
	v_pk_mul_f32 v[8:9], v[10:11], v[8:9]
	s_nop 0
	v_add_f32_e32 v8, v27, v8
	v_add_f32_e32 v30, v8, v9
	v_lshlrev_b32_e32 v9, 16, v134
	v_lshlrev_b32_e32 v8, 16, v66
	v_pk_mul_f32 v[8:9], v[32:33], v[8:9]
	s_nop 0
	v_add_f32_e32 v8, v16, v8
	v_add_f32_e32 v16, v8, v9
	v_and_b32_e32 v9, 0xffff0000, v134
	v_and_b32_e32 v8, 0xffff0000, v66
	v_pk_mul_f32 v[8:9], v[12:13], v[8:9]
	v_and_b32_e32 v13, 0xffff0000, v135
	v_add_f32_e32 v8, v17, v8
	v_add_f32_e32 v17, v8, v9
	v_lshlrev_b32_e32 v9, 16, v135
	v_lshlrev_b32_e32 v8, 16, v67
	v_pk_mul_f32 v[8:9], v[34:35], v[8:9]
	v_and_b32_e32 v12, 0xffff0000, v67
	v_add_f32_e32 v8, v18, v8
	v_add_f32_e32 v18, v8, v9
	ds_read_b128 v[8:11], v148 offset:25088
	ds_read_b128 v[24:27], v148 offset:25344
	v_pk_mul_f32 v[12:13], v[14:15], v[12:13]
	s_nop 0
	v_add_f32_e32 v12, v19, v12
	v_add_f32_e32 v14, v12, v13
	s_waitcnt lgkmcnt(0)
	v_lshlrev_b32_e32 v13, 16, v24
	v_lshlrev_b32_e32 v12, 16, v8
	v_pk_mul_f32 v[12:13], v[50:51], v[12:13]
	s_nop 0
	v_add_f32_e32 v12, v60, v12
	v_add_f32_e32 v15, v12, v13
	v_and_b32_e32 v13, 0xffff0000, v24
	v_and_b32_e32 v12, 0xffff0000, v8
	v_pk_mul_f32 v[4:5], v[4:5], v[12:13]
	s_nop 0
	v_add_f32_e32 v4, v28, v4
	v_add_f32_e32 v8, v4, v5
	v_lshlrev_b32_e32 v5, 16, v25
	v_lshlrev_b32_e32 v4, 16, v9
	v_pk_mul_f32 v[4:5], v[52:53], v[4:5]
	s_nop 0
	v_add_f32_e32 v4, v29, v4
	v_add_f32_e32 v12, v4, v5
	v_and_b32_e32 v5, 0xffff0000, v25
	v_and_b32_e32 v4, 0xffff0000, v9
	v_pk_mul_f32 v[4:5], v[6:7], v[4:5]
	s_nop 0
	v_add_f32_e32 v4, v30, v4
	v_add_f32_e32 v6, v4, v5
	v_lshlrev_b32_e32 v5, 16, v26
	v_lshlrev_b32_e32 v4, 16, v10
	v_pk_mul_f32 v[4:5], v[54:55], v[4:5]
	v_add_f32_e32 v55, v157, v158
	v_add_f32_e32 v4, v16, v4
	v_add_f32_e32 v7, v4, v5
	v_and_b32_e32 v5, 0xffff0000, v26
	v_and_b32_e32 v4, 0xffff0000, v10
	v_pk_mul_f32 v[4:5], v[20:21], v[4:5]
	v_sub_f32_e32 v24, v157, v55
	v_add_f32_e32 v4, v17, v4
	v_add_f32_e32 v9, v4, v5
	v_lshlrev_b32_e32 v5, 16, v27
	v_lshlrev_b32_e32 v4, 16, v11
	v_pk_mul_f32 v[4:5], v[56:57], v[4:5]
	v_add_f32_e32 v66, v158, v24
	v_add_f32_e32 v4, v18, v4
	v_add_f32_e32 v10, v4, v5
	v_and_b32_e32 v5, 0xffff0000, v27
	v_and_b32_e32 v4, 0xffff0000, v11
	v_pk_mul_f32 v[4:5], v[22:23], v[4:5]
	s_nop 0
	v_add_f32_e32 v4, v14, v4
	v_add_f32_e32 v11, v4, v5
	v_cvt_pk_bf16_f32 v4, v15, v8
	v_cvt_pk_bf16_f32 v5, v12, v6
	v_cvt_pk_bf16_f32 v6, v7, v9
	v_cvt_pk_bf16_f32 v7, v10, v11
	ds_write_b128 v149, v[4:7] offset:61440
	s_waitcnt vmcnt(0) lgkmcnt(0)
	s_barrier
; #define LAS __attribute__((address_space(3)))
; __device__ __forceinline__ float bf2f(unsigned short b) { return __uint_as_float(((unsigned)b) << 16); }
; #define MFMA32(a, b, c) __builtin_amdgcn_mfma_f32_32x32x16_bf16((a), (b), (c), 0, 0, 0)
; template <int PASS> __device__ __forceinline__ void lru_pass(const bf16* __restrict__ Z, const bf16* __restrict__ LW, const float* __restrict__ cw_g, const float* __restrict__ cb_g, const float* __restrict__ b_a, const float* __restrict__ b_x, const float* __restrict__ lam, ...
;     ...
;             const float bav = b_a[d], bxv = b_x[d], sp8 = 8.f * log1pf(expf(-lam[d]));
;     ...
;             for (int tt = 0; tt < 2; ++tt) {
;                 const int tl0 = 64 * th + 32 * tt;
;                 f32x16 accA, accX;
; #pragma unroll
;                 for (int i = 0; i < 16; ++i) { accA[i] = 0.f; accX[i] = 0.f; }
; #pragma unroll
;                 for (int s = 0; s < 8; ++s) { const bf16x8 af = *(const LAS bf16x8*)(XC + (tl0 + r) * 256 + (((2 * s + hh) ^ (r & 15)) << 4)); accA = MFMA32(af, ba[s], accA); accX = MFMA32(af, bx[s], accX); }
; #pragma unroll
;                 for (int gq = 0; gq < 4; ++gq) { const int t0 = tl0 + 8 * gq + 4 * hh; float cxr[7];
; #pragma unroll
;                     for (int q = 0; q < 7; ++q) cxr[q] = bf2f(RAW[(t0 + q) * 128 + dd]);
; #pragma unroll
;                     for (int e = 0; e < 4; ++e) { const int i = 4 * gq + e;
;                         const float xc = wb + w0 * cxr[e] + w1 * cxr[e + 1] + w2 * cxr[e + 2] + w3 * cxr[e + 3];
;                         const float rr = __builtin_amdgcn_rcpf(1.f + __expf(-(accA[i] + bav))), ig = __builtin_amdgcn_rcpf(1.f + __expf(-(accX[i] + bxv)));
	v_add_u32_e32 v4, v138, v139
	ds_read_b128 v[20:23], v4 offset:36864
	v_sub_f32_e32 v4, v155, v160
	v_add_f32_e32 v4, v156, v4
	v_add_f32_e32 v64, v159, v4
	v_rcp_f32_e32 v132, v64
	v_sub_f32_e32 v5, v159, v64
	v_add_f32_e32 v65, v4, v5
	v_add_u32_e32 v4, v138, v140
	v_mul_f32_e32 v133, v55, v132
	v_mul_f32_e32 v60, v64, v133
	v_fma_f32 v56, v133, v64, -v60
	v_fmac_f32_e32 v56, v133, v65
	v_add_f32_e32 v54, v60, v56
	v_sub_f32_e32 v61, v55, v54
	v_pk_add_f32 v[62:63], v[54:55], v[60:61] neg_lo:[0,1] neg_hi:[0,1]
	v_mov_b32_e32 v57, v54
	v_pk_add_f32 v[54:55], v[62:63], v[56:57] neg_lo:[0,1] neg_hi:[0,1]
	ds_read_b128 v[50:53], v4 offset:36864
	v_add_f32_e32 v55, v66, v55
	v_add_f32_e32 v62, v54, v55
	v_add_u32_e32 v54, v138, v141
	ds_read_b128 v[54:57], v54 offset:36864
	s_waitcnt lgkmcnt(2)
	v_mfma_f32_32x32x16_bf16 v[4:19], v[20:23], v[40:43], 0
	v_add_f32_e32 v63, v61, v62
	v_mul_f32_e32 v134, v132, v63
	v_mul_f32_e32 v60, v64, v134
	v_fma_f32 v64, v134, v64, -v60
	v_fmac_f32_e32 v64, v134, v65
	v_mfma_f32_32x32x16_bf16 v[20:35], v[20:23], v[44:47], 0
	s_waitcnt lgkmcnt(1)
	v_mfma_f32_32x32x16_bf16 v[4:19], v[50:53], v[36:39], v[4:19]
	v_mfma_f32_32x32x16_bf16 v[20:35], v[50:53], v[116:119], v[20:35]
	v_sub_f32_e32 v50, v61, v63
	v_add_f32_e32 v135, v62, v50
	v_add_f32_e32 v62, v60, v64
	v_sub_f32_e32 v61, v63, v62
	v_add_f32_e64 v66, v62, -v60
	v_add_f32_e64 v67, v63, -v61
	v_mov_b32_e32 v65, v62
	v_pk_add_f32 v[62:63], v[66:67], v[64:65] neg_lo:[0,1] neg_hi:[0,1]
	v_add_u32_e32 v50, v138, v142
	v_add_f32_e32 v60, v135, v63
	v_add_f32_e32 v60, v62, v60
	v_add_f32_e32 v60, v61, v60
	v_add_f32_e32 v61, v133, v134
	s_waitcnt lgkmcnt(0)
	v_mfma_f32_32x32x16_bf16 v[4:19], v[54:57], v[112:115], v[4:19]
	ds_read_b128 v[50:53], v50 offset:36864
	v_mul_f32_e32 v60, v132, v60
	v_mfma_f32_32x32x16_bf16 v[20:35], v[54:57], v[108:111], v[20:35]
	v_sub_f32_e32 v54, v61, v133
	v_sub_f32_e32 v54, v134, v54
	v_add_f32_e32 v54, v54, v60
	v_add_f32_e32 v62, v61, v54
	v_mul_f32_e32 v64, v62, v62
	v_fmamk_f32 v55, v64, 0x3e9b6dac, v190
	v_fmaak_f32 v173, v64, v55, 0x3f2aaada
	v_sub_f32_e32 v55, v62, v61
	v_sub_f32_e32 v54, v54, v55
	v_cvt_f32_i32_e32 v60, v59
	v_ldexp_f32 v59, v54, 1
	v_add_u32_e32 v54, v138, v143
	ds_read_b128 v[54:57], v54 offset:36864
	s_waitcnt lgkmcnt(1)
	v_mfma_f32_32x32x16_bf16 v[4:19], v[50:53], v[104:107], v[4:19]
	v_mul_f32_e32 v61, v62, v64
	v_mul_f32_e64 v64, v60, v172
	v_mul_f32_e64 v65, v61, v173
	v_ldexp_f32 v63, v62, 1
	v_fma_f32 v62, v60, s2, -v64
	v_fmac_f32_e32 v62, 0xb102e308, v60
	v_pk_add_f32 v[60:61], v[64:65], v[62:63]
	v_mov_b32_e32 v66, v64
	v_mfma_f32_32x32x16_bf16 v[20:35], v[50:53], v[100:103], v[20:35]
	v_add_u32_e32 v50, v138, v144
	v_sub_f32_e32 v63, v61, v63
	ds_read_b128 v[50:53], v50 offset:36864
	v_sub_f32_e32 v63, v65, v63
	v_add_f32_e32 v67, v59, v63
	v_pk_add_f32 v[64:65], v[60:61], v[64:65] neg_lo:[0,1] neg_hi:[0,1]
	v_pk_add_f32 v[132:133], v[60:61], v[66:67]
	s_waitcnt lgkmcnt(1)
	v_mfma_f32_32x32x16_bf16 v[4:19], v[54:57], v[96:99], v[4:19]
	v_mov_b32_e32 v65, v133
	v_mov_b32_e32 v63, v60
	v_add_f32_e64 v134, v62, -v64
	v_add_f32_e64 v135, v63, -v65
	v_add_f32_e64 v62, v62, v64
	v_add_f32_e64 v63, v63, v65
	v_mov_b32_e32 v66, v67
	v_mov_b32_e32 v67, v60
	v_mov_b32_e32 v135, v63
	v_mfma_f32_32x32x16_bf16 v[20:35], v[54:57], v[92:95], v[20:35]
	v_add_f32_e64 v54, v63, -v60
	v_add_f32_e64 v55, v62, -v61
	v_add_f32_e64 v64, v132, -v54
	v_add_f32_e64 v65, v133, -v54
	v_mov_b32_e32 v56, v133
	v_mov_b32_e32 v57, v63
	v_pk_mov_b32 v[54:55], v[60:61], v[54:55] op_sel:[1,0]
	v_mov_b32_e32 v64, v134
	v_pk_add_f32 v[132:133], v[56:57], v[54:55] neg_lo:[0,1] neg_hi:[0,1]
	v_add_u32_e32 v54, v138, v145
	ds_read_b128 v[54:57], v54 offset:36864
	s_waitcnt lgkmcnt(1)
	v_mfma_f32_32x32x16_bf16 v[4:19], v[50:53], v[88:91], v[4:19]
	v_add_f32_e64 v60, v66, -v132
	v_add_f32_e64 v61, v67, -v133
	s_mov_b32 s2, 0x33800000
	v_add_f32_e64 v64, v64, v60
	v_add_f32_e64 v65, v65, v61
	v_pk_add_f32 v[66:67], v[64:65], v[64:65] op_sel:[0,1] op_sel_hi:[1,0]
	s_nop 0
	v_pk_add_f32 v[62:63], v[62:63], v[66:67] op_sel:[1,0] op_sel_hi:[0,1]
	v_mfma_f32_32x32x16_bf16 v[20:35], v[50:53], v[80:83], v[20:35]
	v_add_u32_e32 v50, v138, v146
	ds_read_b128 v[50:53], v50 offset:36864
	v_mov_b32_e32 v65, v62
	v_add_f32_e64 v132, v64, -v134
	v_add_f32_e64 v133, v65, -v135
	v_mov_b32_e32 v61, v66
	v_sub_f32_e32 v59, v64, v132
	v_pk_add_f32 v[60:61], v[60:61], v[132:133] neg_lo:[0,1] neg_hi:[0,1]
	s_waitcnt lgkmcnt(1)
	v_mfma_f32_32x32x16_bf16 v[4:19], v[54:57], v[84:87], v[4:19]
	v_sub_f32_e32 v59, v134, v59
	v_add_f32_e32 v59, v60, v59
	v_mfma_f32_32x32x16_bf16 v[20:35], v[54:57], v[72:75], v[20:35]
	v_add_f32_e32 v54, v59, v61
	v_add_f32_e32 v54, v62, v54
	v_cndmask_b32_e32 v54, v194, v54, vcc
	v_cmp_lt_f32_e64 vcc, |v58|, s2
	s_mov_b32 s2, 0xbe800000
	s_nop 0
	v_cndmask_b32_e32 v58, v54, v58, vcc
	s_waitcnt lgkmcnt(0)
	v_mfma_f32_32x32x16_bf16 v[4:19], v[50:53], v[76:79], v[4:19]
	v_mul_f32_e32 v215, 0xc1000000, v58
	v_add_u32_e32 v54, s47, v136
	v_ashrrev_i32_e32 v55, 31, v54
	v_lshlrev_b64 v[54:55], 12, v[54:55]
	v_lshl_add_u64 v[56:57], s[40:41], 0, v[54:55]
	v_lshl_add_u64 v[54:55], s[42:43], 0, v[54:55]
	v_lshl_add_u64 v[134:135], v[56:57], 0, v[48:49]
	v_mfma_f32_32x32x16_bf16 v[20:35], v[50:53], v[68:71], v[20:35]
	s_nop 3
	v_add_f32_e32 v4, v154, v4
	v_mul_f32_e32 v4, 0xbfb8aa3b, v4
	v_exp_f32_e32 v4, v4
	v_lshl_add_u64 v[132:133], v[54:55], 0, v[48:49]
	ds_read_u16 v48, v150
	ds_read_u16 v49, v150 offset:256
	ds_read_u16 v50, v150 offset:512
	ds_read_u16 v51, v150 offset:768
	ds_read_u16 v52, v150 offset:1024
	ds_read_u16 v53, v150 offset:1280
	ds_read_u16 v54, v150 offset:1536
	ds_read_u16 v55, v150 offset:2048
	s_waitcnt lgkmcnt(7)
; __device__ __forceinline__ float bf2f(unsigned short b) { return __uint_as_float(((unsigned)b) << 16); }
; template <int PASS> __device__ __forceinline__ void lru_pass(const bf16* __restrict__ Z, const bf16* __restrict__ LW, const float* __restrict__ cw_g, const float* __restrict__ cb_g, const float* __restrict__ b_a, const float* __restrict__ b_x, const float* __restrict__ lam, ...
;     ...
;                 for (int gq = 0; gq < 4; ++gq) { const int t0 = tl0 + 8 * gq + 4 * hh; float cxr[7];
; #pragma unroll
;                     for (int q = 0; q < 7; ++q) cxr[q] = bf2f(RAW[(t0 + q) * 128 + dd]);
; #pragma unroll
;                     for (int e = 0; e < 4; ++e) { const int i = 4 * gq + e;
;                         const float xc = wb + w0 * cxr[e] + w1 * cxr[e + 1] + w2 * cxr[e + 2] + w3 * cxr[e + 3];
;                         const float rr = __builtin_amdgcn_rcpf(1.f + __expf(-(accA[i] + bav))), ig = __builtin_amdgcn_rcpf(1.f + __expf(-(accX[i] + bxv)));
;                         const float la = -sp8 * rr, a_ = __expf(la); av[tt][i] = a_; uv[tt][i] = __builtin_amdgcn_sqrtf(neg_expm1_small(2.f * la, a_)) * (ig * xc);
;                         pa[(32 * tt + 8 * gq + e) * 1024] = av[tt][i]; pu[(32 * tt + 8 * gq + e) * 1024] = uv[tt][i]; } }
	v_lshlrev_b32_e32 v180, 16, v48
	v_add_f32_e32 v4, 1.0, v4
	v_add_f32_e32 v20, v153, v20
	v_mul_f32_e32 v20, 0xbfb8aa3b, v20
	v_exp_f32_e32 v20, v20
	v_rcp_f32_e32 v4, v4
	v_add_f32_e32 v6, v154, v6
	v_mul_f32_e32 v6, 0xbfb8aa3b, v6
	v_add_f32_e32 v20, 1.0, v20
	v_mul_f32_e32 v4, v215, v4
	v_rcp_f32_e32 v162, v20
	v_mul_f32_e32 v20, 0x3fb8aa3b, v4
	v_add_f32_e32 v4, v4, v4
	v_exp_f32_e32 v219, v20
	v_fmamk_f32 v20, v4, 0x3ab60b61, v185
	v_fmaak_f32 v20, v4, v20, 0x3d2aaaab
	v_fmaak_f32 v20, v4, v20, 0x3e2aaaab
	v_fma_f32 v20, v4, v20, 0.5
	v_fma_f32 v20, v4, v20, 1.0
	v_mul_f32_e64 v20, v20, -v4
	v_fma_f32 v48, -v219, v219, 1.0
	v_cmp_lt_f32_e32 vcc, s2, v4
	v_exp_f32_e32 v6, v6
	global_store_dword v[134:135], v219, off
	v_cndmask_b32_e32 v4, v48, v20, vcc
	v_sqrt_f32_e32 v173, v4
	v_add_f32_e32 v4, v154, v5
	v_mul_f32_e32 v4, 0xbfb8aa3b, v4
	v_exp_f32_e32 v4, v4
	v_add_f32_e32 v5, v153, v21
	v_mul_f32_e32 v5, 0xbfb8aa3b, v5
	v_exp_f32_e32 v5, v5
	v_add_f32_e32 v4, 1.0, v4
	v_rcp_f32_e32 v4, v4
	v_add_f32_e32 v6, 1.0, v6
	v_add_f32_e32 v5, 1.0, v5
	v_rcp_f32_e32 v174, v5
	v_mul_f32_e32 v4, v215, v4
	v_mul_f32_e32 v5, 0x3fb8aa3b, v4
	v_add_f32_e32 v4, v4, v4
	v_exp_f32_e32 v156, v5
	v_fmamk_f32 v5, v4, 0x3ab60b61, v185
	v_fmaak_f32 v5, v4, v5, 0x3d2aaaab
	v_fmaak_f32 v5, v4, v5, 0x3e2aaaab
	v_fma_f32 v5, v4, v5, 0.5
	v_fma_f32 v5, v4, v5, 1.0
	v_mul_f32_e64 v5, v5, -v4
	v_fma_f32 v20, -v156, v156, 1.0
	v_cmp_lt_f32_e32 vcc, s2, v4
	v_rcp_f32_e32 v6, v6
	s_mov_b32 s47, 0x11000
	v_cndmask_b32_e32 v4, v20, v5, vcc
	v_add_f32_e32 v20, v153, v22
	v_mul_f32_e32 v20, 0xbfb8aa3b, v20
	v_exp_f32_e32 v20, v20
	v_mul_f32_e32 v6, v215, v6
	v_sqrt_f32_e32 v176, v4
	v_add_co_u32_e32 v4, vcc, s88, v134
	v_add_f32_e32 v20, 1.0, v20
	v_rcp_f32_e32 v177, v20
	v_mul_f32_e32 v20, 0x3fb8aa3b, v6
	v_add_f32_e32 v6, v6, v6
	v_exp_f32_e32 v157, v20
	v_fmamk_f32 v20, v6, 0x3ab60b61, v185
	v_fmaak_f32 v20, v6, v20, 0x3d2aaaab
	v_fmaak_f32 v20, v6, v20, 0x3e2aaaab
	v_fma_f32 v20, v6, v20, 0.5
	v_addc_co_u32_e32 v5, vcc, 0, v135, vcc
	v_fma_f32 v20, v6, v20, 1.0
	v_mul_f32_e64 v20, v20, -v6
	v_fma_f32 v21, -v157, v157, 1.0
	v_cmp_lt_f32_e32 vcc, s2, v6
	global_store_dword v[4:5], v156, off offset:-4096
	global_store_dword v[4:5], v157, off
	v_cndmask_b32_e32 v6, v21, v20, vcc
	v_sqrt_f32_e32 v178, v6
	v_add_f32_e32 v6, v154, v7
	v_mul_f32_e32 v6, 0xbfb8aa3b, v6
	v_exp_f32_e32 v6, v6
	v_add_f32_e32 v7, v153, v23
	v_mul_f32_e32 v7, 0xbfb8aa3b, v7
	v_exp_f32_e32 v7, v7
	v_add_f32_e32 v6, 1.0, v6
	v_rcp_f32_e32 v6, v6
	s_waitcnt lgkmcnt(3)
	v_lshlrev_b32_e32 v160, 16, v52
	v_add_f32_e32 v4, 1.0, v7
	v_rcp_f32_e32 v23, v4
	v_mul_f32_e32 v4, v215, v6
	v_mul_f32_e32 v5, 0x3fb8aa3b, v4
	v_add_f32_e32 v4, v4, v4
	v_exp_f32_e32 v155, v5
	v_fmamk_f32 v5, v4, 0x3ab60b61, v185
	v_fmaak_f32 v5, v4, v5, 0x3d2aaaab
	v_fmaak_f32 v5, v4, v5, 0x3e2aaaab
	v_fma_f32 v5, v4, v5, 0.5
	v_fma_f32 v5, v4, v5, 1.0
	v_mul_f32_e64 v5, v5, -v4
	v_fma_f32 v6, -v155, v155, 1.0
	v_cmp_lt_f32_e32 vcc, s2, v4
	s_waitcnt lgkmcnt(2)
	v_lshlrev_b32_e32 v158, 16, v53
	s_waitcnt lgkmcnt(1)
	v_lshlrev_b32_e32 v159, 16, v54
	v_cndmask_b32_e32 v4, v6, v5, vcc
	v_sqrt_f32_e32 v179, v4
	v_add_co_u32_e32 v4, vcc, s48, v134
	s_waitcnt lgkmcnt(0)
	v_lshlrev_b32_e32 v206, 16, v55
	v_addc_co_u32_e32 v5, vcc, 0, v135, vcc
	global_store_dword v[4:5], v155, off
	ds_read_u16 v4, v150 offset:2304
	ds_read_u16 v5, v150 offset:2560
	ds_read_u16 v6, v150 offset:2816
	ds_read_u16 v7, v150 offset:3072
	ds_read_u16 v20, v150 offset:3328
	ds_read_u16 v21, v150 offset:3584
	ds_read_u16 v217, v150 offset:4096
	ds_read_u16 v218, v150 offset:4352
	s_waitcnt lgkmcnt(7)
	v_lshlrev_b32_e32 v211, 16, v4
	v_add_f32_e32 v4, v154, v8
	v_mul_f32_e32 v4, 0xbfb8aa3b, v4
	v_exp_f32_e32 v4, v4
	s_waitcnt lgkmcnt(6)
	v_lshlrev_b32_e32 v208, 16, v5
	v_add_f32_e32 v5, v153, v24
	v_mul_f32_e32 v5, 0xbfb8aa3b, v5
	v_add_f32_e32 v4, 1.0, v4
	v_exp_f32_e32 v5, v5
	v_rcp_f32_e32 v4, v4
	s_waitcnt lgkmcnt(5)
	v_lshlrev_b32_e32 v203, 16, v6
	s_waitcnt lgkmcnt(4)
	v_lshlrev_b32_e32 v183, 16, v7
	v_add_f32_e32 v5, 1.0, v5
	v_mul_f32_e32 v4, v215, v4
	v_rcp_f32_e32 v204, v5
	v_mul_f32_e32 v5, 0x3fb8aa3b, v4
	v_add_f32_e32 v4, v4, v4
	v_exp_f32_e32 v8, v5
	v_fmamk_f32 v5, v4, 0x3ab60b61, v185
	v_fmaak_f32 v5, v4, v5, 0x3d2aaaab
	v_fmaak_f32 v5, v4, v5, 0x3e2aaaab
	v_fma_f32 v5, v4, v5, 0.5
	v_fma_f32 v5, v4, v5, 1.0
	v_mul_f32_e64 v5, v5, -v4
	v_fma_f32 v6, -v8, v8, 1.0
	v_cmp_lt_f32_e32 vcc, s2, v4
	v_add_f32_e32 v7, v153, v25
	v_mul_f32_e32 v7, 0xbfb8aa3b, v7
	v_cndmask_b32_e32 v4, v6, v5, vcc
	v_add_f32_e32 v6, v154, v9
	v_mul_f32_e32 v6, 0xbfb8aa3b, v6
	v_exp_f32_e32 v6, v6
	v_exp_f32_e32 v7, v7
	s_waitcnt lgkmcnt(3)
	v_lshlrev_b32_e32 v182, 16, v20
	v_sqrt_f32_e32 v205, v4
	v_add_f32_e32 v6, 1.0, v6
	v_rcp_f32_e32 v6, v6
	v_add_f32_e32 v7, 1.0, v7
	v_rcp_f32_e32 v207, v7
	v_add_co_u32_e32 v4, vcc, s4, v134
	v_mul_f32_e32 v6, v215, v6
	v_mul_f32_e32 v7, 0x3fb8aa3b, v6
	v_add_f32_e32 v6, v6, v6
	v_exp_f32_e32 v20, v7
	v_fmamk_f32 v7, v6, 0x3ab60b61, v185
	v_fmaak_f32 v7, v6, v7, 0x3d2aaaab
	v_fmaak_f32 v7, v6, v7, 0x3e2aaaab
	v_fma_f32 v7, v6, v7, 0.5
	v_addc_co_u32_e32 v5, vcc, 0, v135, vcc
	v_fma_f32 v7, v6, v7, 1.0
	v_mul_f32_e64 v7, v7, -v6
	v_fma_f32 v9, -v20, v20, 1.0
	v_cmp_lt_f32_e32 vcc, s2, v6
	global_store_dword v[4:5], v8, off offset:-4096
	global_store_dword v[4:5], v20, off
	v_cndmask_b32_e32 v6, v9, v7, vcc
	v_sqrt_f32_e32 v209, v6
	v_add_f32_e32 v6, v154, v10
	v_mul_f32_e32 v6, 0xbfb8aa3b, v6
	v_exp_f32_e32 v6, v6
	v_add_f32_e32 v7, v153, v26
	v_mul_f32_e32 v7, 0xbfb8aa3b, v7
	v_exp_f32_e32 v7, v7
	v_add_f32_e32 v6, 1.0, v6
	v_rcp_f32_e32 v6, v6
	s_waitcnt lgkmcnt(2)
; __device__ __forceinline__ float bf2f(unsigned short b) { return __uint_as_float(((unsigned)b) << 16); }
; template <int PASS> __device__ __forceinline__ void lru_pass(const bf16* __restrict__ Z, const bf16* __restrict__ LW, const float* __restrict__ cw_g, const float* __restrict__ cb_g, const float* __restrict__ b_a, const float* __restrict__ b_x, const float* __restrict__ lam, ...
;     ...
;                 for (int gq = 0; gq < 4; ++gq) { const int t0 = tl0 + 8 * gq + 4 * hh; float cxr[7];
; #pragma unroll
;                     for (int q = 0; q < 7; ++q) cxr[q] = bf2f(RAW[(t0 + q) * 128 + dd]);
; #pragma unroll
;                     for (int e = 0; e < 4; ++e) { const int i = 4 * gq + e;
;                         const float xc = wb + w0 * cxr[e] + w1 * cxr[e + 1] + w2 * cxr[e + 2] + w3 * cxr[e + 3];
;                         const float rr = __builtin_amdgcn_rcpf(1.f + __expf(-(accA[i] + bav))), ig = __builtin_amdgcn_rcpf(1.f + __expf(-(accX[i] + bxv)));
;                         const float la = -sp8 * rr, a_ = __expf(la); av[tt][i] = a_; uv[tt][i] = __builtin_amdgcn_sqrtf(neg_expm1_small(2.f * la, a_)) * (ig * xc);
;                         pa[(32 * tt + 8 * gq + e) * 1024] = av[tt][i]; pu[(32 * tt + 8 * gq + e) * 1024] = uv[tt][i]; } }
	v_lshlrev_b32_e32 v181, 16, v21
	v_add_f32_e32 v4, 1.0, v7
	v_rcp_f32_e32 v210, v4
	v_mul_f32_e32 v4, v215, v6
	v_mul_f32_e32 v5, 0x3fb8aa3b, v4
	v_add_f32_e32 v4, v4, v4
	v_exp_f32_e32 v10, v5
	v_fmamk_f32 v5, v4, 0x3ab60b61, v185
	v_fmaak_f32 v5, v4, v5, 0x3d2aaaab
	v_fmaak_f32 v5, v4, v5, 0x3e2aaaab
	v_fma_f32 v5, v4, v5, 0.5
	v_fma_f32 v5, v4, v5, 1.0
	v_mul_f32_e64 v5, v5, -v4
	v_fma_f32 v6, -v10, v10, 1.0
	v_cmp_lt_f32_e32 vcc, s2, v4
	v_add_f32_e32 v7, v153, v27
	v_mul_f32_e32 v7, 0xbfb8aa3b, v7
	v_cndmask_b32_e32 v4, v6, v5, vcc
	v_add_f32_e32 v6, v154, v11
	v_mul_f32_e32 v6, 0xbfb8aa3b, v6
	v_exp_f32_e32 v6, v6
	v_exp_f32_e32 v7, v7
	v_add_f32_e32 v11, v154, v12
	v_mul_f32_e32 v11, 0xbfb8aa3b, v11
	v_add_f32_e32 v6, 1.0, v6
	v_rcp_f32_e32 v6, v6
	v_add_f32_e32 v7, 1.0, v7
	v_rcp_f32_e32 v213, v7
	v_exp_f32_e32 v11, v11
	v_mul_f32_e32 v6, v215, v6
	v_mul_f32_e32 v7, 0x3fb8aa3b, v6
	v_exp_f32_e32 v22, v7
	v_sqrt_f32_e32 v212, v4
	v_add_co_u32_e32 v4, vcc, s5, v134
	v_add_f32_e32 v6, v6, v6
	s_nop 0
	v_addc_co_u32_e32 v5, vcc, 0, v135, vcc
	global_store_dword v[4:5], v10, off offset:-4096
	global_store_dword v[4:5], v22, off
	v_add_f32_e32 v5, v153, v28
	v_add_f32_e32 v4, 1.0, v11
	v_mul_f32_e32 v5, 0xbfb8aa3b, v5
	v_rcp_f32_e32 v4, v4
	v_exp_f32_e32 v5, v5
	v_fmamk_f32 v7, v6, 0x3ab60b61, v185
	v_fmaak_f32 v7, v6, v7, 0x3d2aaaab
	v_mul_f32_e32 v4, v215, v4
	v_add_f32_e32 v5, 1.0, v5
	v_fmaak_f32 v7, v6, v7, 0x3e2aaaab
	v_rcp_f32_e32 v223, v5
	v_mul_f32_e32 v5, 0x3fb8aa3b, v4
	v_add_f32_e32 v4, v4, v4
	v_fma_f32 v7, v6, v7, 0.5
	v_exp_f32_e32 v21, v5
	v_fmamk_f32 v5, v4, 0x3ab60b61, v185
	v_fma_f32 v7, v6, v7, 1.0
	v_fmaak_f32 v5, v4, v5, 0x3d2aaaab
	v_mul_f32_e64 v7, v7, -v6
	v_fma_f32 v9, -v22, v22, 1.0
	v_cmp_lt_f32_e32 vcc, s2, v6
	v_fmaak_f32 v5, v4, v5, 0x3e2aaaab
	v_fma_f32 v5, v4, v5, 0.5
	v_cndmask_b32_e32 v6, v9, v7, vcc
	v_sqrt_f32_e32 v214, v6
	ds_read_u16 v28, v150 offset:4608
	ds_read_u16 v26, v150 offset:4864
	ds_read_u16 v6, v150 offset:5120
	ds_read_u16 v220, v150 offset:5376
	ds_read_u16 v221, v150 offset:5632
	ds_read_u16 v24, v150 offset:6144
	ds_read_u16 v224, v150 offset:6400
	ds_read_u16 v9, v150 offset:6656
	v_fma_f32 v5, v4, v5, 1.0
	s_waitcnt lgkmcnt(5)
	v_lshlrev_b32_e32 v27, 16, v6
	v_mul_f32_e64 v5, v5, -v4
	v_fma_f32 v6, -v21, v21, 1.0
	v_cmp_lt_f32_e32 vcc, s2, v4
	v_lshlrev_b32_e32 v175, 16, v49
	v_lshlrev_b32_e32 v163, 16, v50
	v_cndmask_b32_e32 v4, v6, v5, vcc
	v_sqrt_f32_e32 v25, v4
	v_add_f32_e32 v4, v154, v13
	v_mul_f32_e32 v4, 0xbfb8aa3b, v4
	v_exp_f32_e32 v4, v4
	v_add_f32_e32 v5, v153, v29
	v_mul_f32_e32 v5, 0xbfb8aa3b, v5
	v_exp_f32_e32 v5, v5
	v_add_f32_e32 v4, 1.0, v4
	v_rcp_f32_e32 v4, v4
	v_add_co_u32_e32 v164, vcc, s47, v134
	v_add_f32_e32 v5, 1.0, v5
	v_mul_f32_e32 v11, v215, v4
	v_add_u32_e32 v4, v147, v139
	v_mul_f32_e32 v12, 0x3fb8aa3b, v11
	v_add_f32_e32 v11, v11, v11
	v_rcp_f32_e32 v216, v5
	ds_read_b128 v[4:7], v4 offset:36864
	v_exp_f32_e32 v29, v12
	v_fmamk_f32 v12, v11, 0x3ab60b61, v185
	v_fmaak_f32 v12, v11, v12, 0x3d2aaaab
	v_fmaak_f32 v12, v11, v12, 0x3e2aaaab
	v_fma_f32 v12, v11, v12, 0.5
	v_addc_co_u32_e32 v165, vcc, 0, v135, vcc
	v_add_u32_e32 v13, v147, v140
	v_fma_f32 v12, v11, v12, 1.0
	ds_read_b128 v[226:229], v13 offset:36864
	v_mul_f32_e64 v12, v12, -v11
	v_fma_f32 v13, -v29, v29, 1.0
	v_cmp_lt_f32_e32 vcc, s2, v11
	s_waitcnt lgkmcnt(1)
	v_mfma_f32_32x32x16_bf16 v[52:67], v[4:7], v[40:43], 0
	v_lshlrev_b32_e32 v161, 16, v51
	v_cndmask_b32_e32 v11, v13, v12, vcc
	v_add_f32_e32 v12, v154, v14
	v_mul_f32_e32 v12, 0xbfb8aa3b, v12
	v_exp_f32_e32 v12, v12
	v_add_f32_e32 v13, v153, v30
	v_mul_f32_e32 v13, 0xbfb8aa3b, v13
	v_exp_f32_e32 v13, v13
	v_add_f32_e32 v12, 1.0, v12
	v_rcp_f32_e32 v12, v12
	s_waitcnt lgkmcnt(0)
	v_mfma_f32_32x32x16_bf16 v[52:67], v[226:229], v[36:39], v[52:67]
	v_add_f32_e32 v15, v154, v15
	v_sqrt_f32_e32 v222, v11
	v_add_f32_e32 v11, 1.0, v13
	v_mul_f32_e32 v15, 0xbfb8aa3b, v15
	v_exp_f32_e32 v15, v15
	global_store_dword v[164:165], v21, off offset:-4096
	global_store_dword v[164:165], v29, off
	v_mfma_f32_32x32x16_bf16 v[36:51], v[4:7], v[44:47], 0
	v_mul_f32_e32 v4, v215, v12
	v_add_f32_e32 v12, v4, v4
	v_mul_f32_e32 v5, 0x3fb8aa3b, v4
	v_fmamk_f32 v14, v12, 0x3ab60b61, v185
	v_exp_f32_e32 v13, v5
	v_fmaak_f32 v14, v12, v14, 0x3d2aaaab
	v_fmaak_f32 v14, v12, v14, 0x3e2aaaab
	v_fma_f32 v14, v12, v14, 0.5
	v_fma_f32 v14, v12, v14, 1.0
	v_mul_f32_e64 v14, v14, -v12
	v_fma_f32 v30, -v13, v13, 1.0
	v_cmp_lt_f32_e32 vcc, s2, v12
	v_mfma_f32_32x32x16_bf16 v[36:51], v[226:229], v[116:119], v[36:51]
	v_add_u32_e32 v4, v147, v141
	v_cndmask_b32_e32 v12, v30, v14, vcc
	v_add_f32_e32 v14, 1.0, v15
	v_rcp_f32_e32 v14, v14
	v_add_f32_e32 v30, v153, v31
	v_mul_f32_e32 v30, 0xbfb8aa3b, v30
	v_exp_f32_e32 v31, v30
	v_mul_f32_e32 v14, v215, v14
	v_mul_f32_e32 v15, 0x3fb8aa3b, v14
	v_add_f32_e32 v14, v14, v14
	v_fmamk_f32 v30, v14, 0x3ab60b61, v185
	v_exp_f32_e32 v15, v15
	v_fmaak_f32 v30, v14, v30, 0x3d2aaaab
	v_fmaak_f32 v30, v14, v30, 0x3e2aaaab
	v_add_co_u32_e32 v116, vcc, s49, v134
	v_fma_f32 v30, v14, v30, 0.5
	s_nop 0
	v_addc_co_u32_e32 v117, vcc, 0, v135, vcc
	v_fma_f32 v30, v14, v30, 1.0
	v_mul_f32_e64 v30, v30, -v14
	v_cmp_lt_f32_e32 vcc, s2, v14
	v_fma_f32 v14, -v15, v15, 1.0
	ds_read_b128 v[4:7], v4 offset:36864
	v_cndmask_b32_e32 v14, v14, v30, vcc
	v_rcp_f32_e32 v30, v11
	v_add_f32_e32 v11, 1.0, v31
	global_store_dword v[116:117], v13, off offset:-4096
	global_store_dword v[116:117], v15, off
	v_rcp_f32_e32 v116, v11
	v_add_f32_e32 v11, v154, v16
	v_mul_f32_e32 v11, 0xbfb8aa3b, v11
	v_exp_f32_e32 v11, v11
	v_add_f32_e32 v16, v153, v32
	v_mul_f32_e32 v16, 0xbfb8aa3b, v16
	v_exp_f32_e32 v16, v16
	v_add_f32_e32 v11, 1.0, v11
	v_rcp_f32_e32 v11, v11
	s_waitcnt lgkmcnt(0)
; #define LAS __attribute__((address_space(3)))
; __device__ __forceinline__ float bf2f(unsigned short b) { return __uint_as_float(((unsigned)b) << 16); }
; #define MFMA32(a, b, c) __builtin_amdgcn_mfma_f32_32x32x16_bf16((a), (b), (c), 0, 0, 0)
; template <int PASS> __device__ __forceinline__ void lru_pass(const bf16* __restrict__ Z, const bf16* __restrict__ LW, const float* __restrict__ cw_g, const float* __restrict__ cb_g, const float* __restrict__ b_a, const float* __restrict__ b_x, const float* __restrict__ lam, ...
;     ...
;                 for (int s = 0; s < 8; ++s) { const bf16x8 af = *(const LAS bf16x8*)(XC + (tl0 + r) * 256 + (((2 * s + hh) ^ (r & 15)) << 4)); accA = MFMA32(af, ba[s], accA); accX = MFMA32(af, bx[s], accX); }
; #pragma unroll
;                 for (int gq = 0; gq < 4; ++gq) { const int t0 = tl0 + 8 * gq + 4 * hh; float cxr[7];
; #pragma unroll
;                     for (int q = 0; q < 7; ++q) cxr[q] = bf2f(RAW[(t0 + q) * 128 + dd]);
; #pragma unroll
;                     for (int e = 0; e < 4; ++e) { const int i = 4 * gq + e;
;                         const float xc = wb + w0 * cxr[e] + w1 * cxr[e + 1] + w2 * cxr[e + 2] + w3 * cxr[e + 3];
;                         const float rr = __builtin_amdgcn_rcpf(1.f + __expf(-(accA[i] + bav))), ig = __builtin_amdgcn_rcpf(1.f + __expf(-(accX[i] + bxv)));
;                         const float la = -sp8 * rr, a_ = __expf(la); av[tt][i] = a_; uv[tt][i] = __builtin_amdgcn_sqrtf(neg_expm1_small(2.f * la, a_)) * (ig * xc);
;                         pa[(32 * tt + 8 * gq + e) * 1024] = av[tt][i]; pu[(32 * tt + 8 * gq + e) * 1024] = uv[tt][i]; } }
	v_mfma_f32_32x32x16_bf16 v[52:67], v[4:7], v[112:115], v[52:67]
	v_lshlrev_b32_e32 v113, 16, v9
	v_add_f32_e32 v9, 1.0, v16
	v_rcp_f32_e32 v31, v9
	v_mul_f32_e32 v9, v215, v11
	v_mul_f32_e32 v11, 0x3fb8aa3b, v9
	v_add_f32_e32 v9, v9, v9
	v_cmp_lt_f32_e32 vcc, s2, v9
	v_mfma_f32_32x32x16_bf16 v[36:51], v[4:7], v[108:111], v[36:51]
	v_fmamk_f32 v4, v9, 0x3ab60b61, v185
	v_exp_f32_e32 v110, v11
	v_fmaak_f32 v4, v9, v4, 0x3d2aaaab
	v_fmaak_f32 v4, v9, v4, 0x3e2aaaab
	v_fma_f32 v4, v9, v4, 0.5
	v_fma_f32 v11, v9, v4, 1.0
	v_mul_f32_e64 v11, v11, -v9
	v_fma_f32 v16, -v110, v110, 1.0
	v_cndmask_b32_e32 v9, v16, v11, vcc
	v_sqrt_f32_e32 v109, v9
	v_add_f32_e32 v9, v154, v17
	v_mul_f32_e32 v9, 0xbfb8aa3b, v9
	v_exp_f32_e32 v9, v9
	v_add_u32_e32 v4, v147, v142
	ds_read_u16 v118, v150 offset:15872
	ds_read_b128 v[4:7], v4 offset:36864
	v_add_f32_e32 v11, v153, v33
	v_mul_f32_e32 v11, 0xbfb8aa3b, v11
	v_add_f32_e32 v9, 1.0, v9
	v_exp_f32_e32 v11, v11
	v_rcp_f32_e32 v9, v9
	s_waitcnt lgkmcnt(0)
	v_mfma_f32_32x32x16_bf16 v[36:51], v[4:7], v[100:103], v[36:51]
	v_add_f32_e32 v11, 1.0, v11
	v_mul_f32_e32 v9, v215, v9
	v_rcp_f32_e32 v117, v11
	v_mul_f32_e32 v11, 0x3fb8aa3b, v9
	v_add_f32_e32 v9, v9, v9
	v_exp_f32_e32 v100, v11
	v_fmamk_f32 v11, v9, 0x3ab60b61, v185
	v_fmaak_f32 v11, v9, v11, 0x3d2aaaab
	v_fmaak_f32 v11, v9, v11, 0x3e2aaaab
	v_add_co_u32_e32 v16, vcc, s55, v134
	v_fma_f32 v11, v9, v11, 0.5
	v_add_f32_e32 v18, v154, v18
	v_addc_co_u32_e32 v17, vcc, 0, v135, vcc
	v_add_u32_e32 v32, v147, v143
	v_fma_f32 v11, v9, v11, 1.0
	v_mul_f32_e32 v18, 0xbfb8aa3b, v18
	v_mfma_f32_32x32x16_bf16 v[52:67], v[4:7], v[104:107], v[52:67]
	ds_read_b128 v[4:7], v32 offset:36864
	v_mul_f32_e64 v11, v11, -v9
	v_fma_f32 v32, -v100, v100, 1.0
	v_exp_f32_e32 v18, v18
	v_cmp_lt_f32_e32 vcc, s2, v9
	global_store_dword v[16:17], v110, off offset:-4096
	global_store_dword v[16:17], v100, off
	v_cndmask_b32_e32 v9, v32, v11, vcc
	v_sqrt_f32_e32 v103, v9
	v_add_f32_e32 v9, v153, v34
	v_mul_f32_e32 v9, 0xbfb8aa3b, v9
	v_exp_f32_e32 v9, v9
	v_add_f32_e32 v11, 1.0, v18
	v_rcp_f32_e32 v11, v11
	v_add_u32_e32 v16, v147, v144
	v_add_f32_e32 v9, 1.0, v9
	v_rcp_f32_e32 v102, v9
	v_mul_f32_e32 v9, v215, v11
	v_mul_f32_e32 v11, 0x3fb8aa3b, v9
	v_add_f32_e32 v9, v9, v9
	s_waitcnt lgkmcnt(0)
	v_mfma_f32_32x32x16_bf16 v[52:67], v[4:7], v[96:99], v[52:67]
	ds_read_b128 v[96:99], v16 offset:36864
	v_exp_f32_e32 v104, v11
	v_fmamk_f32 v11, v9, 0x3ab60b61, v185
	v_fmaak_f32 v11, v9, v11, 0x3d2aaaab
	v_fmaak_f32 v11, v9, v11, 0x3e2aaaab
	v_fma_f32 v11, v9, v11, 0.5
	v_fma_f32 v11, v9, v11, 1.0
	v_mfma_f32_32x32x16_bf16 v[36:51], v[4:7], v[92:95], v[36:51]
	v_mul_f32_e64 v4, v11, -v9
	v_fma_f32 v5, -v104, v104, 1.0
	v_cmp_lt_f32_e32 vcc, s2, v9
	v_add_u32_e32 v9, v147, v146
	v_add_f32_e32 v6, v153, v35
	v_cndmask_b32_e32 v4, v5, v4, vcc
	v_add_u32_e32 v5, v147, v145
	ds_read_b128 v[92:95], v5 offset:36864
	s_waitcnt lgkmcnt(1)
	v_mfma_f32_32x32x16_bf16 v[52:67], v[96:99], v[88:91], v[52:67]
	v_add_f32_e32 v5, v154, v19
	v_mul_f32_e32 v5, 0xbfb8aa3b, v5
	v_exp_f32_e32 v5, v5
	ds_read_b128 v[16:19], v9 offset:36864
	v_mul_f32_e32 v6, 0xbfb8aa3b, v6
	v_exp_f32_e32 v6, v6
	v_add_f32_e32 v5, 1.0, v5
	v_mfma_f32_32x32x16_bf16 v[36:51], v[96:99], v[80:83], v[36:51]
	v_rcp_f32_e32 v5, v5
	v_add_f32_e32 v6, 1.0, v6
	v_rcp_f32_e32 v119, v6
	s_mov_b32 s55, 0x1b000
	v_mul_f32_e32 v5, v215, v5
	v_mul_f32_e32 v6, 0x3fb8aa3b, v5
	v_add_f32_e32 v5, v5, v5
	s_waitcnt lgkmcnt(1)
	v_mfma_f32_32x32x16_bf16 v[52:67], v[92:95], v[84:87], v[52:67]
	v_exp_f32_e32 v7, v6
	v_fmamk_f32 v6, v5, 0x3ab60b61, v185
	v_fmaak_f32 v6, v5, v6, 0x3d2aaaab
	v_fmaak_f32 v6, v5, v6, 0x3e2aaaab
	v_add_co_u32_e32 v32, vcc, s55, v134
	v_fma_f32 v6, v5, v6, 0.5
	v_mfma_f32_32x32x16_bf16 v[36:51], v[92:95], v[72:75], v[36:51]
	v_addc_co_u32_e32 v33, vcc, 0, v135, vcc
	v_fma_f32 v6, v5, v6, 1.0
	v_mul_f32_e64 v6, v6, -v5
	v_fma_f32 v9, -v7, v7, 1.0
	v_cmp_lt_f32_e32 vcc, s2, v5
	global_store_dword v[32:33], v104, off offset:-4096
	s_waitcnt lgkmcnt(0)
	v_mfma_f32_32x32x16_bf16 v[52:67], v[16:19], v[76:79], v[52:67]
	v_cndmask_b32_e32 v5, v9, v6, vcc
	v_sqrt_f32_e32 v6, v5
	ds_read_u16 v85, v151
	ds_read_u16 v101, v151 offset:256
	ds_read_u16 v75, v151 offset:512
	global_store_dword v[32:33], v7, off
	v_mul_f32_e32 v21, v21, v29
	v_mul_f32_e32 v21, v13, v21
	v_lshlrev_b32_e32 v240, 16, v28
	v_mfma_f32_32x32x16_bf16 v[36:51], v[16:19], v[68:71], v[36:51]
	s_nop 1
	v_add_f32_e32 v5, v154, v52
	v_mul_f32_e32 v5, 0xbfb8aa3b, v5
	v_exp_f32_e32 v5, v5
	ds_read_u16 v84, v151 offset:768
	ds_read_u16 v71, v151 offset:1024
	ds_read_u16 v90, v151 offset:1280
	ds_read_u16 v91, v151 offset:1536
	v_add_f32_e32 v81, v154, v65
	v_add_f32_e32 v80, v154, v64
	v_add_f32_e32 v5, 1.0, v5
	v_add_f32_e32 v9, v153, v36
	v_mul_f32_e32 v9, 0xbfb8aa3b, v9
	v_rcp_f32_e32 v5, v5
	v_exp_f32_e32 v9, v9
	v_add_f32_e32 v44, v153, v44
	v_mul_f32_e32 v44, 0xbfb8aa3b, v44
	v_mul_f32_e32 v5, v215, v5
	v_add_f32_e32 v9, 1.0, v9
	v_rcp_f32_e32 v33, v9
	v_mul_f32_e32 v9, 0x3fb8aa3b, v5
	v_add_f32_e32 v5, v5, v5
	v_exp_f32_e32 v72, v9
	v_fmamk_f32 v9, v5, 0x3ab60b61, v185
	v_fmaak_f32 v9, v5, v9, 0x3d2aaaab
	v_fmaak_f32 v9, v5, v9, 0x3e2aaaab
	v_fma_f32 v9, v5, v9, 0.5
	v_fma_f32 v9, v5, v9, 1.0
	v_mul_f32_e64 v9, v9, -v5
	v_fma_f32 v11, -v72, v72, 1.0
	v_cmp_lt_f32_e32 vcc, s2, v5
	v_exp_f32_e32 v44, v44
	v_add_f32_e32 v45, v153, v45
	v_cndmask_b32_e32 v5, v11, v9, vcc
	v_sqrt_f32_e32 v35, v5
	v_add_f32_e32 v5, v154, v53
	v_mul_f32_e32 v5, 0xbfb8aa3b, v5
	v_exp_f32_e32 v5, v5
	v_add_f32_e32 v9, v153, v37
	v_mul_f32_e32 v9, 0xbfb8aa3b, v9
	v_exp_f32_e32 v9, v9
; __device__ __forceinline__ float bf2f(unsigned short b) { return __uint_as_float(((unsigned)b) << 16); }
; template <int PASS> __device__ __forceinline__ void lru_pass(const bf16* __restrict__ Z, const bf16* __restrict__ LW, const float* __restrict__ cw_g, const float* __restrict__ cb_g, const float* __restrict__ b_a, const float* __restrict__ b_x, const float* __restrict__ lam, ...
;     ...
;                 for (int gq = 0; gq < 4; ++gq) { const int t0 = tl0 + 8 * gq + 4 * hh; float cxr[7];
; #pragma unroll
;                     for (int q = 0; q < 7; ++q) cxr[q] = bf2f(RAW[(t0 + q) * 128 + dd]);
; #pragma unroll
;                     for (int e = 0; e < 4; ++e) { const int i = 4 * gq + e;
;                         const float xc = wb + w0 * cxr[e] + w1 * cxr[e + 1] + w2 * cxr[e + 2] + w3 * cxr[e + 3];
;                         const float rr = __builtin_amdgcn_rcpf(1.f + __expf(-(accA[i] + bav))), ig = __builtin_amdgcn_rcpf(1.f + __expf(-(accX[i] + bxv)));
;                         const float la = -sp8 * rr, a_ = __expf(la); av[tt][i] = a_; uv[tt][i] = __builtin_amdgcn_sqrtf(neg_expm1_small(2.f * la, a_)) * (ig * xc);
;                         pa[(32 * tt + 8 * gq + e) * 1024] = av[tt][i]; pu[(32 * tt + 8 * gq + e) * 1024] = uv[tt][i]; } }
	v_add_f32_e32 v5, 1.0, v5
	v_rcp_f32_e32 v5, v5
	v_add_co_u32_e32 v16, vcc, s56, v134
	v_add_f32_e32 v9, 1.0, v9
	v_mul_f32_e32 v5, v215, v5
	v_rcp_f32_e32 v32, v9
	v_mul_f32_e32 v9, 0x3fb8aa3b, v5
	v_add_f32_e32 v5, v5, v5
	v_exp_f32_e32 v73, v9
	v_fmamk_f32 v9, v5, 0x3ab60b61, v185
	v_fmaak_f32 v9, v5, v9, 0x3d2aaaab
	v_fmaak_f32 v9, v5, v9, 0x3e2aaaab
	v_fma_f32 v9, v5, v9, 0.5
	v_addc_co_u32_e32 v17, vcc, 0, v135, vcc
	v_fma_f32 v9, v5, v9, 1.0
	v_mul_f32_e64 v9, v9, -v5
	v_fma_f32 v11, -v73, v73, 1.0
	v_cmp_lt_f32_e32 vcc, s2, v5
	global_store_dword v[16:17], v72, off offset:-4096
	global_store_dword v[16:17], v73, off
	v_cndmask_b32_e32 v5, v11, v9, vcc
	v_sqrt_f32_e32 v34, v5
	v_add_f32_e32 v5, v154, v54
	v_mul_f32_e32 v5, 0xbfb8aa3b, v5
	v_exp_f32_e32 v5, v5
	v_add_f32_e32 v9, v153, v38
	v_mul_f32_e32 v9, 0xbfb8aa3b, v9
	v_exp_f32_e32 v9, v9
	v_add_f32_e32 v5, 1.0, v5
	v_rcp_f32_e32 v11, v5
	v_mul_f32_e32 v45, 0xbfb8aa3b, v45
	v_add_f32_e32 v5, 1.0, v9
	v_exp_f32_e32 v45, v45
	v_mul_f32_e32 v9, v215, v11
	v_mul_f32_e32 v11, 0x3fb8aa3b, v9
	v_add_f32_e32 v9, v9, v9
	v_exp_f32_e32 v17, v11
	v_fmamk_f32 v11, v9, 0x3ab60b61, v185
	v_fmaak_f32 v11, v9, v11, 0x3d2aaaab
	v_fmaak_f32 v11, v9, v11, 0x3e2aaaab
	v_fma_f32 v11, v9, v11, 0.5
	v_fma_f32 v11, v9, v11, 1.0
	v_mul_f32_e64 v11, v11, -v9
	v_fma_f32 v16, -v17, v17, 1.0
	v_cmp_lt_f32_e32 vcc, s2, v9
	v_add_f32_e32 v45, 1.0, v45
	v_add_f32_e32 v82, v154, v66
	v_cndmask_b32_e32 v9, v16, v11, vcc
	v_sqrt_f32_e32 v16, v9
	v_add_f32_e32 v9, v154, v55
	v_mul_f32_e32 v9, 0xbfb8aa3b, v9
	v_exp_f32_e32 v9, v9
	v_add_f32_e32 v11, v153, v39
	v_mul_f32_e32 v11, 0xbfb8aa3b, v11
	v_exp_f32_e32 v11, v11
	v_add_f32_e32 v9, 1.0, v9
	v_rcp_f32_e32 v18, v9
	v_add_co_u32_e32 v36, vcc, s57, v134
	v_add_f32_e32 v9, 1.0, v11
	v_mul_f32_e32 v11, v215, v18
	v_mul_f32_e32 v18, 0x3fb8aa3b, v11
	v_exp_f32_e32 v18, v18
	v_addc_co_u32_e32 v37, vcc, 0, v135, vcc
	global_store_dword v[36:37], v17, off offset:-4096
	global_store_dword v[36:37], v18, off
	v_add_f32_e32 v36, v154, v56
	v_add_f32_e32 v11, v11, v11
	v_mul_f32_e32 v36, 0xbfb8aa3b, v36
	v_fmamk_f32 v19, v11, 0x3ab60b61, v185
	v_exp_f32_e32 v36, v36
	v_fmaak_f32 v19, v11, v19, 0x3d2aaaab
	v_fmaak_f32 v19, v11, v19, 0x3e2aaaab
	v_add_f32_e32 v37, v153, v40
	v_fma_f32 v19, v11, v19, 0.5
	v_mul_f32_e32 v37, 0xbfb8aa3b, v37
	v_fma_f32 v19, v11, v19, 1.0
	v_exp_f32_e32 v37, v37
	v_add_f32_e32 v36, 1.0, v36
	v_mul_f32_e64 v19, v19, -v11
	v_fma_f32 v38, -v18, v18, 1.0
	v_cmp_lt_f32_e32 vcc, s2, v11
	v_rcp_f32_e32 v36, v36
	v_add_f32_e32 v86, v154, v67
	v_cndmask_b32_e32 v11, v38, v19, vcc
	ds_read_u16 v68, v150 offset:6912
	ds_read_u16 v108, v150 offset:7168
	ds_read_u16 v38, v150 offset:7424
	ds_read_u16 v52, v150 offset:7680
	ds_read_u16 v19, v150 offset:10240
	ds_read_u16 v107, v150 offset:10496
	ds_read_u16 v114, v150 offset:10752
	ds_read_u16 v54, v150 offset:11008
	v_add_f32_e32 v83, v153, v47
	s_waitcnt lgkmcnt(3)
	v_lshlrev_b32_e32 v70, 16, v19
	v_add_f32_e32 v19, 1.0, v37
	v_rcp_f32_e32 v106, v19
	v_mul_f32_e32 v19, v215, v36
	v_mul_f32_e32 v36, 0x3fb8aa3b, v19
	v_add_f32_e32 v19, v19, v19
	v_fmamk_f32 v37, v19, 0x3ab60b61, v185
	v_exp_f32_e32 v36, v36
	v_fmaak_f32 v37, v19, v37, 0x3d2aaaab
	v_fmaak_f32 v37, v19, v37, 0x3e2aaaab
	v_fma_f32 v37, v19, v37, 0.5
	v_fma_f32 v37, v19, v37, 1.0
	v_mul_f32_e64 v37, v37, -v19
	v_fma_f32 v39, -v36, v36, 1.0
	v_cmp_lt_f32_e32 vcc, s2, v19
	v_add_f32_e32 v87, v153, v49
	v_add_f32_e32 v48, v153, v48
	v_cndmask_b32_e32 v19, v39, v37, vcc
	v_sqrt_f32_e32 v55, v19
	v_add_f32_e32 v19, v154, v57
	v_mul_f32_e32 v19, 0xbfb8aa3b, v19
	v_exp_f32_e32 v19, v19
	v_add_f32_e32 v37, v153, v41
	v_mul_f32_e32 v37, 0xbfb8aa3b, v37
	v_exp_f32_e32 v37, v37
	v_add_f32_e32 v19, 1.0, v19
	v_rcp_f32_e32 v19, v19
	v_add_co_u32_e32 v76, vcc, s58, v134
	v_add_f32_e32 v37, 1.0, v37
	v_mul_f32_e32 v19, v215, v19
	v_rcp_f32_e32 v112, v37
	v_mul_f32_e32 v37, 0x3fb8aa3b, v19
	v_add_f32_e32 v19, v19, v19
	v_exp_f32_e32 v39, v37
	v_fmamk_f32 v37, v19, 0x3ab60b61, v185
	v_fmaak_f32 v37, v19, v37, 0x3d2aaaab
	v_fmaak_f32 v37, v19, v37, 0x3e2aaaab
	v_fma_f32 v37, v19, v37, 0.5
	v_addc_co_u32_e32 v77, vcc, 0, v135, vcc
	v_fma_f32 v37, v19, v37, 1.0
	v_mul_f32_e64 v37, v37, -v19
	v_fma_f32 v40, -v39, v39, 1.0
	v_cmp_lt_f32_e32 vcc, s2, v19
	global_store_dword v[76:77], v36, off offset:-4096
	global_store_dword v[76:77], v39, off
	v_cndmask_b32_e32 v19, v40, v37, vcc
	v_sqrt_f32_e32 v225, v19
	v_add_f32_e32 v19, v154, v58
	v_mul_f32_e32 v19, 0xbfb8aa3b, v19
	v_exp_f32_e32 v19, v19
	v_add_f32_e32 v37, v153, v42
	v_mul_f32_e32 v37, 0xbfb8aa3b, v37
	v_exp_f32_e32 v37, v37
	v_add_f32_e32 v19, 1.0, v19
	v_rcp_f32_e32 v19, v19
	v_add_f32_e32 v88, v153, v50
	v_add_f32_e32 v37, 1.0, v37
	v_rcp_f32_e32 v58, v37
	v_mul_f32_e32 v19, v215, v19
	v_mul_f32_e32 v37, 0x3fb8aa3b, v19
	v_add_f32_e32 v19, v19, v19
	v_exp_f32_e32 v41, v37
	v_fmamk_f32 v37, v19, 0x3ab60b61, v185
	v_fmaak_f32 v37, v19, v37, 0x3d2aaaab
	v_fmaak_f32 v37, v19, v37, 0x3e2aaaab
	v_fma_f32 v37, v19, v37, 0.5
	v_fma_f32 v37, v19, v37, 1.0
	v_mul_f32_e64 v37, v37, -v19
	v_fma_f32 v40, -v41, v41, 1.0
	v_cmp_lt_f32_e32 vcc, s2, v19
	v_add_f32_e32 v92, v153, v51
	s_waitcnt lgkmcnt(0)
; __device__ __forceinline__ float bf2f(unsigned short b) { return __uint_as_float(((unsigned)b) << 16); }
; template <int PASS> __device__ __forceinline__ void lru_pass(const bf16* __restrict__ Z, const bf16* __restrict__ LW, const float* __restrict__ cw_g, const float* __restrict__ cb_g, const float* __restrict__ b_a, const float* __restrict__ b_x, const float* __restrict__ lam, ...
;     ...
;                 for (int gq = 0; gq < 4; ++gq) { const int t0 = tl0 + 8 * gq + 4 * hh; float cxr[7];
; #pragma unroll
;                     for (int q = 0; q < 7; ++q) cxr[q] = bf2f(RAW[(t0 + q) * 128 + dd]);
; #pragma unroll
;                     for (int e = 0; e < 4; ++e) { const int i = 4 * gq + e;
;                         const float xc = wb + w0 * cxr[e] + w1 * cxr[e + 1] + w2 * cxr[e + 2] + w3 * cxr[e + 3];
;                         const float rr = __builtin_amdgcn_rcpf(1.f + __expf(-(accA[i] + bav))), ig = __builtin_amdgcn_rcpf(1.f + __expf(-(accX[i] + bxv)));
;                         const float la = -sp8 * rr, a_ = __expf(la); av[tt][i] = a_; uv[tt][i] = __builtin_amdgcn_sqrtf(neg_expm1_small(2.f * la, a_)) * (ig * xc);
;                         pa[(32 * tt + 8 * gq + e) * 1024] = av[tt][i]; pu[(32 * tt + 8 * gq + e) * 1024] = uv[tt][i]; } }
	v_lshlrev_b32_e32 v164, 16, v54
	v_cndmask_b32_e32 v19, v40, v37, vcc
	v_sqrt_f32_e32 v40, v19
	v_add_f32_e32 v19, v154, v59
	v_mul_f32_e32 v19, 0xbfb8aa3b, v19
	v_exp_f32_e32 v19, v19
	v_add_f32_e32 v37, v153, v43
	v_mul_f32_e32 v37, 0xbfb8aa3b, v37
	v_exp_f32_e32 v37, v37
	v_add_f32_e32 v19, 1.0, v19
	v_rcp_f32_e32 v19, v19
	v_add_co_u32_e32 v56, vcc, s59, v134
	v_add_f32_e32 v37, 1.0, v37
	v_mul_f32_e32 v19, v215, v19
	v_rcp_f32_e32 v111, v37
	v_mul_f32_e32 v37, 0x3fb8aa3b, v19
	v_add_f32_e32 v19, v19, v19
	v_exp_f32_e32 v42, v37
	v_fmamk_f32 v37, v19, 0x3ab60b61, v185
	v_fmaak_f32 v37, v19, v37, 0x3d2aaaab
	v_fmaak_f32 v37, v19, v37, 0x3e2aaaab
	v_fma_f32 v37, v19, v37, 0.5
	v_addc_co_u32_e32 v57, vcc, 0, v135, vcc
	v_fma_f32 v37, v19, v37, 1.0
	v_mul_f32_e64 v37, v37, -v19
	v_fma_f32 v43, -v42, v42, 1.0
	v_cmp_lt_f32_e32 vcc, s2, v19
	global_store_dword v[56:57], v41, off offset:-4096
	global_store_dword v[56:57], v42, off
	v_cndmask_b32_e32 v19, v43, v37, vcc
	v_add_f32_e32 v43, v154, v60
	v_mul_f32_e32 v43, 0xbfb8aa3b, v43
	v_exp_f32_e32 v43, v43
	v_sqrt_f32_e32 v105, v19
	ds_read_u16 v89, v150 offset:11264
	ds_read_u16 v96, v150 offset:11520
	ds_read_u16 v97, v150 offset:11776
	ds_read_u16 v19, v150 offset:12288
	ds_read_u16 v59, v150 offset:12544
	ds_read_u16 v226, v150 offset:12800
	ds_read_u16 v37, v150 offset:13056
	ds_read_u16 v77, v150 offset:13312
	s_waitcnt lgkmcnt(4)
	v_lshlrev_b32_e32 v74, 16, v19
	v_add_f32_e32 v43, 1.0, v43
	v_rcp_f32_e32 v53, v43
	v_add_f32_e32 v19, 1.0, v44
	v_rcp_f32_e32 v43, v19
	v_rcp_f32_e32 v60, v45
	v_mul_f32_e32 v19, v215, v53
	v_mul_f32_e32 v44, 0x3fb8aa3b, v19
	v_add_f32_e32 v19, v19, v19
	v_fmamk_f32 v53, v19, 0x3ab60b61, v185
	v_exp_f32_e32 v44, v44
	v_fmaak_f32 v53, v19, v53, 0x3d2aaaab
	v_fmaak_f32 v53, v19, v53, 0x3e2aaaab
	v_fma_f32 v53, v19, v53, 0.5
	v_fma_f32 v53, v19, v53, 1.0
	v_mul_f32_e64 v53, v53, -v19
	v_fma_f32 v56, -v44, v44, 1.0
	v_cmp_lt_f32_e32 vcc, s2, v19
	v_add_f32_e32 v45, v154, v62
	s_waitcnt lgkmcnt(1)
	v_lshlrev_b32_e32 v76, 16, v37
	v_cndmask_b32_e32 v19, v56, v53, vcc
	v_sqrt_f32_e32 v69, v19
	v_add_f32_e32 v19, v154, v61
	v_mul_f32_e32 v19, 0xbfb8aa3b, v19
	v_exp_f32_e32 v19, v19
	v_add_co_u32_e32 v56, vcc, s60, v134
	v_add_f32_e32 v61, v154, v63
	v_add_f32_e32 v19, 1.0, v19
	v_rcp_f32_e32 v19, v19
	v_addc_co_u32_e32 v57, vcc, 0, v135, vcc
	global_store_dword v[56:57], v44, off offset:-4096
	v_mul_f32_e32 v19, v215, v19
	v_mul_f32_e32 v53, 0x3fb8aa3b, v19
	v_add_f32_e32 v19, v19, v19
	v_fmamk_f32 v62, v19, 0x3ab60b61, v185
	v_exp_f32_e32 v53, v53
	v_fmaak_f32 v62, v19, v62, 0x3d2aaaab
	v_fmaak_f32 v62, v19, v62, 0x3e2aaaab
	v_fma_f32 v62, v19, v62, 0.5
	v_fma_f32 v62, v19, v62, 1.0
	v_mul_f32_e64 v62, v62, -v19
	v_fma_f32 v63, -v53, v53, 1.0
	v_cmp_lt_f32_e32 vcc, s2, v19
	global_store_dword v[56:57], v53, off
	s_waitcnt lgkmcnt(0)
	v_lshlrev_b32_e32 v77, 16, v77
	v_cndmask_b32_e32 v19, v63, v62, vcc
	v_sqrt_f32_e32 v65, v19
	v_mul_f32_e32 v19, 0xbfb8aa3b, v45
	v_exp_f32_e32 v19, v19
	v_add_f32_e32 v45, v153, v46
	v_mul_f32_e32 v45, 0xbfb8aa3b, v45
	v_exp_f32_e32 v45, v45
	v_add_f32_e32 v19, 1.0, v19
	v_rcp_f32_e32 v19, v19
	v_pk_mul_f32 v[66:67], v[128:129], v[76:77]
	v_add_f32_e32 v45, 1.0, v45
	v_rcp_f32_e32 v64, v45
	v_mul_f32_e32 v19, v215, v19
	v_mul_f32_e32 v45, 0x3fb8aa3b, v19
	v_add_f32_e32 v19, v19, v19
	v_exp_f32_e32 v57, v45
	v_fmamk_f32 v45, v19, 0x3ab60b61, v185
	v_fmaak_f32 v45, v19, v45, 0x3d2aaaab
	v_fmaak_f32 v45, v19, v45, 0x3e2aaaab
	v_fma_f32 v45, v19, v45, 0.5
	v_fma_f32 v45, v19, v45, 1.0
	v_mul_f32_e64 v45, v45, -v19
	v_fma_f32 v46, -v57, v57, 1.0
	v_cmp_lt_f32_e32 vcc, s2, v19
	v_lshlrev_b32_e32 v165, 16, v89
	v_pk_mul_f32 v[170:171], v[128:129], v[164:165]
	v_cndmask_b32_e32 v19, v46, v45, vcc
	v_add_co_u32_e32 v62, vcc, s61, v134
	v_sqrt_f32_e32 v56, v19
	s_nop 0
	v_addc_co_u32_e32 v63, vcc, 0, v135, vcc
	global_store_dword v[62:63], v57, off offset:-4096
	v_add_f32_e32 v19, v130, v66
	v_add_f32_e32 v19, v19, v67
	ds_read_u16 v37, v150 offset:13568
	ds_read_u16 v45, v150 offset:13824
	ds_read_u16 v66, v150 offset:14336
	ds_read_u16 v95, v150 offset:14592
	ds_read_u16 v115, v150 offset:14848
	ds_read_u16 v67, v150 offset:15104
	s_waitcnt lgkmcnt(5)
	v_lshlrev_b32_e32 v78, 16, v37
	v_mul_f32_e32 v37, 0xbfb8aa3b, v61
	v_exp_f32_e32 v37, v37
	s_waitcnt lgkmcnt(4)
	v_lshlrev_b32_e32 v79, 16, v45
	v_pk_mul_f32 v[46:47], v[126:127], v[78:79]
	v_mul_f32_e32 v45, 0xbfb8aa3b, v83
	v_add_f32_e32 v37, 1.0, v37
	v_add_f32_e32 v19, v19, v46
	v_exp_f32_e32 v45, v45
	v_rcp_f32_e32 v46, v37
	v_add_f32_e32 v47, v19, v47
	v_mul_f32_e32 v61, 0xbfb8aa3b, v81
	v_add_f32_e32 v19, 1.0, v45
	v_mul_f32_e32 v45, v215, v46
	v_rcp_f32_e32 v37, v19
	v_mul_f32_e32 v19, 0x3fb8aa3b, v45
	v_add_f32_e32 v45, v45, v45
	v_fmamk_f32 v46, v45, 0x3ab60b61, v185
	v_exp_f32_e32 v19, v19
	v_fmaak_f32 v46, v45, v46, 0x3d2aaaab
	v_fmaak_f32 v46, v45, v46, 0x3e2aaaab
	v_fma_f32 v46, v45, v46, 0.5
	v_fma_f32 v46, v45, v46, 1.0
	v_mul_f32_e64 v46, v46, -v45
	v_fma_f32 v49, -v19, v19, 1.0
	v_cmp_lt_f32_e32 vcc, s2, v45
	v_exp_f32_e32 v61, v61
	ds_read_u16 v93, v150 offset:15360
	ds_read_u16 v154, v150 offset:15616
	v_cndmask_b32_e32 v45, v49, v46, vcc
	v_sqrt_f32_e32 v49, v45
	v_mul_f32_e32 v45, 0xbfb8aa3b, v80
	v_exp_f32_e32 v45, v45
	v_mul_f32_e32 v46, 0xbfb8aa3b, v48
	global_store_dword v[62:63], v19, off
	v_mul_f32_e32 v63, 0xbfb8aa3b, v82
	v_add_f32_e32 v45, 1.0, v45
	v_rcp_f32_e32 v45, v45
	v_exp_f32_e32 v63, v63
	s_waitcnt lgkmcnt(5)
	v_lshlrev_b32_e32 v94, 16, v66
	s_waitcnt lgkmcnt(2)
; __device__ __forceinline__ float bf2f(unsigned short b) { return __uint_as_float(((unsigned)b) << 16); }
; template <int PASS> __device__ __forceinline__ void lru_pass(const bf16* __restrict__ Z, const bf16* __restrict__ LW, const float* __restrict__ cw_g, const float* __restrict__ cb_g, const float* __restrict__ b_a, const float* __restrict__ b_x, const float* __restrict__ lam, ...
;     ...
;                 for (int gq = 0; gq < 4; ++gq) { const int t0 = tl0 + 8 * gq + 4 * hh; float cxr[7];
; #pragma unroll
;                     for (int q = 0; q < 7; ++q) cxr[q] = bf2f(RAW[(t0 + q) * 128 + dd]);
; #pragma unroll
;                     for (int e = 0; e < 4; ++e) { const int i = 4 * gq + e;
;                         const float xc = wb + w0 * cxr[e] + w1 * cxr[e + 1] + w2 * cxr[e + 2] + w3 * cxr[e + 3];
;                         const float rr = __builtin_amdgcn_rcpf(1.f + __expf(-(accA[i] + bav))), ig = __builtin_amdgcn_rcpf(1.f + __expf(-(accX[i] + bxv)));
;                         const float la = -sp8 * rr, a_ = __expf(la); av[tt][i] = a_; uv[tt][i] = __builtin_amdgcn_sqrtf(neg_expm1_small(2.f * la, a_)) * (ig * xc);
;                         pa[(32 * tt + 8 * gq + e) * 1024] = av[tt][i]; pu[(32 * tt + 8 * gq + e) * 1024] = uv[tt][i]; } }
	v_lshlrev_b32_e32 v98, 16, v67
	v_mul_f32_e32 v48, v215, v45
	v_mul_f32_e32 v45, 0x3fb8aa3b, v48
	v_add_f32_e32 v48, v48, v48
	v_fmamk_f32 v50, v48, 0x3ab60b61, v185
	v_exp_f32_e32 v45, v45
	v_fmaak_f32 v50, v48, v50, 0x3d2aaaab
	v_fmaak_f32 v50, v48, v50, 0x3e2aaaab
	v_fma_f32 v50, v48, v50, 0.5
	v_fma_f32 v50, v48, v50, 1.0
	v_mul_f32_e64 v50, v50, -v48
	v_fma_f32 v51, -v45, v45, 1.0
	v_cmp_lt_f32_e32 vcc, s2, v48
	v_add_f32_e32 v63, 1.0, v63
	v_rcp_f32_e32 v63, v63
	v_cndmask_b32_e32 v48, v51, v50, vcc
	v_sqrt_f32_e32 v83, v48
	v_add_f32_e32 v48, 1.0, v61
	v_rcp_f32_e32 v48, v48
	v_add_co_u32_e32 v50, vcc, s62, v134
	v_mul_f32_e32 v67, 0xbfb8aa3b, v92
	v_mul_f32_e32 v48, v215, v48
	v_mul_f32_e32 v61, 0x3fb8aa3b, v48
	v_exp_f32_e32 v61, v61
	v_add_f32_e32 v48, v48, v48
	v_addc_co_u32_e32 v51, vcc, 0, v135, vcc
	v_fmamk_f32 v62, v48, 0x3ab60b61, v185
	global_store_dword v[50:51], v45, off offset:-4096
	v_fmaak_f32 v62, v48, v62, 0x3d2aaaab
	global_store_dword v[50:51], v61, off
	v_mul_f32_e32 v50, v215, v63
	v_fmaak_f32 v62, v48, v62, 0x3e2aaaab
	v_mul_f32_e32 v51, 0x3fb8aa3b, v50
	v_add_f32_e32 v50, v50, v50
	v_fma_f32 v62, v48, v62, 0.5
	v_exp_f32_e32 v63, v51
	v_fmamk_f32 v51, v50, 0x3ab60b61, v185
	v_fma_f32 v62, v48, v62, 1.0
	v_fmaak_f32 v51, v50, v51, 0x3d2aaaab
	v_mul_f32_e64 v62, v62, -v48
	v_fma_f32 v66, -v61, v61, 1.0
	v_cmp_lt_f32_e32 vcc, s2, v48
	v_fmaak_f32 v51, v50, v51, 0x3e2aaaab
	v_fma_f32 v51, v50, v51, 0.5
	v_cndmask_b32_e32 v48, v66, v62, vcc
	v_add_co_u32_e32 v80, vcc, s63, v134
	v_fma_f32 v51, v50, v51, 1.0
	s_nop 0
	v_addc_co_u32_e32 v81, vcc, 0, v135, vcc
	v_mul_f32_e64 v51, v51, -v50
	v_fma_f32 v62, -v63, v63, 1.0
	v_cmp_lt_f32_e32 vcc, s2, v50
	v_mul_f32_e32 v50, 0xbfb8aa3b, v87
	v_mul_f32_e32 v66, 0xbfb8aa3b, v86
	v_exp_f32_e32 v50, v50
	v_cndmask_b32_e32 v51, v62, v51, vcc
	v_mul_f32_e32 v62, 0xbfb8aa3b, v88
	v_exp_f32_e32 v66, v66
	v_exp_f32_e32 v62, v62
	v_add_f32_e32 v50, 1.0, v50
	v_exp_f32_e32 v67, v67
	v_add_f32_e32 v66, 1.0, v66
	v_rcp_f32_e32 v79, v50
	v_add_f32_e32 v50, 1.0, v62
	s_waitcnt lgkmcnt(1)
	v_lshlrev_b32_e32 v99, 16, v93
	v_rcp_f32_e32 v66, v66
	v_sqrt_f32_e32 v62, v51
	v_rcp_f32_e32 v88, v50
	v_pk_mul_f32 v[50:51], v[128:129], v[98:99]
	global_store_dword v[80:81], v63, off offset:-4096
	v_add_f32_e32 v50, v130, v50
	v_add_f32_e32 v227, v50, v51
	v_add_f32_e32 v50, 1.0, v67
	v_rcp_f32_e32 v230, v50
	v_mul_f32_e32 v50, v215, v66
	v_mul_f32_e32 v51, 0x3fb8aa3b, v50
	v_add_f32_e32 v50, v50, v50
	v_exp_f32_e32 v67, v51
	v_fmamk_f32 v51, v50, 0x3ab60b61, v185
	v_fmaak_f32 v51, v50, v51, 0x3d2aaaab
	v_fmaak_f32 v51, v50, v51, 0x3e2aaaab
	v_fma_f32 v51, v50, v51, 0.5
	v_fma_f32 v51, v50, v51, 1.0
	v_mul_f32_e64 v51, v51, -v50
	v_fma_f32 v66, -v67, v67, 1.0
	v_cmp_lt_f32_e32 vcc, s2, v50
	global_store_dword v[80:81], v67, off
	v_lshlrev_b32_e32 v80, 16, v95
	v_cndmask_b32_e32 v50, v66, v51, vcc
	v_xor_b32_e32 v51, 32, v186
	v_cmp_lt_i32_e32 vcc, v51, v192
	v_exp_f32_e32 v46, v46
	v_mov_b32_e32 v95, v80
	v_cndmask_b32_e32 v51, v186, v51, vcc
	v_lshlrev_b32_e32 v135, 2, v51
	v_mul_f32_e32 v51, v15, v21
	v_mul_f32_e32 v21, v219, v156
	v_mul_f32_e32 v153, v157, v21
	v_pk_mul_f32 v[94:95], v[128:129], v[94:95]
	v_add_f32_e32 v21, v130, v170
	v_lshlrev_b32_e32 v93, 16, v118
	v_lshlrev_b32_e32 v81, 16, v115
	v_add_f32_e32 v118, v21, v171
	v_add_f32_e32 v21, v130, v94
	v_add_f32_e32 v21, v21, v95
	v_pk_mul_f32 v[94:95], v[128:129], v[80:81]
	v_add_f32_e32 v46, 1.0, v46
	v_add_f32_e32 v54, v130, v94
	v_rcp_f32_e32 v46, v46
	v_add_f32_e32 v54, v54, v95
	v_pk_mov_b32 v[94:95], v[80:81], v[98:99] op_sel:[1,0]
	s_waitcnt lgkmcnt(0)
	v_lshlrev_b32_e32 v92, 16, v154
	v_pk_mul_f32 v[94:95], v[126:127], v[94:95]
	v_mov_b32_e32 v86, v129
	v_mov_b32_e32 v87, v126
	v_add_f32_e32 v21, v21, v94
	v_sqrt_f32_e32 v48, v48
	v_add_f32_e32 v21, v21, v95
	v_pk_mul_f32 v[170:171], v[126:127], v[92:93]
	v_pk_mul_f32 v[94:95], v[86:87], v[98:99]
	v_pk_mul_f32 v[98:99], v[126:127], v[98:99]
	v_lshlrev_b32_e32 v115, 16, v114
	v_lshlrev_b32_e32 v114, 16, v107
	v_mul_f32_e32 v93, v46, v21
	v_add_f32_e32 v21, v227, v170
	v_add_f32_e32 v46, v54, v98
	v_lshlrev_b32_e32 v170, 16, v90
	v_lshlrev_b32_e32 v90, 16, v84
	v_lshlrev_b32_e32 v84, 16, v71
	v_mov_b32_e32 v71, v114
	v_mov_b32_e32 v82, v127
	v_add_f32_e32 v46, v46, v99
	v_add_co_u32_e32 v228, vcc, s62, v132
	v_add_f32_e32 v21, v21, v171
	v_pk_mul_f32 v[70:71], v[128:129], v[70:71]
	v_pk_mul_f32 v[98:99], v[82:83], v[92:93]
	v_mul_f32_e32 v46, v79, v46
	v_addc_co_u32_e32 v229, vcc, 0, v133, vcc
	v_mul_f32_e32 v80, v230, v21
	v_add_f32_e32 v21, v130, v70
	v_mul_f32_e32 v89, v48, v46
	global_store_dword v[228:229], v99, off offset:-4096
	global_store_dword v[228:229], v89, off
	v_pk_mul_f32 v[228:229], v[128:129], v[114:115]
	v_add_f32_e32 v46, v21, v71
	v_mov_b32_e32 v70, v90
	v_mov_b32_e32 v71, v84
	v_add_f32_e32 v21, v130, v228
	v_pk_mul_f32 v[70:71], v[128:129], v[70:71]
	v_lshlrev_b32_e32 v171, 16, v91
	v_add_f32_e32 v48, v21, v229
	v_add_f32_e32 v21, v130, v70
	v_add_f32_e32 v21, v21, v71
	v_pk_mul_f32 v[70:71], v[126:127], v[170:171]
	v_lshlrev_b32_e32 v91, 16, v75
	v_add_f32_e32 v21, v21, v70
	v_lshlrev_b32_e32 v70, 16, v59
	v_mov_b32_e32 v75, v70
	v_pk_mul_f32 v[74:75], v[128:129], v[74:75]
	v_add_f32_e32 v21, v21, v71
	v_lshlrev_b32_e32 v71, 16, v226
	v_add_f32_e32 v59, v130, v74
	v_pk_mul_f32 v[226:227], v[128:129], v[70:71]
	v_add_f32_e32 v79, v59, v75
	v_mov_b32_e32 v74, v91
	v_mov_b32_e32 v75, v90
	v_add_f32_e32 v59, v130, v226
	v_pk_mul_f32 v[74:75], v[128:129], v[74:75]
	v_add_f32_e32 v114, v59, v227
	v_add_f32_e32 v59, v130, v74
	v_mov_b32_e32 v171, v170
; __device__ __forceinline__ float bf2f(unsigned short b) { return __uint_as_float(((unsigned)b) << 16); }
; template <int PASS> __device__ __forceinline__ void lru_pass(const bf16* __restrict__ Z, const bf16* __restrict__ LW, const float* __restrict__ cw_g, const float* __restrict__ cb_g, const float* __restrict__ b_a, const float* __restrict__ b_x, const float* __restrict__ lam, ...
;     ...
;                 for (int gq = 0; gq < 4; ++gq) { const int t0 = tl0 + 8 * gq + 4 * hh; float cxr[7];
; #pragma unroll
;                     for (int q = 0; q < 7; ++q) cxr[q] = bf2f(RAW[(t0 + q) * 128 + dd]);
; #pragma unroll
;                     for (int e = 0; e < 4; ++e) { const int i = 4 * gq + e;
;                         const float xc = wb + w0 * cxr[e] + w1 * cxr[e + 1] + w2 * cxr[e + 2] + w3 * cxr[e + 3];
;                         const float rr = __builtin_amdgcn_rcpf(1.f + __expf(-(accA[i] + bav))), ig = __builtin_amdgcn_rcpf(1.f + __expf(-(accX[i] + bxv)));
;                         const float la = -sp8 * rr, a_ = __expf(la); av[tt][i] = a_; uv[tt][i] = __builtin_amdgcn_sqrtf(neg_expm1_small(2.f * la, a_)) * (ig * xc);
;                         pa[(32 * tt + 8 * gq + e) * 1024] = av[tt][i]; pu[(32 * tt + 8 * gq + e) * 1024] = uv[tt][i]; } }
	v_mov_b32_e32 v170, v84
	v_lshlrev_b32_e32 v97, 16, v97
	v_lshlrev_b32_e32 v96, 16, v96
	v_add_f32_e32 v59, v59, v75
	v_pk_mul_f32 v[170:171], v[126:127], v[170:171]
	v_pk_mul_f32 v[74:75], v[126:127], v[96:97]
	v_add_f32_e32 v59, v59, v170
	v_add_f32_e32 v70, v118, v74
	v_add_f32_e32 v118, v59, v171
	v_pk_mov_b32 v[170:171], v[114:115], v[164:165] op_sel:[1,0]
	v_add_co_u32_e32 v228, vcc, s58, v132
	v_pk_mul_f32 v[170:171], v[126:127], v[170:171]
	v_mov_b32_e32 v54, v127
	v_add_f32_e32 v46, v46, v170
	v_add_f32_e32 v46, v46, v171
	v_pk_mul_f32 v[170:171], v[86:87], v[164:165]
	v_pk_mul_f32 v[164:165], v[126:127], v[164:165]
	v_mul_f32_e32 v97, v106, v46
	v_add_f32_e32 v46, v48, v164
	v_add_f32_e32 v46, v46, v165
	v_mul_f32_e32 v46, v112, v46
	v_lshlrev_b32_e32 v226, 16, v101
	v_addc_co_u32_e32 v229, vcc, 0, v133, vcc
	v_mul_f32_e32 v59, v225, v46
	v_add_f32_e32 v101, v70, v75
	v_lshlrev_b32_e32 v225, 16, v224
	v_pk_mul_f32 v[164:165], v[54:55], v[96:97]
	v_pk_mul_f32 v[110:111], v[110:111], v[100:101]
	v_add_co_u32_e32 v74, vcc, s59, v132
	v_lshlrev_b32_e32 v224, 16, v24
	v_mov_b32_e32 v112, v225
	global_store_dword v[228:229], v165, off offset:-4096
	global_store_dword v[228:229], v59, off
	v_pk_mul_f32 v[228:229], v[104:105], v[110:111]
	v_addc_co_u32_e32 v75, vcc, 0, v133, vcc
	v_pk_mul_f32 v[230:231], v[128:129], v[224:225]
	v_pk_mul_f32 v[224:225], v[128:129], v[112:113]
	global_store_dword v[74:75], v229, off
	v_lshlrev_b32_e32 v75, 16, v108
	v_lshlrev_b32_e32 v74, 16, v68
	v_add_f32_e32 v46, v130, v224
	v_add_f32_e32 v46, v46, v225
	v_pk_mul_f32 v[224:225], v[128:129], v[74:75]
	v_rcp_f32_e32 v5, v5
	v_add_f32_e32 v68, v130, v224
	v_add_f32_e32 v24, v130, v230
	v_add_f32_e32 v101, v68, v225
	v_mov_b32_e32 v224, v113
	v_mov_b32_e32 v225, v74
	v_add_f32_e32 v24, v24, v231
	v_lshlrev_b32_e32 v219, 16, v218
	v_lshlrev_b32_e32 v218, 16, v217
	v_pk_mul_f32 v[224:225], v[126:127], v[224:225]
	v_pk_mul_f32 v[230:231], v[128:129], v[218:219]
	v_add_f32_e32 v24, v24, v224
	v_add_f32_e32 v48, v130, v230
	v_add_f32_e32 v24, v24, v225
	v_pk_mul_f32 v[224:225], v[126:127], v[74:75]
	v_lshlrev_b32_e32 v232, 16, v38
	s_mov_b32 s2, 0x18000
	v_add_f32_e32 v48, v48, v231
	v_add_f32_e32 v46, v46, v224
	v_mul_f32_e32 v70, v5, v118
	v_mov_b32_e32 v108, v127
	v_mul_f32_e32 v231, v31, v24
	v_mov_b32_e32 v230, v232
	v_add_co_u32_e32 v236, vcc, s2, v132
	v_add_f32_e32 v46, v46, v225
	v_pk_mul_f32 v[234:235], v[108:109], v[230:231]
	v_addc_co_u32_e32 v237, vcc, 0, v133, vcc
	v_pk_mul_f32 v[238:239], v[86:87], v[74:75]
	v_pk_mov_b32 v[74:75], v[70:71], v[76:77] op_sel:[1,0]
	v_mul_f32_e32 v24, v117, v46
	v_lshlrev_b32_e32 v233, 16, v52
	global_store_dword v[236:237], v235, off
	v_pk_mul_f32 v[236:237], v[126:127], v[76:77]
	v_pk_mul_f32 v[74:75], v[126:127], v[74:75]
	s_mov_b32 s2, 0x1a000
	v_pk_mul_f32 v[224:225], v[86:87], v[76:77]
	v_mul_f32_e32 v103, v103, v24
	v_add_f32_e32 v24, v114, v236
	v_add_f32_e32 v31, v79, v74
	v_pk_mul_f32 v[76:77], v[126:127], v[232:233]
	v_add_co_u32_e32 v232, vcc, s2, v132
	v_add_f32_e32 v38, v101, v76
	s_nop 0
	v_addc_co_u32_e32 v233, vcc, 0, v133, vcc
	v_add_f32_e32 v31, v31, v75
	v_add_f32_e32 v24, v24, v237
	v_mov_b32_e32 v68, v127
	v_add_f32_e32 v38, v38, v77
	v_mul_f32_e32 v79, v43, v31
	v_add_co_u32_e32 v76, vcc, s60, v132
	v_mul_f32_e32 v24, v60, v24
	v_mul_f32_e32 v74, v119, v38
	v_pk_mul_f32 v[118:119], v[68:69], v[78:79]
	v_addc_co_u32_e32 v77, vcc, 0, v133, vcc
	v_mul_f32_e32 v65, v65, v24
	v_lshlrev_b32_e32 v241, 16, v26
	global_store_dword v[76:77], v119, off offset:-4096
	global_store_dword v[76:77], v65, off
	v_pk_mov_b32 v[76:77], v[218:219], v[240:241] op_sel:[1,0]
	v_fma_f32 v38, v128, v115, v130
	v_pk_mul_f32 v[76:77], v[128:129], v[76:77]
	v_add_f32_e32 v38, v38, v170
	v_add_f32_e32 v26, v130, v76
	v_add_f32_e32 v28, v26, v77
	v_pk_mul_f32 v[76:77], v[126:127], v[240:241]
	v_fma_f32 v60, v128, v81, v130
	v_add_f32_e32 v26, v48, v76
	v_add_f32_e32 v38, v38, v171
	v_lshlrev_b32_e32 v221, 16, v221
	v_lshlrev_b32_e32 v220, 16, v220
	v_add_f32_e32 v26, v26, v77
	v_add_f32_e32 v60, v60, v94
	v_pk_fma_f32 v[54:55], v[54:55], v[96:97], v[38:39]
	v_pk_mul_f32 v[236:237], v[126:127], v[220:221]
	v_mul_f32_e32 v221, v223, v26
	v_add_co_u32_e32 v242, vcc, s47, v132
	v_mov_b32_e32 v26, v241
	v_fma_f32 v52, v128, v71, v130
	v_add_f32_e32 v60, v60, v95
	v_pk_mul_f32 v[54:55], v[58:59], v[54:55]
	v_pk_fma_f32 v[58:59], v[38:39], v[164:165], v[58:59]
	v_addc_co_u32_e32 v243, vcc, 0, v133, vcc
	v_pk_mul_f32 v[244:245], v[126:127], v[26:27]
	v_pk_fma_f32 v[76:77], v[82:83], v[92:93], v[60:61]
	v_pk_fma_f32 v[82:83], v[60:61], v[98:99], v[88:89]
	v_add_f32_e32 v52, v52, v224
	v_mov_b32_e32 v55, v59
	v_add_f32_e32 v31, v28, v244
	v_fma_f32 v43, v128, v180, v130
	v_fma_f32 v28, v128, v113, v130
	v_pk_mul_f32 v[76:77], v[88:89], v[76:77]
	v_add_co_u32_e32 v82, vcc, s63, v132
	v_add_f32_e32 v52, v52, v225
	v_pk_mul_f32 v[54:55], v[40:41], v[54:55]
	v_lshlrev_b32_e32 v227, 16, v85
	v_fma_f32 v46, v128, v175, v130
	v_mov_b32_e32 v77, v83
	v_addc_co_u32_e32 v83, vcc, 0, v133, vcc
	s_mov_b32 s2, 0x2a000
	v_add_f32_e32 v38, v54, v55
	v_add_f32_e32 v28, v28, v238
	v_pk_fma_f32 v[68:69], v[68:69], v[78:79], v[52:53]
	v_pk_mul_f32 v[78:79], v[128:129], v[26:27]
	v_fmac_f32_e32 v43, v129, v175
	v_mov_b32_e32 v106, v91
	v_mov_b32_e32 v107, v226
	v_fma_f32 v48, v128, v163, v130
	v_fma_f32 v75, v128, v161, v130
	v_fma_f32 v101, v128, v206, v130
	v_fma_f32 v112, v128, v211, v130
	v_fma_f32 v71, v128, v208, v130
	v_fma_f32 v81, v128, v203, v130
	v_pk_fma_f32 v[92:93], v[128:129], v[226:227], v[130:131] op_sel_hi:[0,1,0]
; __device__ __forceinline__ float bf2f(unsigned short b) { return __uint_as_float(((unsigned)b) << 16); }
; template <int PASS> __device__ __forceinline__ void lru_pass(const bf16* __restrict__ Z, const bf16* __restrict__ LW, const float* __restrict__ cw_g, const float* __restrict__ cb_g, const float* __restrict__ b_a, const float* __restrict__ b_x, const float* __restrict__ lam, ...
;     ...
;                 for (int gq = 0; gq < 4; ++gq) { const int t0 = tl0 + 8 * gq + 4 * hh; float cxr[7];
; #pragma unroll
;                     for (int q = 0; q < 7; ++q) cxr[q] = bf2f(RAW[(t0 + q) * 128 + dd]);
; #pragma unroll
;                     for (int e = 0; e < 4; ++e) { const int i = 4 * gq + e;
;                         const float xc = wb + w0 * cxr[e] + w1 * cxr[e + 1] + w2 * cxr[e + 2] + w3 * cxr[e + 3];
;                         const float rr = __builtin_amdgcn_rcpf(1.f + __expf(-(accA[i] + bav))), ig = __builtin_amdgcn_rcpf(1.f + __expf(-(accX[i] + bxv)));
;                         const float la = -sp8 * rr, a_ = __expf(la); av[tt][i] = a_; uv[tt][i] = __builtin_amdgcn_sqrtf(neg_expm1_small(2.f * la, a_)) * (ig * xc);
;                         pa[(32 * tt + 8 * gq + e) * 1024] = av[tt][i]; pu[(32 * tt + 8 * gq + e) * 1024] = uv[tt][i]; } }
;     ...
;         float Aw = 1.f, Hw = 0.f; float Ag[2][4], Hg[2][4], Ap[2][4], Hp[2][4];
; #pragma unroll
;         for (int tt = 0; tt < 2; ++tt) {
; #pragma unroll
;             for (int gq = 0; gq < 4; ++gq) { float A = av[tt][4 * gq], H = uv[tt][4 * gq];
; #pragma unroll
;                 for (int e = 1; e < 4; ++e) { H = H * av[tt][4 * gq + e] + uv[tt][4 * gq + e]; A *= av[tt][4 * gq + e]; }
;                 Ag[tt][gq] = A; Hg[tt][gq] = H; Ap[tt][gq] = __shfl_xor(A, 32); Hp[tt][gq] = __shfl_xor(H, 32); }
	v_add_co_u32_e32 v58, vcc, s2, v132
	v_mul_f32_e32 v55, v42, v38
	v_add_f32_e32 v94, v28, v239
	v_pk_mul_f32 v[68:69], v[64:65], v[68:69]
	v_pk_fma_f32 v[64:65], v[52:53], v[118:119], v[64:65]
	v_add_f32_e32 v38, v130, v78
	v_fmac_f32_e32 v130, v128, v240
	v_fmac_f32_e32 v46, v129, v163
	v_mov_b32_e32 v28, v129
	v_pk_mul_f32 v[26:27], v[86:87], v[26:27]
	v_fmac_f32_e32 v43, v126, v163
	v_addc_co_u32_e32 v59, vcc, 0, v133, vcc
	v_mov_b32_e32 v69, v65
	v_fmac_f32_e32 v48, v129, v161
	v_pk_fma_f32 v[92:93], v[28:29], v[106:107], v[92:93] op_sel_hi:[0,1,1]
	v_add_f32_e32 v26, v130, v26
	v_add_f32_e32 v28, v38, v79
	v_fmac_f32_e32 v46, v126, v161
	v_fmac_f32_e32 v43, v127, v161
	v_pk_mul_f32 v[64:65], v[56:57], v[68:69]
	v_add_co_u32_e32 v68, vcc, s61, v132
	v_add_f32_e32 v38, v28, v236
	v_fmac_f32_e32 v48, v126, v160
	v_add_f32_e32 v28, v26, v27
	v_mul_f32_e32 v26, v162, v43
	v_fmac_f32_e32 v46, v127, v160
	v_addc_co_u32_e32 v69, vcc, 0, v133, vcc
	v_fmac_f32_e32 v75, v129, v160
	v_mul_f32_e32 v43, v26, v173
	v_mul_f32_e32 v26, v174, v46
	v_fmac_f32_e32 v48, v127, v158
	v_fmac_f32_e32 v75, v126, v158
	v_mul_f32_e32 v46, v26, v176
	v_add_co_u32_e32 v26, vcc, s88, v132
	v_mul_f32_e32 v48, v177, v48
	v_fmac_f32_e32 v101, v129, v211
	v_addc_co_u32_e32 v27, vcc, 0, v133, vcc
	v_mul_f32_e32 v48, v48, v178
	v_fmac_f32_e32 v75, v127, v159
	v_fmac_f32_e32 v112, v129, v208
	v_fmac_f32_e32 v101, v126, v208
	global_store_dword v[26:27], v46, off offset:-4096
	global_store_dword v[26:27], v48, off
	v_mul_f32_e32 v23, v23, v75
	v_add_co_u32_e32 v26, vcc, s48, v132
	v_fmac_f32_e32 v112, v126, v203
	v_mul_f32_e32 v23, v23, v179
	v_addc_co_u32_e32 v27, vcc, 0, v133, vcc
	v_fmac_f32_e32 v101, v127, v203
	v_fmac_f32_e32 v71, v129, v203
	global_store_dword v[26:27], v23, off
	v_mul_f32_e32 v26, v204, v101
	v_fmac_f32_e32 v112, v127, v183
	v_fmac_f32_e32 v81, v129, v183
	v_fmac_f32_e32 v71, v126, v183
	v_mul_f32_e32 v52, v205, v26
	v_add_co_u32_e32 v26, vcc, s4, v132
	v_mul_f32_e32 v56, v207, v112
	global_store_dword v[58:59], v54, off
	v_mov_b32_e32 v54, v7
	v_fmac_f32_e32 v81, v126, v182
	v_addc_co_u32_e32 v27, vcc, 0, v133, vcc
	v_mul_f32_e32 v56, v209, v56
	v_fmac_f32_e32 v71, v127, v182
	v_pk_mul_f32 v[58:59], v[54:55], v[228:229]
	global_store_dword v[26:27], v52, off offset:-4096
	global_store_dword v[26:27], v56, off
	v_mul_f32_e32 v26, v210, v71
	v_fmac_f32_e32 v81, v127, v181
	v_mul_f32_e32 v59, v212, v26
	v_add_co_u32_e32 v26, vcc, s5, v132
	v_mul_f32_e32 v60, v213, v81
	s_nop 0
	v_addc_co_u32_e32 v27, vcc, 0, v133, vcc
	v_mul_f32_e32 v60, v214, v60
	global_store_dword v[26:27], v59, off offset:-4096
	global_store_dword v[26:27], v60, off
	v_add_f32_e32 v26, v31, v245
	v_sqrt_f32_e32 v4, v4
	v_mov_b32_e32 v24, v127
	v_mov_b32_e32 v95, v100
	v_mul_f32_e32 v26, v216, v26
	v_pk_mul_f32 v[218:219], v[24:25], v[220:221]
	v_pk_fma_f32 v[96:97], v[108:109], v[230:231], v[94:95]
	v_mul_f32_e32 v31, v222, v26
	v_pk_fma_f32 v[24:25], v[24:25], v[220:221], v[28:29]
	v_mov_b32_e32 v85, v90
	v_pk_mul_f32 v[96:97], v[102:103], v[96:97]
	v_pk_fma_f32 v[94:95], v[94:95], v[234:235], v[102:103]
	v_pk_fma_f32 v[78:79], v[126:127], v[90:91], v[92:93] op_sel_hi:[0,1,1]
	v_pk_mul_f32 v[24:25], v[30:31], v[24:25]
	v_pk_fma_f32 v[26:27], v[28:29], v[218:219], v[30:31]
	v_add_f32_e32 v30, v38, v237
	v_mov_b32_e32 v38, v127
	v_mov_b32_e32 v5, v104
	v_mov_b32_e32 v97, v95
	v_add_co_u32_e32 v28, vcc, s49, v132
	v_pk_fma_f32 v[78:79], v[38:39], v[84:85], v[78:79] op_sel_hi:[0,1,1]
	v_sqrt_f32_e32 v12, v12
	v_pk_mul_f32 v[94:95], v[4:5], v[96:97]
	v_addc_co_u32_e32 v29, vcc, 0, v133, vcc
	v_pk_mul_f32 v[32:33], v[32:33], v[78:79]
	v_pk_fma_f32 v[4:5], v[4:5], v[96:97], v[94:95] op_sel_hi:[1,1,0]
	v_pk_mul_f32 v[32:33], v[32:33], v[34:35]
	v_add_co_u32_e32 v34, vcc, s56, v132
	v_mov_b32_e32 v75, v5
	s_nop 0
	v_addc_co_u32_e32 v35, vcc, 0, v133, vcc
	v_mov_b32_e32 v25, v27
	v_pk_mul_f32 v[4:5], v[6:7], v[74:75]
	v_add_co_u32_e32 v6, vcc, s55, v132
	v_sqrt_f32_e32 v14, v14
	v_pk_mul_f32 v[88:89], v[62:63], v[76:77]
	v_pk_mul_f32 v[26:27], v[12:13], v[24:25]
	v_addc_co_u32_e32 v7, vcc, 0, v133, vcc
	global_store_dword v[232:233], v103, off offset:-4096
	global_store_dword v[242:243], v219, off offset:-4096
	global_store_dword v[82:83], v88, off offset:-4096
	global_store_dword v[232:233], v94, off
	global_store_dword v[68:69], v64, off offset:-4096
	global_store_dword v[132:133], v43, off
	global_store_dword v[242:243], v31, off
	global_store_dword v[28:29], v26, off offset:-4096
	global_store_dword v[34:35], v33, off offset:-4096
	global_store_dword v[34:35], v32, off
	v_fmac_f32_e32 v46, v156, v43
	v_fmac_f32_e32 v56, v20, v52
	global_store_dword v[6:7], v4, off
	v_add_f32_e32 v4, v4, v5
	v_fmac_f32_e32 v48, v157, v46
	v_fmac_f32_e32 v59, v10, v56
	v_pk_fma_f32 v[12:13], v[12:13], v[24:25], v[26:27] op_sel_hi:[1,1,0]
	ds_bpermute_b32 v5, v135, v4
	v_mul_f32_e32 v30, v116, v30
	v_fmac_f32_e32 v23, v155, v48
	v_fmac_f32_e32 v60, v22, v59
	v_mov_b32_e32 v31, v13
	ds_bpermute_b32 v34, v135, v23
	ds_bpermute_b32 v35, v135, v60
	v_pk_mul_f32 v[12:13], v[14:15], v[30:31]
	global_store_dword v[28:29], v12, off
	v_add_f32_e32 v12, v12, v13
	v_fmac_f32_e32 v32, v73, v33
	ds_bpermute_b32 v13, v135, v12
	v_mov_b32_e32 v71, v32
	v_add_co_u32_e32 v6, vcc, s57, v132
	s_waitcnt lgkmcnt(3)
	v_cndmask_b32_e64 v75, v5, v4, s[0:1]
	v_cndmask_b32_e64 v78, v4, v5, s[0:1]
	v_pk_mul_f32 v[4:5], v[70:71], v[16:17]
	v_addc_co_u32_e32 v7, vcc, 0, v133, vcc
	v_sqrt_f32_e32 v66, v50
	global_store_dword v[6:7], v4, off offset:-4096
	v_add_f32_e32 v4, v4, v5
	s_waitcnt lgkmcnt(2)
; #define LRU_BAR() do { asm volatile("s_waitcnt vmcnt(0) lgkmcnt(0)" ::: "memory"); __builtin_amdgcn_s_barrier(); asm volatile("" ::: "memory"); } while (0)
; template <int PASS> __device__ __forceinline__ void lru_pass(const bf16* __restrict__ Z, const bf16* __restrict__ LW, const float* __restrict__ cw_g, const float* __restrict__ cb_g, const float* __restrict__ b_a, const float* __restrict__ b_x, const float* __restrict__ lam, ...
;     ...
;         float Aw = 1.f, Hw = 0.f; float Ag[2][4], Hg[2][4], Ap[2][4], Hp[2][4];
; #pragma unroll
;         for (int tt = 0; tt < 2; ++tt) {
; #pragma unroll
;             for (int gq = 0; gq < 4; ++gq) { float A = av[tt][4 * gq], H = uv[tt][4 * gq];
; #pragma unroll
;                 for (int e = 1; e < 4; ++e) { H = H * av[tt][4 * gq + e] + uv[tt][4 * gq + e]; A *= av[tt][4 * gq + e]; }
;                 Ag[tt][gq] = A; Hg[tt][gq] = H; Ap[tt][gq] = __shfl_xor(A, 32); Hp[tt][gq] = __shfl_xor(H, 32); }
; #pragma unroll
;             for (int p = 0; p < 8; ++p) { const bool own = ((p & 1) == hh); const float A = own ? Ag[tt][p >> 1] : Ap[tt][p >> 1], H = own ? Hg[tt][p >> 1] : Hp[tt][p >> 1]; Hw = Hw * A + H; Aw *= A; }
;         }
;         if (hh == 0) { xcomp[(wave * 32 + r) * 2] = Aw; xcomp[(wave * 32 + r) * 2 + 1] = Hw; }
;         LRU_BAR();
;         if (PASS == 1) {
;             if (th == 0 && hh == 0) { const float A1 = xcomp[((wave + 4) * 32 + r) * 2], H1 = xcomp[((wave + 4) * 32 + r) * 2 + 1]; CARRY[(size_t)R * 1024 + d] = make_float2(Aw * A1, Hw * A1 + H1); }
	v_cndmask_b32_e64 v38, v34, v23, s[0:1]
	v_cndmask_b32_e64 v34, v23, v34, s[0:1]
	s_waitcnt lgkmcnt(1)
	v_cndmask_b32_e64 v52, v35, v60, s[0:1]
	v_cndmask_b32_e64 v35, v60, v35, s[0:1]
	v_mul_f32_e32 v23, v18, v4
	v_add_f32_e32 v4, v64, v65
	v_mov_b32_e32 v60, v53
	v_mul_f32_e32 v43, v19, v4
	v_pk_fma_f32 v[4:5], v[62:63], v[76:77], v[88:89] op_sel_hi:[1,1,0]
	v_mov_b32_e32 v46, v39
	v_pk_mul_f32 v[28:29], v[44:45], v[60:61]
	v_mul_f32_e32 v72, v72, v73
	s_waitcnt lgkmcnt(0)
	v_cndmask_b32_e64 v59, v13, v12, s[0:1]
	v_cndmask_b32_e64 v74, v12, v13, s[0:1]
	v_mov_b32_e32 v81, v5
	v_pk_mul_f32 v[12:13], v[36:37], v[46:47]
	v_mov_b32_e32 v48, v41
	v_mov_b32_e32 v56, v17
	v_mov_b32_e32 v73, v28
	v_pk_mul_f32 v[4:5], v[66:67], v[80:81]
	v_pk_mul_f32 v[14:15], v[48:49], v[12:13]
	v_pk_mul_f32 v[16:17], v[56:57], v[72:73]
	global_store_dword v[82:83], v4, off
	v_pk_fma_f32 v[4:5], v[66:67], v[80:81], v[4:5] op_sel:[0,0,1] op_sel_hi:[1,1,0]
	v_pk_mul_f32 v[24:25], v[42:43], v[14:15]
	v_pk_mul_f32 v[16:17], v[18:19], v[16:17]
	ds_bpermute_b32 v5, v135, v24
	ds_bpermute_b32 v30, v135, v16
	v_rcp_f32_e32 v9, v9
	v_sqrt_f32_e32 v11, v11
	v_mov_b32_e32 v62, v57
	v_pk_mul_f32 v[28:29], v[62:63], v[28:29]
	v_mov_b32_e32 v66, v19
	global_store_dword v[68:69], v15, off
	s_waitcnt lgkmcnt(1)
	v_cndmask_b32_e64 v15, v24, v5, s[0:1]
	v_pk_mul_f32 v[18:19], v[66:67], v[28:29]
	s_waitcnt lgkmcnt(0)
	v_cndmask_b32_e64 v28, v30, v16, s[0:1]
	v_cndmask_b32_e64 v30, v16, v30, s[0:1]
	v_cndmask_b32_e64 v16, v5, v24, s[0:1]
	v_pk_mul_f32 v[8:9], v[8:9], v[20:21]
	v_mul_f32_e32 v5, v155, v153
	v_pk_mul_f32 v[20:21], v[10:11], v[8:9]
	ds_bpermute_b32 v24, v135, v5
	global_store_dword v[6:7], v21, off
	v_pk_mul_f32 v[6:7], v[22:23], v[20:21]
	v_pk_fma_f32 v[8:9], v[10:11], v[8:9], v[22:23]
	ds_bpermute_b32 v10, v135, v6
	ds_bpermute_b32 v134, v135, v51
	s_waitcnt lgkmcnt(2)
	v_cndmask_b32_e64 v7, v24, v5, s[0:1]
	ds_bpermute_b32 v40, v135, v58
	v_fmac_f32_e32 v38, 0, v7
	v_cndmask_b32_e64 v7, v5, v24, s[0:1]
	v_fmac_f32_e32 v34, v7, v38
	s_waitcnt lgkmcnt(2)
	v_cndmask_b32_e64 v8, v10, v6, s[0:1]
	v_fmac_f32_e32 v52, v8, v34
	v_cndmask_b32_e64 v6, v6, v10, s[0:1]
	s_waitcnt lgkmcnt(1)
	v_cndmask_b32_e64 v50, v134, v51, s[0:1]
	ds_bpermute_b32 v20, v135, v9
	v_fmac_f32_e32 v35, v6, v52
	v_fmac_f32_e32 v59, v50, v35
	v_cndmask_b32_e64 v10, v51, v134, s[0:1]
	s_waitcnt lgkmcnt(1)
	v_cndmask_b32_e64 v14, v40, v58, s[0:1]
	v_fmac_f32_e32 v74, v10, v59
	v_pk_fma_f32 v[54:55], v[104:105], v[110:111], v[54:55]
	v_cndmask_b32_e64 v26, v58, v40, s[0:1]
	v_fmac_f32_e32 v75, v14, v74
	ds_bpermute_b32 v54, v135, v55
	v_fmac_f32_e32 v78, v26, v75
	s_waitcnt lgkmcnt(1)
	v_cndmask_b32_e64 v7, v9, v20, s[0:1]
	v_cndmask_b32_e64 v9, v20, v9, s[0:1]
	v_mul_f32_e32 v21, v28, v78
	v_mul_f32_e32 v20, v5, v24
	v_add_f32_e32 v21, v21, v9
	v_mov_b32_e32 v9, v30
	v_pk_mul_f32 v[22:23], v[20:21], v[8:9]
	v_pk_fma_f32 v[12:13], v[48:49], v[12:13], v[42:43]
	ds_bpermute_b32 v32, v135, v17
	v_pk_mul_f32 v[22:23], v[6:7], v[22:23]
	v_pk_fma_f32 v[6:7], v[20:21], v[8:9], v[6:7]
	v_mov_b32_e32 v51, v16
	ds_bpermute_b32 v12, v135, v13
	s_waitcnt lgkmcnt(2)
	v_cndmask_b32_e64 v11, v54, v55, s[0:1]
	v_mov_b32_e32 v6, v22
	v_pk_mul_f32 v[8:9], v[22:23], v[50:51]
	v_pk_fma_f32 v[6:7], v[6:7], v[50:51], v[10:11]
	v_pk_mul_f32 v[8:9], v[10:11], v[8:9]
	v_cndmask_b32_e64 v27, v55, v54, s[0:1]
	v_mov_b32_e32 v9, v7
	v_pk_mul_f32 v[10:11], v[8:9], v[14:15]
	ds_bpermute_b32 v33, v135, v19
	s_waitcnt lgkmcnt(2)
	v_cndmask_b32_e64 v29, v32, v17, s[0:1]
	v_pk_mul_f32 v[10:11], v[26:27], v[10:11]
	v_pk_fma_f32 v[8:9], v[8:9], v[14:15], v[26:27]
	ds_bpermute_b32 v25, v135, v4
	s_waitcnt lgkmcnt(2)
	v_cndmask_b32_e64 v31, v12, v13, s[0:1]
	v_mov_b32_e32 v8, v10
	v_pk_mul_f32 v[10:11], v[10:11], v[28:29]
	v_pk_fma_f32 v[8:9], v[8:9], v[28:29], v[30:31]
	v_pk_mul_f32 v[10:11], v[30:31], v[10:11]
	v_cndmask_b32_e64 v17, v17, v32, s[0:1]
	v_mov_b32_e32 v11, v9
	v_cndmask_b32_e64 v7, v13, v12, s[0:1]
	v_mov_b32_e32 v6, v15
	v_pk_mul_f32 v[14:15], v[10:11], v[16:17]
	s_waitcnt lgkmcnt(1)
	v_cndmask_b32_e64 v13, v33, v19, s[0:1]
	v_cndmask_b32_e64 v12, v32, v18, s[0:1]
	v_pk_mul_f32 v[14:15], v[6:7], v[14:15]
	v_pk_fma_f32 v[6:7], v[10:11], v[16:17], v[6:7]
	s_waitcnt lgkmcnt(0)
	v_cndmask_b32_e64 v9, v25, v4, s[0:1]
	v_mov_b32_e32 v8, v17
	v_mov_b32_e32 v6, v14
	v_pk_mul_f32 v[14:15], v[14:15], v[12:13]
	v_pk_fma_f32 v[6:7], v[6:7], v[12:13], v[8:9]
	v_pk_mul_f32 v[14:15], v[8:9], v[14:15]
	v_cndmask_b32_e64 v11, v19, v33, s[0:1]
	v_mov_b32_e32 v10, v13
	v_mov_b32_e32 v15, v7
	v_cndmask_b32_e64 v7, v4, v25, s[0:1]
	v_mov_b32_e32 v6, v11
	v_pk_mul_f32 v[4:5], v[14:15], v[10:11]
	s_nop 0
	v_pk_mul_f32 v[4:5], v[6:7], v[4:5]
	v_pk_fma_f32 v[6:7], v[14:15], v[10:11], v[6:7]
	s_nop 0
	v_mov_b32_e32 v6, v4
	s_and_saveexec_b64 s[4:5], s[0:1]
	v_add_u32_e32 v8, s52, v137
	ds_write_b64 v8, v[6:7]
	s_or_b64 exec, exec, s[4:5]
	s_waitcnt vmcnt(0) lgkmcnt(0)
	s_barrier
	s_and_saveexec_b64 s[4:5], s[44:45]
	s_cbranch_execz .LBB0_949
	v_add_u32_e32 v8, s53, v137
	ds_read_b64 v[8:9], v8 offset:1024
	s_ashr_i32 s47, s46, 31
	s_lshl_b64 s[46:47], s[46:47], 13
	s_add_u32 s46, s21, s46
	s_addc_u32 s47, s51, s47
	s_waitcnt lgkmcnt(0)
	v_pk_mul_f32 v[4:5], v[4:5], v[8:9]
	v_pk_fma_f32 v[6:7], v[6:7], v[8:9], v[8:9] op_sel_hi:[1,0,1]
	v_lshlrev_b32_e32 v10, 3, v152
	v_mov_b32_e32 v5, v7
	global_store_dwordx2 v10, v[4:5], s[46:47]
	s_branch .LBB0_949
; #define LAS __attribute__((address_space(3)))
; template <int PASS> __device__ __forceinline__ void lru_unit(const int u, const bf16* __restrict__ Z, const bf16* __restrict__ LW, const float* __restrict__ cw_g, const float* __restrict__ cb_g, const float* __restrict__ b_a, const float* __restrict__ b_x, const float* __restrict__ lam, ...
;     ...
;             { int t_ = tid; asm volatile("" : "+v"(t_));
; #pragma unroll
;               for (int i = 0; i < 5; ++i) { const int idx = t_ + 512 * i; if (idx < 131 * 16) { const int row = idx >> 4, c = idx & 15, t = tok0 - 3 + row; u32x4v v = (u32x4v){0u, 0u, 0u, 0u};
;                   if (t >= 0) v = *(const u32x4v*)(Z + (size_t)t * NZ + Z_CX + blk * 128 + c * 8); *(LAS u32x4v*)(RAW + row * 128 + c * 8) = v; } } }
.LBB0_974:
	s_mov_b64 s[28:29], s[70:71]
	s_waitcnt vmcnt(0) lgkmcnt(0)
	s_barrier
	s_load_dwordx2 s[12:13], s[28:29], 0xd8
	s_mov_b32 s2, s67
	s_load_dwordx4 s[8:11], s[28:29], 0x50
	s_load_dwordx2 s[0:1], s[28:29], 0x68
	s_load_dwordx4 s[4:7], s[28:29], 0x78
	s_waitcnt vmcnt(19)
	v_mov_b32_e32 v111, v0
	s_waitcnt lgkmcnt(0)
	s_add_u32 s36, s12, 0x40400000
	s_addc_u32 s37, s13, 0
	s_ashr_i32 s28, s2, 3
	s_waitcnt vmcnt(0) lgkmcnt(0)
	s_barrier
	v_mov_b32_e32 v9, v111
	s_and_b32 s44, s2, 7
	s_lshl_b32 s45, s28, 7
	s_movk_i32 s2, 0x830
	v_and_b32_e32 v1, 15, v9
	v_readfirstlane_b32 s21, v111
	s_lshl_b32 s29, s44, 7
	s_add_i32 s45, s45, -3
	v_lshlrev_b32_e32 v8, 3, v1
	v_lshl_add_u32 v1, v1, 4, 0
	v_cmp_gt_i32_e32 vcc, s2, v9
	s_and_saveexec_b64 s[40:41], vcc
	s_cbranch_execz .LBB0_978
	v_ashrrev_i32_e32 v10, 4, v9
	v_add_u32_e32 v2, s45, v10
	v_cmp_lt_i32_e32 vcc, -1, v2
	v_mov_b32_e32 v204, 0
	v_mov_b32_e32 v205, 0
	v_mov_b32_e32 v206, 0
	s_waitcnt vmcnt(8)
	v_mov_b32_e32 v207, 0
	s_and_saveexec_b64 s[42:43], vcc
	s_cbranch_execz .LBB0_977
	v_mov_b64_e32 v[204:205], s[36:37]
	v_mad_u64_u32 v[204:205], s[46:47], v2, s25, v[204:205]
	s_lshl_b32 s2, s29, 1
	v_lshl_add_u64 v[204:205], v[204:205], 0, s[2:3]
	v_lshlrev_b32_e32 v2, 1, v8
	v_lshl_add_u64 v[204:205], v[204:205], 0, v[2:3]
	v_add_co_u32_e32 v204, vcc, 0x2000, v204
	s_nop 1
	v_addc_co_u32_e32 v205, vcc, 0, v205, vcc
	global_load_dwordx4 v[204:207], v[204:205], off offset:2048
.LBB0_977:
	s_or_b64 exec, exec, s[42:43]
	v_lshl_add_u32 v224, v10, 8, v1
.LBB0_978:
	s_or_b64 exec, exec, s[40:41]
	s_movk_i32 s2, 0x630
	v_cmp_gt_i32_e32 vcc, s2, v9
	s_and_saveexec_b64 s[40:41], vcc
	s_cbranch_execz .LBB0_982
	v_add_u32_e32 v2, 0x200, v9
	v_ashrrev_i32_e32 v10, 4, v2
	v_add_u32_e32 v2, s45, v10
	v_cmp_lt_i32_e32 vcc, -1, v2
	v_mov_b32_e32 v208, 0
	v_mov_b32_e32 v209, 0
	v_mov_b32_e32 v210, 0
	s_waitcnt vmcnt(8)
	v_mov_b32_e32 v211, 0
	s_and_saveexec_b64 s[42:43], vcc
	s_cbranch_execz .LBB0_981
	v_mov_b64_e32 v[208:209], s[36:37]
	v_mad_u64_u32 v[208:209], s[46:47], v2, s25, v[208:209]
	s_lshl_b32 s2, s29, 1
	v_lshl_add_u64 v[208:209], v[208:209], 0, s[2:3]
	v_lshlrev_b32_e32 v2, 1, v8
	v_lshl_add_u64 v[208:209], v[208:209], 0, v[2:3]
	v_add_co_u32_e32 v208, vcc, 0x2000, v208
	s_nop 1
	v_addc_co_u32_e32 v209, vcc, 0, v209, vcc
	global_load_dwordx4 v[208:211], v[208:209], off offset:2048
.LBB0_981:
	s_or_b64 exec, exec, s[42:43]
	v_lshl_add_u32 v225, v10, 8, v1
.LBB0_982:
	s_or_b64 exec, exec, s[40:41]
	s_movk_i32 s2, 0x430
	v_cmp_gt_i32_e32 vcc, s2, v9
	s_and_saveexec_b64 s[40:41], vcc
	s_cbranch_execz .LBB0_986
	v_add_u32_e32 v2, 0x400, v9
	v_ashrrev_i32_e32 v10, 4, v2
	v_add_u32_e32 v2, s45, v10
	v_cmp_lt_i32_e32 vcc, -1, v2
	v_mov_b32_e32 v212, 0
	v_mov_b32_e32 v213, 0
	v_mov_b32_e32 v214, 0
	s_waitcnt vmcnt(8)
	v_mov_b32_e32 v215, 0
	s_and_saveexec_b64 s[42:43], vcc
	s_cbranch_execz .LBB0_985
	v_mov_b64_e32 v[212:213], s[36:37]
	v_mad_u64_u32 v[212:213], s[46:47], v2, s25, v[212:213]
	s_lshl_b32 s2, s29, 1
	v_lshl_add_u64 v[212:213], v[212:213], 0, s[2:3]
	v_lshlrev_b32_e32 v2, 1, v8
	v_lshl_add_u64 v[212:213], v[212:213], 0, v[2:3]
	v_add_co_u32_e32 v212, vcc, 0x2000, v212
	s_nop 1
	v_addc_co_u32_e32 v213, vcc, 0, v213, vcc
	global_load_dwordx4 v[212:215], v[212:213], off offset:2048
.LBB0_985:
	s_or_b64 exec, exec, s[42:43]
	v_lshl_add_u32 v226, v10, 8, v1
.LBB0_986:
	s_or_b64 exec, exec, s[40:41]
	s_movk_i32 s2, 0x230
	v_cmp_gt_i32_e32 vcc, s2, v9
	s_and_saveexec_b64 s[40:41], vcc
	s_cbranch_execz .LBB0_990
	v_add_u32_e32 v2, 0x600, v9
	v_ashrrev_i32_e32 v10, 4, v2
	v_add_u32_e32 v2, s45, v10
	v_cmp_lt_i32_e32 vcc, -1, v2
	v_mov_b32_e32 v216, 0
	v_mov_b32_e32 v217, 0
	v_mov_b32_e32 v218, 0
	s_waitcnt vmcnt(8)
	v_mov_b32_e32 v219, 0
	s_and_saveexec_b64 s[42:43], vcc
	s_cbranch_execz .LBB0_989
	v_mov_b64_e32 v[216:217], s[36:37]
	v_mad_u64_u32 v[216:217], s[46:47], v2, s25, v[216:217]
	s_lshl_b32 s2, s29, 1
	v_lshl_add_u64 v[216:217], v[216:217], 0, s[2:3]
	v_lshlrev_b32_e32 v2, 1, v8
	v_lshl_add_u64 v[216:217], v[216:217], 0, v[2:3]
	v_add_co_u32_e32 v216, vcc, 0x2000, v216
	s_nop 1
	v_addc_co_u32_e32 v217, vcc, 0, v217, vcc
	global_load_dwordx4 v[216:219], v[216:217], off offset:2048
.LBB0_989:
	s_or_b64 exec, exec, s[42:43]
	v_lshl_add_u32 v227, v10, 8, v1
.LBB0_990:
	s_or_b64 exec, exec, s[40:41]
	v_cmp_gt_i32_e32 vcc, 48, v9
	s_and_saveexec_b64 s[40:41], vcc
	s_cbranch_execz .LBB0_994
	v_add_u32_e32 v2, 0x800, v9
	v_ashrrev_i32_e32 v9, 4, v2
	v_add_u32_e32 v2, s45, v9
	v_cmp_lt_i32_e32 vcc, -1, v2
	v_mov_b32_e32 v220, 0
	v_mov_b32_e32 v221, 0
	v_mov_b32_e32 v222, 0
	s_waitcnt vmcnt(8)
	v_mov_b32_e32 v223, 0
	s_and_saveexec_b64 s[42:43], vcc
	s_cbranch_execz .LBB0_993
	v_mov_b64_e32 v[220:221], s[36:37]
	v_mad_u64_u32 v[220:221], s[36:37], v2, s25, v[220:221]
	s_lshl_b32 s2, s29, 1
	v_lshl_add_u64 v[220:221], v[220:221], 0, s[2:3]
	v_lshlrev_b32_e32 v2, 1, v8
	v_lshl_add_u64 v[220:221], v[220:221], 0, v[2:3]
	v_add_co_u32_e32 v220, vcc, 0x2000, v220
	s_nop 1
	v_addc_co_u32_e32 v221, vcc, 0, v221, vcc
	global_load_dwordx4 v[220:223], v[220:221], off offset:2048
.LBB0_993:
	s_or_b64 exec, exec, s[42:43]
	v_lshl_add_u32 v228, v9, 8, v1
; #define LAS __attribute__((address_space(3)))
; template <int PASS> __device__ __forceinline__ void lru_unit(const int u, const bf16* __restrict__ Z, const bf16* __restrict__ LW, const float* __restrict__ cw_g, const float* __restrict__ cb_g, const float* __restrict__ b_a, const float* __restrict__ b_x, const float* __restrict__ lam, ...
;     ...
; #pragma unroll
;               for (int i = 0; i < 5; ++i) { const int idx = t_ + 512 * i; if (idx < 131 * 16) { const int row = idx >> 4, c = idx & 15, t = tok0 - 3 + row; u32x4v v = (u32x4v){0u, 0u, 0u, 0u};
;                   if (t >= 0) v = *(const u32x4v*)(Z + (size_t)t * NZ + Z_CX + blk * 128 + c * 8); *(LAS u32x4v*)(RAW + row * 128 + c * 8) = v; } } }
;             const bf16* wt = LW + (size_t)blk * 256 * 128;
;             bf16x8 ba[8], bx[8];
; #pragma unroll
;             for (int s = 0; s < 8; ++s) { ba[s] = *(const bf16x8*)(wt + (size_t)dd * 128 + 16 * s + 8 * hh); bx[s] = *(const bf16x8*)(wt + (size_t)(128 + dd) * 128 + 16 * s + 8 * hh); }
;             const float bav = b_a[d], bxv = b_x[d], sp8 = 8.f * log1pf(expf(-lam[d]));
;             const float w0 = cw_g[d], w1 = cw_g[1024 + d], w2 = cw_g[2048 + d], w3 = cw_g[3072 + d], wb = cb_g[d];
.LBB0_994:
	s_or_b64 exec, exec, s[40:41]
	s_waitcnt vmcnt(0)
	ds_write_b128 v224, v[204:207]
	ds_write_b128 v225, v[208:211]
	ds_write_b128 v226, v[212:215]
	ds_write_b128 v227, v[216:219]
	v_cmp_gt_i32_e32 vcc, 48, v0
	s_and_saveexec_b64 s[40:41], vcc
	ds_write_b128 v228, v[220:223]
	s_or_b64 exec, exec, s[40:41]
	s_add_u32 s2, s12, s27
	s_addc_u32 s36, s13, s26
	s_lshl_b64 s[26:27], s[34:35], 2
	s_add_u32 s34, s8, s26
	s_addc_u32 s35, s9, s27
	s_lshl_b64 s[26:27], s[30:31], 2
	s_add_u32 s8, s10, s26
	s_addc_u32 s9, s11, s27
	s_add_u32 s10, s0, s26
	s_addc_u32 s11, s1, s27
	s_add_u32 s4, s4, s26
	s_addc_u32 s5, s5, s27
	s_add_u32 s0, s6, s26
	s_addc_u32 s1, s7, s27
	s_lshr_b32 s6, s21, 1
	s_and_b32 s6, s6, 0x60
	v_and_b32_e32 v123, 31, v111
	v_or_b32_e32 v113, s6, v123
	s_lshl_b32 s6, s44, 16
	s_add_u32 s6, s2, s6
	v_bfe_u32 v115, v111, 5, 1
	s_addc_u32 s7, s36, 0
	v_lshlrev_b32_e32 v2, 8, v113
	v_lshl_add_u64 v[4:5], s[6:7], 0, v[2:3]
	v_lshlrev_b32_e32 v2, 4, v115
	v_lshl_add_u64 v[4:5], v[4:5], 0, v[2:3]
	s_mov_b32 s2, 0xd400000
	s_mov_b64 s[6:7], 0xd400000
	v_add_co_u32_e32 v10, vcc, s2, v4
	s_waitcnt vmcnt(8)
	v_lshl_add_u64 v[6:7], v[4:5], 0, s[6:7]
	s_mov_b64 s[6:7], 0xd408000
	v_addc_co_u32_e32 v11, vcc, 0, v5, vcc
	s_mov_b32 s2, 0xd408000
	v_lshl_add_u64 v[8:9], v[4:5], 0, s[6:7]
	v_add_co_u32_e32 v4, vcc, s2, v4
	v_or_b32_e32 v140, s29, v113
	s_nop 0
	v_addc_co_u32_e32 v5, vcc, 0, v5, vcc
	v_lshlrev_b32_e32 v2, 2, v140
	global_load_dwordx4 v[92:95], v[10:11], off
	global_load_dwordx4 v[96:99], v[4:5], off
	global_load_dwordx4 v[84:87], v[6:7], off offset:32
	global_load_dwordx4 v[88:91], v[8:9], off offset:32
	global_load_dwordx4 v[76:79], v[6:7], off offset:64
	global_load_dwordx4 v[80:83], v[8:9], off offset:64
	global_load_dwordx4 v[68:71], v[6:7], off offset:96
	global_load_dwordx4 v[72:75], v[8:9], off offset:96
	global_load_dwordx4 v[60:63], v[6:7], off offset:128
	global_load_dwordx4 v[64:67], v[8:9], off offset:128
	global_load_dwordx4 v[56:59], v[6:7], off offset:160
	global_load_dwordx4 v[52:55], v[8:9], off offset:160
	global_load_dwordx4 v[44:47], v[6:7], off offset:192
	global_load_dwordx4 v[48:51], v[8:9], off offset:192
	global_load_dwordx4 v[40:43], v[6:7], off offset:224
	global_load_dwordx4 v[36:39], v[8:9], off offset:224
	global_load_dword v119, v2, s[10:11]
	global_load_dword v1, v2, s[4:5]
	global_load_dword v4, v2, s[0:1]
	s_mov_b32 s0, 0x42ce8ed0
	s_movk_i32 s4, 0x3000
	global_load_dword v120, v2, s[34:35]
	s_lshl_b32 s2, s29, 2
	v_lshrrev_b32_e32 v112, 5, v111
	s_waitcnt vmcnt(1)
	v_mul_f32_e32 v5, 0xbfb8aa3b, v4
	v_fma_f32 v6, v4, s18, -v5
	v_rndne_f32_e32 v7, v5
	v_fmac_f32_e32 v6, 0xb2a5705f, v4
	v_sub_f32_e32 v5, v5, v7
	v_add_f32_e32 v5, v5, v6
	v_exp_f32_e32 v5, v5
	v_cvt_i32_f32_e32 v6, v7
	v_cmp_nlt_f32_e32 vcc, s0, v4
	s_mov_b32 s0, 0xc2b17218
	v_ldexp_f32 v5, v5, v6
	v_cndmask_b32_e32 v5, 0, v5, vcc
	v_cmp_ngt_f32_e32 vcc, s0, v4
	s_mov_b32 s0, 0x3f2aaaab
	s_nop 0
	v_cndmask_b32_e32 v114, v194, v5, vcc
	v_add_f32_e32 v6, 1.0, v114
	v_add_f32_e32 v4, -1.0, v6
	v_sub_f32_e32 v5, v4, v6
	v_add_f32_e32 v5, 1.0, v5
	v_sub_f32_e32 v4, v114, v4
	v_add_f32_e32 v7, v4, v5
	v_frexp_mant_f32_e32 v4, v6
	v_cmp_gt_f32_e32 vcc, s0, v4
	v_cvt_f64_f32_e32 v[4:5], v6
	v_frexp_exp_i32_f64_e32 v4, v[4:5]
	v_subbrev_co_u32_e32 v12, vcc, 0, v4, vcc
	v_sub_u32_e32 v4, 0, v12
	v_ldexp_f32 v5, v6, v4
	v_add_f32_e32 v6, -1.0, v5
	v_add_f32_e32 v8, 1.0, v5
	v_ldexp_f32 v4, v7, v4
	v_add_f32_e32 v7, 1.0, v6
	v_add_f32_e32 v9, -1.0, v8
	v_sub_f32_e32 v7, v5, v7
	v_sub_f32_e32 v5, v5, v9
	v_add_f32_e32 v7, v4, v7
	v_add_f32_e32 v4, v4, v5
	v_add_f32_e32 v13, v8, v4
	v_rcp_f32_e32 v15, v13
	v_sub_f32_e32 v5, v8, v13
	v_add_f32_e32 v14, v4, v5
	v_add_f32_e32 v5, v6, v7
	v_mul_f32_e32 v17, v5, v15
	v_sub_f32_e32 v4, v6, v5
	v_mul_f32_e32 v6, v13, v17
	v_fma_f32 v8, v17, v13, -v6
	v_fmac_f32_e32 v8, v17, v14
	v_add_f32_e32 v16, v7, v4
	v_add_f32_e32 v4, v6, v8
	v_sub_f32_e32 v7, v5, v4
	v_pk_add_f32 v[10:11], v[4:5], v[6:7] neg_lo:[0,1] neg_hi:[0,1]
	v_mov_b32_e32 v9, v4
	v_pk_add_f32 v[4:5], v[10:11], v[8:9] neg_lo:[0,1] neg_hi:[0,1]
	s_mov_b32 s0, 0x3f317218
	v_add_f32_e32 v5, v16, v5
	v_add_f32_e32 v4, v4, v5
	v_add_f32_e32 v5, v7, v4
	v_mul_f32_e32 v16, v15, v5
	v_mul_f32_e32 v6, v13, v16
	v_fma_f32 v8, v16, v13, -v6
	v_fmac_f32_e32 v8, v16, v14
	v_sub_f32_e32 v7, v7, v5
	v_add_f32_e32 v13, v4, v7
	v_add_f32_e32 v4, v6, v8
	v_sub_f32_e32 v7, v5, v4
	v_pk_add_f32 v[10:11], v[4:5], v[6:7] neg_lo:[0,1] neg_hi:[0,1]
	v_mov_b32_e32 v9, v4
	v_pk_add_f32 v[4:5], v[10:11], v[8:9] neg_lo:[0,1] neg_hi:[0,1]
	s_nop 0
	v_add_f32_e32 v5, v13, v5
	v_add_f32_e32 v4, v4, v5
	v_add_f32_e32 v5, v17, v16
	v_add_f32_e32 v4, v7, v4
	v_sub_f32_e32 v6, v5, v17
	v_mul_f32_e32 v4, v15, v4
	v_sub_f32_e32 v6, v16, v6
	v_add_f32_e32 v6, v6, v4
	v_add_f32_e32 v8, v5, v6
	v_mul_f32_e32 v9, v8, v8
	v_fmamk_f32 v4, v9, 0x3e9b6dac, v190
	v_fmaak_f32 v173, v9, v4, 0x3f2aaada
	v_cvt_f32_i32_e32 v4, v12
	v_sub_f32_e32 v5, v8, v5
	v_sub_f32_e32 v5, v6, v5
	v_ldexp_f32 v10, v5, 1
	v_mul_f32_e32 v5, v8, v9
	v_ldexp_f32 v7, v8, 1
	v_pk_mul_f32 v[8:9], v[4:5], v[172:173]
	s_nop 0
	v_fma_f32 v6, v4, s0, -v8
	v_fmac_f32_e32 v6, 0xb102e308, v4
	v_pk_add_f32 v[4:5], v[8:9], v[6:7]
	s_mov_b32 s0, 0x33800000
	v_sub_f32_e32 v7, v5, v7
	v_sub_f32_e32 v7, v9, v7
	v_add_f32_e32 v11, v10, v7
	v_mov_b32_e32 v10, v8
	v_pk_add_f32 v[8:9], v[4:5], v[8:9] neg_lo:[0,1] neg_hi:[0,1]
	v_pk_add_f32 v[12:13], v[4:5], v[10:11]
	v_mov_b32_e32 v7, v4
	v_mov_b32_e32 v9, v13
	v_pk_add_f32 v[20:21], v[6:7], v[8:9] neg_lo:[0,1] neg_hi:[0,1]
	v_pk_add_f32 v[6:7], v[6:7], v[8:9]
; #define LAS __attribute__((address_space(3)))
; __device__ __forceinline__ float lo_bf(unsigned w) { return __uint_as_float(w << 16); }
; __device__ __forceinline__ float hi_bf(unsigned w) { return __uint_as_float(w & 0xffff0000u); }
; #define LRU_BAR() do { asm volatile("s_waitcnt vmcnt(0) lgkmcnt(0)" ::: "memory"); __builtin_amdgcn_s_barrier(); asm volatile("" ::: "memory"); } while (0)
; template <int PASS> __device__ __forceinline__ void lru_unit(const int u, const bf16* __restrict__ Z, const bf16* __restrict__ LW, const float* __restrict__ cw_g, const float* __restrict__ cb_g, const float* __restrict__ b_a, const float* __restrict__ b_x, const float* __restrict__ lam, ...
;     ...
;             const float bav = b_a[d], bxv = b_x[d], sp8 = 8.f * log1pf(expf(-lam[d]));
;             const float w0 = cw_g[d], w1 = cw_g[1024 + d], w2 = cw_g[2048 + d], w3 = cw_g[3072 + d], wb = cb_g[d];
;             LRU_BAR();
;             { const int c8 = tid & 15; const float* cwp = cw_g + blk * 128 + c8 * 8; float cw[4][8], cbv[8];
; #pragma unroll
;               for (int jj = 0; jj < 4; ++jj) { const float4 q0 = *(const float4*)(cwp + jj * 1024), q1 = *(const float4*)(cwp + jj * 1024 + 4); cw[jj][0] = q0.x; cw[jj][1] = q0.y; cw[jj][2] = q0.z; cw[jj][3] = q0.w; cw[jj][4] = q1.x; cw[jj][5] = q1.y; cw[jj][6] = q1.z; cw[jj][7] = q1.w; }
;               { const float4 q0 = *(const float4*)(cb_g + blk * 128 + c8 * 8), q1 = *(const float4*)(cb_g + blk * 128 + c8 * 8 + 4); cbv[0] = q0.x; cbv[1] = q0.y; cbv[2] = q0.z; cbv[3] = q0.w; cbv[4] = q1.x; cbv[5] = q1.y; cbv[6] = q1.z; cbv[7] = q1.w; }
; #pragma unroll
;               for (int i = 0; i < 4; ++i) { const int t = (tid >> 4) + 32 * i; float xv[8];
; #pragma unroll
;                   for (int e = 0; e < 8; ++e) xv[e] = cbv[e];
; #pragma unroll
;                   for (int jj = 0; jj < 4; ++jj) { const u32x4v raw = *(const LAS u32x4v*)(RAW + (t + jj) * 128 + c8 * 8);
;                       xv[0] += cw[jj][0] * lo_bf(raw[0]); xv[1] += cw[jj][1] * hi_bf(raw[0]); xv[2] += cw[jj][2] * lo_bf(raw[1]); xv[3] += cw[jj][3] * hi_bf(raw[1]);
;                       xv[4] += cw[jj][4] * lo_bf(raw[2]); xv[5] += cw[jj][5] * hi_bf(raw[2]); xv[6] += cw[jj][6] * lo_bf(raw[3]); xv[7] += cw[jj][7] * hi_bf(raw[3]); }
;                   *(LAS bf16x8*)(XC + t * 256 + ((c8 ^ (t & 15)) << 4)) = pack8(xv); } }
	v_mov_b32_e32 v10, v11
	v_pk_add_f32 v[8:9], v[6:7], v[4:5] op_sel:[1,0] op_sel_hi:[0,1] neg_lo:[0,1] neg_hi:[0,1]
	v_pk_add_f32 v[14:15], v[12:13], v[8:9] op_sel_hi:[1,0] neg_lo:[0,1] neg_hi:[0,1]
	v_mov_b32_e32 v12, v13
	v_mov_b32_e32 v13, v7
	v_pk_mov_b32 v[8:9], v[4:5], v[8:9] op_sel:[1,0]
	v_mov_b32_e32 v11, v4
	v_pk_add_f32 v[8:9], v[12:13], v[8:9] neg_lo:[0,1] neg_hi:[0,1]
	v_mov_b32_e32 v14, v20
	v_pk_add_f32 v[4:5], v[10:11], v[8:9] neg_lo:[0,1] neg_hi:[0,1]
	v_mov_b32_e32 v21, v7
	v_pk_add_f32 v[24:25], v[14:15], v[4:5]
	v_cmp_lt_f32_e64 vcc, |v114|, s0
	v_pk_add_f32 v[8:9], v[24:25], v[24:25] op_sel:[0,1] op_sel_hi:[1,0]
	s_nop 0
	v_pk_add_f32 v[22:23], v[6:7], v[8:9] op_sel:[1,0] op_sel_hi:[0,1]
	v_mov_b32_e32 v25, v22
	v_pk_add_f32 v[108:109], v[24:25], v[20:21] neg_lo:[0,1] neg_hi:[0,1]
	v_mov_b32_e32 v5, v8
	v_pk_add_f32 v[26:27], v[4:5], v[108:109] neg_lo:[0,1] neg_hi:[0,1]
	v_lshl_add_u64 v[4:5], s[34:35], 0, v[2:3]
	v_add_co_u32_e64 v6, s[0:1], s88, v4
	v_sub_f32_e32 v21, v24, v108
	s_nop 0
	v_addc_co_u32_e64 v7, s[0:1], 0, v5, s[0:1]
	v_add_co_u32_e64 v4, s[0:1], s4, v4
	global_load_dword v121, v[6:7], off offset:-4096
	global_load_dword v118, v[6:7], off
	v_addc_co_u32_e64 v5, s[0:1], 0, v5, s[0:1]
	global_load_dword v110, v[4:5], off
	global_load_dword v122, v2, s[8:9]
	v_lshlrev_b32_e32 v2, 3, v111
	s_add_u32 s0, s34, s2
	v_and_b32_e32 v109, 0x78, v2
	s_waitcnt vmcnt(0) lgkmcnt(0)
	s_barrier
	s_addc_u32 s1, s35, 0
	v_lshlrev_b32_e32 v2, 2, v109
	v_lshl_add_u64 v[4:5], s[0:1], 0, v[2:3]
	global_load_dwordx4 v[100:103], v2, s[0:1] offset:16
	global_load_dwordx4 v[104:107], v2, s[0:1]
	s_mov_b64 s[0:1], 0x1000
	v_lshl_add_u64 v[6:7], v[4:5], 0, s[0:1]
	v_add_co_u32_e64 v8, s[0:1], s88, v4
	v_sub_f32_e32 v20, v20, v21
	s_nop 0
	v_addc_co_u32_e64 v9, s[0:1], 0, v5, s[0:1]
	s_mov_b64 s[0:1], 0x2000
	global_load_dwordx4 v[16:19], v[8:9], off offset:-4096
	global_load_dwordx4 v[12:15], v[6:7], off offset:16
	v_lshl_add_u64 v[6:7], v[4:5], 0, s[0:1]
	s_mov_b64 s[0:1], 0x3000
	global_load_dwordx4 v[32:35], v[8:9], off
	global_load_dwordx4 v[28:31], v[6:7], off offset:16
	v_lshl_add_u64 v[6:7], v[4:5], 0, s[0:1]
	v_add_co_u32_e64 v4, s[0:1], s4, v4
	v_add_f32_e32 v20, v26, v20
	s_nop 0
	v_addc_co_u32_e64 v5, s[0:1], 0, v5, s[0:1]
	v_add_f32_e32 v20, v20, v27
	v_add_f32_e32 v20, v22, v20
	v_cmp_neq_f32_e64 s[0:1], s19, v114
	global_load_dwordx4 v[8:11], v[4:5], off
	s_nop 0
	global_load_dwordx4 v[4:7], v[6:7], off offset:16
	v_cndmask_b32_e64 v116, v194, v20, s[0:1]
	s_add_u32 s0, s8, s2
	s_addc_u32 s1, s9, 0
	global_load_dwordx4 v[20:23], v2, s[0:1] offset:16
	global_load_dwordx4 v[24:27], v2, s[0:1]
	v_ashrrev_i32_e32 v2, 4, v111
	v_lshlrev_b32_e32 v108, 1, v109
	v_lshlrev_b32_e32 v134, 8, v2
	v_xor_b32_e32 v109, v2, v111
	v_add3_u32 v2, 0, v108, v134
	ds_read_b128 v[124:127], v2
	ds_read_b128 v[128:131], v2 offset:256
	v_lshlrev_b32_e32 v109, 4, v109
	v_and_b32_e32 v117, 0xf0, v109
	s_ashr_i32 s0, s21, 2
	s_waitcnt lgkmcnt(1)
	v_lshlrev_b32_e32 v132, 16, v124
	s_waitcnt lgkmcnt(0)
	v_lshlrev_b32_e32 v133, 16, v128
	s_andn2_b32 s0, s0, 63
	s_mov_b32 s1, 0xbe800000
	s_waitcnt vmcnt(8)
	v_mov_b32_e32 v108, v104
	s_waitcnt vmcnt(7)
	v_mov_b32_e32 v109, v16
	v_pk_mul_f32 v[132:133], v[108:109], v[132:133]
	s_waitcnt vmcnt(0)
	v_add_f32_e32 v16, v24, v132
	v_add_f32_e32 v135, v16, v133
	v_and_b32_e32 v133, 0xffff0000, v128
	v_and_b32_e32 v132, 0xffff0000, v124
	v_mov_b32_e32 v16, v105
	v_pk_mul_f32 v[104:105], v[16:17], v[132:133]
	v_lshlrev_b32_e32 v133, 16, v129
	v_add_f32_e32 v104, v25, v104
	v_add_f32_e32 v136, v104, v105
	v_lshlrev_b32_e32 v132, 16, v125
	v_mov_b32_e32 v104, v106
	v_mov_b32_e32 v105, v18
	v_pk_mul_f32 v[132:133], v[104:105], v[132:133]
	v_and_b32_e32 v129, 0xffff0000, v129
	v_add_f32_e32 v18, v26, v132
	v_add_f32_e32 v137, v18, v133
	v_and_b32_e32 v128, 0xffff0000, v125
	v_mov_b32_e32 v18, v107
	v_pk_mul_f32 v[106:107], v[18:19], v[128:129]
	v_lshlrev_b32_e32 v125, 16, v130
	v_add_f32_e32 v106, v27, v106
	v_add_f32_e32 v138, v106, v107
	v_lshlrev_b32_e32 v124, 16, v126
	v_mov_b32_e32 v106, v100
	v_mov_b32_e32 v107, v12
	v_pk_mul_f32 v[124:125], v[106:107], v[124:125]
	s_nop 0
	v_add_f32_e32 v12, v20, v124
	v_add_f32_e32 v139, v12, v125
	v_and_b32_e32 v125, 0xffff0000, v130
	v_and_b32_e32 v124, 0xffff0000, v126
	v_mov_b32_e32 v12, v101
	v_pk_mul_f32 v[100:101], v[12:13], v[124:125]
	v_lshlrev_b32_e32 v125, 16, v131
	v_add_f32_e32 v100, v21, v100
	v_add_f32_e32 v141, v100, v101
	v_lshlrev_b32_e32 v124, 16, v127
	v_mov_b32_e32 v100, v102
	v_mov_b32_e32 v101, v14
	v_pk_mul_f32 v[124:125], v[100:101], v[124:125]
	s_nop 0
	v_add_f32_e32 v14, v22, v124
	v_add_f32_e32 v142, v14, v125
	v_and_b32_e32 v125, 0xffff0000, v131
	v_and_b32_e32 v124, 0xffff0000, v127
	v_mov_b32_e32 v14, v103
	v_pk_mul_f32 v[102:103], v[14:15], v[124:125]
	ds_read_b128 v[124:127], v2 offset:512
	ds_read_b128 v[128:131], v2 offset:768
	v_add_f32_e32 v102, v23, v102
	v_add_f32_e32 v143, v102, v103
	v_mov_b32_e32 v102, v32
	s_waitcnt lgkmcnt(1)
	v_lshlrev_b32_e32 v132, 16, v124
	s_waitcnt lgkmcnt(0)
; #define LAS __attribute__((address_space(3)))
; __device__ __forceinline__ float lo_bf(unsigned w) { return __uint_as_float(w << 16); }
; __device__ __forceinline__ float hi_bf(unsigned w) { return __uint_as_float(w & 0xffff0000u); }
; __device__ __forceinline__ bf16x8 pack8(const float* v) { typedef unsigned u32x4_ __attribute__((ext_vector_type(4))); u32x4_ w; w.x = pk_bf16(v[0], v[1]); w.y = pk_bf16(v[2], v[3]); w.z = pk_bf16(v[4], v[5]); w.w = pk_bf16(v[6], v[7]); return __builtin_bit_cast(bf16x8, w); }
; template <int PASS> __device__ __forceinline__ void lru_unit(const int u, const bf16* __restrict__ Z, const bf16* __restrict__ LW, const float* __restrict__ cw_g, const float* __restrict__ cb_g, const float* __restrict__ b_a, const float* __restrict__ b_x, const float* __restrict__ lam, ...
;     ...
; #pragma unroll
;               for (int i = 0; i < 4; ++i) { const int t = (tid >> 4) + 32 * i; float xv[8];
; #pragma unroll
;                   for (int e = 0; e < 8; ++e) xv[e] = cbv[e];
; #pragma unroll
;                   for (int jj = 0; jj < 4; ++jj) { const u32x4v raw = *(const LAS u32x4v*)(RAW + (t + jj) * 128 + c8 * 8);
;                       xv[0] += cw[jj][0] * lo_bf(raw[0]); xv[1] += cw[jj][1] * hi_bf(raw[0]); xv[2] += cw[jj][2] * lo_bf(raw[1]); xv[3] += cw[jj][3] * hi_bf(raw[1]);
;                       xv[4] += cw[jj][4] * lo_bf(raw[2]); xv[5] += cw[jj][5] * hi_bf(raw[2]); xv[6] += cw[jj][6] * lo_bf(raw[3]); xv[7] += cw[jj][7] * hi_bf(raw[3]); }
;                   *(LAS bf16x8*)(XC + t * 256 + ((c8 ^ (t & 15)) << 4)) = pack8(xv); } }
	v_lshlrev_b32_e32 v133, 16, v128
	v_mov_b32_e32 v103, v8
	v_pk_mul_f32 v[132:133], v[102:103], v[132:133]
	s_nop 0
	v_add_f32_e32 v8, v135, v132
	v_add_f32_e32 v135, v8, v133
	v_and_b32_e32 v133, 0xffff0000, v128
	v_and_b32_e32 v132, 0xffff0000, v124
	v_mov_b32_e32 v8, v33
	v_pk_mul_f32 v[32:33], v[8:9], v[132:133]
	v_lshlrev_b32_e32 v133, 16, v129
	v_add_f32_e32 v32, v136, v32
	v_add_f32_e32 v136, v32, v33
	v_lshlrev_b32_e32 v132, 16, v125
	v_mov_b32_e32 v32, v34
	v_mov_b32_e32 v33, v10
	v_pk_mul_f32 v[132:133], v[32:33], v[132:133]
	v_and_b32_e32 v129, 0xffff0000, v129
	v_add_f32_e32 v10, v137, v132
	v_add_f32_e32 v132, v10, v133
	v_and_b32_e32 v128, 0xffff0000, v125
	v_mov_b32_e32 v10, v35
	v_pk_mul_f32 v[34:35], v[10:11], v[128:129]
	v_lshlrev_b32_e32 v125, 16, v130
	v_add_f32_e32 v34, v138, v34
	v_add_f32_e32 v128, v34, v35
	v_lshlrev_b32_e32 v124, 16, v126
	v_mov_b32_e32 v34, v28
	v_mov_b32_e32 v35, v4
	v_pk_mul_f32 v[124:125], v[34:35], v[124:125]
	s_nop 0
	v_add_f32_e32 v4, v139, v124
	v_add_f32_e32 v129, v4, v125
	v_and_b32_e32 v125, 0xffff0000, v130
	v_and_b32_e32 v124, 0xffff0000, v126
	v_mov_b32_e32 v4, v29
	v_pk_mul_f32 v[28:29], v[4:5], v[124:125]
	v_lshlrev_b32_e32 v125, 16, v131
	v_add_f32_e32 v28, v141, v28
	v_add_f32_e32 v126, v28, v29
	v_lshlrev_b32_e32 v124, 16, v127
	v_mov_b32_e32 v28, v30
	v_mov_b32_e32 v29, v6
	v_pk_mul_f32 v[124:125], v[28:29], v[124:125]
	s_nop 0
	v_add_f32_e32 v6, v142, v124
	v_add_f32_e32 v130, v6, v125
	v_and_b32_e32 v125, 0xffff0000, v131
	v_and_b32_e32 v124, 0xffff0000, v127
	v_mov_b32_e32 v6, v31
	v_pk_mul_f32 v[30:31], v[6:7], v[124:125]
	v_cvt_pk_bf16_f32 v124, v135, v136
	v_cvt_pk_bf16_f32 v125, v132, v128
	v_cvt_pk_bf16_f32 v126, v129, v126
	s_nop 0
	v_add_f32_e32 v30, v143, v30
	v_add_f32_e32 v30, v30, v31
	v_cvt_pk_bf16_f32 v127, v130, v30
	v_add3_u32 v30, 0, v117, v134
	ds_write_b128 v30, v[124:127] offset:36864
	ds_read_b128 v[124:127], v2 offset:8192
	ds_read_b128 v[128:131], v2 offset:8448
	s_waitcnt lgkmcnt(1)
	v_lshlrev_b32_e32 v132, 16, v124
	s_waitcnt lgkmcnt(0)
	v_lshlrev_b32_e32 v133, 16, v128
	v_pk_mul_f32 v[132:133], v[108:109], v[132:133]
	s_nop 0
	v_add_f32_e32 v31, v24, v132
	v_add_f32_e32 v31, v31, v133
	v_and_b32_e32 v133, 0xffff0000, v128
	v_and_b32_e32 v132, 0xffff0000, v124
	v_pk_mul_f32 v[132:133], v[16:17], v[132:133]
	v_and_b32_e32 v128, 0xffff0000, v125
	v_add_f32_e32 v117, v25, v132
	v_add_f32_e32 v117, v117, v133
	v_lshlrev_b32_e32 v133, 16, v129
	v_lshlrev_b32_e32 v132, 16, v125
	v_pk_mul_f32 v[132:133], v[104:105], v[132:133]
	v_and_b32_e32 v129, 0xffff0000, v129
	v_add_f32_e32 v124, v26, v132
	v_add_f32_e32 v134, v124, v133
	v_pk_mul_f32 v[124:125], v[18:19], v[128:129]
	s_nop 0
	v_add_f32_e32 v124, v27, v124
	v_add_f32_e32 v135, v124, v125
	v_lshlrev_b32_e32 v125, 16, v130
	v_lshlrev_b32_e32 v124, 16, v126
	v_pk_mul_f32 v[124:125], v[106:107], v[124:125]
	s_nop 0
	v_add_f32_e32 v124, v20, v124
	v_add_f32_e32 v136, v124, v125
	v_and_b32_e32 v125, 0xffff0000, v130
	v_and_b32_e32 v124, 0xffff0000, v126
	v_pk_mul_f32 v[124:125], v[12:13], v[124:125]
	s_nop 0
	v_add_f32_e32 v124, v21, v124
	v_add_f32_e32 v137, v124, v125
	v_lshlrev_b32_e32 v125, 16, v131
	v_lshlrev_b32_e32 v124, 16, v127
	v_pk_mul_f32 v[124:125], v[100:101], v[124:125]
	s_nop 0
	v_add_f32_e32 v124, v22, v124
	v_add_f32_e32 v138, v124, v125
	v_and_b32_e32 v125, 0xffff0000, v131
	v_and_b32_e32 v124, 0xffff0000, v127
	v_pk_mul_f32 v[124:125], v[14:15], v[124:125]
	s_nop 0
	v_add_f32_e32 v124, v23, v124
	v_add_f32_e32 v139, v124, v125
	ds_read_b128 v[124:127], v2 offset:8704
	ds_read_b128 v[128:131], v2 offset:8960
	s_waitcnt lgkmcnt(1)
	v_lshlrev_b32_e32 v132, 16, v124
	s_waitcnt lgkmcnt(0)
	v_lshlrev_b32_e32 v133, 16, v128
	v_pk_mul_f32 v[132:133], v[102:103], v[132:133]
	s_nop 0
	v_add_f32_e32 v31, v31, v132
	v_add_f32_e32 v31, v31, v133
	v_and_b32_e32 v133, 0xffff0000, v128
	v_and_b32_e32 v132, 0xffff0000, v124
	v_pk_mul_f32 v[132:133], v[8:9], v[132:133]
	v_and_b32_e32 v128, 0xffff0000, v125
	v_add_f32_e32 v117, v117, v132
	v_add_f32_e32 v117, v117, v133
	v_lshlrev_b32_e32 v133, 16, v129
	v_lshlrev_b32_e32 v132, 16, v125
	v_pk_mul_f32 v[132:133], v[32:33], v[132:133]
	v_and_b32_e32 v129, 0xffff0000, v129
	v_add_f32_e32 v124, v134, v132
	v_add_f32_e32 v132, v124, v133
	v_pk_mul_f32 v[124:125], v[10:11], v[128:129]
	s_nop 0
	v_add_f32_e32 v124, v135, v124
	v_add_f32_e32 v128, v124, v125
	v_lshlrev_b32_e32 v125, 16, v130
	v_lshlrev_b32_e32 v124, 16, v126
	v_pk_mul_f32 v[124:125], v[34:35], v[124:125]
	s_nop 0
	v_add_f32_e32 v124, v136, v124
	v_add_f32_e32 v129, v124, v125
	v_and_b32_e32 v125, 0xffff0000, v130
	v_and_b32_e32 v124, 0xffff0000, v126
	v_pk_mul_f32 v[124:125], v[4:5], v[124:125]
	s_nop 0
	v_add_f32_e32 v124, v137, v124
	v_add_f32_e32 v126, v124, v125
	v_lshlrev_b32_e32 v125, 16, v131
	v_lshlrev_b32_e32 v124, 16, v127
	v_pk_mul_f32 v[124:125], v[28:29], v[124:125]
	s_nop 0
	v_add_f32_e32 v124, v138, v124
	v_add_f32_e32 v130, v124, v125
	v_and_b32_e32 v125, 0xffff0000, v131
	v_and_b32_e32 v124, 0xffff0000, v127
	v_pk_mul_f32 v[124:125], v[6:7], v[124:125]
	s_nop 0
	v_add_f32_e32 v124, v139, v124
	v_add_f32_e32 v127, v124, v125
	v_cvt_pk_bf16_f32 v124, v31, v117
	v_cvt_pk_bf16_f32 v125, v132, v128
	v_cvt_pk_bf16_f32 v126, v129, v126
	v_cvt_pk_bf16_f32 v127, v130, v127
	ds_write_b128 v30, v[124:127] offset:45056
	ds_read_b128 v[124:127], v2 offset:16384
	ds_read_b128 v[128:131], v2 offset:16640
	s_waitcnt lgkmcnt(1)
	v_lshlrev_b32_e32 v132, 16, v124
	s_waitcnt lgkmcnt(0)
; #define LAS __attribute__((address_space(3)))
; __device__ __forceinline__ float lo_bf(unsigned w) { return __uint_as_float(w << 16); }
; __device__ __forceinline__ float hi_bf(unsigned w) { return __uint_as_float(w & 0xffff0000u); }
; __device__ __forceinline__ bf16x8 pack8(const float* v) { typedef unsigned u32x4_ __attribute__((ext_vector_type(4))); u32x4_ w; w.x = pk_bf16(v[0], v[1]); w.y = pk_bf16(v[2], v[3]); w.z = pk_bf16(v[4], v[5]); w.w = pk_bf16(v[6], v[7]); return __builtin_bit_cast(bf16x8, w); }
; #define LRU_BAR() do { asm volatile("s_waitcnt vmcnt(0) lgkmcnt(0)" ::: "memory"); __builtin_amdgcn_s_barrier(); asm volatile("" ::: "memory"); } while (0)
; template <int PASS> __device__ __forceinline__ void lru_unit(const int u, const bf16* __restrict__ Z, const bf16* __restrict__ LW, const float* __restrict__ cw_g, const float* __restrict__ cb_g, const float* __restrict__ b_a, const float* __restrict__ b_x, const float* __restrict__ lam, ...
;     ...
; #pragma unroll
;               for (int i = 0; i < 4; ++i) { const int t = (tid >> 4) + 32 * i; float xv[8];
; #pragma unroll
;                   for (int e = 0; e < 8; ++e) xv[e] = cbv[e];
; #pragma unroll
;                   for (int jj = 0; jj < 4; ++jj) { const u32x4v raw = *(const LAS u32x4v*)(RAW + (t + jj) * 128 + c8 * 8);
;                       xv[0] += cw[jj][0] * lo_bf(raw[0]); xv[1] += cw[jj][1] * hi_bf(raw[0]); xv[2] += cw[jj][2] * lo_bf(raw[1]); xv[3] += cw[jj][3] * hi_bf(raw[1]);
;                       xv[4] += cw[jj][4] * lo_bf(raw[2]); xv[5] += cw[jj][5] * hi_bf(raw[2]); xv[6] += cw[jj][6] * lo_bf(raw[3]); xv[7] += cw[jj][7] * hi_bf(raw[3]); }
;                   *(LAS bf16x8*)(XC + t * 256 + ((c8 ^ (t & 15)) << 4)) = pack8(xv); } }
;             LRU_BAR();
	v_lshlrev_b32_e32 v133, 16, v128
	v_pk_mul_f32 v[132:133], v[108:109], v[132:133]
	s_nop 0
	v_add_f32_e32 v31, v24, v132
	v_add_f32_e32 v31, v31, v133
	v_and_b32_e32 v133, 0xffff0000, v128
	v_and_b32_e32 v132, 0xffff0000, v124
	v_pk_mul_f32 v[132:133], v[16:17], v[132:133]
	v_and_b32_e32 v128, 0xffff0000, v125
	v_add_f32_e32 v117, v25, v132
	v_add_f32_e32 v117, v117, v133
	v_lshlrev_b32_e32 v133, 16, v129
	v_lshlrev_b32_e32 v132, 16, v125
	v_pk_mul_f32 v[132:133], v[104:105], v[132:133]
	v_and_b32_e32 v129, 0xffff0000, v129
	v_add_f32_e32 v124, v26, v132
	v_add_f32_e32 v134, v124, v133
	v_pk_mul_f32 v[124:125], v[18:19], v[128:129]
	s_nop 0
	v_add_f32_e32 v124, v27, v124
	v_add_f32_e32 v135, v124, v125
	v_lshlrev_b32_e32 v125, 16, v130
	v_lshlrev_b32_e32 v124, 16, v126
	v_pk_mul_f32 v[124:125], v[106:107], v[124:125]
	s_nop 0
	v_add_f32_e32 v124, v20, v124
	v_add_f32_e32 v136, v124, v125
	v_and_b32_e32 v125, 0xffff0000, v130
	v_and_b32_e32 v124, 0xffff0000, v126
	v_pk_mul_f32 v[124:125], v[12:13], v[124:125]
	s_nop 0
	v_add_f32_e32 v124, v21, v124
	v_add_f32_e32 v137, v124, v125
	v_lshlrev_b32_e32 v125, 16, v131
	v_lshlrev_b32_e32 v124, 16, v127
	v_pk_mul_f32 v[124:125], v[100:101], v[124:125]
	s_nop 0
	v_add_f32_e32 v124, v22, v124
	v_add_f32_e32 v138, v124, v125
	v_and_b32_e32 v125, 0xffff0000, v131
	v_and_b32_e32 v124, 0xffff0000, v127
	v_pk_mul_f32 v[124:125], v[14:15], v[124:125]
	s_nop 0
	v_add_f32_e32 v124, v23, v124
	v_add_f32_e32 v139, v124, v125
	ds_read_b128 v[124:127], v2 offset:16896
	ds_read_b128 v[128:131], v2 offset:17152
	s_waitcnt lgkmcnt(1)
	v_lshlrev_b32_e32 v132, 16, v124
	s_waitcnt lgkmcnt(0)
	v_lshlrev_b32_e32 v133, 16, v128
	v_pk_mul_f32 v[132:133], v[102:103], v[132:133]
	s_nop 0
	v_add_f32_e32 v31, v31, v132
	v_add_f32_e32 v31, v31, v133
	v_and_b32_e32 v133, 0xffff0000, v128
	v_and_b32_e32 v132, 0xffff0000, v124
	v_pk_mul_f32 v[132:133], v[8:9], v[132:133]
	v_and_b32_e32 v128, 0xffff0000, v125
	v_add_f32_e32 v117, v117, v132
	v_add_f32_e32 v117, v117, v133
	v_lshlrev_b32_e32 v133, 16, v129
	v_lshlrev_b32_e32 v132, 16, v125
	v_pk_mul_f32 v[132:133], v[32:33], v[132:133]
	v_and_b32_e32 v129, 0xffff0000, v129
	v_add_f32_e32 v124, v134, v132
	v_add_f32_e32 v132, v124, v133
	v_pk_mul_f32 v[124:125], v[10:11], v[128:129]
	s_nop 0
	v_add_f32_e32 v124, v135, v124
	v_add_f32_e32 v128, v124, v125
	v_lshlrev_b32_e32 v125, 16, v130
	v_lshlrev_b32_e32 v124, 16, v126
	v_pk_mul_f32 v[124:125], v[34:35], v[124:125]
	s_nop 0
	v_add_f32_e32 v124, v136, v124
	v_add_f32_e32 v129, v124, v125
	v_and_b32_e32 v125, 0xffff0000, v130
	v_and_b32_e32 v124, 0xffff0000, v126
	v_pk_mul_f32 v[124:125], v[4:5], v[124:125]
	s_nop 0
	v_add_f32_e32 v124, v137, v124
	v_add_f32_e32 v126, v124, v125
	v_lshlrev_b32_e32 v125, 16, v131
	v_lshlrev_b32_e32 v124, 16, v127
	v_pk_mul_f32 v[124:125], v[28:29], v[124:125]
	s_nop 0
	v_add_f32_e32 v124, v138, v124
	v_add_f32_e32 v130, v124, v125
	v_and_b32_e32 v125, 0xffff0000, v131
	v_and_b32_e32 v124, 0xffff0000, v127
	v_pk_mul_f32 v[124:125], v[6:7], v[124:125]
	s_nop 0
	v_add_f32_e32 v124, v139, v124
	v_add_f32_e32 v127, v124, v125
	v_cvt_pk_bf16_f32 v124, v31, v117
	v_cvt_pk_bf16_f32 v125, v132, v128
	v_cvt_pk_bf16_f32 v126, v129, v126
	v_cvt_pk_bf16_f32 v127, v130, v127
	ds_write_b128 v30, v[124:127] offset:53248
	ds_read_b128 v[124:127], v2 offset:24576
	ds_read_b128 v[128:131], v2 offset:24832
	s_waitcnt lgkmcnt(1)
	v_lshlrev_b32_e32 v132, 16, v124
	s_waitcnt lgkmcnt(0)
	v_lshlrev_b32_e32 v133, 16, v128
	v_pk_mul_f32 v[108:109], v[108:109], v[132:133]
	s_nop 0
	v_add_f32_e32 v24, v24, v108
	v_add_f32_e32 v24, v24, v109
	v_and_b32_e32 v109, 0xffff0000, v128
	v_and_b32_e32 v108, 0xffff0000, v124
	v_pk_mul_f32 v[16:17], v[16:17], v[108:109]
	s_nop 0
	v_add_f32_e32 v16, v25, v16
	v_add_f32_e32 v25, v16, v17
	v_lshlrev_b32_e32 v17, 16, v129
	v_lshlrev_b32_e32 v16, 16, v125
	v_pk_mul_f32 v[16:17], v[104:105], v[16:17]
	s_nop 0
	v_add_f32_e32 v16, v26, v16
	v_add_f32_e32 v26, v16, v17
	v_and_b32_e32 v17, 0xffff0000, v129
	v_and_b32_e32 v16, 0xffff0000, v125
	v_pk_mul_f32 v[16:17], v[18:19], v[16:17]
	s_nop 0
	v_add_f32_e32 v16, v27, v16
	v_add_f32_e32 v27, v16, v17
	v_lshlrev_b32_e32 v17, 16, v130
	v_lshlrev_b32_e32 v16, 16, v126
	v_pk_mul_f32 v[16:17], v[106:107], v[16:17]
	s_nop 0
	v_add_f32_e32 v16, v20, v16
	v_add_f32_e32 v31, v16, v17
	v_and_b32_e32 v17, 0xffff0000, v130
	v_and_b32_e32 v16, 0xffff0000, v126
	v_pk_mul_f32 v[12:13], v[12:13], v[16:17]
	s_nop 0
	v_add_f32_e32 v12, v21, v12
	v_add_f32_e32 v104, v12, v13
	v_lshlrev_b32_e32 v13, 16, v131
	v_lshlrev_b32_e32 v12, 16, v127
	v_pk_mul_f32 v[12:13], v[100:101], v[12:13]
	v_and_b32_e32 v100, 15, v111
	v_add_f32_e32 v12, v22, v12
	v_add_f32_e32 v22, v12, v13
	v_and_b32_e32 v13, 0xffff0000, v131
	v_and_b32_e32 v12, 0xffff0000, v127
	v_pk_mul_f32 v[12:13], v[14:15], v[12:13]
	v_lshlrev_b32_e32 v101, 2, v115
	v_add_f32_e32 v12, v23, v12
	v_add_f32_e32 v23, v12, v13
	ds_read_b128 v[12:15], v2 offset:25088
	ds_read_b128 v[16:19], v2 offset:25344
	s_waitcnt lgkmcnt(1)
	v_lshlrev_b32_e32 v20, 16, v12
	s_waitcnt lgkmcnt(0)
	v_lshlrev_b32_e32 v21, 16, v16
	v_pk_mul_f32 v[20:21], v[102:103], v[20:21]
	v_lshl_add_u32 v103, v113, 1, 0
	v_add_f32_e32 v2, v24, v20
	v_add_f32_e32 v2, v2, v21
	v_and_b32_e32 v21, 0xffff0000, v16
	v_and_b32_e32 v20, 0xffff0000, v12
	v_pk_mul_f32 v[8:9], v[8:9], v[20:21]
	s_nop 0
	v_add_f32_e32 v8, v25, v8
	v_add_f32_e32 v12, v8, v9
	v_lshlrev_b32_e32 v9, 16, v17
	v_lshlrev_b32_e32 v8, 16, v13
	v_pk_mul_f32 v[8:9], v[32:33], v[8:9]
	s_nop 0
	v_add_f32_e32 v8, v26, v8
	v_add_f32_e32 v16, v8, v9
	v_and_b32_e32 v9, 0xffff0000, v17
	v_and_b32_e32 v8, 0xffff0000, v13
	v_pk_mul_f32 v[8:9], v[10:11], v[8:9]
	s_nop 0
	v_add_f32_e32 v8, v27, v8
	v_add_f32_e32 v10, v8, v9
	v_lshlrev_b32_e32 v9, 16, v18
	v_lshlrev_b32_e32 v8, 16, v14
	v_pk_mul_f32 v[8:9], v[34:35], v[8:9]
	s_nop 0
	v_add_f32_e32 v8, v31, v8
	v_add_f32_e32 v11, v8, v9
	v_and_b32_e32 v9, 0xffff0000, v18
	v_and_b32_e32 v8, 0xffff0000, v14
	v_pk_mul_f32 v[4:5], v[4:5], v[8:9]
	s_nop 0
	v_add_f32_e32 v4, v104, v4
	v_add_f32_e32 v8, v4, v5
	v_lshlrev_b32_e32 v5, 16, v19
	v_lshlrev_b32_e32 v4, 16, v15
	v_pk_mul_f32 v[4:5], v[28:29], v[4:5]
	v_bitop3_b32 v104, v115, v100, 2 bitop3:0x36
	v_add_f32_e32 v4, v22, v4
	v_add_f32_e32 v9, v4, v5
	v_and_b32_e32 v5, 0xffff0000, v19
	v_and_b32_e32 v4, 0xffff0000, v15
	v_pk_mul_f32 v[4:5], v[6:7], v[4:5]
	v_lshlrev_b32_e32 v133, 4, v104
	v_add_f32_e32 v4, v23, v4
	v_add_f32_e32 v7, v4, v5
	v_cvt_pk_bf16_f32 v4, v2, v12
	v_cvt_pk_bf16_f32 v5, v16, v10
	v_cvt_pk_bf16_f32 v6, v11, v8
	v_cvt_pk_bf16_f32 v7, v9, v7
	ds_write_b128 v30, v[4:7] offset:61440
	v_or_b32_e32 v4, s0, v123
	v_lshl_add_u32 v102, v4, 8, 0
	v_bitop3_b32 v4, v112, v100, 1 bitop3:0x6c
	v_lshlrev_b32_e32 v131, 4, v4
	s_waitcnt vmcnt(0) lgkmcnt(0)
	s_barrier
; #define LAS __attribute__((address_space(3)))
; __device__ __forceinline__ float bf2f(unsigned short b) { return __uint_as_float(((unsigned)b) << 16); }
; #define MFMA32(a, b, c) __builtin_amdgcn_mfma_f32_32x32x16_bf16((a), (b), (c), 0, 0, 0)
; template <int PASS> __device__ __forceinline__ void lru_unit(const int u, const bf16* __restrict__ Z, const bf16* __restrict__ LW, const float* __restrict__ cw_g, const float* __restrict__ cb_g, const float* __restrict__ b_a, const float* __restrict__ b_x, const float* __restrict__ lam, ...
;     ...
; #pragma unroll
;             for (int tt = 0; tt < 2; ++tt) {
;                 const int tl0 = 64 * th + 32 * tt;
;                 f32x16 accA, accX;
; #pragma unroll
;                 for (int i = 0; i < 16; ++i) { accA[i] = 0.f; accX[i] = 0.f; }
; #pragma unroll
;                 for (int s = 0; s < 8; ++s) { const bf16x8 af = *(const LAS bf16x8*)(XC + (tl0 + r) * 256 + (((2 * s + hh) ^ (r & 15)) << 4)); accA = MFMA32(af, ba[s], accA); accX = MFMA32(af, bx[s], accX); }
; #pragma unroll
;                 for (int gq = 0; gq < 4; ++gq) { const int t0 = tl0 + 8 * gq + 4 * hh; float cxr[7];
; #pragma unroll
;                     for (int q = 0; q < 7; ++q) cxr[q] = bf2f(RAW[(t0 + q) * 128 + dd]);
; #pragma unroll
;                     for (int e = 0; e < 4; ++e) { const int i = 4 * gq + e;
;                         const float xc = wb + w0 * cxr[e] + w1 * cxr[e + 1] + w2 * cxr[e + 2] + w3 * cxr[e + 3];
;                         const float rr = __builtin_amdgcn_rcpf(1.f + __expf(-(accA[i] + bav))), ig = __builtin_amdgcn_rcpf(1.f + __expf(-(accX[i] + bxv)));
;                         const float la = -sp8 * rr, a_ = __expf(la); av[tt][i] = a_; uv[tt][i] = __builtin_amdgcn_sqrtf(neg_expm1_small(2.f * la, a_)) * (ig * xc);
;                     } }
	v_add_u32_e32 v4, v102, v131
	ds_read_b128 v[4:7], v4 offset:36864
	v_add_u32_e32 v104, v102, v133
	ds_read_b128 v[104:107], v104 offset:36864
	s_waitcnt lgkmcnt(1)
	v_mfma_f32_32x32x16_bf16 v[20:35], v[4:7], v[92:95], 0
	v_cndmask_b32_e32 v2, v116, v114, vcc
	v_mul_f32_e32 v2, 0xc1000000, v2
	v_mfma_f32_32x32x16_bf16 v[4:19], v[4:7], v[96:99], 0
	s_waitcnt lgkmcnt(0)
	v_mfma_f32_32x32x16_bf16 v[20:35], v[104:107], v[84:87], v[20:35]
	v_mfma_f32_32x32x16_bf16 v[4:19], v[104:107], v[88:91], v[4:19]
	v_bitop3_b32 v104, v115, v100, 4 bitop3:0x36
	v_lshlrev_b32_e32 v127, 4, v104
	v_add_u32_e32 v104, v102, v127
	ds_read_b128 v[104:107], v104 offset:36864
	s_waitcnt lgkmcnt(0)
	v_mfma_f32_32x32x16_bf16 v[20:35], v[104:107], v[76:79], v[20:35]
	v_mfma_f32_32x32x16_bf16 v[4:19], v[104:107], v[80:83], v[4:19]
	v_bitop3_b32 v104, v115, v100, 6 bitop3:0x36
	v_lshlrev_b32_e32 v117, 4, v104
	v_add_u32_e32 v104, v102, v117
	ds_read_b128 v[104:107], v104 offset:36864
	s_waitcnt lgkmcnt(0)
	v_mfma_f32_32x32x16_bf16 v[20:35], v[104:107], v[68:71], v[20:35]
	v_mfma_f32_32x32x16_bf16 v[4:19], v[104:107], v[72:75], v[4:19]
	v_bitop3_b32 v104, v115, v100, 8 bitop3:0x36
	v_lshlrev_b32_e32 v113, 4, v104
	v_add_u32_e32 v104, v102, v113
	ds_read_b128 v[104:107], v104 offset:36864
	s_waitcnt lgkmcnt(0)
	v_mfma_f32_32x32x16_bf16 v[20:35], v[104:107], v[60:63], v[20:35]
	v_mfma_f32_32x32x16_bf16 v[4:19], v[104:107], v[64:67], v[4:19]
	v_bitop3_b32 v104, v115, v100, 10 bitop3:0x36
	v_lshlrev_b32_e32 v111, 4, v104
	v_add_u32_e32 v104, v102, v111
	ds_read_b128 v[104:107], v104 offset:36864
	s_waitcnt lgkmcnt(0)
	v_mfma_f32_32x32x16_bf16 v[20:35], v[104:107], v[56:59], v[20:35]
	v_mfma_f32_32x32x16_bf16 v[4:19], v[104:107], v[52:55], v[4:19]
	v_bitop3_b32 v104, v115, v100, 12 bitop3:0x36
	v_lshlrev_b32_e32 v107, 4, v104
	v_add_u32_e32 v104, v102, v107
	ds_read_b128 v[134:137], v104 offset:36864
	v_bitop3_b32 v100, v115, v100, 14 bitop3:0x36
	v_lshlrev_b32_e32 v105, 4, v100
	v_add_u32_e32 v100, v102, v105
	s_waitcnt lgkmcnt(0)
	v_mfma_f32_32x32x16_bf16 v[20:35], v[134:137], v[44:47], v[20:35]
	v_mfma_f32_32x32x16_bf16 v[4:19], v[134:137], v[48:51], v[4:19]
	ds_read_b128 v[134:137], v100 offset:36864
	v_or_b32_e32 v100, s0, v101
	v_lshl_add_u32 v124, v100, 8, v103
	ds_read_u16 v100, v124
	s_or_b32 s0, s0, 32
	s_waitcnt lgkmcnt(1)
	v_mfma_f32_32x32x16_bf16 v[20:35], v[134:137], v[40:43], v[20:35]
	v_mfma_f32_32x32x16_bf16 v[4:19], v[134:137], v[36:39], v[4:19]
	s_nop 10
	v_add_f32_e32 v20, v119, v20
	v_mul_f32_e32 v20, 0xbfb8aa3b, v20
	v_exp_f32_e32 v20, v20
	s_nop 0
	v_add_f32_e32 v20, 1.0, v20
	v_add_f32_e32 v4, v1, v4
	v_mul_f32_e32 v4, 0xbfb8aa3b, v4
	v_exp_f32_e32 v4, v4
	v_rcp_f32_e32 v20, v20
	v_add_f32_e32 v5, v1, v5
	v_mul_f32_e32 v5, 0xbfb8aa3b, v5
	v_add_f32_e32 v4, 1.0, v4
	v_rcp_f32_e32 v148, v4
	v_mul_f32_e32 v4, v2, v20
	v_mul_f32_e32 v20, 0x3fb8aa3b, v4
	v_add_f32_e32 v4, v4, v4
	v_exp_f32_e32 v116, v20
	v_fmamk_f32 v20, v4, 0x3ab60b61, v185
	v_fmaak_f32 v20, v4, v20, 0x3d2aaaab
	v_fmaak_f32 v20, v4, v20, 0x3e2aaaab
	v_fma_f32 v20, v4, v20, 0.5
	v_fma_f32 v20, v4, v20, 1.0
	v_mul_f32_e64 v20, v20, -v4
	v_cmp_lt_f32_e32 vcc, s1, v4
	v_fma_f32 v4, -v116, v116, 1.0
	v_exp_f32_e32 v5, v5
	v_cndmask_b32_e32 v4, v4, v20, vcc
	v_sqrt_f32_e32 v149, v4
	v_add_f32_e32 v4, v119, v21
	v_mul_f32_e32 v4, 0xbfb8aa3b, v4
	v_exp_f32_e32 v4, v4
	v_add_f32_e32 v5, 1.0, v5
	v_rcp_f32_e32 v151, v5
	v_add_f32_e32 v4, 1.0, v4
	v_rcp_f32_e32 v4, v4
	s_nop 0
	v_mul_f32_e32 v4, v2, v4
	v_mul_f32_e32 v5, 0x3fb8aa3b, v4
	v_add_f32_e32 v4, v4, v4
	v_exp_f32_e32 v114, v5
	v_fmamk_f32 v5, v4, 0x3ab60b61, v185
	v_fmaak_f32 v5, v4, v5, 0x3d2aaaab
	v_fmaak_f32 v5, v4, v5, 0x3e2aaaab
	v_fma_f32 v5, v4, v5, 0.5
	v_fma_f32 v5, v4, v5, 1.0
	v_mul_f32_e64 v5, v5, -v4
	v_cmp_lt_f32_e32 vcc, s1, v4
	v_fma_f32 v4, -v114, v114, 1.0
	s_nop 0
	v_cndmask_b32_e32 v4, v4, v5, vcc
	v_sqrt_f32_e32 v152, v4
	v_add_f32_e32 v4, v119, v22
	v_mul_f32_e32 v4, 0xbfb8aa3b, v4
	v_exp_f32_e32 v4, v4
	v_add_f32_e32 v5, v1, v6
	v_mul_f32_e32 v5, 0xbfb8aa3b, v5
	v_exp_f32_e32 v5, v5
	v_add_f32_e32 v4, 1.0, v4
	v_rcp_f32_e32 v4, v4
	v_add_f32_e32 v5, 1.0, v5
	v_rcp_f32_e32 v153, v5
	v_mul_f32_e32 v4, v2, v4
	v_mul_f32_e32 v5, 0x3fb8aa3b, v4
	v_add_f32_e32 v4, v4, v4
	v_exp_f32_e32 v112, v5
	v_fmamk_f32 v5, v4, 0x3ab60b61, v185
	v_fmaak_f32 v5, v4, v5, 0x3d2aaaab
	v_fmaak_f32 v5, v4, v5, 0x3e2aaaab
	v_fma_f32 v5, v4, v5, 0.5
	v_fma_f32 v5, v4, v5, 1.0
	v_mul_f32_e64 v5, v5, -v4
	v_cmp_lt_f32_e32 vcc, s1, v4
	v_fma_f32 v4, -v112, v112, 1.0
	s_nop 0
	v_cndmask_b32_e32 v4, v4, v5, vcc
	v_sqrt_f32_e32 v154, v4
	v_add_f32_e32 v4, v119, v23
	v_mul_f32_e32 v4, 0xbfb8aa3b, v4
	v_exp_f32_e32 v4, v4
	v_add_f32_e32 v5, v1, v7
	v_mul_f32_e32 v5, 0xbfb8aa3b, v5
	v_exp_f32_e32 v5, v5
	v_add_f32_e32 v4, 1.0, v4
	v_rcp_f32_e32 v4, v4
	v_add_f32_e32 v5, 1.0, v5
	v_rcp_f32_e32 v155, v5
	v_mul_f32_e32 v4, v2, v4
	v_mul_f32_e32 v5, 0x3fb8aa3b, v4
	v_add_f32_e32 v4, v4, v4
	v_exp_f32_e32 v108, v5
	v_fmamk_f32 v5, v4, 0x3ab60b61, v185
	v_fmaak_f32 v5, v4, v5, 0x3d2aaaab
	v_fmaak_f32 v5, v4, v5, 0x3e2aaaab
	v_fma_f32 v5, v4, v5, 0.5
	v_fma_f32 v5, v4, v5, 1.0
	v_mul_f32_e64 v5, v5, -v4
	v_cmp_lt_f32_e32 vcc, s1, v4
	v_fma_f32 v4, -v108, v108, 1.0
	s_nop 0
	v_cndmask_b32_e32 v4, v4, v5, vcc
	v_sqrt_f32_e32 v156, v4
	ds_read_u16 v4, v124 offset:2048
	s_waitcnt lgkmcnt(1)
	v_lshlrev_b32_e32 v139, 16, v100
	ds_read_u16 v100, v124 offset:256
	v_add_f32_e32 v5, v1, v8
	v_mul_f32_e32 v5, 0xbfb8aa3b, v5
	s_waitcnt lgkmcnt(1)
	v_lshlrev_b32_e32 v180, 16, v4
	ds_read_u16 v4, v124 offset:2304
	s_waitcnt lgkmcnt(1)
; __device__ __forceinline__ float bf2f(unsigned short b) { return __uint_as_float(((unsigned)b) << 16); }
; template <int PASS> __device__ __forceinline__ void lru_unit(const int u, const bf16* __restrict__ Z, const bf16* __restrict__ LW, const float* __restrict__ cw_g, const float* __restrict__ cb_g, const float* __restrict__ b_a, const float* __restrict__ b_x, const float* __restrict__ lam, ...
;     ...
;                 for (int gq = 0; gq < 4; ++gq) { const int t0 = tl0 + 8 * gq + 4 * hh; float cxr[7];
; #pragma unroll
;                     for (int q = 0; q < 7; ++q) cxr[q] = bf2f(RAW[(t0 + q) * 128 + dd]);
; #pragma unroll
;                     for (int e = 0; e < 4; ++e) { const int i = 4 * gq + e;
;                         const float xc = wb + w0 * cxr[e] + w1 * cxr[e + 1] + w2 * cxr[e + 2] + w3 * cxr[e + 3];
;                         const float rr = __builtin_amdgcn_rcpf(1.f + __expf(-(accA[i] + bav))), ig = __builtin_amdgcn_rcpf(1.f + __expf(-(accX[i] + bxv)));
;                         const float la = -sp8 * rr, a_ = __expf(la); av[tt][i] = a_; uv[tt][i] = __builtin_amdgcn_sqrtf(neg_expm1_small(2.f * la, a_)) * (ig * xc);
;                     } }
	v_lshlrev_b32_e32 v150, 16, v100
	ds_read_u16 v100, v124 offset:512
	v_exp_f32_e32 v5, v5
	s_waitcnt lgkmcnt(1)
	v_lshlrev_b32_e32 v174, 16, v4
	ds_read_u16 v4, v124 offset:2560
	s_waitcnt lgkmcnt(1)
	v_lshlrev_b32_e32 v147, 16, v100
	ds_read_u16 v100, v124 offset:768
	v_add_f32_e32 v5, 1.0, v5
	v_rcp_f32_e32 v161, v5
	s_waitcnt lgkmcnt(1)
	v_lshlrev_b32_e32 v162, 16, v4
	ds_read_u16 v4, v124 offset:2816
	s_waitcnt lgkmcnt(1)
	v_lshlrev_b32_e32 v109, 16, v100
	ds_read_u16 v100, v124 offset:1024
	s_waitcnt lgkmcnt(1)
	v_lshlrev_b32_e32 v157, 16, v4
	ds_read_u16 v4, v124 offset:3072
	s_waitcnt lgkmcnt(1)
	v_lshlrev_b32_e32 v125, 16, v100
	ds_read_u16 v100, v124 offset:1280
	s_waitcnt lgkmcnt(1)
	v_lshlrev_b32_e32 v158, 16, v4
	ds_read_u16 v4, v124 offset:3328
	s_waitcnt lgkmcnt(1)
	v_lshlrev_b32_e32 v145, 16, v100
	ds_read_u16 v100, v124 offset:1536
	s_waitcnt lgkmcnt(1)
	v_lshlrev_b32_e32 v159, 16, v4
	ds_read_u16 v4, v124 offset:3584
	s_waitcnt lgkmcnt(1)
	v_lshlrev_b32_e32 v146, 16, v100
	s_waitcnt lgkmcnt(0)
	v_lshlrev_b32_e32 v160, 16, v4
	v_add_f32_e32 v4, v119, v24
	v_mul_f32_e32 v4, 0xbfb8aa3b, v4
	v_exp_f32_e32 v4, v4
	s_nop 0
	v_add_f32_e32 v4, 1.0, v4
	v_rcp_f32_e32 v4, v4
	s_nop 0
	v_mul_f32_e32 v4, v2, v4
	v_mul_f32_e32 v5, 0x3fb8aa3b, v4
	v_add_f32_e32 v4, v4, v4
	v_exp_f32_e32 v143, v5
	v_fmamk_f32 v5, v4, 0x3ab60b61, v185
	v_fmaak_f32 v5, v4, v5, 0x3d2aaaab
	v_fmaak_f32 v5, v4, v5, 0x3e2aaaab
	v_fma_f32 v5, v4, v5, 0.5
	v_fma_f32 v5, v4, v5, 1.0
	v_mul_f32_e64 v5, v5, -v4
	v_cmp_lt_f32_e32 vcc, s1, v4
	v_fma_f32 v4, -v143, v143, 1.0
	s_nop 0
	v_cndmask_b32_e32 v4, v4, v5, vcc
	v_sqrt_f32_e32 v163, v4
	v_add_f32_e32 v4, v119, v25
	v_mul_f32_e32 v4, 0xbfb8aa3b, v4
	v_exp_f32_e32 v4, v4
	v_add_f32_e32 v5, v1, v9
	v_mul_f32_e32 v5, 0xbfb8aa3b, v5
	v_exp_f32_e32 v5, v5
	v_add_f32_e32 v4, 1.0, v4
	v_rcp_f32_e32 v4, v4
	v_add_f32_e32 v5, 1.0, v5
	v_rcp_f32_e32 v173, v5
	v_mul_f32_e32 v4, v2, v4
	v_mul_f32_e32 v5, 0x3fb8aa3b, v4
	v_add_f32_e32 v4, v4, v4
	v_exp_f32_e32 v144, v5
	v_fmamk_f32 v5, v4, 0x3ab60b61, v185
	v_fmaak_f32 v5, v4, v5, 0x3d2aaaab
	v_fmaak_f32 v5, v4, v5, 0x3e2aaaab
	v_fma_f32 v5, v4, v5, 0.5
	v_fma_f32 v5, v4, v5, 1.0
	v_mul_f32_e64 v5, v5, -v4
	v_cmp_lt_f32_e32 vcc, s1, v4
	v_fma_f32 v4, -v144, v144, 1.0
	s_nop 0
	v_cndmask_b32_e32 v4, v4, v5, vcc
	v_sqrt_f32_e32 v175, v4
	v_add_f32_e32 v4, v119, v26
	v_mul_f32_e32 v4, 0xbfb8aa3b, v4
	v_exp_f32_e32 v4, v4
	v_add_f32_e32 v5, v1, v10
	v_mul_f32_e32 v5, 0xbfb8aa3b, v5
	v_exp_f32_e32 v5, v5
	v_add_f32_e32 v4, 1.0, v4
	v_rcp_f32_e32 v4, v4
	v_add_f32_e32 v5, 1.0, v5
	v_rcp_f32_e32 v176, v5
	v_mul_f32_e32 v4, v2, v4
	v_mul_f32_e32 v5, 0x3fb8aa3b, v4
	v_add_f32_e32 v4, v4, v4
	v_exp_f32_e32 v142, v5
	v_fmamk_f32 v5, v4, 0x3ab60b61, v185
	v_fmaak_f32 v5, v4, v5, 0x3d2aaaab
	v_fmaak_f32 v5, v4, v5, 0x3e2aaaab
	v_fma_f32 v5, v4, v5, 0.5
	v_fma_f32 v5, v4, v5, 1.0
	v_mul_f32_e64 v5, v5, -v4
	v_cmp_lt_f32_e32 vcc, s1, v4
	v_fma_f32 v4, -v142, v142, 1.0
	s_nop 0
	v_cndmask_b32_e32 v4, v4, v5, vcc
	v_sqrt_f32_e32 v177, v4
	v_add_f32_e32 v4, v119, v27
	v_mul_f32_e32 v4, 0xbfb8aa3b, v4
	v_exp_f32_e32 v4, v4
	v_add_f32_e32 v5, v1, v11
	v_mul_f32_e32 v5, 0xbfb8aa3b, v5
	v_exp_f32_e32 v5, v5
	v_add_f32_e32 v4, 1.0, v4
	v_rcp_f32_e32 v4, v4
	v_add_f32_e32 v5, 1.0, v5
	v_rcp_f32_e32 v178, v5
	v_mul_f32_e32 v4, v2, v4
	v_mul_f32_e32 v5, 0x3fb8aa3b, v4
	v_add_f32_e32 v4, v4, v4
	v_exp_f32_e32 v141, v5
	v_fmamk_f32 v5, v4, 0x3ab60b61, v185
	v_fmaak_f32 v5, v4, v5, 0x3d2aaaab
	v_fmaak_f32 v5, v4, v5, 0x3e2aaaab
	v_fma_f32 v5, v4, v5, 0.5
	v_fma_f32 v5, v4, v5, 1.0
	v_mul_f32_e64 v5, v5, -v4
	v_cmp_lt_f32_e32 vcc, s1, v4
	v_fma_f32 v4, -v141, v141, 1.0
	s_nop 0
	v_cndmask_b32_e32 v4, v4, v5, vcc
	v_sqrt_f32_e32 v179, v4
	ds_read_u16 v4, v124 offset:4096
	v_add_f32_e32 v5, v1, v12
	v_mul_f32_e32 v5, 0xbfb8aa3b, v5
	v_exp_f32_e32 v5, v5
	s_waitcnt lgkmcnt(0)
	v_lshlrev_b32_e32 v181, 16, v4
	ds_read_u16 v4, v124 offset:4352
	v_add_f32_e32 v5, 1.0, v5
	v_rcp_f32_e32 v206, v5
	v_fma_f32 v181, v120, v181, v122
	s_waitcnt lgkmcnt(0)
	v_lshlrev_b32_e32 v182, 16, v4
	ds_read_u16 v4, v124 offset:4608
	v_fmac_f32_e32 v181, v121, v182
	s_waitcnt lgkmcnt(0)
	v_lshlrev_b32_e32 v208, 16, v4
	ds_read_u16 v4, v124 offset:4864
	v_fmac_f32_e32 v181, v118, v208
	s_waitcnt lgkmcnt(0)
	v_lshlrev_b32_e32 v183, 16, v4
	ds_read_u16 v4, v124 offset:5120
	v_fmac_f32_e32 v181, v110, v183
	s_waitcnt lgkmcnt(0)
	v_lshlrev_b32_e32 v203, 16, v4
	ds_read_u16 v4, v124 offset:5376
	s_waitcnt lgkmcnt(0)
	v_lshlrev_b32_e32 v204, 16, v4
	ds_read_u16 v4, v124 offset:5632
	s_waitcnt lgkmcnt(0)
; __device__ __forceinline__ float bf2f(unsigned short b) { return __uint_as_float(((unsigned)b) << 16); }
; template <int PASS> __device__ __forceinline__ void lru_unit(const int u, const bf16* __restrict__ Z, const bf16* __restrict__ LW, const float* __restrict__ cw_g, const float* __restrict__ cb_g, const float* __restrict__ b_a, const float* __restrict__ b_x, const float* __restrict__ lam, ...
;     ...
;                 for (int gq = 0; gq < 4; ++gq) { const int t0 = tl0 + 8 * gq + 4 * hh; float cxr[7];
; #pragma unroll
;                     for (int q = 0; q < 7; ++q) cxr[q] = bf2f(RAW[(t0 + q) * 128 + dd]);
; #pragma unroll
;                     for (int e = 0; e < 4; ++e) { const int i = 4 * gq + e;
;                         const float xc = wb + w0 * cxr[e] + w1 * cxr[e + 1] + w2 * cxr[e + 2] + w3 * cxr[e + 3];
;                         const float rr = __builtin_amdgcn_rcpf(1.f + __expf(-(accA[i] + bav))), ig = __builtin_amdgcn_rcpf(1.f + __expf(-(accX[i] + bxv)));
;                         const float la = -sp8 * rr, a_ = __expf(la); av[tt][i] = a_; uv[tt][i] = __builtin_amdgcn_sqrtf(neg_expm1_small(2.f * la, a_)) * (ig * xc);
;                     } }
	v_lshlrev_b32_e32 v205, 16, v4
	v_add_f32_e32 v4, v119, v28
	v_mul_f32_e32 v4, 0xbfb8aa3b, v4
	v_exp_f32_e32 v4, v4
	s_nop 0
	v_add_f32_e32 v4, 1.0, v4
	v_rcp_f32_e32 v4, v4
	s_nop 0
	v_mul_f32_e32 v4, v2, v4
	v_mul_f32_e32 v5, 0x3fb8aa3b, v4
	v_add_f32_e32 v4, v4, v4
	v_exp_f32_e32 v106, v5
	v_fmamk_f32 v5, v4, 0x3ab60b61, v185
	v_fmaak_f32 v5, v4, v5, 0x3d2aaaab
	v_fmaak_f32 v5, v4, v5, 0x3e2aaaab
	v_fma_f32 v5, v4, v5, 0.5
	v_fma_f32 v5, v4, v5, 1.0
	v_mul_f32_e64 v5, v5, -v4
	v_cmp_lt_f32_e32 vcc, s1, v4
	v_fma_f32 v4, -v106, v106, 1.0
	s_nop 0
	v_cndmask_b32_e32 v4, v4, v5, vcc
	v_sqrt_f32_e32 v207, v4
	v_add_f32_e32 v4, v119, v29
	v_mul_f32_e32 v4, 0xbfb8aa3b, v4
	v_exp_f32_e32 v4, v4
	v_add_f32_e32 v5, v1, v13
	v_mul_f32_e32 v5, 0xbfb8aa3b, v5
	v_exp_f32_e32 v5, v5
	v_add_f32_e32 v4, 1.0, v4
	v_rcp_f32_e32 v4, v4
	v_add_f32_e32 v5, 1.0, v5
	v_rcp_f32_e32 v209, v5
	v_mul_f32_e32 v4, v2, v4
	v_mul_f32_e32 v5, 0x3fb8aa3b, v4
	v_add_f32_e32 v4, v4, v4
	v_exp_f32_e32 v104, v5
	v_fmamk_f32 v5, v4, 0x3ab60b61, v185
	v_fmaak_f32 v5, v4, v5, 0x3d2aaaab
	v_fmaak_f32 v5, v4, v5, 0x3e2aaaab
	v_fma_f32 v5, v4, v5, 0.5
	v_fma_f32 v5, v4, v5, 1.0
	v_mul_f32_e64 v5, v5, -v4
	v_cmp_lt_f32_e32 vcc, s1, v4
	v_fma_f32 v4, -v104, v104, 1.0
	s_nop 0
	v_cndmask_b32_e32 v4, v4, v5, vcc
	v_sqrt_f32_e32 v210, v4
	v_add_f32_e32 v4, v119, v30
	v_mul_f32_e32 v4, 0xbfb8aa3b, v4
	v_exp_f32_e32 v4, v4
	v_add_f32_e32 v5, v1, v14
	v_mul_f32_e32 v5, 0xbfb8aa3b, v5
	v_exp_f32_e32 v5, v5
	v_add_f32_e32 v4, 1.0, v4
	v_rcp_f32_e32 v4, v4
	v_add_f32_e32 v5, 1.0, v5
	v_rcp_f32_e32 v211, v5
	v_mul_f32_e32 v4, v2, v4
	v_mul_f32_e32 v5, 0x3fb8aa3b, v4
	v_add_f32_e32 v4, v4, v4
	v_exp_f32_e32 v102, v5
	v_fmamk_f32 v5, v4, 0x3ab60b61, v185
	v_fmaak_f32 v5, v4, v5, 0x3d2aaaab
	v_fmaak_f32 v5, v4, v5, 0x3e2aaaab
	v_fma_f32 v5, v4, v5, 0.5
	v_fma_f32 v5, v4, v5, 1.0
	v_mul_f32_e64 v5, v5, -v4
	v_cmp_lt_f32_e32 vcc, s1, v4
	v_fma_f32 v4, -v102, v102, 1.0
	s_nop 0
	v_cndmask_b32_e32 v4, v4, v5, vcc
	v_sqrt_f32_e32 v212, v4
	v_add_f32_e32 v4, v119, v31
	v_mul_f32_e32 v4, 0xbfb8aa3b, v4
	v_exp_f32_e32 v4, v4
	v_add_f32_e32 v5, v1, v15
	v_mul_f32_e32 v5, 0xbfb8aa3b, v5
	v_exp_f32_e32 v5, v5
	v_add_f32_e32 v4, 1.0, v4
	v_rcp_f32_e32 v4, v4
	v_add_f32_e32 v5, 1.0, v5
	v_rcp_f32_e32 v213, v5
	v_mul_f32_e32 v4, v2, v4
	v_mul_f32_e32 v5, 0x3fb8aa3b, v4
	v_add_f32_e32 v4, v4, v4
	v_exp_f32_e32 v100, v5
	v_fmamk_f32 v5, v4, 0x3ab60b61, v185
	v_fmaak_f32 v5, v4, v5, 0x3d2aaaab
	v_fmaak_f32 v5, v4, v5, 0x3e2aaaab
	v_fma_f32 v5, v4, v5, 0.5
	v_fma_f32 v5, v4, v5, 1.0
	v_mul_f32_e64 v5, v5, -v4
	v_cmp_lt_f32_e32 vcc, s1, v4
	v_fma_f32 v4, -v100, v100, 1.0
	s_nop 0
	v_cndmask_b32_e32 v4, v4, v5, vcc
	v_sqrt_f32_e32 v214, v4
	ds_read_u16 v4, v124 offset:6144
	v_add_f32_e32 v5, v1, v16
	v_mul_f32_e32 v5, 0xbfb8aa3b, v5
	v_exp_f32_e32 v5, v5
	ds_read_u16 v221, v124 offset:6400
	ds_read_u16 v222, v124 offset:6656
	ds_read_u16 v224, v124 offset:6912
	ds_read_u16 v223, v124 offset:7168
	ds_read_u16 v219, v124 offset:7424
	ds_read_u16 v220, v124 offset:7680
	s_waitcnt lgkmcnt(6)
	v_lshlrev_b32_e32 v138, 16, v4
	v_add_f32_e32 v4, v119, v32
	v_mul_f32_e32 v4, 0xbfb8aa3b, v4
	v_exp_f32_e32 v4, v4
	v_add_f32_e32 v5, 1.0, v5
	v_rcp_f32_e32 v215, v5
	s_waitcnt lgkmcnt(5)
	v_lshlrev_b32_e32 v170, 16, v221
	v_add_f32_e32 v4, 1.0, v4
	v_rcp_f32_e32 v4, v4
	s_waitcnt lgkmcnt(4)
	v_lshlrev_b32_e32 v171, 16, v222
	v_fma_f32 v221, v120, v182, v122
	v_fmac_f32_e32 v221, v121, v208
	v_mul_f32_e32 v4, v2, v4
	v_mul_f32_e32 v5, 0x3fb8aa3b, v4
	v_add_f32_e32 v4, v4, v4
	v_exp_f32_e32 v132, v5
	v_fmamk_f32 v5, v4, 0x3ab60b61, v185
	v_fmaak_f32 v5, v4, v5, 0x3d2aaaab
	v_fmaak_f32 v5, v4, v5, 0x3e2aaaab
	v_fma_f32 v5, v4, v5, 0.5
	v_fma_f32 v5, v4, v5, 1.0
	v_mul_f32_e64 v5, v5, -v4
	v_cmp_lt_f32_e32 vcc, s1, v4
	v_fma_f32 v4, -v132, v132, 1.0
	v_fmac_f32_e32 v221, v118, v183
	v_cndmask_b32_e32 v4, v4, v5, vcc
	v_sqrt_f32_e32 v135, v4
	v_add_f32_e32 v4, v119, v33
	v_mul_f32_e32 v4, 0xbfb8aa3b, v4
	v_exp_f32_e32 v4, v4
	v_add_f32_e32 v5, v1, v17
	v_mul_f32_e32 v5, 0xbfb8aa3b, v5
	v_exp_f32_e32 v5, v5
	v_add_f32_e32 v4, 1.0, v4
	v_rcp_f32_e32 v4, v4
	v_fmac_f32_e32 v221, v110, v203
	v_add_f32_e32 v5, 1.0, v5
	v_rcp_f32_e32 v216, v5
	v_mul_f32_e32 v4, v2, v4
	v_mul_f32_e32 v5, 0x3fb8aa3b, v4
	v_add_f32_e32 v4, v4, v4
	v_exp_f32_e32 v126, v5
	v_fmamk_f32 v5, v4, 0x3ab60b61, v185
	v_fmaak_f32 v5, v4, v5, 0x3d2aaaab
	v_fmaak_f32 v5, v4, v5, 0x3e2aaaab
	v_fma_f32 v5, v4, v5, 0.5
	v_fma_f32 v5, v4, v5, 1.0
	v_mul_f32_e64 v5, v5, -v4
	v_cmp_lt_f32_e32 vcc, s1, v4
	v_fma_f32 v4, -v126, v126, 1.0
	s_nop 0
	v_cndmask_b32_e32 v4, v4, v5, vcc
	v_sqrt_f32_e32 v217, v4
	v_add_f32_e32 v4, v119, v34
	v_mul_f32_e32 v4, 0xbfb8aa3b, v4
	v_exp_f32_e32 v4, v4
	v_add_f32_e32 v5, v1, v18
	v_mul_f32_e32 v5, 0xbfb8aa3b, v5
	v_exp_f32_e32 v5, v5
	v_add_f32_e32 v4, 1.0, v4
	v_rcp_f32_e32 v4, v4
	v_add_f32_e32 v5, 1.0, v5
	v_rcp_f32_e32 v124, v5
	v_mul_f32_e32 v4, v2, v4
	v_mul_f32_e32 v5, 0x3fb8aa3b, v4
	v_add_f32_e32 v4, v4, v4
	v_exp_f32_e32 v130, v5
	v_fmamk_f32 v5, v4, 0x3ab60b61, v185
	v_fmaak_f32 v5, v4, v5, 0x3d2aaaab
	v_fmaak_f32 v5, v4, v5, 0x3e2aaaab
	v_fma_f32 v5, v4, v5, 0.5
	v_fma_f32 v5, v4, v5, 1.0
	v_mul_f32_e64 v5, v5, -v4
	v_cmp_lt_f32_e32 vcc, s1, v4
	v_fma_f32 v4, -v130, v130, 1.0
	v_mov_b32_e32 v137, v130
	v_cndmask_b32_e32 v4, v4, v5, vcc
	v_sqrt_f32_e32 v136, v4
	v_add_f32_e32 v4, v119, v35
	v_mul_f32_e32 v4, 0xbfb8aa3b, v4
	v_exp_f32_e32 v4, v4
	v_add_f32_e32 v5, v1, v19
	v_mul_f32_e32 v5, 0xbfb8aa3b, v5
	v_exp_f32_e32 v5, v5
	v_add_f32_e32 v4, 1.0, v4
	v_rcp_f32_e32 v4, v4
	v_add_f32_e32 v5, 1.0, v5
	v_rcp_f32_e32 v218, v5
	v_mul_f32_e32 v4, v2, v4
	v_mul_f32_e32 v5, 0x3fb8aa3b, v4
	v_add_f32_e32 v4, v4, v4
	v_exp_f32_e32 v129, v5
	v_fmamk_f32 v5, v4, 0x3ab60b61, v185
	v_fmaak_f32 v5, v4, v5, 0x3d2aaaab
	v_fmaak_f32 v5, v4, v5, 0x3e2aaaab
	v_fma_f32 v5, v4, v5, 0.5
	v_fma_f32 v5, v4, v5, 1.0
	v_mul_f32_e64 v5, v5, -v4
	v_cmp_lt_f32_e32 vcc, s1, v4
	v_fma_f32 v4, -v129, v129, 1.0
	s_nop 0
	v_cndmask_b32_e32 v4, v4, v5, vcc
	v_sqrt_f32_e32 v128, v4
	v_or_b32_e32 v4, s0, v123
	v_lshl_add_u32 v134, v4, 8, 0
	v_add_u32_e32 v4, v134, v131
	ds_read_b128 v[4:7], v4 offset:36864
	s_waitcnt lgkmcnt(0)
; #define LAS __attribute__((address_space(3)))
; __device__ __forceinline__ float bf2f(unsigned short b) { return __uint_as_float(((unsigned)b) << 16); }
; #define MFMA32(a, b, c) __builtin_amdgcn_mfma_f32_32x32x16_bf16((a), (b), (c), 0, 0, 0)
; template <int PASS> __device__ __forceinline__ void lru_unit(const int u, const bf16* __restrict__ Z, const bf16* __restrict__ LW, const float* __restrict__ cw_g, const float* __restrict__ cb_g, const float* __restrict__ b_a, const float* __restrict__ b_x, const float* __restrict__ lam, ...
;     ...
;                 for (int s = 0; s < 8; ++s) { const bf16x8 af = *(const LAS bf16x8*)(XC + (tl0 + r) * 256 + (((2 * s + hh) ^ (r & 15)) << 4)); accA = MFMA32(af, ba[s], accA); accX = MFMA32(af, bx[s], accX); }
; #pragma unroll
;                 for (int gq = 0; gq < 4; ++gq) { const int t0 = tl0 + 8 * gq + 4 * hh; float cxr[7];
; #pragma unroll
;                     for (int q = 0; q < 7; ++q) cxr[q] = bf2f(RAW[(t0 + q) * 128 + dd]);
; #pragma unroll
;                     for (int e = 0; e < 4; ++e) { const int i = 4 * gq + e;
;                         const float xc = wb + w0 * cxr[e] + w1 * cxr[e + 1] + w2 * cxr[e + 2] + w3 * cxr[e + 3];
;                         const float rr = __builtin_amdgcn_rcpf(1.f + __expf(-(accA[i] + bav))), ig = __builtin_amdgcn_rcpf(1.f + __expf(-(accX[i] + bxv)));
;                         const float la = -sp8 * rr, a_ = __expf(la); av[tt][i] = a_; uv[tt][i] = __builtin_amdgcn_sqrtf(neg_expm1_small(2.f * la, a_)) * (ig * xc);
;                     } }
	v_mfma_f32_32x32x16_bf16 v[20:35], v[4:7], v[92:95], 0
	v_add_u32_e32 v92, v134, v133
	ds_read_b128 v[92:95], v92 offset:36864
	v_mfma_f32_32x32x16_bf16 v[4:19], v[4:7], v[96:99], 0
	s_waitcnt lgkmcnt(0)
	v_mfma_f32_32x32x16_bf16 v[20:35], v[92:95], v[84:87], v[20:35]
	v_add_u32_e32 v84, v134, v127
	ds_read_b128 v[84:87], v84 offset:36864
	v_mfma_f32_32x32x16_bf16 v[4:19], v[92:95], v[88:91], v[4:19]
	s_waitcnt lgkmcnt(0)
	v_mfma_f32_32x32x16_bf16 v[20:35], v[84:87], v[76:79], v[20:35]
	v_add_u32_e32 v76, v134, v117
	ds_read_b128 v[76:79], v76 offset:36864
	v_mfma_f32_32x32x16_bf16 v[4:19], v[84:87], v[80:83], v[4:19]
	s_waitcnt lgkmcnt(0)
	v_mfma_f32_32x32x16_bf16 v[20:35], v[76:79], v[68:71], v[20:35]
	v_add_u32_e32 v68, v134, v113
	ds_read_b128 v[68:71], v68 offset:36864
	v_mfma_f32_32x32x16_bf16 v[4:19], v[76:79], v[72:75], v[4:19]
	v_mov_b32_e32 v76, v121
	v_mov_b32_e32 v77, v118
	s_waitcnt lgkmcnt(0)
	v_mfma_f32_32x32x16_bf16 v[20:35], v[68:71], v[60:63], v[20:35]
	v_add_u32_e32 v60, v134, v111
	ds_read_b128 v[60:63], v60 offset:36864
	v_mfma_f32_32x32x16_bf16 v[4:19], v[68:71], v[64:67], v[4:19]
	s_waitcnt lgkmcnt(0)
	v_mfma_f32_32x32x16_bf16 v[4:19], v[60:63], v[52:55], v[4:19]
	v_add_u32_e32 v52, v134, v107
	ds_read_b128 v[52:55], v52 offset:36864
	v_mfma_f32_32x32x16_bf16 v[20:35], v[60:63], v[56:59], v[20:35]
	s_waitcnt lgkmcnt(0)
	v_mfma_f32_32x32x16_bf16 v[20:35], v[52:55], v[44:47], v[20:35]
	v_add_u32_e32 v44, v134, v105
	ds_read_b128 v[44:47], v44 offset:36864
	v_mov_b32_e32 v134, v110
	v_mfma_f32_32x32x16_bf16 v[4:19], v[52:55], v[48:51], v[4:19]
	s_waitcnt lgkmcnt(0)
	v_mfma_f32_32x32x16_bf16 v[20:35], v[44:47], v[40:43], v[20:35]
	v_mfma_f32_32x32x16_bf16 v[4:19], v[44:47], v[36:39], v[4:19]
	s_nop 10
	v_add_f32_e32 v20, v119, v20
	v_mul_f32_e32 v20, 0xbfb8aa3b, v20
	v_exp_f32_e32 v20, v20
	v_or_b32_e32 v36, s0, v101
	v_lshl_add_u32 v45, v36, 8, v103
	ds_read_u16 v60, v45
	ds_read_u16 v57, v45 offset:256
	ds_read_u16 v61, v45 offset:512
	ds_read_u16 v55, v45 offset:768
	ds_read_u16 v53, v45 offset:1024
	ds_read_u16 v37, v45 offset:1280
	ds_read_u16 v41, v45 offset:1536
	v_add_f32_e32 v20, 1.0, v20
	v_add_f32_e32 v4, v1, v4
	v_mul_f32_e32 v4, 0xbfb8aa3b, v4
	v_exp_f32_e32 v4, v4
	v_rcp_f32_e32 v20, v20
	v_add_f32_e32 v5, v1, v5
	v_mul_f32_e32 v5, 0xbfb8aa3b, v5
	v_add_f32_e32 v4, 1.0, v4
	v_rcp_f32_e32 v43, v4
	v_mul_f32_e32 v4, v2, v20
	v_mul_f32_e32 v20, 0x3fb8aa3b, v4
	v_add_f32_e32 v4, v4, v4
	v_fmamk_f32 v36, v4, 0x3ab60b61, v185
	v_exp_f32_e32 v20, v20
	v_fmaak_f32 v36, v4, v36, 0x3d2aaaab
	v_fmaak_f32 v36, v4, v36, 0x3e2aaaab
	v_fma_f32 v36, v4, v36, 0.5
	v_fma_f32 v36, v4, v36, 1.0
	v_mul_f32_e64 v36, v36, -v4
	v_cmp_lt_f32_e32 vcc, s1, v4
	v_fma_f32 v4, -v20, v20, 1.0
	v_exp_f32_e32 v5, v5
	v_cndmask_b32_e32 v4, v4, v36, vcc
	v_sqrt_f32_e32 v47, v4
	v_add_f32_e32 v4, v119, v21
	v_mul_f32_e32 v4, 0xbfb8aa3b, v4
	v_exp_f32_e32 v4, v4
	v_add_f32_e32 v5, 1.0, v5
	v_rcp_f32_e32 v42, v5
	s_waitcnt lgkmcnt(4)
	v_lshlrev_b32_e32 v61, 16, v61
	v_add_f32_e32 v4, 1.0, v4
	v_rcp_f32_e32 v4, v4
	s_nop 0
	v_mul_f32_e32 v4, v2, v4
	v_mul_f32_e32 v5, 0x3fb8aa3b, v4
	v_add_f32_e32 v4, v4, v4
	v_exp_f32_e32 v36, v5
	v_fmamk_f32 v5, v4, 0x3ab60b61, v185
	v_fmaak_f32 v5, v4, v5, 0x3d2aaaab
	v_fmaak_f32 v5, v4, v5, 0x3e2aaaab
	v_fma_f32 v5, v4, v5, 0.5
	v_fma_f32 v5, v4, v5, 1.0
	v_mul_f32_e64 v5, v5, -v4
	v_cmp_lt_f32_e32 vcc, s1, v4
	v_fma_f32 v4, -v36, v36, 1.0
	s_nop 0
	v_cndmask_b32_e32 v4, v4, v5, vcc
	v_sqrt_f32_e32 v46, v4
	v_add_f32_e32 v4, v119, v22
	v_mul_f32_e32 v4, 0xbfb8aa3b, v4
	v_exp_f32_e32 v4, v4
	v_add_f32_e32 v5, v1, v6
	v_mul_f32_e32 v5, 0xbfb8aa3b, v5
	v_exp_f32_e32 v5, v5
	v_add_f32_e32 v4, 1.0, v4
	v_rcp_f32_e32 v4, v4
	ds_read_u16 v54, v45 offset:2048
	ds_read_u16 v51, v45 offset:2304
	ds_read_u16 v62, v45 offset:2560
	ds_read_u16 v49, v45 offset:2816
	ds_read_u16 v22, v45 offset:3072
	ds_read_u16 v63, v45 offset:3328
	ds_read_u16 v64, v45 offset:3584
	v_add_f32_e32 v5, 1.0, v5
	v_rcp_f32_e32 v52, v5
	v_mul_f32_e32 v4, v2, v4
	v_mul_f32_e32 v5, 0x3fb8aa3b, v4
	v_add_f32_e32 v4, v4, v4
	v_exp_f32_e32 v39, v5
	v_fmamk_f32 v5, v4, 0x3ab60b61, v185
	v_fmaak_f32 v5, v4, v5, 0x3d2aaaab
	v_fmaak_f32 v5, v4, v5, 0x3e2aaaab
	v_fma_f32 v5, v4, v5, 0.5
	v_fma_f32 v5, v4, v5, 1.0
	v_mul_f32_e64 v5, v5, -v4
	v_cmp_lt_f32_e32 vcc, s1, v4
	v_fma_f32 v4, -v39, v39, 1.0
	s_waitcnt lgkmcnt(3)
; __device__ __forceinline__ float bf2f(unsigned short b) { return __uint_as_float(((unsigned)b) << 16); }
; template <int PASS> __device__ __forceinline__ void lru_unit(const int u, const bf16* __restrict__ Z, const bf16* __restrict__ LW, const float* __restrict__ cw_g, const float* __restrict__ cb_g, const float* __restrict__ b_a, const float* __restrict__ b_x, const float* __restrict__ lam, ...
;     ...
;                 for (int gq = 0; gq < 4; ++gq) { const int t0 = tl0 + 8 * gq + 4 * hh; float cxr[7];
; #pragma unroll
;                     for (int q = 0; q < 7; ++q) cxr[q] = bf2f(RAW[(t0 + q) * 128 + dd]);
; #pragma unroll
;                     for (int e = 0; e < 4; ++e) { const int i = 4 * gq + e;
;                         const float xc = wb + w0 * cxr[e] + w1 * cxr[e + 1] + w2 * cxr[e + 2] + w3 * cxr[e + 3];
;                         const float rr = __builtin_amdgcn_rcpf(1.f + __expf(-(accA[i] + bav))), ig = __builtin_amdgcn_rcpf(1.f + __expf(-(accX[i] + bxv)));
;                         const float la = -sp8 * rr, a_ = __expf(la); av[tt][i] = a_; uv[tt][i] = __builtin_amdgcn_sqrtf(neg_expm1_small(2.f * la, a_)) * (ig * xc);
;                     } }
	v_lshlrev_b32_e32 v86, 16, v49
	v_cndmask_b32_e32 v4, v4, v5, vcc
	v_sqrt_f32_e32 v38, v4
	v_add_f32_e32 v4, v119, v23
	v_mul_f32_e32 v4, 0xbfb8aa3b, v4
	v_exp_f32_e32 v4, v4
	v_add_f32_e32 v5, v1, v7
	v_mul_f32_e32 v5, 0xbfb8aa3b, v5
	v_exp_f32_e32 v5, v5
	v_add_f32_e32 v4, 1.0, v4
	v_rcp_f32_e32 v4, v4
	v_lshlrev_b32_e32 v87, 16, v62
	v_add_f32_e32 v5, 1.0, v5
	v_rcp_f32_e32 v117, v5
	v_mul_f32_e32 v4, v2, v4
	v_mul_f32_e32 v5, 0x3fb8aa3b, v4
	v_add_f32_e32 v4, v4, v4
	v_exp_f32_e32 v40, v5
	v_fmamk_f32 v5, v4, 0x3ab60b61, v185
	v_fmaak_f32 v5, v4, v5, 0x3d2aaaab
	v_fmaak_f32 v5, v4, v5, 0x3e2aaaab
	v_fma_f32 v5, v4, v5, 0.5
	v_fma_f32 v5, v4, v5, 1.0
	v_mul_f32_e64 v5, v5, -v4
	v_cmp_lt_f32_e32 vcc, s1, v4
	v_fma_f32 v4, -v40, v40, 1.0
	v_mov_b32_e32 v90, v86
	v_cndmask_b32_e32 v4, v4, v5, vcc
	v_sqrt_f32_e32 v113, v4
	v_add_f32_e32 v4, v119, v24
	v_mul_f32_e32 v4, 0xbfb8aa3b, v4
	v_exp_f32_e32 v4, v4
	v_add_f32_e32 v5, v1, v8
	v_lshlrev_b32_e32 v62, 16, v51
	v_mul_f32_e32 v5, 0xbfb8aa3b, v5
	v_add_f32_e32 v4, 1.0, v4
	v_rcp_f32_e32 v4, v4
	v_exp_f32_e32 v5, v5
	v_mov_b32_e32 v88, v87
	v_mov_b32_e32 v89, v62
	v_mul_f32_e32 v4, v2, v4
	v_mul_f32_e32 v6, 0x3fb8aa3b, v4
	v_add_f32_e32 v4, v4, v4
	v_exp_f32_e32 v107, v6
	v_fmamk_f32 v6, v4, 0x3ab60b61, v185
	v_fmaak_f32 v6, v4, v6, 0x3d2aaaab
	v_fmaak_f32 v6, v4, v6, 0x3e2aaaab
	v_fma_f32 v6, v4, v6, 0.5
	v_fma_f32 v6, v4, v6, 1.0
	v_mul_f32_e64 v6, v6, -v4
	v_cmp_lt_f32_e32 vcc, s1, v4
	v_fma_f32 v4, -v107, v107, 1.0
	v_add_f32_e32 v5, 1.0, v5
	v_cndmask_b32_e32 v4, v4, v6, vcc
	v_sqrt_f32_e32 v7, v4
	v_add_f32_e32 v4, v119, v25
	v_mul_f32_e32 v4, 0xbfb8aa3b, v4
	v_exp_f32_e32 v4, v4
	v_rcp_f32_e32 v5, v5
	v_add_f32_e32 v4, 1.0, v4
	v_rcp_f32_e32 v6, v4
	v_add_f32_e32 v4, v1, v9
	v_add_f32_e32 v9, v1, v10
	v_mul_f32_e32 v9, 0xbfb8aa3b, v9
	v_mul_f32_e32 v6, v2, v6
	v_mul_f32_e32 v8, 0x3fb8aa3b, v6
	v_add_f32_e32 v6, v6, v6
	v_exp_f32_e32 v105, v8
	v_fmamk_f32 v8, v6, 0x3ab60b61, v185
	v_fmaak_f32 v8, v6, v8, 0x3d2aaaab
	v_fmaak_f32 v8, v6, v8, 0x3e2aaaab
	v_fma_f32 v8, v6, v8, 0.5
	v_fma_f32 v8, v6, v8, 1.0
	v_mul_f32_e64 v8, v8, -v6
	v_cmp_lt_f32_e32 vcc, s1, v6
	v_fma_f32 v6, -v105, v105, 1.0
	v_exp_f32_e32 v9, v9
	v_cndmask_b32_e32 v6, v6, v8, vcc
	v_add_f32_e32 v8, v119, v26
	v_mul_f32_e32 v8, 0xbfb8aa3b, v8
	v_exp_f32_e32 v8, v8
	v_add_f32_e32 v9, 1.0, v9
	v_rcp_f32_e32 v10, v9
	v_mul_f32_e32 v4, 0xbfb8aa3b, v4
	v_add_f32_e32 v8, 1.0, v8
	v_rcp_f32_e32 v8, v8
	v_exp_f32_e32 v4, v4
	v_sqrt_f32_e32 v6, v6
	v_mul_f32_e32 v8, v2, v8
	v_mul_f32_e32 v9, 0x3fb8aa3b, v8
	v_add_f32_e32 v8, v8, v8
	v_exp_f32_e32 v103, v9
	v_fmamk_f32 v9, v8, 0x3ab60b61, v185
	v_fmaak_f32 v9, v8, v9, 0x3d2aaaab
	v_fmaak_f32 v9, v8, v9, 0x3e2aaaab
	v_fma_f32 v9, v8, v9, 0.5
	v_fma_f32 v9, v8, v9, 1.0
	v_mul_f32_e64 v9, v9, -v8
	v_cmp_lt_f32_e32 vcc, s1, v8
	v_fma_f32 v8, -v103, v103, 1.0
	v_add_f32_e32 v4, 1.0, v4
	v_cndmask_b32_e32 v8, v8, v9, vcc
	v_sqrt_f32_e32 v48, v8
	v_add_f32_e32 v8, v119, v27
	v_mul_f32_e32 v8, 0xbfb8aa3b, v8
	v_exp_f32_e32 v8, v8
	v_add_f32_e32 v9, v1, v11
	v_mul_f32_e32 v9, 0xbfb8aa3b, v9
	v_exp_f32_e32 v9, v9
	v_add_f32_e32 v8, 1.0, v8
	v_rcp_f32_e32 v8, v8
	v_rcp_f32_e32 v4, v4
	v_add_f32_e32 v9, 1.0, v9
	v_rcp_f32_e32 v133, v9
	v_mul_f32_e32 v8, v2, v8
	v_mul_f32_e32 v9, 0x3fb8aa3b, v8
	v_add_f32_e32 v8, v8, v8
	v_exp_f32_e32 v101, v9
	v_fmamk_f32 v9, v8, 0x3ab60b61, v185
	v_fmaak_f32 v9, v8, v9, 0x3d2aaaab
	v_fmaak_f32 v9, v8, v9, 0x3e2aaaab
	v_fma_f32 v9, v8, v9, 0.5
	v_fma_f32 v9, v8, v9, 1.0
	v_mul_f32_e64 v9, v9, -v8
	v_cmp_lt_f32_e32 vcc, s1, v8
	v_fma_f32 v8, -v101, v101, 1.0
	v_mov_b32_e32 v49, v103
	v_cndmask_b32_e32 v8, v8, v9, vcc
	v_sqrt_f32_e32 v131, v8
	ds_read_u16 v8, v45 offset:4096
	ds_read_u16 v72, v45 offset:4352
	ds_read_u16 v73, v45 offset:4608
	ds_read_u16 v68, v45 offset:4864
	ds_read_u16 v66, v45 offset:5120
	ds_read_u16 v74, v45 offset:5376
	ds_read_u16 v75, v45 offset:5632
	s_waitcnt lgkmcnt(5)
	v_lshlrev_b32_e32 v72, 16, v72
	s_waitcnt lgkmcnt(3)
	v_lshlrev_b32_e32 v92, 16, v68
	s_waitcnt lgkmcnt(2)
	v_lshlrev_b32_e32 v93, 16, v66
	v_lshlrev_b32_e32 v50, 16, v8
	v_add_f32_e32 v8, v119, v28
	v_mul_f32_e32 v8, 0xbfb8aa3b, v8
	v_exp_f32_e32 v8, v8
	v_pk_mul_f32 v[94:95], v[120:121], v[92:93]
	v_mov_b32_e32 v51, v72
	v_pk_mul_f32 v[50:51], v[120:121], v[50:51]
	v_add_f32_e32 v8, 1.0, v8
	v_rcp_f32_e32 v9, v8
	v_add_f32_e32 v8, v1, v12
	v_lshlrev_b32_e32 v73, 16, v73
	v_mul_f32_e32 v8, 0xbfb8aa3b, v8
	v_mul_f32_e32 v9, v2, v9
	v_mul_f32_e32 v11, 0x3fb8aa3b, v9
	v_add_f32_e32 v9, v9, v9
	v_exp_f32_e32 v21, v11
	v_fmamk_f32 v11, v9, 0x3ab60b61, v185
	v_fmaak_f32 v11, v9, v11, 0x3d2aaaab
	v_fmaak_f32 v11, v9, v11, 0x3e2aaaab
	v_fma_f32 v11, v9, v11, 0.5
	v_fma_f32 v11, v9, v11, 1.0
	v_mul_f32_e64 v11, v11, -v9
	v_cmp_lt_f32_e32 vcc, s1, v9
	v_fma_f32 v9, -v21, v21, 1.0
	v_exp_f32_e32 v8, v8
	v_cndmask_b32_e32 v9, v9, v11, vcc
	v_sqrt_f32_e32 v67, v9
	v_add_f32_e32 v9, v119, v29
	v_mul_f32_e32 v9, 0xbfb8aa3b, v9
	v_exp_f32_e32 v9, v9
	v_add_f32_e32 v11, v1, v13
	v_mul_f32_e32 v11, 0xbfb8aa3b, v11
	v_exp_f32_e32 v11, v11
	v_add_f32_e32 v9, 1.0, v9
	v_rcp_f32_e32 v9, v9
	v_add_f32_e32 v8, 1.0, v8
	v_add_f32_e32 v11, 1.0, v11
	v_rcp_f32_e32 v25, v11
	v_mul_f32_e32 v9, v2, v9
	v_mul_f32_e32 v11, 0x3fb8aa3b, v9
	v_add_f32_e32 v9, v9, v9
	v_exp_f32_e32 v23, v11
	v_fmamk_f32 v11, v9, 0x3ab60b61, v185
	v_fmaak_f32 v11, v9, v11, 0x3d2aaaab
	v_fmaak_f32 v11, v9, v11, 0x3e2aaaab
	v_fma_f32 v11, v9, v11, 0.5
	v_fma_f32 v11, v9, v11, 1.0
	v_mul_f32_e64 v11, v11, -v9
	v_cmp_lt_f32_e32 vcc, s1, v9
	v_fma_f32 v9, -v23, v23, 1.0
	v_rcp_f32_e32 v8, v8
	v_cndmask_b32_e32 v9, v9, v11, vcc
; __device__ __forceinline__ float bf2f(unsigned short b) { return __uint_as_float(((unsigned)b) << 16); }
; template <int PASS> __device__ __forceinline__ void lru_unit(const int u, const bf16* __restrict__ Z, const bf16* __restrict__ LW, const float* __restrict__ cw_g, const float* __restrict__ cb_g, const float* __restrict__ b_a, const float* __restrict__ b_x, const float* __restrict__ lam, ...
;     ...
;                 for (int gq = 0; gq < 4; ++gq) { const int t0 = tl0 + 8 * gq + 4 * hh; float cxr[7];
; #pragma unroll
;                     for (int q = 0; q < 7; ++q) cxr[q] = bf2f(RAW[(t0 + q) * 128 + dd]);
; #pragma unroll
;                     for (int e = 0; e < 4; ++e) { const int i = 4 * gq + e;
;                         const float xc = wb + w0 * cxr[e] + w1 * cxr[e + 1] + w2 * cxr[e + 2] + w3 * cxr[e + 3];
;                         const float rr = __builtin_amdgcn_rcpf(1.f + __expf(-(accA[i] + bav))), ig = __builtin_amdgcn_rcpf(1.f + __expf(-(accX[i] + bxv)));
;                         const float la = -sp8 * rr, a_ = __expf(la); av[tt][i] = a_; uv[tt][i] = __builtin_amdgcn_sqrtf(neg_expm1_small(2.f * la, a_)) * (ig * xc);
;                     } }
	v_sqrt_f32_e32 v65, v9
	v_add_f32_e32 v9, v119, v30
	v_mul_f32_e32 v9, 0xbfb8aa3b, v9
	v_exp_f32_e32 v9, v9
	v_add_f32_e32 v11, v1, v14
	v_mul_f32_e32 v11, 0xbfb8aa3b, v11
	v_exp_f32_e32 v11, v11
	v_add_f32_e32 v9, 1.0, v9
	v_rcp_f32_e32 v9, v9
	v_mov_b32_e32 v66, v110
	v_add_f32_e32 v11, 1.0, v11
	v_rcp_f32_e32 v24, v11
	v_mul_f32_e32 v9, v2, v9
	v_mul_f32_e32 v11, 0x3fb8aa3b, v9
	v_add_f32_e32 v9, v9, v9
	v_exp_f32_e32 v27, v11
	v_fmamk_f32 v11, v9, 0x3ab60b61, v185
	v_fmaak_f32 v11, v9, v11, 0x3d2aaaab
	v_fmaak_f32 v11, v9, v11, 0x3e2aaaab
	v_fma_f32 v11, v9, v11, 0.5
	v_fma_f32 v11, v9, v11, 1.0
	v_mul_f32_e64 v11, v11, -v9
	v_cmp_lt_f32_e32 vcc, s1, v9
	v_fma_f32 v9, -v27, v27, 1.0
	s_nop 0
	v_cndmask_b32_e32 v9, v9, v11, vcc
	v_sqrt_f32_e32 v26, v9
	v_add_f32_e32 v9, v119, v31
	v_mul_f32_e32 v9, 0xbfb8aa3b, v9
	v_exp_f32_e32 v9, v9
	v_add_f32_e32 v11, v1, v15
	v_mul_f32_e32 v11, 0xbfb8aa3b, v11
	v_exp_f32_e32 v11, v11
	v_add_f32_e32 v9, 1.0, v9
	v_rcp_f32_e32 v9, v9
	v_add_f32_e32 v11, 1.0, v11
	v_rcp_f32_e32 v69, v11
	v_mul_f32_e32 v9, v2, v9
	v_mul_f32_e32 v11, 0x3fb8aa3b, v9
	v_add_f32_e32 v9, v9, v9
	v_exp_f32_e32 v29, v11
	v_fmamk_f32 v11, v9, 0x3ab60b61, v185
	v_fmaak_f32 v11, v9, v11, 0x3d2aaaab
	v_fmaak_f32 v11, v9, v11, 0x3e2aaaab
	v_fma_f32 v11, v9, v11, 0.5
	v_fma_f32 v11, v9, v11, 1.0
	v_mul_f32_e64 v11, v11, -v9
	v_cmp_lt_f32_e32 vcc, s1, v9
	v_fma_f32 v9, -v29, v29, 1.0
	s_nop 0
	v_cndmask_b32_e32 v9, v9, v11, vcc
	v_sqrt_f32_e32 v28, v9
	ds_read_u16 v9, v45 offset:6144
	v_add_f32_e32 v11, v1, v16
	v_mul_f32_e32 v11, 0xbfb8aa3b, v11
	v_exp_f32_e32 v11, v11
	ds_read_u16 v13, v45 offset:6400
	ds_read_u16 v70, v45 offset:6656
	ds_read_u16 v30, v45 offset:6912
	ds_read_u16 v31, v45 offset:7168
	ds_read_u16 v71, v45 offset:7424
	ds_read_u16 v45, v45 offset:7680
	s_waitcnt lgkmcnt(6)
	v_lshlrev_b32_e32 v44, 16, v9
	v_add_f32_e32 v9, v119, v32
	v_mul_f32_e32 v9, 0xbfb8aa3b, v9
	v_exp_f32_e32 v9, v9
	v_add_f32_e32 v11, 1.0, v11
	v_rcp_f32_e32 v96, v11
	s_waitcnt lgkmcnt(3)
	v_lshlrev_b32_e32 v32, 16, v30
	v_add_f32_e32 v9, 1.0, v9
	v_rcp_f32_e32 v9, v9
	v_lshlrev_b32_e32 v78, 16, v13
	v_lshlrev_b32_e32 v79, 16, v70
	s_waitcnt lgkmcnt(1)
	v_lshlrev_b32_e32 v30, 16, v71
	v_mul_f32_e32 v11, v2, v9
	v_mul_f32_e32 v9, 0x3fb8aa3b, v11
	v_add_f32_e32 v11, v11, v11
	v_fmamk_f32 v12, v11, 0x3ab60b61, v185
	v_exp_f32_e32 v9, v9
	v_fmaak_f32 v12, v11, v12, 0x3d2aaaab
	v_fmaak_f32 v12, v11, v12, 0x3e2aaaab
	v_fma_f32 v12, v11, v12, 0.5
	v_fma_f32 v12, v11, v12, 1.0
	v_mul_f32_e64 v12, v12, -v11
	v_cmp_lt_f32_e32 vcc, s1, v11
	v_fma_f32 v11, -v9, v9, 1.0
	v_lshlrev_b32_e32 v71, 16, v64
	v_cndmask_b32_e32 v11, v11, v12, vcc
	v_sqrt_f32_e32 v111, v11
	v_add_f32_e32 v11, v119, v33
	v_mul_f32_e32 v11, 0xbfb8aa3b, v11
	v_exp_f32_e32 v11, v11
	v_add_f32_e32 v12, v1, v17
	v_mul_f32_e32 v12, 0xbfb8aa3b, v12
	v_exp_f32_e32 v12, v12
	v_add_f32_e32 v11, 1.0, v11
	v_rcp_f32_e32 v11, v11
	v_lshlrev_b32_e32 v33, 16, v31
	v_add_f32_e32 v12, 1.0, v12
	v_rcp_f32_e32 v97, v12
	v_mul_f32_e32 v12, v2, v11
	v_mul_f32_e32 v11, 0x3fb8aa3b, v12
	v_add_f32_e32 v12, v12, v12
	v_fmamk_f32 v14, v12, 0x3ab60b61, v185
	v_exp_f32_e32 v11, v11
	v_fmaak_f32 v14, v12, v14, 0x3d2aaaab
	v_fmaak_f32 v14, v12, v14, 0x3e2aaaab
	v_fma_f32 v14, v12, v14, 0.5
	v_fma_f32 v14, v12, v14, 1.0
	v_mul_f32_e64 v14, v14, -v12
	v_cmp_lt_f32_e32 vcc, s1, v12
	v_fma_f32 v12, -v11, v11, 1.0
	s_waitcnt lgkmcnt(0)
	v_lshlrev_b32_e32 v31, 16, v45
	v_cndmask_b32_e32 v12, v12, v14, vcc
	v_sqrt_f32_e32 v98, v12
	v_add_f32_e32 v12, v119, v34
	v_mul_f32_e32 v12, 0xbfb8aa3b, v12
	v_exp_f32_e32 v12, v12
	v_mov_b32_e32 v45, v78
	v_pk_mul_f32 v[80:81], v[76:77], v[32:33]
	v_add_f32_e32 v12, 1.0, v12
	v_rcp_f32_e32 v14, v12
	v_add_f32_e32 v12, v1, v18
	v_add_f32_e32 v1, v1, v19
	v_pk_mul_f32 v[18:19], v[106:107], v[104:105]
	v_mul_f32_e32 v14, v2, v14
	v_mul_f32_e32 v15, 0x3fb8aa3b, v14
	v_add_f32_e32 v14, v14, v14
	v_fmamk_f32 v16, v14, 0x3ab60b61, v185
	v_exp_f32_e32 v15, v15
	v_fmaak_f32 v16, v14, v16, 0x3d2aaaab
	v_fmaak_f32 v16, v14, v16, 0x3e2aaaab
	v_fma_f32 v16, v14, v16, 0.5
	v_fma_f32 v16, v14, v16, 1.0
	v_mul_f32_e64 v16, v16, -v14
	v_cmp_lt_f32_e32 vcc, s1, v14
	v_fma_f32 v14, -v15, v15, 1.0
	v_pk_mul_f32 v[18:19], v[102:103], v[18:19]
	v_cndmask_b32_e32 v14, v14, v16, vcc
	v_pk_mul_f32 v[16:17], v[120:121], v[32:33]
	v_pk_mul_f32 v[58:59], v[100:101], v[18:19]
	v_add_f32_e32 v16, v122, v16
	v_add_f32_e32 v84, v16, v17
	v_add_f32_e32 v16, v119, v35
	v_pk_mul_f32 v[18:19], v[120:121], v[78:79]
	v_pk_mul_f32 v[34:35], v[120:121], v[44:45]
	v_mov_b32_e32 v119, v110
	v_add_f32_e32 v13, v122, v18
	v_add_f32_e32 v18, v122, v34
	v_add_f32_e32 v70, v18, v35
	v_add_f32_e32 v13, v13, v19
	v_pk_mul_f32 v[18:19], v[118:119], v[32:33]
	v_pk_mov_b32 v[32:33], v[78:79], v[32:33] op_sel:[1,0]
	v_mul_f32_e32 v16, 0xbfb8aa3b, v16
	v_pk_mul_f32 v[44:45], v[118:119], v[32:33]
	v_lshlrev_b32_e32 v32, 16, v22
	v_exp_f32_e32 v16, v16
	v_pk_mul_f32 v[34:35], v[118:119], v[30:31]
	v_mov_b32_e32 v91, v32
	v_add_f32_e32 v31, v122, v94
	v_mul_f32_e32 v1, 0xbfb8aa3b, v1
	v_pk_mul_f32 v[90:91], v[120:121], v[90:91]
	v_add_f32_e32 v64, v31, v95
	v_mov_b32_e32 v94, v87
	v_mov_b32_e32 v95, v86
	v_exp_f32_e32 v1, v1
	v_add_f32_e32 v13, v13, v18
	v_add_f32_e32 v18, v70, v44
	v_lshlrev_b32_e32 v70, 16, v63
	v_add_f32_e32 v22, v122, v90
	v_pk_mul_f32 v[94:95], v[120:121], v[94:95]
	v_add_f32_e32 v22, v22, v91
	v_add_f32_e32 v31, v122, v94
	v_mov_b32_e32 v90, v32
	v_mov_b32_e32 v91, v70
	v_add_f32_e32 v16, 1.0, v16
	v_add_f32_e32 v34, v84, v34
	v_pk_mul_f32 v[84:85], v[118:119], v[70:71]
	v_add_f32_e32 v31, v31, v95
; __device__ __forceinline__ float bf2f(unsigned short b) { return __uint_as_float(((unsigned)b) << 16); }
; template <int PASS> __device__ __forceinline__ void lru_unit(const int u, const bf16* __restrict__ Z, const bf16* __restrict__ LW, const float* __restrict__ cw_g, const float* __restrict__ cb_g, const float* __restrict__ b_a, const float* __restrict__ b_x, const float* __restrict__ lam, ...
;     ...
;                 for (int gq = 0; gq < 4; ++gq) { const int t0 = tl0 + 8 * gq + 4 * hh; float cxr[7];
; #pragma unroll
;                     for (int q = 0; q < 7; ++q) cxr[q] = bf2f(RAW[(t0 + q) * 128 + dd]);
; #pragma unroll
;                     for (int e = 0; e < 4; ++e) { const int i = 4 * gq + e;
;                         const float xc = wb + w0 * cxr[e] + w1 * cxr[e + 1] + w2 * cxr[e + 2] + w3 * cxr[e + 3];
;                         const float rr = __builtin_amdgcn_rcpf(1.f + __expf(-(accA[i] + bav))), ig = __builtin_amdgcn_rcpf(1.f + __expf(-(accX[i] + bxv)));
;                         const float la = -sp8 * rr, a_ = __expf(la); av[tt][i] = a_; uv[tt][i] = __builtin_amdgcn_sqrtf(neg_expm1_small(2.f * la, a_)) * (ig * xc);
;                     } }
;     ...
;             for (int gq = 0; gq < 4; ++gq) { float A = av[tt][4 * gq], H = uv[tt][4 * gq];
; #pragma unroll
;                 for (int e = 1; e < 4; ++e) { H = H * av[tt][4 * gq + e] + uv[tt][4 * gq + e]; A *= av[tt][4 * gq + e]; }
;                 Ag[tt][gq] = A; Hg[tt][gq] = H; Ap[tt][gq] = __shfl_xor(A, 32); Hp[tt][gq] = __shfl_xor(H, 32); }
	v_pk_mul_f32 v[70:71], v[118:119], v[90:91]
	v_rcp_f32_e32 v16, v16
	v_add_f32_e32 v31, v31, v70
	v_add_f32_e32 v1, 1.0, v1
	v_add_f32_e32 v31, v31, v71
	v_rcp_f32_e32 v99, v1
	v_lshlrev_b32_e32 v63, 16, v54
	v_mul_f32_e32 v54, v10, v31
	v_add_f32_e32 v10, v18, v45
	v_add_f32_e32 v22, v22, v84
	v_mul_f32_e32 v31, v96, v10
	v_add_f32_e32 v10, v13, v19
	v_mul_f32_e32 v1, v2, v16
	v_add_f32_e32 v127, v22, v85
	v_mul_f32_e32 v10, v97, v10
	v_add_f32_e32 v22, v122, v50
	v_mul_f32_e32 v2, 0x3fb8aa3b, v1
	v_add_f32_e32 v1, v1, v1
	v_mul_f32_e32 v13, v98, v10
	v_add_f32_e32 v10, v34, v35
	v_lshlrev_b32_e32 v35, 16, v75
	v_lshlrev_b32_e32 v34, 16, v74
	v_pk_mul_f32 v[74:75], v[120:121], v[72:73]
	v_add_f32_e32 v22, v22, v51
	v_pk_mul_f32 v[50:51], v[76:77], v[92:93]
	v_pk_mul_f32 v[84:85], v[118:119], v[92:93]
	v_pk_mov_b32 v[90:91], v[72:73], v[92:93] op_sel:[1,0]
	v_lshlrev_b32_e32 v93, 16, v60
	v_lshlrev_b32_e32 v60, 16, v55
	v_exp_f32_e32 v17, v2
	v_fmamk_f32 v2, v1, 0x3ab60b61, v185
	v_mul_f32_e32 v68, v99, v10
	v_add_f32_e32 v10, v122, v74
	v_mov_b32_e32 v98, v61
	v_mov_b32_e32 v99, v60
	v_fmaak_f32 v2, v1, v2, 0x3d2aaaab
	v_add_f32_e32 v10, v10, v75
	v_pk_mul_f32 v[98:99], v[120:121], v[98:99]
	v_fmaak_f32 v2, v1, v2, 0x3e2aaaab
	v_add_f32_e32 v84, v10, v84
	v_add_f32_e32 v10, v122, v98
	v_fma_f32 v2, v1, v2, 0.5
	v_lshlrev_b32_e32 v92, 16, v57
	v_lshlrev_b32_e32 v96, 16, v53
	v_add_f32_e32 v53, v10, v99
	v_lshlrev_b32_e32 v98, 16, v224
	v_lshlrev_b32_e32 v99, 16, v223
	v_fma_f32 v57, v120, v139, v122
	v_mov_b32_e32 v139, v170
	v_fma_f32 v2, v1, v2, 1.0
	v_pk_mul_f32 v[74:75], v[118:119], v[34:35]
	v_pk_mul_f32 v[90:91], v[118:119], v[90:91]
	v_pk_mul_f32 v[164:165], v[120:121], v[98:99]
	v_pk_mul_f32 v[138:139], v[120:121], v[138:139]
	v_mul_f32_e64 v2, v2, -v1
	v_cmp_lt_f32_e32 vcc, s1, v1
	v_fma_f32 v1, -v17, v17, 1.0
	v_add_f32_e32 v227, v64, v74
	v_add_f32_e32 v35, v22, v90
	v_add_f32_e32 v22, v122, v164
	v_add_f32_e32 v64, v122, v138
	v_fma_f32 v72, v120, v73, v122
	v_cndmask_b32_e32 v1, v1, v2, vcc
	v_pk_mul_f32 v[222:223], v[120:121], v[170:171]
	v_add_f32_e32 v139, v64, v139
	v_add_f32_e32 v64, v22, v165
	v_add_f32_e32 v22, v72, v50
	v_mov_b32_e32 v72, v60
	v_mov_b32_e32 v73, v96
	v_sqrt_f32_e32 v16, v1
	v_xor_b32_e32 v1, 32, v186
	v_add_f32_e32 v55, v122, v222
	v_fma_f32 v74, v120, v150, v122
	v_pk_mul_f32 v[72:73], v[120:121], v[72:73]
	v_fmac_f32_e32 v57, v121, v150
	v_cmp_lt_i32_e32 vcc, v1, v192
	v_mov_b32_e32 v95, v92
	v_fma_f32 v90, v120, v147, v122
	v_fma_f32 v138, v120, v171, v122
	v_fma_f32 v10, v120, v79, v122
	v_add_f32_e32 v55, v55, v223
	v_add_f32_e32 v22, v22, v51
	v_pk_fma_f32 v[50:51], v[120:121], v[92:93], v[122:123] op_sel_hi:[0,1,0]
	v_add_f32_e32 v72, v122, v72
	v_pk_mul_f32 v[92:93], v[118:119], v[98:99]
	v_fmac_f32_e32 v74, v121, v147
	v_pk_mul_f32 v[76:77], v[76:77], v[98:99]
	v_fmac_f32_e32 v57, v118, v147
	v_cndmask_b32_e32 v1, v186, v1, vcc
	v_cmp_eq_u32_e32 vcc, 0, v115
	v_fma_f32 v115, v120, v109, v122
	v_add_f32_e32 v10, v10, v80
	v_add_f32_e32 v165, v72, v73
	v_lshlrev_b32_e32 v73, 16, v41
	v_lshlrev_b32_e32 v79, 16, v220
	v_lshlrev_b32_e32 v78, 16, v219
	v_add_f32_e32 v41, v55, v92
	v_fmac_f32_e32 v90, v121, v109
	v_add_f32_e32 v55, v138, v76
	v_fmac_f32_e32 v74, v118, v109
	v_fmac_f32_e32 v57, v110, v109
	v_pk_mul_f32 v[70:71], v[132:133], v[126:127]
	v_fma_f32 v127, v120, v180, v122
	v_add_f32_e32 v10, v10, v81
	v_pk_mul_f32 v[80:81], v[118:119], v[78:79]
	v_fmac_f32_e32 v115, v121, v125
	v_fmac_f32_e32 v90, v118, v125
	v_add_f32_e32 v76, v55, v77
	v_mul_f32_e32 v55, v148, v57
	v_fmac_f32_e32 v74, v110, v125
	v_fma_f32 v133, v120, v174, v122
	v_pk_fma_f32 v[62:63], v[120:121], v[62:63], v[122:123] op_sel_hi:[0,1,0]
	v_lshlrev_b32_e32 v72, 16, v37
	v_add_f32_e32 v37, v64, v80
	v_fmac_f32_e32 v127, v121, v174
	v_mov_b32_e32 v64, v121
	v_fmac_f32_e32 v115, v118, v145
	v_mul_f32_e32 v148, v55, v149
	v_mul_f32_e32 v55, v151, v74
	v_fmac_f32_e32 v90, v110, v145
	v_fma_f32 v164, v120, v162, v122
	v_fmac_f32_e32 v133, v121, v162
	v_pk_fma_f32 v[62:63], v[64:65], v[88:89], v[62:63] op_sel_hi:[0,1,1]
	v_fmac_f32_e32 v127, v118, v162
	v_pk_mov_b32 v[88:89], v[170:171], v[98:99] op_sel:[1,0]
	v_mul_f32_e32 v147, v55, v152
	v_mul_f32_e32 v55, v153, v90
	v_fmac_f32_e32 v115, v110, v146
	v_mov_b32_e32 v94, v61
	v_fma_f32 v180, v120, v157, v122
	v_fmac_f32_e32 v164, v121, v157
	v_fmac_f32_e32 v133, v118, v157
	v_pk_mul_f32 v[88:89], v[118:119], v[88:89]
	v_mul_f32_e32 v145, v55, v154
	v_mul_f32_e32 v55, v155, v115
	v_fmac_f32_e32 v127, v110, v157
	v_fmac_f32_e32 v180, v121, v158
	v_pk_fma_f32 v[50:51], v[64:65], v[94:95], v[50:51] op_sel_hi:[0,1,1]
	v_fmac_f32_e32 v164, v118, v158
	v_add_f32_e32 v64, v139, v88
	v_mul_f32_e32 v139, v55, v156
	v_mul_f32_e32 v55, v161, v127
	v_fmac_f32_e32 v133, v110, v158
	v_fmac_f32_e32 v180, v118, v159
	v_mul_f32_e32 v138, v55, v163
	v_mul_f32_e32 v55, v173, v133
	v_fmac_f32_e32 v164, v110, v159
	v_fma_f32 v222, v120, v208, v122
	v_mul_f32_e32 v133, v55, v175
	v_mul_f32_e32 v55, v176, v164
	v_fmac_f32_e32 v180, v110, v160
	v_mov_b32_e32 v33, v86
	v_mov_b32_e32 v97, v60
	v_fma_f32 v224, v120, v183, v122
	v_fmac_f32_e32 v222, v121, v183
	v_pk_fma_f32 v[86:87], v[118:119], v[86:87], v[62:63] op_sel_hi:[0,1,1]
	v_mul_f32_e32 v127, v55, v177
	v_mul_f32_e32 v55, v178, v180
	v_pk_fma_f32 v[50:51], v[118:119], v[60:61], v[50:51] op_sel_hi:[0,1,1]
	v_fmac_f32_e32 v224, v121, v203
	v_fmac_f32_e32 v222, v118, v203
	v_mul_f32_e32 v122, v179, v55
	v_mul_f32_e32 v55, v206, v181
	v_pk_fma_f32 v[50:51], v[110:111], v[96:97], v[50:51] op_sel_hi:[0,1,1]
	v_pk_fma_f32 v[32:33], v[110:111], v[32:33], v[86:87] op_sel_hi:[0,1,1]
; template <int PASS> __device__ __forceinline__ void lru_unit(const int u, const bf16* __restrict__ Z, const bf16* __restrict__ LW, const float* __restrict__ cw_g, const float* __restrict__ cb_g, const float* __restrict__ b_a, const float* __restrict__ b_x, const float* __restrict__ lam, ...
;     ...
;             for (int gq = 0; gq < 4; ++gq) { float A = av[tt][4 * gq], H = uv[tt][4 * gq];
; #pragma unroll
;                 for (int e = 1; e < 4; ++e) { H = H * av[tt][4 * gq + e] + uv[tt][4 * gq + e]; A *= av[tt][4 * gq + e]; }
;                 Ag[tt][gq] = A; Hg[tt][gq] = H; Ap[tt][gq] = __shfl_xor(A, 32); Hp[tt][gq] = __shfl_xor(H, 32); }
; #pragma unroll
;             for (int p = 0; p < 8; ++p) { const bool own = ((p & 1) == hh); const float A = own ? Ag[tt][p >> 1] : Ap[tt][p >> 1], H = own ? Hg[tt][p >> 1] : Hp[tt][p >> 1]; Hw = Hw * A + H; Aw *= A; }
	v_fmac_f32_e32 v224, v118, v204
	v_mul_f32_e32 v121, v207, v55
	v_mul_f32_e32 v55, v209, v221
	v_fmac_f32_e32 v222, v110, v204
	v_pk_mul_f32 v[42:43], v[42:43], v[50:51]
	v_pk_mul_f32 v[4:5], v[4:5], v[32:33]
	v_mul_f32_e32 v120, v210, v55
	v_mul_f32_e32 v55, v211, v222
	v_fmac_f32_e32 v224, v110, v205
	v_pk_mul_f32 v[50:51], v[42:43], v[46:47]
	v_pk_mul_f32 v[46:47], v[4:5], v[6:7]
	v_fma_f32 v6, v144, v138, v133
	v_mul_f32_e32 v99, v212, v55
	v_mul_f32_e32 v55, v213, v224
	v_add_f32_e32 v37, v37, v81
	v_mov_b32_e32 v80, v96
	v_mov_b32_e32 v81, v72
	v_fma_f32 v6, v142, v6, v127
	v_pk_mul_f32 v[94:95], v[118:119], v[72:73]
	v_mul_f32_e32 v98, v214, v55
	v_add_f32_e32 v55, v64, v89
	v_add_f32_e32 v41, v41, v93
	v_pk_mul_f32 v[72:73], v[118:119], v[80:81]
	v_fma_f32 v119, v141, v6, v122
	v_fma_f32 v6, v104, v121, v120
	v_mov_b32_e32 v77, v126
	v_mul_f32_e32 v79, v215, v55
	v_mul_f32_e32 v41, v216, v41
	v_mul_f32_e32 v74, v218, v37
	v_add_f32_e32 v37, v53, v72
	v_fma_f32 v6, v102, v6, v99
	v_pk_mul_f32 v[62:63], v[134:135], v[78:79]
	v_mul_f32_e32 v125, v217, v41
	v_add_f32_e32 v37, v37, v73
	v_add_f32_e32 v4, v35, v91
	v_fma_f32 v146, v100, v6, v98
	v_pk_fma_f32 v[6:7], v[134:135], v[78:79], v[76:77]
	v_mul_f32_e32 v42, v52, v37
	v_mul_f32_e32 v35, v8, v4
	v_add_f32_e32 v4, v84, v85
	v_pk_mul_f32 v[6:7], v[124:125], v[6:7]
	v_pk_fma_f32 v[52:53], v[76:77], v[62:63], v[124:125]
	v_mul_f32_e32 v4, v25, v4
	v_mov_b32_e32 v7, v53
	v_mul_f32_e32 v25, v65, v4
	v_pk_mul_f32 v[64:65], v[136:137], v[6:7]
	v_add_f32_e32 v4, v227, v75
	v_pk_fma_f32 v[6:7], v[136:137], v[6:7], v[64:65] op_sel_hi:[1,1,0]
	v_lshlrev_b32_e32 v1, 2, v1
	v_mov_b32_e32 v75, v7
	v_pk_mul_f32 v[60:61], v[128:129], v[74:75]
	v_add_f32_e32 v41, v165, v94
	v_add_f32_e32 v61, v60, v61
	ds_bpermute_b32 v6, v1, v61
	ds_bpermute_b32 v37, v1, v146
	v_fma_f32 v43, v36, v51, v50
	v_mul_f32_e32 v2, v143, v144
	v_add_f32_e32 v115, v41, v95
	v_pk_mul_f32 v[52:53], v[42:43], v[38:39]
	v_mul_f32_e32 v2, v142, v2
	v_fma_f32 v5, v114, v148, v147
	s_waitcnt lgkmcnt(1)
	v_cndmask_b32_e32 v86, v6, v61, vcc
	v_cndmask_b32_e32 v88, v61, v6, vcc
	v_add_f32_e32 v6, v52, v53
	v_fma_f32 v55, v105, v47, v46
	v_pk_mul_f32 v[42:43], v[116:117], v[114:115]
	v_mul_f32_e32 v56, v141, v2
	v_fma_f32 v5, v112, v5, v145
	v_mul_f32_e32 v109, v40, v6
	v_pk_mul_f32 v[48:49], v[54:55], v[48:49]
	v_pk_mul_f32 v[54:55], v[112:113], v[42:43]
	ds_bpermute_b32 v2, v1, v56
	v_fma_f32 v118, v108, v5, v139
	v_pk_mul_f32 v[78:79], v[108:109], v[54:55]
	ds_bpermute_b32 v5, v1, v118
	s_waitcnt lgkmcnt(2)
	v_cndmask_b32_e32 v62, v37, v146, vcc
	v_cndmask_b32_e32 v65, v146, v37, vcc
	ds_bpermute_b32 v37, v1, v78
	ds_bpermute_b32 v8, v1, v119
	v_mul_f32_e32 v12, 0xbfb8aa3b, v12
	s_waitcnt lgkmcnt(3)
	v_cndmask_b32_e32 v83, v2, v56, vcc
	v_cndmask_b32_e32 v82, v56, v2, vcc
	ds_bpermute_b32 v2, v1, v58
	v_exp_f32_e32 v12, v12
	s_waitcnt lgkmcnt(3)
	v_cndmask_b32_e32 v41, v5, v118, vcc
	v_pk_fma_f32 v[80:81], v[112:113], v[42:43], v[108:109]
	s_waitcnt lgkmcnt(2)
	v_cndmask_b32_e32 v42, v37, v78, vcc
	v_pk_mul_f32 v[32:33], v[66:67], v[34:35]
	v_cndmask_b32_e32 v5, v118, v5, vcc
	v_fmac_f32_e32 v41, 0, v42
	v_cndmask_b32_e32 v42, v78, v37, vcc
	v_pk_fma_f32 v[34:35], v[66:67], v[34:35], v[22:23]
	s_waitcnt lgkmcnt(1)
	v_cndmask_b32_e32 v57, v8, v119, vcc
	v_fmac_f32_e32 v5, v42, v41
	v_mul_f32_e32 v37, v78, v37
	v_pk_mul_f32 v[34:35], v[24:25], v[34:35]
	v_pk_fma_f32 v[42:43], v[22:23], v[32:33], v[24:25]
	v_fmac_f32_e32 v57, v83, v5
	v_mul_f32_e32 v5, v37, v83
	v_mov_b32_e32 v35, v43
	v_add_f32_e32 v12, 1.0, v12
	s_waitcnt lgkmcnt(0)
; template <int PASS> __device__ __forceinline__ void lru_unit(const int u, const bf16* __restrict__ Z, const bf16* __restrict__ LW, const float* __restrict__ cw_g, const float* __restrict__ cb_g, const float* __restrict__ b_a, const float* __restrict__ b_x, const float* __restrict__ lam, ...
;     ...
;             for (int gq = 0; gq < 4; ++gq) { float A = av[tt][4 * gq], H = uv[tt][4 * gq];
; #pragma unroll
;                 for (int e = 1; e < 4; ++e) { H = H * av[tt][4 * gq + e] + uv[tt][4 * gq + e]; A *= av[tt][4 * gq + e]; }
;                 Ag[tt][gq] = A; Hg[tt][gq] = H; Ap[tt][gq] = __shfl_xor(A, 32); Hp[tt][gq] = __shfl_xor(H, 32); }
; #pragma unroll
;             for (int p = 0; p < 8; ++p) { const bool own = ((p & 1) == hh); const float A = own ? Ag[tt][p >> 1] : Ap[tt][p >> 1], H = own ? Hg[tt][p >> 1] : Hp[tt][p >> 1]; Hw = Hw * A + H; Aw *= A; }
;         }
;         if (hh == 0) { xcomp[(wave * 32 + r) * 2] = Aw; xcomp[(wave * 32 + r) * 2 + 1] = Hw; }
	v_cndmask_b32_e32 v225, v2, v58, vcc
	v_add_f32_e32 v6, v48, v49
	v_mul_f32_e32 v5, v82, v5
	v_pk_mul_f32 v[42:43], v[26:27], v[34:35]
	v_rcp_f32_e32 v12, v12
	v_cndmask_b32_e32 v226, v58, v2, vcc
	v_pk_mul_f32 v[44:45], v[130:131], v[70:71]
	v_mul_f32_e32 v7, v101, v6
	v_mov_b32_e32 v6, v129
	v_mul_f32_e32 v5, v5, v225
	v_pk_fma_f32 v[34:35], v[26:27], v[34:35], v[42:43] op_sel_hi:[1,1,0]
	v_mul_f32_e32 v4, v69, v4
	v_pk_mul_f32 v[76:77], v[6:7], v[44:45]
	v_pk_fma_f32 v[6:7], v[130:131], v[70:71], v[6:7]
	v_mul_f32_e32 v70, v226, v5
	v_mov_b32_e32 v5, v35
	v_sqrt_f32_e32 v14, v14
	v_cndmask_b32_e32 v8, v119, v8, vcc
	v_pk_mul_f32 v[34:35], v[28:29], v[4:5]
	v_pk_mul_f32 v[18:19], v[110:111], v[30:31]
	v_fmac_f32_e32 v8, v82, v57
	v_pk_fma_f32 v[82:83], v[28:29], v[4:5], v[34:35] op_sel:[0,0,1] op_sel_hi:[1,1,0]
	v_pk_fma_f32 v[4:5], v[110:111], v[30:31], v[10:11]
	v_pk_fma_f32 v[30:31], v[10:11], v[18:19], v[12:13]
	v_pk_mul_f32 v[4:5], v[12:13], v[4:5]
	v_mov_b32_e32 v37, v23
	v_mov_b32_e32 v5, v31
	v_pk_mul_f32 v[30:31], v[14:15], v[4:5]
	v_fmac_f32_e32 v62, v225, v8
	v_pk_fma_f32 v[4:5], v[14:15], v[4:5], v[30:31] op_sel_hi:[1,1,0]
	v_pk_mul_f32 v[66:67], v[20:21], v[36:37]
	v_mov_b32_e32 v69, v5
	v_pk_mul_f32 v[4:5], v[16:17], v[68:69]
	v_mov_b32_e32 v8, v21
	v_mov_b32_e32 v10, v23
	v_mov_b32_e32 v26, v39
	ds_bpermute_b32 v38, v1, v76
	v_pk_fma_f32 v[84:85], v[16:17], v[68:69], v[4:5] op_sel:[0,0,1] op_sel_hi:[1,1,0]
	v_pk_mul_f32 v[68:69], v[8:9], v[10:11]
	v_pk_mul_f32 v[66:67], v[26:27], v[66:67]
	v_mov_b32_e32 v14, v27
	v_mov_b32_e32 v41, v29
	v_pk_mul_f32 v[72:73], v[14:15], v[68:69]
	v_pk_mul_f32 v[68:69], v[40:41], v[66:67]
	ds_bpermute_b32 v44, v1, v81
	ds_bpermute_b32 v5, v1, v68
	ds_bpermute_b32 v2, v1, v59
	ds_bpermute_b32 v49, v1, v7
	v_mov_b32_e32 v16, v29
	v_fmac_f32_e32 v65, v226, v62
	v_pk_mul_f32 v[66:67], v[16:17], v[72:73]
	s_waitcnt lgkmcnt(4)
	v_cndmask_b32_e32 v72, v38, v76, vcc
	v_fmac_f32_e32 v86, v72, v65
	v_cndmask_b32_e32 v74, v76, v38, vcc
	ds_bpermute_b32 v8, v1, v66
	s_waitcnt lgkmcnt(4)
	v_cndmask_b32_e32 v14, v44, v81, vcc
	v_fmac_f32_e32 v88, v74, v86
	s_waitcnt lgkmcnt(3)
	v_cndmask_b32_e32 v86, v5, v68, vcc
	ds_bpermute_b32 v22, v1, v82
	v_cndmask_b32_e32 v16, v81, v44, vcc
	v_fmac_f32_e32 v14, v86, v88
	v_cndmask_b32_e32 v88, v68, v5, vcc
	v_fmac_f32_e32 v16, v88, v14
	s_waitcnt lgkmcnt(2)
	v_cndmask_b32_e32 v71, v49, v7, vcc
	v_cndmask_b32_e32 v90, v2, v59, vcc
	v_cndmask_b32_e32 v73, v59, v2, vcc
	v_fmac_f32_e32 v71, v90, v16
	v_cndmask_b32_e32 v75, v7, v49, vcc
	v_pk_mul_f32 v[94:95], v[70:71], v[72:73]
	ds_bpermute_b32 v10, v1, v67
	s_waitcnt lgkmcnt(2)
	v_cndmask_b32_e32 v87, v8, v66, vcc
	v_pk_mul_f32 v[94:95], v[74:75], v[94:95]
	v_pk_fma_f32 v[70:71], v[70:71], v[72:73], v[74:75]
	ds_bpermute_b32 v12, v1, v84
	s_waitcnt lgkmcnt(2)
	v_cndmask_b32_e32 v89, v22, v82, vcc
	v_mov_b32_e32 v70, v94
	v_pk_mul_f32 v[74:75], v[94:95], v[86:87]
	v_pk_fma_f32 v[70:71], v[70:71], v[86:87], v[88:89]
	v_pk_mul_f32 v[74:75], v[88:89], v[74:75]
	v_cndmask_b32_e32 v91, v66, v8, vcc
	v_mov_b32_e32 v75, v71
	v_cndmask_b32_e32 v93, v82, v22, vcc
	v_mov_b32_e32 v92, v73
	v_mov_b32_e32 v72, v87
	v_pk_mul_f32 v[86:87], v[74:75], v[90:91]
	s_waitcnt lgkmcnt(1)
	v_cndmask_b32_e32 v73, v10, v67, vcc
	v_pk_mul_f32 v[86:87], v[92:93], v[86:87]
	v_pk_fma_f32 v[74:75], v[74:75], v[90:91], v[92:93]
	s_waitcnt lgkmcnt(0)
	v_cndmask_b32_e32 v71, v12, v84, vcc
	v_mov_b32_e32 v70, v91
	v_mov_b32_e32 v74, v86
	v_pk_mul_f32 v[86:87], v[86:87], v[72:73]
	v_cndmask_b32_e32 v89, v67, v10, vcc
	v_pk_mul_f32 v[86:87], v[70:71], v[86:87]
	v_pk_fma_f32 v[70:71], v[74:75], v[72:73], v[70:71]
	v_mov_b32_e32 v88, v73
	v_mov_b32_e32 v87, v71
	v_cndmask_b32_e32 v73, v84, v12, vcc
	v_mov_b32_e32 v72, v89
	v_pk_mul_f32 v[70:71], v[86:87], v[88:89]
	s_nop 0
	v_pk_mul_f32 v[70:71], v[72:73], v[70:71]
	v_pk_fma_f32 v[72:73], v[86:87], v[88:89], v[72:73]
	s_nop 0
	v_mov_b32_e32 v72, v70
	s_and_saveexec_b64 s[0:1], vcc
	s_cbranch_execz .LBB0_996
	s_and_b32 s2, s21, 0x3fffffc0
	s_lshl_b32 s2, s2, 2
	s_add_i32 s2, s2, 0
	v_lshl_add_u32 v2, v123, 3, s2
	v_add_u32_e32 v2, 0x20400, v2
	ds_write_b64 v2, v[72:73]

; #define LAS __attribute__((address_space(3)))
; template <int PASS> __device__ __forceinline__ void lru_pass(const bf16* __restrict__ Z, const bf16* __restrict__ LW, const float* __restrict__ cw_g, const float* __restrict__ cb_g, const float* __restrict__ b_a, const float* __restrict__ b_x, const float* __restrict__ lam, ...
;     ...
;             { int t_ = tid; asm volatile("" : "+v"(t_));
; #pragma unroll
;               for (int i = 0; i < 4; ++i) { const int idx = t_ + 512 * i, row = idx >> 4, c = idx & 15; *(LAS u32x4v*)(GT + row * 128 + c * 8) = *(const u32x4v*)(Z + (size_t)(tok0 + row) * NZ + Z_CG + blk * 128 + c * 8); } }
.LBB0_1585:
	s_ashr_i32 s27, s35, 3
	v_mov_b32_e32 v10, v66
	s_lshl_b32 s26, s27, 7
	s_lshl_b32 s2, s35, 7
	s_waitcnt vmcnt(0) lgkmcnt(0)
	s_barrier
	s_and_b32 s36, s2, 0x380
	v_ashrrev_i32_e32 v12, 4, v10
	v_add_u32_e32 v214, s26, v12
	v_mov_b64_e32 v[8:9], s[4:5]
	v_lshlrev_b32_e32 v2, 4, v10
	v_mad_i64_i32 v[214:215], s[30:31], v214, s25, v[8:9]
	s_lshl_b32 s2, s36, 1
	v_and_b32_e32 v2, 0xf0, v2
	v_lshl_add_u64 v[214:215], v[214:215], 0, s[2:3]
	v_lshl_add_u64 v[214:215], v[214:215], 0, v[2:3]
	s_movk_i32 s37, 0x3000
	v_add_co_u32_e32 v214, vcc, s37, v214
	v_add_u32_e32 v11, s51, v2
	s_nop 0
	v_addc_co_u32_e32 v215, vcc, 0, v215, vcc
	global_load_dwordx4 v[214:217], v[214:215], off
	v_lshl_add_u32 v230, v12, 8, v11
	v_add_u32_e32 v48, s26, v68
	v_ashrrev_i32_e32 v49, 31, v48
	v_or_b32_e32 v127, s36, v67
	s_cmp_lt_i32 s27, 1
	v_add_u32_e32 v218, 0x200, v10
	v_ashrrev_i32_e32 v12, 4, v218
	v_add_u32_e32 v218, s26, v12
	v_mad_i64_i32 v[218:219], s[30:31], v218, s25, v[8:9]
	v_lshl_add_u64 v[218:219], v[218:219], 0, s[2:3]
	v_lshl_add_u64 v[218:219], v[218:219], 0, v[2:3]
	v_add_co_u32_e32 v218, vcc, s37, v218
	v_lshl_add_u32 v231, v12, 8, v11
	s_nop 0
	v_addc_co_u32_e32 v219, vcc, 0, v219, vcc
	global_load_dwordx4 v[218:221], v[218:219], off
	v_add_u32_e32 v222, 0x400, v10
	v_ashrrev_i32_e32 v12, 4, v222
	v_add_u32_e32 v222, s26, v12
	v_mad_i64_i32 v[222:223], s[30:31], v222, s25, v[8:9]
	v_lshl_add_u64 v[222:223], v[222:223], 0, s[2:3]
	v_lshl_add_u64 v[222:223], v[222:223], 0, v[2:3]
	v_add_co_u32_e32 v222, vcc, s37, v222
	v_lshl_add_u32 v232, v12, 8, v11
	s_nop 0
	v_addc_co_u32_e32 v223, vcc, 0, v223, vcc
	global_load_dwordx4 v[222:225], v[222:223], off
	v_add_u32_e32 v226, 0x600, v10
	v_ashrrev_i32_e32 v10, 4, v226
	v_add_u32_e32 v226, s26, v10
	v_mad_i64_i32 v[226:227], s[30:31], v226, s25, v[8:9]
	v_lshl_add_u64 v[226:227], v[226:227], 0, s[2:3]
	v_lshl_add_u64 v[226:227], v[226:227], 0, v[2:3]
	v_add_co_u32_e32 v226, vcc, s37, v226
	v_lshl_add_u32 v233, v10, 8, v11
	s_nop 0
	v_addc_co_u32_e32 v227, vcc, 0, v227, vcc
	global_load_dwordx4 v[226:229], v[226:227], off
	s_mov_b32 s2, 0x9000
	s_waitcnt vmcnt(0)
; #define LAS __attribute__((address_space(3)))
; template <int PASS> __device__ __forceinline__ void lru_pass(const bf16* __restrict__ Z, const bf16* __restrict__ LW, const float* __restrict__ cw_g, const float* __restrict__ cb_g, const float* __restrict__ b_a, const float* __restrict__ b_x, const float* __restrict__ lam, ...
;     ...
;               for (int i = 0; i < 4; ++i) { const int idx = t_ + 512 * i, row = idx >> 4, c = idx & 15; *(LAS u32x4v*)(GT + row * 128 + c * 8) = *(const u32x4v*)(Z + (size_t)(tok0 + row) * NZ + Z_CG + blk * 128 + c * 8); } }
;             const float* pa = LA + (size_t)(tok0 + 64 * th + 4 * hh) * 1024 + d; const float* pu = LU + (size_t)(tok0 + 64 * th + 4 * hh) * 1024 + d;
; #pragma unroll
;             for (int tt = 0; tt < 2; ++tt)
; #pragma unroll
;                 for (int i = 0; i < 16; ++i) { av[tt][i] = pa[(32 * tt + 8 * (i >> 2) + (i & 3)) * 1024]; uv[tt][i] = pu[(32 * tt + 8 * (i >> 2) + (i & 3)) * 1024]; }
;             for (int q0 = 0; q0 < R; q0 += 8) { float2 cc[8];
; #pragma unroll
;                 for (int j = 0; j < 8; ++j) cc[j] = (q0 + j < R) ? CARRY[(size_t)(q0 + j) * 1024 + d] : make_float2(1.f, 0.f);
	ds_write_b128 v230, v[214:217]
	ds_write_b128 v231, v[218:221]
	ds_write_b128 v232, v[222:225]
	ds_write_b128 v233, v[226:229]
	v_lshlrev_b64 v[4:5], 12, v[48:49]
	v_lshl_add_u64 v[6:7], s[8:9], 0, v[4:5]
	v_lshlrev_b32_e32 v2, 2, v127
	v_lshl_add_u64 v[8:9], v[6:7], 0, v[2:3]
	v_lshl_add_u64 v[4:5], s[10:11], 0, v[4:5]
	v_add_co_u32_e32 v6, vcc, s88, v8
	v_lshl_add_u64 v[4:5], v[4:5], 0, v[2:3]
	s_nop 0
	v_addc_co_u32_e32 v7, vcc, 0, v9, vcc
	v_add_co_u32_e32 v10, vcc, s88, v4
	global_load_dword v126, v[8:9], off
	global_load_dword v124, v[4:5], off
	v_addc_co_u32_e32 v11, vcc, 0, v5, vcc
	global_load_dword v125, v[6:7], off offset:-4096
	global_load_dword v123, v[10:11], off offset:-4096
	global_load_dword v26, v[6:7], off
	global_load_dword v122, v[10:11], off
	v_add_co_u32_e32 v6, vcc, s37, v8
	s_nop 1
	v_addc_co_u32_e32 v7, vcc, 0, v9, vcc
	global_load_dword v24, v[6:7], off
	v_add_co_u32_e32 v6, vcc, s37, v4
	s_nop 1
	v_addc_co_u32_e32 v7, vcc, 0, v5, vcc
	global_load_dword v118, v[6:7], off
	v_add_co_u32_e32 v6, vcc, s2, v8
	s_nop 1
	v_addc_co_u32_e32 v7, vcc, 0, v9, vcc
	v_add_co_u32_e32 v10, vcc, s2, v4
	s_mov_b32 s2, 0xb000
	s_nop 0
	v_addc_co_u32_e32 v11, vcc, 0, v5, vcc
	global_load_dword v119, v[6:7], off offset:-4096
	global_load_dword v120, v[10:11], off offset:-4096
	global_load_dword v121, v[6:7], off
	global_load_dword v116, v[10:11], off
	v_add_co_u32_e32 v6, vcc, s2, v8
	s_nop 1
	v_addc_co_u32_e32 v7, vcc, 0, v9, vcc
	v_add_co_u32_e32 v10, vcc, s2, v4
	s_mov_b32 s2, 0x11000
	s_nop 0
	v_addc_co_u32_e32 v11, vcc, 0, v5, vcc
	global_load_dword v117, v[6:7], off offset:-4096
	global_load_dword v114, v[10:11], off offset:-4096
	global_load_dword v115, v[6:7], off
	global_load_dword v112, v[10:11], off
	v_add_co_u32_e32 v6, vcc, s2, v8
	s_nop 1
	v_addc_co_u32_e32 v7, vcc, 0, v9, vcc
	v_add_co_u32_e32 v10, vcc, s2, v4
	s_mov_b32 s2, 0x13000
	s_nop 0
	v_addc_co_u32_e32 v11, vcc, 0, v5, vcc
	global_load_dword v28, v[6:7], off offset:-4096
	global_load_dword v113, v[10:11], off offset:-4096
	global_load_dword v22, v[6:7], off
	global_load_dword v111, v[10:11], off
	v_add_co_u32_e32 v6, vcc, s2, v8
	s_nop 1
	v_addc_co_u32_e32 v7, vcc, 0, v9, vcc
	v_add_co_u32_e32 v10, vcc, s2, v4
	s_mov_b32 s2, 0x19000
	s_nop 0
	v_addc_co_u32_e32 v11, vcc, 0, v5, vcc
	global_load_dword v20, v[6:7], off offset:-4096
	global_load_dword v110, v[10:11], off offset:-4096
	global_load_dword v18, v[6:7], off
	global_load_dword v108, v[10:11], off
	v_add_co_u32_e32 v6, vcc, s2, v8
	s_nop 1
	v_addc_co_u32_e32 v7, vcc, 0, v9, vcc
	v_add_co_u32_e32 v10, vcc, s2, v4
	s_mov_b32 s2, 0x1b000
	s_nop 0
	v_addc_co_u32_e32 v11, vcc, 0, v5, vcc
	global_load_dword v109, v[6:7], off offset:-4096
	global_load_dword v106, v[10:11], off offset:-4096
	global_load_dword v107, v[6:7], off
	global_load_dword v104, v[10:11], off
	v_add_co_u32_e32 v6, vcc, s2, v8
	s_nop 1
	v_addc_co_u32_e32 v7, vcc, 0, v9, vcc
	v_add_co_u32_e32 v10, vcc, s2, v4
	s_mov_b32 s2, 0x21000
	s_nop 0
	v_addc_co_u32_e32 v11, vcc, 0, v5, vcc
	global_load_dword v105, v[6:7], off offset:-4096
	global_load_dword v102, v[10:11], off offset:-4096
	global_load_dword v103, v[6:7], off
	global_load_dword v101, v[10:11], off
	v_add_co_u32_e32 v6, vcc, s2, v8
	s_nop 1
	v_addc_co_u32_e32 v7, vcc, 0, v9, vcc
	v_add_co_u32_e32 v10, vcc, s2, v4
	s_mov_b32 s2, 0x23000
	s_nop 0
	v_addc_co_u32_e32 v11, vcc, 0, v5, vcc
	global_load_dword v32, v[6:7], off offset:-4096
	global_load_dword v100, v[10:11], off offset:-4096
	global_load_dword v30, v[6:7], off
	global_load_dword v99, v[10:11], off
	v_add_co_u32_e32 v6, vcc, s2, v8
	s_nop 1
	v_addc_co_u32_e32 v7, vcc, 0, v9, vcc
	v_add_co_u32_e32 v10, vcc, s2, v4
	s_mov_b32 s2, 0x29000
	s_nop 0
	v_addc_co_u32_e32 v11, vcc, 0, v5, vcc
	global_load_dword v12, v[6:7], off offset:-4096
	global_load_dword v98, v[10:11], off offset:-4096
	global_load_dword v27, v[6:7], off
	global_load_dword v25, v[10:11], off
	v_add_co_u32_e32 v6, vcc, s2, v8
	s_nop 1
	v_addc_co_u32_e32 v7, vcc, 0, v9, vcc
	v_add_co_u32_e32 v10, vcc, s2, v4
	s_mov_b32 s2, 0x2b000
	s_nop 0
	v_addc_co_u32_e32 v11, vcc, 0, v5, vcc
	global_load_dword v29, v[6:7], off offset:-4096
	global_load_dword v97, v[10:11], off offset:-4096
	global_load_dword v23, v[6:7], off
	global_load_dword v96, v[10:11], off
	v_add_co_u32_e32 v6, vcc, s2, v8
	s_nop 1
	v_addc_co_u32_e32 v7, vcc, 0, v9, vcc
	v_add_co_u32_e32 v10, vcc, s2, v4
	s_mov_b32 s2, 0x31000
	s_nop 0
	v_addc_co_u32_e32 v11, vcc, 0, v5, vcc
	global_load_dword v21, v[6:7], off offset:-4096
	global_load_dword v95, v[10:11], off offset:-4096
	global_load_dword v19, v[6:7], off
	global_load_dword v94, v[10:11], off
	v_add_co_u32_e32 v6, vcc, s2, v8
	s_nop 1
	v_addc_co_u32_e32 v7, vcc, 0, v9, vcc
	v_add_co_u32_e32 v10, vcc, s2, v4
	s_mov_b32 s2, 0x33000
	s_nop 0
	v_addc_co_u32_e32 v11, vcc, 0, v5, vcc
	global_load_dword v14, v[6:7], off offset:-4096
	global_load_dword v93, v[10:11], off offset:-4096
	s_nop 0
	global_load_dword v6, v[6:7], off
	s_nop 0
	global_load_dword v92, v[10:11], off
	v_add_co_u32_e32 v10, vcc, s2, v8
	s_nop 1
	v_addc_co_u32_e32 v11, vcc, 0, v9, vcc
	v_add_co_u32_e32 v34, vcc, s2, v4
	s_mov_b32 s2, 0x39000
	s_nop 0
	v_addc_co_u32_e32 v35, vcc, 0, v5, vcc
	global_load_dword v13, v[10:11], off offset:-4096
	global_load_dword v91, v[34:35], off offset:-4096
	global_load_dword v17, v[10:11], off
	global_load_dword v90, v[34:35], off
	v_add_co_u32_e32 v10, vcc, s2, v8
	s_nop 1
	v_addc_co_u32_e32 v11, vcc, 0, v9, vcc
	v_add_co_u32_e32 v34, vcc, s2, v4
	s_mov_b32 s2, 0x3a000
	s_nop 0
	v_addc_co_u32_e32 v35, vcc, 0, v5, vcc
	global_load_dword v15, v[10:11], off offset:-4096
	global_load_dword v89, v[34:35], off offset:-4096
	global_load_dword v7, v[10:11], off
	global_load_dword v88, v[34:35], off
	v_add_co_u32_e32 v10, vcc, s2, v8
	s_nop 1
	v_addc_co_u32_e32 v11, vcc, 0, v9, vcc
	v_add_co_u32_e32 v34, vcc, 0x3a000, v4
	global_load_dword v11, v[10:11], off
	s_nop 0
	v_addc_co_u32_e32 v35, vcc, 0, v5, vcc
	v_add_co_u32_e32 v8, vcc, 0x3b000, v8
	global_load_dword v87, v[34:35], off
	s_nop 0
	v_addc_co_u32_e32 v9, vcc, 0, v9, vcc
	v_add_co_u32_e32 v4, vcc, 0x3b000, v4
	global_load_dword v9, v[8:9], off
	s_nop 0
	v_addc_co_u32_e32 v5, vcc, 0, v5, vcc
	global_load_dword v86, v[4:5], off
	s_cbranch_scc1 .LBB0_1602
	s_lshl_b32 s2, s34, 3
	s_and_b32 s2, s2, 0x1c00
	v_lshl_or_b32 v2, v67, 3, s2
	v_lshl_add_u64 v[4:5], s[28:29], 0, v[2:3]
	s_mov_b32 s2, 0
	v_mov_b32_e32 v128, 0
	s_branch .LBB0_1588

; __device__ __forceinline__ void ml_scan(const float* __restrict__ LST, const float* __restrict__ NL, const float2* __restrict__ BG, bf16* __restrict__ CST, float* __restrict__ NST, float* __restrict__ MST) {
;     int tid_ = threadIdx.x; asm volatile("" : "+v"(tid_));
;     const int lane = tid_ & 63, wave = __builtin_amdgcn_readfirstlane(tid_ >> 6), gw = blockIdx.x * 8 + wave, nw = gridDim.x * 8;
;     for (int u = gw; u < 2048; u += nw) {
;         const int h = u >> 9; const size_t e = ((size_t)u * 64 + lane) * 2;
;         const size_t eh = e - (size_t)h * 65536;
;         float c0 = 0.f, c1 = 0.f, m = 0.f;
;         const bool do_n = (u & 511) < 4;  const int nk = (u & 511) * 64 + lane;
;         float nv = 0.f;
;         unsigned lv[2][8]; float2 bg[2][8]; float nl[2][8];
.LBB0_1743:
	s_mov_b64 s[0:1], s[70:71]
	v_mov_b32_e32 v1, v0
	s_waitcnt lgkmcnt(0)
	s_barrier
	v_readlane_b32 s8, v250, 10
	v_readfirstlane_b32 s4, v1
	s_ashr_i32 s2, s4, 6
	v_readlane_b32 s9, v250, 11
	s_add_i32 s6, s2, s77
	s_load_dword s2, s[8:9], 0x0
	s_cmpk_gt_i32 s6, 0x7ff
	s_cbranch_scc1 .LBB0_1860
	s_load_dwordx2 s[8:9], s[0:1], 0xd8
	v_and_b32_e32 v2, 63, v1
	s_lshr_b32 s34, s6, 9
	s_and_b32 s35, s6, 0x1ff
	s_lshl_b32 s36, s6, 8
	v_lshl_add_u32 v4, v2, 2, s36
	v_lshlrev_b32_e32 v72, 3, v2
	s_lshl_b32 s37, s34, 9
	s_waitcnt lgkmcnt(0)
	s_add_u32 s40, s8, 0x61c00000
	s_addc_u32 s41, s9, 0
	s_add_u32 s40, s40, s37
	s_addc_u32 s41, s41, 0
	s_add_u32 s10, s8, 0x5ba00000
	s_addc_u32 s11, s9, 0
	s_add_u32 s12, s8, 0x5fa00000
	s_addc_u32 s13, s9, 0
	global_load_dwordx2 v[76:77], v72, s[40:41]
	global_load_dword v6, v4, s[10:11]
	s_add_u32 s10, s10, 0x80000
	s_addc_u32 s11, s11, 0
	global_load_dword v7, v4, s[10:11]
	s_add_u32 s10, s10, 0x80000
	s_addc_u32 s11, s11, 0
	global_load_dword v8, v4, s[10:11]
	s_add_u32 s10, s10, 0x80000
	s_addc_u32 s11, s11, 0
	global_load_dword v9, v4, s[10:11]
	s_add_u32 s10, s10, 0x80000
	s_addc_u32 s11, s11, 0
	global_load_dword v10, v4, s[10:11]
	s_add_u32 s10, s10, 0x80000
	s_addc_u32 s11, s11, 0
	global_load_dword v11, v4, s[10:11]
	s_add_u32 s10, s10, 0x80000
	s_addc_u32 s11, s11, 0
	global_load_dword v12, v4, s[10:11]
	s_add_u32 s10, s10, 0x80000
	s_addc_u32 s11, s11, 0
	global_load_dword v13, v4, s[10:11]
	s_add_u32 s10, s10, 0x80000
	s_addc_u32 s11, s11, 0
	global_load_dword v14, v4, s[10:11]
	s_add_u32 s10, s10, 0x80000
	s_addc_u32 s11, s11, 0
	global_load_dword v15, v4, s[10:11]
	s_add_u32 s10, s10, 0x80000
	s_addc_u32 s11, s11, 0
	global_load_dword v16, v4, s[10:11]
	s_add_u32 s10, s10, 0x80000
	s_addc_u32 s11, s11, 0
	global_load_dword v17, v4, s[10:11]
	s_add_u32 s10, s10, 0x80000
	s_addc_u32 s11, s11, 0
	global_load_dword v18, v4, s[10:11]
	s_add_u32 s10, s10, 0x80000
	s_addc_u32 s11, s11, 0
	global_load_dword v19, v4, s[10:11]
	s_add_u32 s10, s10, 0x80000
	s_addc_u32 s11, s11, 0
	global_load_dword v20, v4, s[10:11]
	s_add_u32 s10, s10, 0x80000
	s_addc_u32 s11, s11, 0
	global_load_dword v21, v4, s[10:11]
	s_add_u32 s10, s10, 0x80000
	s_addc_u32 s11, s11, 0
	global_load_dword v22, v4, s[10:11]
	s_add_u32 s10, s10, 0x80000
	s_addc_u32 s11, s11, 0
	global_load_dword v23, v4, s[10:11]
	s_add_u32 s10, s10, 0x80000
	s_addc_u32 s11, s11, 0
	global_load_dword v24, v4, s[10:11]
	s_add_u32 s10, s10, 0x80000
	s_addc_u32 s11, s11, 0
	global_load_dword v25, v4, s[10:11]
	s_add_u32 s10, s10, 0x80000
	s_addc_u32 s11, s11, 0
	global_load_dword v26, v4, s[10:11]
	s_add_u32 s10, s10, 0x80000
	s_addc_u32 s11, s11, 0
	global_load_dword v27, v4, s[10:11]
	s_add_u32 s10, s10, 0x80000
	s_addc_u32 s11, s11, 0
	global_load_dword v28, v4, s[10:11]
	s_add_u32 s10, s10, 0x80000
	s_addc_u32 s11, s11, 0
	global_load_dword v29, v4, s[10:11]
	s_add_u32 s10, s10, 0x80000
	s_addc_u32 s11, s11, 0
	global_load_dword v30, v4, s[10:11]
	s_add_u32 s10, s10, 0x80000
	s_addc_u32 s11, s11, 0
	global_load_dword v31, v4, s[10:11]
	s_add_u32 s10, s10, 0x80000
	s_addc_u32 s11, s11, 0
	global_load_dword v32, v4, s[10:11]
	s_add_u32 s10, s10, 0x80000
	s_addc_u32 s11, s11, 0
	global_load_dword v33, v4, s[10:11]
	s_add_u32 s10, s10, 0x80000
	s_addc_u32 s11, s11, 0
	global_load_dword v34, v4, s[10:11]
	s_add_u32 s10, s10, 0x80000
	s_addc_u32 s11, s11, 0
	global_load_dword v35, v4, s[10:11]
	s_add_u32 s10, s10, 0x80000
	s_addc_u32 s11, s11, 0
	global_load_dword v36, v4, s[10:11]
	s_add_u32 s10, s10, 0x80000
	s_addc_u32 s11, s11, 0
	global_load_dword v37, v4, s[10:11]
	s_add_u32 s10, s10, 0x80000
	s_addc_u32 s11, s11, 0
	global_load_dword v38, v4, s[10:11]
	s_add_u32 s10, s10, 0x80000
	s_addc_u32 s11, s11, 0
	global_load_dword v39, v4, s[10:11]
	s_add_u32 s10, s10, 0x80000
	s_addc_u32 s11, s11, 0
	global_load_dword v40, v4, s[10:11]
	s_add_u32 s10, s10, 0x80000
	s_addc_u32 s11, s11, 0
	global_load_dword v41, v4, s[10:11]
	s_add_u32 s10, s10, 0x80000
	s_addc_u32 s11, s11, 0
	global_load_dword v42, v4, s[10:11]
	s_add_u32 s10, s10, 0x80000
	s_addc_u32 s11, s11, 0
	global_load_dword v43, v4, s[10:11]
	s_add_u32 s10, s10, 0x80000
	s_addc_u32 s11, s11, 0
	global_load_dword v44, v4, s[10:11]
	s_add_u32 s10, s10, 0x80000
	s_addc_u32 s11, s11, 0
	global_load_dword v45, v4, s[10:11]
	s_add_u32 s10, s10, 0x80000
	s_addc_u32 s11, s11, 0
	global_load_dword v46, v4, s[10:11]
	s_add_u32 s10, s10, 0x80000
	s_addc_u32 s11, s11, 0
	global_load_dword v47, v4, s[10:11]
	s_add_u32 s10, s10, 0x80000
	s_addc_u32 s11, s11, 0
	global_load_dword v48, v4, s[10:11]
	s_add_u32 s10, s10, 0x80000
	s_addc_u32 s11, s11, 0
	global_load_dword v49, v4, s[10:11]
	s_add_u32 s10, s10, 0x80000
	s_addc_u32 s11, s11, 0
	global_load_dword v50, v4, s[10:11]
	s_add_u32 s10, s10, 0x80000
	s_addc_u32 s11, s11, 0
	global_load_dword v51, v4, s[10:11]
	s_add_u32 s10, s10, 0x80000
	s_addc_u32 s11, s11, 0
	global_load_dword v52, v4, s[10:11]
	s_add_u32 s10, s10, 0x80000
	s_addc_u32 s11, s11, 0
	global_load_dword v53, v4, s[10:11]
	s_add_u32 s10, s10, 0x80000
	s_addc_u32 s11, s11, 0
	global_load_dword v54, v4, s[10:11]
	s_add_u32 s10, s10, 0x80000
	s_addc_u32 s11, s11, 0
	global_load_dword v55, v4, s[10:11]
	s_add_u32 s10, s10, 0x80000
	s_addc_u32 s11, s11, 0
	global_load_dword v56, v4, s[10:11]
	s_add_u32 s10, s10, 0x80000
	s_addc_u32 s11, s11, 0
	global_load_dword v57, v4, s[10:11]
	s_add_u32 s10, s10, 0x80000
	s_addc_u32 s11, s11, 0
	global_load_dword v58, v4, s[10:11]
	s_add_u32 s10, s10, 0x80000
	s_addc_u32 s11, s11, 0
	global_load_dword v59, v4, s[10:11]
	s_add_u32 s10, s10, 0x80000
	s_addc_u32 s11, s11, 0
	global_load_dword v60, v4, s[10:11]
	s_add_u32 s10, s10, 0x80000
	s_addc_u32 s11, s11, 0
	global_load_dword v61, v4, s[10:11]
	s_add_u32 s10, s10, 0x80000
	s_addc_u32 s11, s11, 0
	global_load_dword v62, v4, s[10:11]
	s_add_u32 s10, s10, 0x80000
	s_addc_u32 s11, s11, 0
	global_load_dword v63, v4, s[10:11]
	s_add_u32 s10, s10, 0x80000
	s_addc_u32 s11, s11, 0
	global_load_dword v64, v4, s[10:11]
	s_add_u32 s10, s10, 0x80000
	s_addc_u32 s11, s11, 0
	global_load_dword v65, v4, s[10:11]
	s_add_u32 s10, s10, 0x80000
	s_addc_u32 s11, s11, 0
	v_mov_b32_e32 v83, 0
	v_mov_b32_e32 v84, 0
	v_mov_b32_e32 v78, 0
	v_mov_b32_e32 v79, 0
	v_mov_b32_e32 v80, 0
	v_mov_b32_e32 v74, 0
	s_mov_b64 s[38:39], 1
	s_waitcnt vmcnt(60)
	v_readlane_b32 s42, v76, 0
	v_readlane_b32 s43, v77, 0
	v_readlane_b32 s44, v76, 1
	v_readlane_b32 s45, v77, 1
	v_readlane_b32 s46, v76, 2
	v_readlane_b32 s47, v77, 2
	v_readlane_b32 s48, v76, 3
	v_readlane_b32 s49, v77, 3
	v_readlane_b32 s50, v76, 4
	v_readlane_b32 s51, v77, 4
	v_readlane_b32 s52, v76, 5
	v_readlane_b32 s53, v77, 5
	v_readlane_b32 s54, v76, 6
	v_readlane_b32 s55, v77, 6
	v_readlane_b32 s56, v76, 7
	v_readlane_b32 s57, v77, 7
	v_add_f32_e32 v72, s42, v74
	v_cndmask_b32_e64 v80, v80, v74, s[38:39]
	v_max_f32_e32 v86, s43, v72
	v_cndmask_b32_e64 v78, v78, v72, s[38:39]
	v_cndmask_b32_e64 v79, v79, v86, s[38:39]
	s_lshl_b64 s[38:39], s[38:39], 1
	v_add_f32_e32 v72, s44, v86
	v_cndmask_b32_e64 v80, v80, v86, s[38:39]
	v_max_f32_e32 v74, s45, v72
	v_cndmask_b32_e64 v78, v78, v72, s[38:39]
	v_cndmask_b32_e64 v79, v79, v74, s[38:39]
	s_lshl_b64 s[38:39], s[38:39], 1
	v_add_f32_e32 v72, s46, v74
	v_cndmask_b32_e64 v80, v80, v74, s[38:39]
	v_max_f32_e32 v86, s47, v72
	v_cndmask_b32_e64 v78, v78, v72, s[38:39]
	v_cndmask_b32_e64 v79, v79, v86, s[38:39]
	s_lshl_b64 s[38:39], s[38:39], 1
	v_add_f32_e32 v72, s48, v86
	v_cndmask_b32_e64 v80, v80, v86, s[38:39]
	v_max_f32_e32 v74, s49, v72
	v_cndmask_b32_e64 v78, v78, v72, s[38:39]
	v_cndmask_b32_e64 v79, v79, v74, s[38:39]
	s_lshl_b64 s[38:39], s[38:39], 1
	v_add_f32_e32 v72, s50, v74
	v_cndmask_b32_e64 v80, v80, v74, s[38:39]
	v_max_f32_e32 v86, s51, v72
	v_cndmask_b32_e64 v78, v78, v72, s[38:39]
	v_cndmask_b32_e64 v79, v79, v86, s[38:39]
	s_lshl_b64 s[38:39], s[38:39], 1
	v_add_f32_e32 v72, s52, v86
	v_cndmask_b32_e64 v80, v80, v86, s[38:39]
	v_max_f32_e32 v74, s53, v72
	v_cndmask_b32_e64 v78, v78, v72, s[38:39]
	v_cndmask_b32_e64 v79, v79, v74, s[38:39]
	s_lshl_b64 s[38:39], s[38:39], 1
	v_add_f32_e32 v72, s54, v74
	v_cndmask_b32_e64 v80, v80, v74, s[38:39]
	v_max_f32_e32 v86, s55, v72
	v_cndmask_b32_e64 v78, v78, v72, s[38:39]
	v_cndmask_b32_e64 v79, v79, v86, s[38:39]
	s_lshl_b64 s[38:39], s[38:39], 1
	v_add_f32_e32 v72, s56, v86
	v_cndmask_b32_e64 v80, v80, v86, s[38:39]
	v_max_f32_e32 v74, s57, v72
	v_cndmask_b32_e64 v78, v78, v72, s[38:39]
	v_cndmask_b32_e64 v79, v79, v74, s[38:39]
	s_lshl_b64 s[38:39], s[38:39], 1
	v_readlane_b32 s42, v76, 8
	v_readlane_b32 s43, v77, 8
	v_readlane_b32 s44, v76, 9
	v_readlane_b32 s45, v77, 9
	v_readlane_b32 s46, v76, 10
	v_readlane_b32 s47, v77, 10
	v_readlane_b32 s48, v76, 11
	v_readlane_b32 s49, v77, 11
	v_readlane_b32 s50, v76, 12
	v_readlane_b32 s51, v77, 12
	v_readlane_b32 s52, v76, 13
	v_readlane_b32 s53, v77, 13
	v_readlane_b32 s54, v76, 14
	v_readlane_b32 s55, v77, 14
	v_readlane_b32 s56, v76, 15
	v_readlane_b32 s57, v77, 15
	v_add_f32_e32 v72, s42, v74
	v_cndmask_b32_e64 v80, v80, v74, s[38:39]
	v_max_f32_e32 v86, s43, v72
	v_cndmask_b32_e64 v78, v78, v72, s[38:39]
	v_cndmask_b32_e64 v79, v79, v86, s[38:39]
	s_lshl_b64 s[38:39], s[38:39], 1
	v_add_f32_e32 v72, s44, v86
	v_cndmask_b32_e64 v80, v80, v86, s[38:39]
	v_max_f32_e32 v74, s45, v72
	v_cndmask_b32_e64 v78, v78, v72, s[38:39]
	v_cndmask_b32_e64 v79, v79, v74, s[38:39]
	s_lshl_b64 s[38:39], s[38:39], 1
	v_add_f32_e32 v72, s46, v74
	v_cndmask_b32_e64 v80, v80, v74, s[38:39]
	v_max_f32_e32 v86, s47, v72
	v_cndmask_b32_e64 v78, v78, v72, s[38:39]
	v_cndmask_b32_e64 v79, v79, v86, s[38:39]
	s_lshl_b64 s[38:39], s[38:39], 1
	v_add_f32_e32 v72, s48, v86
	v_cndmask_b32_e64 v80, v80, v86, s[38:39]
	v_max_f32_e32 v74, s49, v72
	v_cndmask_b32_e64 v78, v78, v72, s[38:39]
	v_cndmask_b32_e64 v79, v79, v74, s[38:39]
	s_lshl_b64 s[38:39], s[38:39], 1
	v_add_f32_e32 v72, s50, v74
	v_cndmask_b32_e64 v80, v80, v74, s[38:39]
	v_max_f32_e32 v86, s51, v72
	v_cndmask_b32_e64 v78, v78, v72, s[38:39]
	v_cndmask_b32_e64 v79, v79, v86, s[38:39]
	s_lshl_b64 s[38:39], s[38:39], 1
	v_add_f32_e32 v72, s52, v86
	v_cndmask_b32_e64 v80, v80, v86, s[38:39]
	v_max_f32_e32 v74, s53, v72
	v_cndmask_b32_e64 v78, v78, v72, s[38:39]
	v_cndmask_b32_e64 v79, v79, v74, s[38:39]
	s_lshl_b64 s[38:39], s[38:39], 1
	v_add_f32_e32 v72, s54, v74
	v_cndmask_b32_e64 v80, v80, v74, s[38:39]
	v_max_f32_e32 v86, s55, v72
	v_cndmask_b32_e64 v78, v78, v72, s[38:39]
	v_cndmask_b32_e64 v79, v79, v86, s[38:39]
	s_lshl_b64 s[38:39], s[38:39], 1
	v_add_f32_e32 v72, s56, v86
	v_cndmask_b32_e64 v80, v80, v86, s[38:39]
	v_max_f32_e32 v74, s57, v72
	v_cndmask_b32_e64 v78, v78, v72, s[38:39]
	v_cndmask_b32_e64 v79, v79, v74, s[38:39]
	s_lshl_b64 s[38:39], s[38:39], 1
	v_readlane_b32 s42, v76, 16
	v_readlane_b32 s43, v77, 16
	v_readlane_b32 s44, v76, 17
	v_readlane_b32 s45, v77, 17
	v_readlane_b32 s46, v76, 18
	v_readlane_b32 s47, v77, 18
	v_readlane_b32 s48, v76, 19
	v_readlane_b32 s49, v77, 19
	v_readlane_b32 s50, v76, 20
	v_readlane_b32 s51, v77, 20
	v_readlane_b32 s52, v76, 21
	v_readlane_b32 s53, v77, 21
	v_readlane_b32 s54, v76, 22
	v_readlane_b32 s55, v77, 22
	v_readlane_b32 s56, v76, 23
	v_readlane_b32 s57, v77, 23
	v_add_f32_e32 v72, s42, v74
	v_cndmask_b32_e64 v80, v80, v74, s[38:39]
	v_max_f32_e32 v86, s43, v72
	v_cndmask_b32_e64 v78, v78, v72, s[38:39]
	v_cndmask_b32_e64 v79, v79, v86, s[38:39]
	s_lshl_b64 s[38:39], s[38:39], 1
	v_add_f32_e32 v72, s44, v86
	v_cndmask_b32_e64 v80, v80, v86, s[38:39]
	v_max_f32_e32 v74, s45, v72
	v_cndmask_b32_e64 v78, v78, v72, s[38:39]
	v_cndmask_b32_e64 v79, v79, v74, s[38:39]
	s_lshl_b64 s[38:39], s[38:39], 1
	v_add_f32_e32 v72, s46, v74
	v_cndmask_b32_e64 v80, v80, v74, s[38:39]
	v_max_f32_e32 v86, s47, v72
	v_cndmask_b32_e64 v78, v78, v72, s[38:39]
	v_cndmask_b32_e64 v79, v79, v86, s[38:39]
	s_lshl_b64 s[38:39], s[38:39], 1
	v_add_f32_e32 v72, s48, v86
	v_cndmask_b32_e64 v80, v80, v86, s[38:39]
	v_max_f32_e32 v74, s49, v72
	v_cndmask_b32_e64 v78, v78, v72, s[38:39]
	v_cndmask_b32_e64 v79, v79, v74, s[38:39]
	s_lshl_b64 s[38:39], s[38:39], 1
	v_add_f32_e32 v72, s50, v74
	v_cndmask_b32_e64 v80, v80, v74, s[38:39]
	v_max_f32_e32 v86, s51, v72
	v_cndmask_b32_e64 v78, v78, v72, s[38:39]
	v_cndmask_b32_e64 v79, v79, v86, s[38:39]
	s_lshl_b64 s[38:39], s[38:39], 1
	v_add_f32_e32 v72, s52, v86
	v_cndmask_b32_e64 v80, v80, v86, s[38:39]
	v_max_f32_e32 v74, s53, v72
	v_cndmask_b32_e64 v78, v78, v72, s[38:39]
	v_cndmask_b32_e64 v79, v79, v74, s[38:39]
	s_lshl_b64 s[38:39], s[38:39], 1
	v_add_f32_e32 v72, s54, v74
	v_cndmask_b32_e64 v80, v80, v74, s[38:39]
	v_max_f32_e32 v86, s55, v72
	v_cndmask_b32_e64 v78, v78, v72, s[38:39]
	v_cndmask_b32_e64 v79, v79, v86, s[38:39]
	s_lshl_b64 s[38:39], s[38:39], 1
	v_add_f32_e32 v72, s56, v86
	v_cndmask_b32_e64 v80, v80, v86, s[38:39]
	v_max_f32_e32 v74, s57, v72
	v_cndmask_b32_e64 v78, v78, v72, s[38:39]
	v_cndmask_b32_e64 v79, v79, v74, s[38:39]
	s_lshl_b64 s[38:39], s[38:39], 1
	v_readlane_b32 s42, v76, 24
	v_readlane_b32 s43, v77, 24
	v_readlane_b32 s44, v76, 25
	v_readlane_b32 s45, v77, 25
	v_readlane_b32 s46, v76, 26
	v_readlane_b32 s47, v77, 26
	v_readlane_b32 s48, v76, 27
	v_readlane_b32 s49, v77, 27
	v_readlane_b32 s50, v76, 28
	v_readlane_b32 s51, v77, 28
	v_readlane_b32 s52, v76, 29
	v_readlane_b32 s53, v77, 29
	v_readlane_b32 s54, v76, 30
	v_readlane_b32 s55, v77, 30
	v_readlane_b32 s56, v76, 31
	v_readlane_b32 s57, v77, 31
	v_add_f32_e32 v72, s42, v74
	v_cndmask_b32_e64 v80, v80, v74, s[38:39]
	v_max_f32_e32 v86, s43, v72
	v_cndmask_b32_e64 v78, v78, v72, s[38:39]
	v_cndmask_b32_e64 v79, v79, v86, s[38:39]
	s_lshl_b64 s[38:39], s[38:39], 1
	v_add_f32_e32 v72, s44, v86
	v_cndmask_b32_e64 v80, v80, v86, s[38:39]
	v_max_f32_e32 v74, s45, v72
	v_cndmask_b32_e64 v78, v78, v72, s[38:39]
	v_cndmask_b32_e64 v79, v79, v74, s[38:39]
	s_lshl_b64 s[38:39], s[38:39], 1
	v_add_f32_e32 v72, s46, v74
	v_cndmask_b32_e64 v80, v80, v74, s[38:39]
	v_max_f32_e32 v86, s47, v72
	v_cndmask_b32_e64 v78, v78, v72, s[38:39]
	v_cndmask_b32_e64 v79, v79, v86, s[38:39]
	s_lshl_b64 s[38:39], s[38:39], 1
	v_add_f32_e32 v72, s48, v86
	v_cndmask_b32_e64 v80, v80, v86, s[38:39]
	v_max_f32_e32 v74, s49, v72
	v_cndmask_b32_e64 v78, v78, v72, s[38:39]
	v_cndmask_b32_e64 v79, v79, v74, s[38:39]
	s_lshl_b64 s[38:39], s[38:39], 1
	v_add_f32_e32 v72, s50, v74
	v_cndmask_b32_e64 v80, v80, v74, s[38:39]
	v_max_f32_e32 v86, s51, v72
	v_cndmask_b32_e64 v78, v78, v72, s[38:39]
	v_cndmask_b32_e64 v79, v79, v86, s[38:39]
	s_lshl_b64 s[38:39], s[38:39], 1
	v_add_f32_e32 v72, s52, v86
	v_cndmask_b32_e64 v80, v80, v86, s[38:39]
	v_max_f32_e32 v74, s53, v72
	v_cndmask_b32_e64 v78, v78, v72, s[38:39]
	v_cndmask_b32_e64 v79, v79, v74, s[38:39]
	s_lshl_b64 s[38:39], s[38:39], 1
	v_add_f32_e32 v72, s54, v74
	v_cndmask_b32_e64 v80, v80, v74, s[38:39]
	v_max_f32_e32 v86, s55, v72
	v_cndmask_b32_e64 v78, v78, v72, s[38:39]
	v_cndmask_b32_e64 v79, v79, v86, s[38:39]
	s_lshl_b64 s[38:39], s[38:39], 1
	v_add_f32_e32 v72, s56, v86
	v_cndmask_b32_e64 v80, v80, v86, s[38:39]
	v_max_f32_e32 v74, s57, v72
	v_cndmask_b32_e64 v78, v78, v72, s[38:39]
	v_cndmask_b32_e64 v79, v79, v74, s[38:39]
	s_lshl_b64 s[38:39], s[38:39], 1
	v_readlane_b32 s42, v76, 32
	v_readlane_b32 s43, v77, 32
	v_readlane_b32 s44, v76, 33
	v_readlane_b32 s45, v77, 33
	v_readlane_b32 s46, v76, 34
	v_readlane_b32 s47, v77, 34
	v_readlane_b32 s48, v76, 35
	v_readlane_b32 s49, v77, 35
	v_readlane_b32 s50, v76, 36
	v_readlane_b32 s51, v77, 36
	v_readlane_b32 s52, v76, 37
	v_readlane_b32 s53, v77, 37
	v_readlane_b32 s54, v76, 38
	v_readlane_b32 s55, v77, 38
	v_readlane_b32 s56, v76, 39
	v_readlane_b32 s57, v77, 39
	v_add_f32_e32 v72, s42, v74
	v_cndmask_b32_e64 v80, v80, v74, s[38:39]
	v_max_f32_e32 v86, s43, v72
	v_cndmask_b32_e64 v78, v78, v72, s[38:39]
	v_cndmask_b32_e64 v79, v79, v86, s[38:39]
	s_lshl_b64 s[38:39], s[38:39], 1
	v_add_f32_e32 v72, s44, v86
	v_cndmask_b32_e64 v80, v80, v86, s[38:39]
	v_max_f32_e32 v74, s45, v72
	v_cndmask_b32_e64 v78, v78, v72, s[38:39]
	v_cndmask_b32_e64 v79, v79, v74, s[38:39]
	s_lshl_b64 s[38:39], s[38:39], 1
	v_add_f32_e32 v72, s46, v74
	v_cndmask_b32_e64 v80, v80, v74, s[38:39]
	v_max_f32_e32 v86, s47, v72
	v_cndmask_b32_e64 v78, v78, v72, s[38:39]
	v_cndmask_b32_e64 v79, v79, v86, s[38:39]
	s_lshl_b64 s[38:39], s[38:39], 1
	v_add_f32_e32 v72, s48, v86
	v_cndmask_b32_e64 v80, v80, v86, s[38:39]
	v_max_f32_e32 v74, s49, v72
	v_cndmask_b32_e64 v78, v78, v72, s[38:39]
	v_cndmask_b32_e64 v79, v79, v74, s[38:39]
	s_lshl_b64 s[38:39], s[38:39], 1
	v_add_f32_e32 v72, s50, v74
	v_cndmask_b32_e64 v80, v80, v74, s[38:39]
	v_max_f32_e32 v86, s51, v72
	v_cndmask_b32_e64 v78, v78, v72, s[38:39]
	v_cndmask_b32_e64 v79, v79, v86, s[38:39]
	s_lshl_b64 s[38:39], s[38:39], 1
	v_add_f32_e32 v72, s52, v86
	v_cndmask_b32_e64 v80, v80, v86, s[38:39]
	v_max_f32_e32 v74, s53, v72
	v_cndmask_b32_e64 v78, v78, v72, s[38:39]
	v_cndmask_b32_e64 v79, v79, v74, s[38:39]
	s_lshl_b64 s[38:39], s[38:39], 1
	v_add_f32_e32 v72, s54, v74
	v_cndmask_b32_e64 v80, v80, v74, s[38:39]
	v_max_f32_e32 v86, s55, v72
	v_cndmask_b32_e64 v78, v78, v72, s[38:39]
	v_cndmask_b32_e64 v79, v79, v86, s[38:39]
	s_lshl_b64 s[38:39], s[38:39], 1
	v_add_f32_e32 v72, s56, v86
	v_cndmask_b32_e64 v80, v80, v86, s[38:39]
	v_max_f32_e32 v74, s57, v72
	v_cndmask_b32_e64 v78, v78, v72, s[38:39]
	v_cndmask_b32_e64 v79, v79, v74, s[38:39]
	s_lshl_b64 s[38:39], s[38:39], 1
	v_readlane_b32 s42, v76, 40
	v_readlane_b32 s43, v77, 40
	v_readlane_b32 s44, v76, 41
	v_readlane_b32 s45, v77, 41
	v_readlane_b32 s46, v76, 42
	v_readlane_b32 s47, v77, 42
	v_readlane_b32 s48, v76, 43
	v_readlane_b32 s49, v77, 43
	v_readlane_b32 s50, v76, 44
	v_readlane_b32 s51, v77, 44
	v_readlane_b32 s52, v76, 45
	v_readlane_b32 s53, v77, 45
	v_readlane_b32 s54, v76, 46
	v_readlane_b32 s55, v77, 46
	v_readlane_b32 s56, v76, 47
	v_readlane_b32 s57, v77, 47
	v_add_f32_e32 v72, s42, v74
	v_cndmask_b32_e64 v80, v80, v74, s[38:39]
	v_max_f32_e32 v86, s43, v72
	v_cndmask_b32_e64 v78, v78, v72, s[38:39]
	v_cndmask_b32_e64 v79, v79, v86, s[38:39]
	s_lshl_b64 s[38:39], s[38:39], 1
	v_add_f32_e32 v72, s44, v86
	v_cndmask_b32_e64 v80, v80, v86, s[38:39]
	v_max_f32_e32 v74, s45, v72
	v_cndmask_b32_e64 v78, v78, v72, s[38:39]
	v_cndmask_b32_e64 v79, v79, v74, s[38:39]
	s_lshl_b64 s[38:39], s[38:39], 1
	v_add_f32_e32 v72, s46, v74
	v_cndmask_b32_e64 v80, v80, v74, s[38:39]
	v_max_f32_e32 v86, s47, v72
	v_cndmask_b32_e64 v78, v78, v72, s[38:39]
	v_cndmask_b32_e64 v79, v79, v86, s[38:39]
	s_lshl_b64 s[38:39], s[38:39], 1
	v_add_f32_e32 v72, s48, v86
	v_cndmask_b32_e64 v80, v80, v86, s[38:39]
	v_max_f32_e32 v74, s49, v72
	v_cndmask_b32_e64 v78, v78, v72, s[38:39]
	v_cndmask_b32_e64 v79, v79, v74, s[38:39]
	s_lshl_b64 s[38:39], s[38:39], 1
	v_add_f32_e32 v72, s50, v74
	v_cndmask_b32_e64 v80, v80, v74, s[38:39]
	v_max_f32_e32 v86, s51, v72
	v_cndmask_b32_e64 v78, v78, v72, s[38:39]
	v_cndmask_b32_e64 v79, v79, v86, s[38:39]
	s_lshl_b64 s[38:39], s[38:39], 1
	v_add_f32_e32 v72, s52, v86
	v_cndmask_b32_e64 v80, v80, v86, s[38:39]
	v_max_f32_e32 v74, s53, v72
	v_cndmask_b32_e64 v78, v78, v72, s[38:39]
	v_cndmask_b32_e64 v79, v79, v74, s[38:39]
	s_lshl_b64 s[38:39], s[38:39], 1
	v_add_f32_e32 v72, s54, v74
	v_cndmask_b32_e64 v80, v80, v74, s[38:39]
	v_max_f32_e32 v86, s55, v72
	v_cndmask_b32_e64 v78, v78, v72, s[38:39]
	v_cndmask_b32_e64 v79, v79, v86, s[38:39]
	s_lshl_b64 s[38:39], s[38:39], 1
	v_add_f32_e32 v72, s56, v86
	v_cndmask_b32_e64 v80, v80, v86, s[38:39]
	v_max_f32_e32 v74, s57, v72
	v_cndmask_b32_e64 v78, v78, v72, s[38:39]
	v_cndmask_b32_e64 v79, v79, v74, s[38:39]
	s_lshl_b64 s[38:39], s[38:39], 1
	v_readlane_b32 s42, v76, 48
	v_readlane_b32 s43, v77, 48
	v_readlane_b32 s44, v76, 49
	v_readlane_b32 s45, v77, 49
	v_readlane_b32 s46, v76, 50
	v_readlane_b32 s47, v77, 50
	v_readlane_b32 s48, v76, 51
	v_readlane_b32 s49, v77, 51
	v_readlane_b32 s50, v76, 52
	v_readlane_b32 s51, v77, 52
	v_readlane_b32 s52, v76, 53
	v_readlane_b32 s53, v77, 53
	v_readlane_b32 s54, v76, 54
	v_readlane_b32 s55, v77, 54
	v_readlane_b32 s56, v76, 55
	v_readlane_b32 s57, v77, 55
	v_add_f32_e32 v72, s42, v74
	v_cndmask_b32_e64 v80, v80, v74, s[38:39]
	v_max_f32_e32 v86, s43, v72
	v_cndmask_b32_e64 v78, v78, v72, s[38:39]
	v_cndmask_b32_e64 v79, v79, v86, s[38:39]
	s_lshl_b64 s[38:39], s[38:39], 1
	v_add_f32_e32 v72, s44, v86
	v_cndmask_b32_e64 v80, v80, v86, s[38:39]
	v_max_f32_e32 v74, s45, v72
	v_cndmask_b32_e64 v78, v78, v72, s[38:39]
	v_cndmask_b32_e64 v79, v79, v74, s[38:39]
	s_lshl_b64 s[38:39], s[38:39], 1
	v_add_f32_e32 v72, s46, v74
	v_cndmask_b32_e64 v80, v80, v74, s[38:39]
	v_max_f32_e32 v86, s47, v72
	v_cndmask_b32_e64 v78, v78, v72, s[38:39]
	v_cndmask_b32_e64 v79, v79, v86, s[38:39]
	s_lshl_b64 s[38:39], s[38:39], 1
	v_add_f32_e32 v72, s48, v86
	v_cndmask_b32_e64 v80, v80, v86, s[38:39]
	v_max_f32_e32 v74, s49, v72
	v_cndmask_b32_e64 v78, v78, v72, s[38:39]
	v_cndmask_b32_e64 v79, v79, v74, s[38:39]
	s_lshl_b64 s[38:39], s[38:39], 1
	v_add_f32_e32 v72, s50, v74
	v_cndmask_b32_e64 v80, v80, v74, s[38:39]
	v_max_f32_e32 v86, s51, v72
	v_cndmask_b32_e64 v78, v78, v72, s[38:39]
	v_cndmask_b32_e64 v79, v79, v86, s[38:39]
	s_lshl_b64 s[38:39], s[38:39], 1
	v_add_f32_e32 v72, s52, v86
	v_cndmask_b32_e64 v80, v80, v86, s[38:39]
	v_max_f32_e32 v74, s53, v72
	v_cndmask_b32_e64 v78, v78, v72, s[38:39]
	v_cndmask_b32_e64 v79, v79, v74, s[38:39]
	s_lshl_b64 s[38:39], s[38:39], 1
	v_add_f32_e32 v72, s54, v74
	v_cndmask_b32_e64 v80, v80, v74, s[38:39]
	v_max_f32_e32 v86, s55, v72
	v_cndmask_b32_e64 v78, v78, v72, s[38:39]
	v_cndmask_b32_e64 v79, v79, v86, s[38:39]
	s_lshl_b64 s[38:39], s[38:39], 1
	v_add_f32_e32 v72, s56, v86
	v_cndmask_b32_e64 v80, v80, v86, s[38:39]
	v_max_f32_e32 v74, s57, v72
	v_cndmask_b32_e64 v78, v78, v72, s[38:39]
	v_cndmask_b32_e64 v79, v79, v74, s[38:39]
	s_lshl_b64 s[38:39], s[38:39], 1
	v_readlane_b32 s42, v76, 56
	v_readlane_b32 s43, v77, 56
	v_readlane_b32 s44, v76, 57
	v_readlane_b32 s45, v77, 57
	v_readlane_b32 s46, v76, 58
	v_readlane_b32 s47, v77, 58
	v_readlane_b32 s48, v76, 59
	v_readlane_b32 s49, v77, 59
	v_readlane_b32 s50, v76, 60
	v_readlane_b32 s51, v77, 60
	v_readlane_b32 s52, v76, 61
	v_readlane_b32 s53, v77, 61
	v_readlane_b32 s54, v76, 62
	v_readlane_b32 s55, v77, 62
	v_readlane_b32 s56, v76, 63
	v_readlane_b32 s57, v77, 63
	v_add_f32_e32 v72, s42, v74
	v_cndmask_b32_e64 v80, v80, v74, s[38:39]
	v_max_f32_e32 v86, s43, v72
	v_cndmask_b32_e64 v78, v78, v72, s[38:39]
	v_cndmask_b32_e64 v79, v79, v86, s[38:39]
	s_lshl_b64 s[38:39], s[38:39], 1
	v_add_f32_e32 v72, s44, v86
	v_cndmask_b32_e64 v80, v80, v86, s[38:39]
	v_max_f32_e32 v74, s45, v72
	v_cndmask_b32_e64 v78, v78, v72, s[38:39]
	v_cndmask_b32_e64 v79, v79, v74, s[38:39]
	s_lshl_b64 s[38:39], s[38:39], 1
	v_add_f32_e32 v72, s46, v74
	v_cndmask_b32_e64 v80, v80, v74, s[38:39]
	v_max_f32_e32 v86, s47, v72
	v_cndmask_b32_e64 v78, v78, v72, s[38:39]
	v_cndmask_b32_e64 v79, v79, v86, s[38:39]
	s_lshl_b64 s[38:39], s[38:39], 1
	v_add_f32_e32 v72, s48, v86
	v_cndmask_b32_e64 v80, v80, v86, s[38:39]
	v_max_f32_e32 v74, s49, v72
	v_cndmask_b32_e64 v78, v78, v72, s[38:39]
	v_cndmask_b32_e64 v79, v79, v74, s[38:39]
	s_lshl_b64 s[38:39], s[38:39], 1
	v_add_f32_e32 v72, s50, v74
	v_cndmask_b32_e64 v80, v80, v74, s[38:39]
	v_max_f32_e32 v86, s51, v72
	v_cndmask_b32_e64 v78, v78, v72, s[38:39]
	v_cndmask_b32_e64 v79, v79, v86, s[38:39]
	s_lshl_b64 s[38:39], s[38:39], 1
	v_add_f32_e32 v72, s52, v86
	v_cndmask_b32_e64 v80, v80, v86, s[38:39]
	v_max_f32_e32 v74, s53, v72
	v_cndmask_b32_e64 v78, v78, v72, s[38:39]
	v_cndmask_b32_e64 v79, v79, v74, s[38:39]
	s_lshl_b64 s[38:39], s[38:39], 1
	v_add_f32_e32 v72, s54, v74
	v_cndmask_b32_e64 v80, v80, v74, s[38:39]
	v_max_f32_e32 v86, s55, v72
	v_cndmask_b32_e64 v78, v78, v72, s[38:39]
	v_cndmask_b32_e64 v79, v79, v86, s[38:39]
	s_lshl_b64 s[38:39], s[38:39], 1
	v_add_f32_e32 v72, s56, v86
	v_cndmask_b32_e64 v80, v80, v86, s[38:39]
	v_max_f32_e32 v74, s57, v72
	v_cndmask_b32_e64 v78, v78, v72, s[38:39]
	v_cndmask_b32_e64 v79, v79, v74, s[38:39]
	s_lshl_b64 s[38:39], s[38:39], 1
	v_sub_f32_e32 v81, v78, v79
	v_sub_f32_e32 v82, v77, v79
	v_mul_f32_e32 v81, 0x3fb8aa3b, v81
	v_mul_f32_e32 v82, 0x3fb8aa3b, v82
	v_exp_f32_e32 v81, v81
	v_exp_f32_e32 v82, v82
	s_nop 1
	v_readlane_b32 s42, v81, 0
	v_readlane_b32 s43, v82, 0
	v_readlane_b32 s44, v81, 1
	v_readlane_b32 s45, v82, 1
	v_readlane_b32 s46, v81, 2
	v_readlane_b32 s47, v82, 2
	s_waitcnt vmcnt(59)
	v_cvt_pk_bf16_f32 v72, v83, v84
	v_lshlrev_b32_e32 v74, 16, v6
	global_store_dword v4, v72, s[12:13]
	v_and_b32_e32 v86, 0xffff0000, v6
	s_add_u32 s12, s12, 0x80000
	s_addc_u32 s13, s13, 0
	v_mul_f32_e32 v83, s42, v83
	v_mul_f32_e32 v84, s42, v84
	v_fmac_f32_e32 v83, s43, v74
	v_fmac_f32_e32 v84, s43, v86
	global_load_dword v66, v4, s[10:11]
	s_add_u32 s10, s10, 0x80000
	s_addc_u32 s11, s11, 0
	v_readlane_b32 s48, v81, 3
	v_readlane_b32 s49, v82, 3
	s_waitcnt vmcnt(60)
	v_cvt_pk_bf16_f32 v72, v83, v84
	v_lshlrev_b32_e32 v74, 16, v7
	global_store_dword v4, v72, s[12:13]
	v_and_b32_e32 v86, 0xffff0000, v7
	s_add_u32 s12, s12, 0x80000
	s_addc_u32 s13, s13, 0
	v_mul_f32_e32 v83, s44, v83
	v_mul_f32_e32 v84, s44, v84
	v_fmac_f32_e32 v83, s45, v74
	v_fmac_f32_e32 v84, s45, v86
	global_load_dword v67, v4, s[10:11]
	s_add_u32 s10, s10, 0x80000
	s_addc_u32 s11, s11, 0
	v_readlane_b32 s42, v81, 4
	v_readlane_b32 s43, v82, 4
	s_waitcnt vmcnt(61)
	v_cvt_pk_bf16_f32 v72, v83, v84
	v_lshlrev_b32_e32 v74, 16, v8
	global_store_dword v4, v72, s[12:13]
	v_and_b32_e32 v86, 0xffff0000, v8
	s_add_u32 s12, s12, 0x80000
	s_addc_u32 s13, s13, 0
	v_mul_f32_e32 v83, s46, v83
	v_mul_f32_e32 v84, s46, v84
	v_fmac_f32_e32 v83, s47, v74
	v_fmac_f32_e32 v84, s47, v86
	global_load_dword v68, v4, s[10:11]
	s_add_u32 s10, s10, 0x80000
	s_addc_u32 s11, s11, 0
	v_readlane_b32 s44, v81, 5
	v_readlane_b32 s45, v82, 5
	s_waitcnt vmcnt(62)
	v_cvt_pk_bf16_f32 v72, v83, v84
	v_lshlrev_b32_e32 v74, 16, v9
	global_store_dword v4, v72, s[12:13]
	v_and_b32_e32 v86, 0xffff0000, v9
	s_add_u32 s12, s12, 0x80000
	s_addc_u32 s13, s13, 0
	v_mul_f32_e32 v83, s48, v83
	v_mul_f32_e32 v84, s48, v84
	v_fmac_f32_e32 v83, s49, v74
	v_fmac_f32_e32 v84, s49, v86
	global_load_dword v69, v4, s[10:11]
	s_add_u32 s10, s10, 0x80000
	s_addc_u32 s11, s11, 0
	v_readlane_b32 s46, v81, 6
	v_readlane_b32 s47, v82, 6
	s_waitcnt vmcnt(63)
	v_cvt_pk_bf16_f32 v72, v83, v84
	v_lshlrev_b32_e32 v74, 16, v10
	global_store_dword v4, v72, s[12:13]
	v_and_b32_e32 v86, 0xffff0000, v10
	s_add_u32 s12, s12, 0x80000
	s_addc_u32 s13, s13, 0
	v_mul_f32_e32 v83, s42, v83
	v_mul_f32_e32 v84, s42, v84
	v_fmac_f32_e32 v83, s43, v74
	v_fmac_f32_e32 v84, s43, v86
	v_readlane_b32 s48, v81, 7
	v_readlane_b32 s49, v82, 7
	s_waitcnt vmcnt(63)
	v_cvt_pk_bf16_f32 v72, v83, v84
	v_lshlrev_b32_e32 v74, 16, v11
	global_store_dword v4, v72, s[12:13]
	v_and_b32_e32 v86, 0xffff0000, v11
	s_add_u32 s12, s12, 0x80000
	s_addc_u32 s13, s13, 0
	v_mul_f32_e32 v83, s44, v83
	v_mul_f32_e32 v84, s44, v84
	v_fmac_f32_e32 v83, s45, v74
	v_fmac_f32_e32 v84, s45, v86
	v_readlane_b32 s42, v81, 8
	v_readlane_b32 s43, v82, 8
	s_waitcnt vmcnt(63)
	v_cvt_pk_bf16_f32 v72, v83, v84
	v_lshlrev_b32_e32 v74, 16, v12
	global_store_dword v4, v72, s[12:13]
	v_and_b32_e32 v86, 0xffff0000, v12
	s_add_u32 s12, s12, 0x80000
	s_addc_u32 s13, s13, 0
	v_mul_f32_e32 v83, s46, v83
	v_mul_f32_e32 v84, s46, v84
	v_fmac_f32_e32 v83, s47, v74
	v_fmac_f32_e32 v84, s47, v86
	v_readlane_b32 s44, v81, 9
	v_readlane_b32 s45, v82, 9
	s_waitcnt vmcnt(63)
	v_cvt_pk_bf16_f32 v72, v83, v84
	v_lshlrev_b32_e32 v74, 16, v13
	global_store_dword v4, v72, s[12:13]
	v_and_b32_e32 v86, 0xffff0000, v13
	s_add_u32 s12, s12, 0x80000
	s_addc_u32 s13, s13, 0
	v_mul_f32_e32 v83, s48, v83
	v_mul_f32_e32 v84, s48, v84
	v_fmac_f32_e32 v83, s49, v74
	v_fmac_f32_e32 v84, s49, v86
	v_readlane_b32 s46, v81, 10
	v_readlane_b32 s47, v82, 10
	s_waitcnt vmcnt(63)
	v_cvt_pk_bf16_f32 v72, v83, v84
	v_lshlrev_b32_e32 v74, 16, v14
	global_store_dword v4, v72, s[12:13]
	v_and_b32_e32 v86, 0xffff0000, v14
	s_add_u32 s12, s12, 0x80000
	s_addc_u32 s13, s13, 0
	v_mul_f32_e32 v83, s42, v83
	v_mul_f32_e32 v84, s42, v84
	v_fmac_f32_e32 v83, s43, v74
	v_fmac_f32_e32 v84, s43, v86
	v_readlane_b32 s48, v81, 11
	v_readlane_b32 s49, v82, 11
	s_waitcnt vmcnt(63)
	v_cvt_pk_bf16_f32 v72, v83, v84
	v_lshlrev_b32_e32 v74, 16, v15
	global_store_dword v4, v72, s[12:13]
	v_and_b32_e32 v86, 0xffff0000, v15
	s_add_u32 s12, s12, 0x80000
	s_addc_u32 s13, s13, 0
	v_mul_f32_e32 v83, s44, v83
	v_mul_f32_e32 v84, s44, v84
	v_fmac_f32_e32 v83, s45, v74
	v_fmac_f32_e32 v84, s45, v86
	v_readlane_b32 s42, v81, 12
	v_readlane_b32 s43, v82, 12
	s_waitcnt vmcnt(63)
	v_cvt_pk_bf16_f32 v72, v83, v84
	v_lshlrev_b32_e32 v74, 16, v16
	global_store_dword v4, v72, s[12:13]
	v_and_b32_e32 v86, 0xffff0000, v16
	s_add_u32 s12, s12, 0x80000
	s_addc_u32 s13, s13, 0
	v_mul_f32_e32 v83, s46, v83
	v_mul_f32_e32 v84, s46, v84
	v_fmac_f32_e32 v83, s47, v74
	v_fmac_f32_e32 v84, s47, v86
	v_readlane_b32 s44, v81, 13
	v_readlane_b32 s45, v82, 13
	s_waitcnt vmcnt(63)
	v_cvt_pk_bf16_f32 v72, v83, v84
	v_lshlrev_b32_e32 v74, 16, v17
	global_store_dword v4, v72, s[12:13]
	v_and_b32_e32 v86, 0xffff0000, v17
	s_add_u32 s12, s12, 0x80000
	s_addc_u32 s13, s13, 0
	v_mul_f32_e32 v83, s48, v83
	v_mul_f32_e32 v84, s48, v84
	v_fmac_f32_e32 v83, s49, v74
	v_fmac_f32_e32 v84, s49, v86
	v_readlane_b32 s46, v81, 14
	v_readlane_b32 s47, v82, 14
	s_waitcnt vmcnt(63)
	v_cvt_pk_bf16_f32 v72, v83, v84
	v_lshlrev_b32_e32 v74, 16, v18
	global_store_dword v4, v72, s[12:13]
	v_and_b32_e32 v86, 0xffff0000, v18
	s_add_u32 s12, s12, 0x80000
	s_addc_u32 s13, s13, 0
	v_mul_f32_e32 v83, s42, v83
	v_mul_f32_e32 v84, s42, v84
	v_fmac_f32_e32 v83, s43, v74
	v_fmac_f32_e32 v84, s43, v86
	v_readlane_b32 s48, v81, 15
	v_readlane_b32 s49, v82, 15
	s_waitcnt vmcnt(63)
	v_cvt_pk_bf16_f32 v72, v83, v84
	v_lshlrev_b32_e32 v74, 16, v19
	global_store_dword v4, v72, s[12:13]
	v_and_b32_e32 v86, 0xffff0000, v19
	s_add_u32 s12, s12, 0x80000
	s_addc_u32 s13, s13, 0
	v_mul_f32_e32 v83, s44, v83
	v_mul_f32_e32 v84, s44, v84
	v_fmac_f32_e32 v83, s45, v74
	v_fmac_f32_e32 v84, s45, v86
	v_readlane_b32 s42, v81, 16
	v_readlane_b32 s43, v82, 16
	s_waitcnt vmcnt(63)
	v_cvt_pk_bf16_f32 v72, v83, v84
	v_lshlrev_b32_e32 v74, 16, v20
	global_store_dword v4, v72, s[12:13]
	v_and_b32_e32 v86, 0xffff0000, v20
	s_add_u32 s12, s12, 0x80000
	s_addc_u32 s13, s13, 0
	v_mul_f32_e32 v83, s46, v83
	v_mul_f32_e32 v84, s46, v84
	v_fmac_f32_e32 v83, s47, v74
	v_fmac_f32_e32 v84, s47, v86
	v_readlane_b32 s44, v81, 17
	v_readlane_b32 s45, v82, 17
	s_waitcnt vmcnt(63)
	v_cvt_pk_bf16_f32 v72, v83, v84
	v_lshlrev_b32_e32 v74, 16, v21
	global_store_dword v4, v72, s[12:13]
	v_and_b32_e32 v86, 0xffff0000, v21
	s_add_u32 s12, s12, 0x80000
	s_addc_u32 s13, s13, 0
	v_mul_f32_e32 v83, s48, v83
	v_mul_f32_e32 v84, s48, v84
	v_fmac_f32_e32 v83, s49, v74
	v_fmac_f32_e32 v84, s49, v86
	v_readlane_b32 s46, v81, 18
	v_readlane_b32 s47, v82, 18
	s_waitcnt vmcnt(63)
	v_cvt_pk_bf16_f32 v72, v83, v84
	v_lshlrev_b32_e32 v74, 16, v22
	global_store_dword v4, v72, s[12:13]
	v_and_b32_e32 v86, 0xffff0000, v22
	s_add_u32 s12, s12, 0x80000
	s_addc_u32 s13, s13, 0
	v_mul_f32_e32 v83, s42, v83
	v_mul_f32_e32 v84, s42, v84
	v_fmac_f32_e32 v83, s43, v74
	v_fmac_f32_e32 v84, s43, v86
	v_readlane_b32 s48, v81, 19
	v_readlane_b32 s49, v82, 19
	s_waitcnt vmcnt(63)
	v_cvt_pk_bf16_f32 v72, v83, v84
	v_lshlrev_b32_e32 v74, 16, v23
	global_store_dword v4, v72, s[12:13]
	v_and_b32_e32 v86, 0xffff0000, v23
	s_add_u32 s12, s12, 0x80000
	s_addc_u32 s13, s13, 0
	v_mul_f32_e32 v83, s44, v83
	v_mul_f32_e32 v84, s44, v84
	v_fmac_f32_e32 v83, s45, v74
	v_fmac_f32_e32 v84, s45, v86
	v_readlane_b32 s42, v81, 20
	v_readlane_b32 s43, v82, 20
	s_waitcnt vmcnt(63)
	v_cvt_pk_bf16_f32 v72, v83, v84
	v_lshlrev_b32_e32 v74, 16, v24
	global_store_dword v4, v72, s[12:13]
	v_and_b32_e32 v86, 0xffff0000, v24
	s_add_u32 s12, s12, 0x80000
	s_addc_u32 s13, s13, 0
	v_mul_f32_e32 v83, s46, v83
	v_mul_f32_e32 v84, s46, v84
	v_fmac_f32_e32 v83, s47, v74
	v_fmac_f32_e32 v84, s47, v86
	v_readlane_b32 s44, v81, 21
	v_readlane_b32 s45, v82, 21
	s_waitcnt vmcnt(63)
	v_cvt_pk_bf16_f32 v72, v83, v84
	v_lshlrev_b32_e32 v74, 16, v25
	global_store_dword v4, v72, s[12:13]
	v_and_b32_e32 v86, 0xffff0000, v25
	s_add_u32 s12, s12, 0x80000
	s_addc_u32 s13, s13, 0
	v_mul_f32_e32 v83, s48, v83
	v_mul_f32_e32 v84, s48, v84
	v_fmac_f32_e32 v83, s49, v74
	v_fmac_f32_e32 v84, s49, v86
	v_readlane_b32 s46, v81, 22
	v_readlane_b32 s47, v82, 22
	s_waitcnt vmcnt(63)
	v_cvt_pk_bf16_f32 v72, v83, v84
	v_lshlrev_b32_e32 v74, 16, v26
	global_store_dword v4, v72, s[12:13]
	v_and_b32_e32 v86, 0xffff0000, v26
	s_add_u32 s12, s12, 0x80000
	s_addc_u32 s13, s13, 0
	v_mul_f32_e32 v83, s42, v83
	v_mul_f32_e32 v84, s42, v84
	v_fmac_f32_e32 v83, s43, v74
	v_fmac_f32_e32 v84, s43, v86
	v_readlane_b32 s48, v81, 23
	v_readlane_b32 s49, v82, 23
	s_waitcnt vmcnt(63)
	v_cvt_pk_bf16_f32 v72, v83, v84
	v_lshlrev_b32_e32 v74, 16, v27
	global_store_dword v4, v72, s[12:13]
	v_and_b32_e32 v86, 0xffff0000, v27
	s_add_u32 s12, s12, 0x80000
	s_addc_u32 s13, s13, 0
	v_mul_f32_e32 v83, s44, v83
	v_mul_f32_e32 v84, s44, v84
	v_fmac_f32_e32 v83, s45, v74
	v_fmac_f32_e32 v84, s45, v86
	v_readlane_b32 s42, v81, 24
	v_readlane_b32 s43, v82, 24
	s_waitcnt vmcnt(63)
	v_cvt_pk_bf16_f32 v72, v83, v84
	v_lshlrev_b32_e32 v74, 16, v28
	global_store_dword v4, v72, s[12:13]
	v_and_b32_e32 v86, 0xffff0000, v28
	s_add_u32 s12, s12, 0x80000
	s_addc_u32 s13, s13, 0
	v_mul_f32_e32 v83, s46, v83
	v_mul_f32_e32 v84, s46, v84
	v_fmac_f32_e32 v83, s47, v74
	v_fmac_f32_e32 v84, s47, v86
	v_readlane_b32 s44, v81, 25
	v_readlane_b32 s45, v82, 25
	s_waitcnt vmcnt(63)
	v_cvt_pk_bf16_f32 v72, v83, v84
	v_lshlrev_b32_e32 v74, 16, v29
	global_store_dword v4, v72, s[12:13]
	v_and_b32_e32 v86, 0xffff0000, v29
	s_add_u32 s12, s12, 0x80000
	s_addc_u32 s13, s13, 0
	v_mul_f32_e32 v83, s48, v83
	v_mul_f32_e32 v84, s48, v84
	v_fmac_f32_e32 v83, s49, v74
	v_fmac_f32_e32 v84, s49, v86
	v_readlane_b32 s46, v81, 26
	v_readlane_b32 s47, v82, 26
	s_waitcnt vmcnt(63)
	v_cvt_pk_bf16_f32 v72, v83, v84
	v_lshlrev_b32_e32 v74, 16, v30
	global_store_dword v4, v72, s[12:13]
	v_and_b32_e32 v86, 0xffff0000, v30
	s_add_u32 s12, s12, 0x80000
	s_addc_u32 s13, s13, 0
	v_mul_f32_e32 v83, s42, v83
	v_mul_f32_e32 v84, s42, v84
	v_fmac_f32_e32 v83, s43, v74
	v_fmac_f32_e32 v84, s43, v86
	v_readlane_b32 s48, v81, 27
	v_readlane_b32 s49, v82, 27
	s_waitcnt vmcnt(63)
	v_cvt_pk_bf16_f32 v72, v83, v84
	v_lshlrev_b32_e32 v74, 16, v31
	global_store_dword v4, v72, s[12:13]
	v_and_b32_e32 v86, 0xffff0000, v31
	s_add_u32 s12, s12, 0x80000
	s_addc_u32 s13, s13, 0
	v_mul_f32_e32 v83, s44, v83
	v_mul_f32_e32 v84, s44, v84
	v_fmac_f32_e32 v83, s45, v74
	v_fmac_f32_e32 v84, s45, v86
	v_readlane_b32 s42, v81, 28
	v_readlane_b32 s43, v82, 28
	s_waitcnt vmcnt(63)
	v_cvt_pk_bf16_f32 v72, v83, v84
	v_lshlrev_b32_e32 v74, 16, v32
	global_store_dword v4, v72, s[12:13]
	v_and_b32_e32 v86, 0xffff0000, v32
	s_add_u32 s12, s12, 0x80000
	s_addc_u32 s13, s13, 0
	v_mul_f32_e32 v83, s46, v83
	v_mul_f32_e32 v84, s46, v84
	v_fmac_f32_e32 v83, s47, v74
	v_fmac_f32_e32 v84, s47, v86
	v_readlane_b32 s44, v81, 29
	v_readlane_b32 s45, v82, 29
	s_waitcnt vmcnt(63)
	v_cvt_pk_bf16_f32 v72, v83, v84
	v_lshlrev_b32_e32 v74, 16, v33
	global_store_dword v4, v72, s[12:13]
	v_and_b32_e32 v86, 0xffff0000, v33
	s_add_u32 s12, s12, 0x80000
	s_addc_u32 s13, s13, 0
	v_mul_f32_e32 v83, s48, v83
	v_mul_f32_e32 v84, s48, v84
	v_fmac_f32_e32 v83, s49, v74
	v_fmac_f32_e32 v84, s49, v86
	v_readlane_b32 s46, v81, 30
	v_readlane_b32 s47, v82, 30
	s_waitcnt vmcnt(63)
	v_cvt_pk_bf16_f32 v72, v83, v84
	v_lshlrev_b32_e32 v74, 16, v34
	global_store_dword v4, v72, s[12:13]
	v_and_b32_e32 v86, 0xffff0000, v34
	s_add_u32 s12, s12, 0x80000
	s_addc_u32 s13, s13, 0
	v_mul_f32_e32 v83, s42, v83
	v_mul_f32_e32 v84, s42, v84
	v_fmac_f32_e32 v83, s43, v74
	v_fmac_f32_e32 v84, s43, v86
	v_readlane_b32 s48, v81, 31
	v_readlane_b32 s49, v82, 31
	s_waitcnt vmcnt(63)
	v_cvt_pk_bf16_f32 v72, v83, v84
	v_lshlrev_b32_e32 v74, 16, v35
	global_store_dword v4, v72, s[12:13]
	v_and_b32_e32 v86, 0xffff0000, v35
	s_add_u32 s12, s12, 0x80000
	s_addc_u32 s13, s13, 0
	v_mul_f32_e32 v83, s44, v83
	v_mul_f32_e32 v84, s44, v84
	v_fmac_f32_e32 v83, s45, v74
	v_fmac_f32_e32 v84, s45, v86
	v_readlane_b32 s42, v81, 32
	v_readlane_b32 s43, v82, 32
	s_waitcnt vmcnt(63)
	v_cvt_pk_bf16_f32 v72, v83, v84
	v_lshlrev_b32_e32 v74, 16, v36
	global_store_dword v4, v72, s[12:13]
	v_and_b32_e32 v86, 0xffff0000, v36
	s_add_u32 s12, s12, 0x80000
	s_addc_u32 s13, s13, 0
	v_mul_f32_e32 v83, s46, v83
	v_mul_f32_e32 v84, s46, v84
	v_fmac_f32_e32 v83, s47, v74
	v_fmac_f32_e32 v84, s47, v86
	v_readlane_b32 s44, v81, 33
	v_readlane_b32 s45, v82, 33
	s_waitcnt vmcnt(63)
	v_cvt_pk_bf16_f32 v72, v83, v84
	v_lshlrev_b32_e32 v74, 16, v37
	global_store_dword v4, v72, s[12:13]
	v_and_b32_e32 v86, 0xffff0000, v37
	s_add_u32 s12, s12, 0x80000
	s_addc_u32 s13, s13, 0
	v_mul_f32_e32 v83, s48, v83
	v_mul_f32_e32 v84, s48, v84
	v_fmac_f32_e32 v83, s49, v74
	v_fmac_f32_e32 v84, s49, v86
	v_readlane_b32 s46, v81, 34
	v_readlane_b32 s47, v82, 34
	s_waitcnt vmcnt(63)
	v_cvt_pk_bf16_f32 v72, v83, v84
	v_lshlrev_b32_e32 v74, 16, v38
	global_store_dword v4, v72, s[12:13]
	v_and_b32_e32 v86, 0xffff0000, v38
	s_add_u32 s12, s12, 0x80000
	s_addc_u32 s13, s13, 0
	v_mul_f32_e32 v83, s42, v83
	v_mul_f32_e32 v84, s42, v84
	v_fmac_f32_e32 v83, s43, v74
	v_fmac_f32_e32 v84, s43, v86
	v_readlane_b32 s48, v81, 35
	v_readlane_b32 s49, v82, 35
	s_waitcnt vmcnt(63)
	v_cvt_pk_bf16_f32 v72, v83, v84
	v_lshlrev_b32_e32 v74, 16, v39
	global_store_dword v4, v72, s[12:13]
	v_and_b32_e32 v86, 0xffff0000, v39
	s_add_u32 s12, s12, 0x80000
	s_addc_u32 s13, s13, 0
	v_mul_f32_e32 v83, s44, v83
	v_mul_f32_e32 v84, s44, v84
	v_fmac_f32_e32 v83, s45, v74
	v_fmac_f32_e32 v84, s45, v86
	v_readlane_b32 s42, v81, 36
	v_readlane_b32 s43, v82, 36
	s_waitcnt vmcnt(63)
	v_cvt_pk_bf16_f32 v72, v83, v84
	v_lshlrev_b32_e32 v74, 16, v40
	global_store_dword v4, v72, s[12:13]
	v_and_b32_e32 v86, 0xffff0000, v40
	s_add_u32 s12, s12, 0x80000
	s_addc_u32 s13, s13, 0
	v_mul_f32_e32 v83, s46, v83
	v_mul_f32_e32 v84, s46, v84
	v_fmac_f32_e32 v83, s47, v74
	v_fmac_f32_e32 v84, s47, v86
	v_readlane_b32 s44, v81, 37
	v_readlane_b32 s45, v82, 37
	s_waitcnt vmcnt(63)
	v_cvt_pk_bf16_f32 v72, v83, v84
	v_lshlrev_b32_e32 v74, 16, v41
	global_store_dword v4, v72, s[12:13]
	v_and_b32_e32 v86, 0xffff0000, v41
	s_add_u32 s12, s12, 0x80000
	s_addc_u32 s13, s13, 0
	v_mul_f32_e32 v83, s48, v83
	v_mul_f32_e32 v84, s48, v84
	v_fmac_f32_e32 v83, s49, v74
	v_fmac_f32_e32 v84, s49, v86
	v_readlane_b32 s46, v81, 38
	v_readlane_b32 s47, v82, 38
	s_waitcnt vmcnt(63)
	v_cvt_pk_bf16_f32 v72, v83, v84
	v_lshlrev_b32_e32 v74, 16, v42
	global_store_dword v4, v72, s[12:13]
	v_and_b32_e32 v86, 0xffff0000, v42
	s_add_u32 s12, s12, 0x80000
	s_addc_u32 s13, s13, 0
	v_mul_f32_e32 v83, s42, v83
	v_mul_f32_e32 v84, s42, v84
	v_fmac_f32_e32 v83, s43, v74
	v_fmac_f32_e32 v84, s43, v86
	v_readlane_b32 s48, v81, 39
	v_readlane_b32 s49, v82, 39
	s_waitcnt vmcnt(63)
	v_cvt_pk_bf16_f32 v72, v83, v84
	v_lshlrev_b32_e32 v74, 16, v43
	global_store_dword v4, v72, s[12:13]
	v_and_b32_e32 v86, 0xffff0000, v43
	s_add_u32 s12, s12, 0x80000
	s_addc_u32 s13, s13, 0
	v_mul_f32_e32 v83, s44, v83
	v_mul_f32_e32 v84, s44, v84
	v_fmac_f32_e32 v83, s45, v74
	v_fmac_f32_e32 v84, s45, v86
	v_readlane_b32 s42, v81, 40
	v_readlane_b32 s43, v82, 40
	s_waitcnt vmcnt(63)
	v_cvt_pk_bf16_f32 v72, v83, v84
	v_lshlrev_b32_e32 v74, 16, v44
	global_store_dword v4, v72, s[12:13]
	v_and_b32_e32 v86, 0xffff0000, v44
	s_add_u32 s12, s12, 0x80000
	s_addc_u32 s13, s13, 0
	v_mul_f32_e32 v83, s46, v83
	v_mul_f32_e32 v84, s46, v84
	v_fmac_f32_e32 v83, s47, v74
	v_fmac_f32_e32 v84, s47, v86
	v_readlane_b32 s44, v81, 41
	v_readlane_b32 s45, v82, 41
	s_waitcnt vmcnt(63)
	v_cvt_pk_bf16_f32 v72, v83, v84
	v_lshlrev_b32_e32 v74, 16, v45
	global_store_dword v4, v72, s[12:13]
	v_and_b32_e32 v86, 0xffff0000, v45
	s_add_u32 s12, s12, 0x80000
	s_addc_u32 s13, s13, 0
	v_mul_f32_e32 v83, s48, v83
	v_mul_f32_e32 v84, s48, v84
	v_fmac_f32_e32 v83, s49, v74
	v_fmac_f32_e32 v84, s49, v86
	v_readlane_b32 s46, v81, 42
	v_readlane_b32 s47, v82, 42
	s_waitcnt vmcnt(63)
	v_cvt_pk_bf16_f32 v72, v83, v84
	v_lshlrev_b32_e32 v74, 16, v46
	global_store_dword v4, v72, s[12:13]
	v_and_b32_e32 v86, 0xffff0000, v46
	s_add_u32 s12, s12, 0x80000
	s_addc_u32 s13, s13, 0
	v_mul_f32_e32 v83, s42, v83
	v_mul_f32_e32 v84, s42, v84
	v_fmac_f32_e32 v83, s43, v74
	v_fmac_f32_e32 v84, s43, v86
	v_readlane_b32 s48, v81, 43
	v_readlane_b32 s49, v82, 43
	s_waitcnt vmcnt(63)
	v_cvt_pk_bf16_f32 v72, v83, v84
	v_lshlrev_b32_e32 v74, 16, v47
	global_store_dword v4, v72, s[12:13]
	v_and_b32_e32 v86, 0xffff0000, v47
	s_add_u32 s12, s12, 0x80000
	s_addc_u32 s13, s13, 0
	v_mul_f32_e32 v83, s44, v83
	v_mul_f32_e32 v84, s44, v84
	v_fmac_f32_e32 v83, s45, v74
	v_fmac_f32_e32 v84, s45, v86
	v_readlane_b32 s42, v81, 44
	v_readlane_b32 s43, v82, 44
	s_waitcnt vmcnt(63)
	v_cvt_pk_bf16_f32 v72, v83, v84
	v_lshlrev_b32_e32 v74, 16, v48
	global_store_dword v4, v72, s[12:13]
	v_and_b32_e32 v86, 0xffff0000, v48
	s_add_u32 s12, s12, 0x80000
	s_addc_u32 s13, s13, 0
	v_mul_f32_e32 v83, s46, v83
	v_mul_f32_e32 v84, s46, v84
	v_fmac_f32_e32 v83, s47, v74
	v_fmac_f32_e32 v84, s47, v86
	v_readlane_b32 s44, v81, 45
	v_readlane_b32 s45, v82, 45
	s_waitcnt vmcnt(63)
	v_cvt_pk_bf16_f32 v72, v83, v84
	v_lshlrev_b32_e32 v74, 16, v49
	global_store_dword v4, v72, s[12:13]
	v_and_b32_e32 v86, 0xffff0000, v49
	s_add_u32 s12, s12, 0x80000
	s_addc_u32 s13, s13, 0
	v_mul_f32_e32 v83, s48, v83
	v_mul_f32_e32 v84, s48, v84
	v_fmac_f32_e32 v83, s49, v74
	v_fmac_f32_e32 v84, s49, v86
	v_readlane_b32 s46, v81, 46
	v_readlane_b32 s47, v82, 46
	s_waitcnt vmcnt(63)
	v_cvt_pk_bf16_f32 v72, v83, v84
	v_lshlrev_b32_e32 v74, 16, v50
	global_store_dword v4, v72, s[12:13]
	v_and_b32_e32 v86, 0xffff0000, v50
	s_add_u32 s12, s12, 0x80000
	s_addc_u32 s13, s13, 0
	v_mul_f32_e32 v83, s42, v83
	v_mul_f32_e32 v84, s42, v84
	v_fmac_f32_e32 v83, s43, v74
	v_fmac_f32_e32 v84, s43, v86
	v_readlane_b32 s48, v81, 47
	v_readlane_b32 s49, v82, 47
	s_waitcnt vmcnt(63)
	v_cvt_pk_bf16_f32 v72, v83, v84
	v_lshlrev_b32_e32 v74, 16, v51
	global_store_dword v4, v72, s[12:13]
	v_and_b32_e32 v86, 0xffff0000, v51
	s_add_u32 s12, s12, 0x80000
	s_addc_u32 s13, s13, 0
	v_mul_f32_e32 v83, s44, v83
	v_mul_f32_e32 v84, s44, v84
	v_fmac_f32_e32 v83, s45, v74
	v_fmac_f32_e32 v84, s45, v86
	v_readlane_b32 s42, v81, 48
	v_readlane_b32 s43, v82, 48
	s_waitcnt vmcnt(63)
	v_cvt_pk_bf16_f32 v72, v83, v84
	v_lshlrev_b32_e32 v74, 16, v52
	global_store_dword v4, v72, s[12:13]
	v_and_b32_e32 v86, 0xffff0000, v52
	s_add_u32 s12, s12, 0x80000
	s_addc_u32 s13, s13, 0
	v_mul_f32_e32 v83, s46, v83
	v_mul_f32_e32 v84, s46, v84
	v_fmac_f32_e32 v83, s47, v74
	v_fmac_f32_e32 v84, s47, v86
	v_readlane_b32 s44, v81, 49
	v_readlane_b32 s45, v82, 49
	s_waitcnt vmcnt(63)
	v_cvt_pk_bf16_f32 v72, v83, v84
	v_lshlrev_b32_e32 v74, 16, v53
	global_store_dword v4, v72, s[12:13]
	v_and_b32_e32 v86, 0xffff0000, v53
	s_add_u32 s12, s12, 0x80000
	s_addc_u32 s13, s13, 0
	v_mul_f32_e32 v83, s48, v83
	v_mul_f32_e32 v84, s48, v84
	v_fmac_f32_e32 v83, s49, v74
	v_fmac_f32_e32 v84, s49, v86
	v_readlane_b32 s46, v81, 50
	v_readlane_b32 s47, v82, 50
	s_waitcnt vmcnt(63)
	v_cvt_pk_bf16_f32 v72, v83, v84
	v_lshlrev_b32_e32 v74, 16, v54
	global_store_dword v4, v72, s[12:13]
	v_and_b32_e32 v86, 0xffff0000, v54
	s_add_u32 s12, s12, 0x80000
	s_addc_u32 s13, s13, 0
	v_mul_f32_e32 v83, s42, v83
	v_mul_f32_e32 v84, s42, v84
	v_fmac_f32_e32 v83, s43, v74
	v_fmac_f32_e32 v84, s43, v86
	v_readlane_b32 s48, v81, 51
	v_readlane_b32 s49, v82, 51
	s_waitcnt vmcnt(63)
	v_cvt_pk_bf16_f32 v72, v83, v84
	v_lshlrev_b32_e32 v74, 16, v55
	global_store_dword v4, v72, s[12:13]
	v_and_b32_e32 v86, 0xffff0000, v55
	s_add_u32 s12, s12, 0x80000
	s_addc_u32 s13, s13, 0
	v_mul_f32_e32 v83, s44, v83
	v_mul_f32_e32 v84, s44, v84
	v_fmac_f32_e32 v83, s45, v74
	v_fmac_f32_e32 v84, s45, v86
	v_readlane_b32 s42, v81, 52
	v_readlane_b32 s43, v82, 52
	s_waitcnt vmcnt(63)
	v_cvt_pk_bf16_f32 v72, v83, v84
	v_lshlrev_b32_e32 v74, 16, v56
	global_store_dword v4, v72, s[12:13]
	v_and_b32_e32 v86, 0xffff0000, v56
	s_add_u32 s12, s12, 0x80000
	s_addc_u32 s13, s13, 0
	v_mul_f32_e32 v83, s46, v83
	v_mul_f32_e32 v84, s46, v84
	v_fmac_f32_e32 v83, s47, v74
	v_fmac_f32_e32 v84, s47, v86
	v_readlane_b32 s44, v81, 53
	v_readlane_b32 s45, v82, 53
	s_waitcnt vmcnt(63)
	v_cvt_pk_bf16_f32 v72, v83, v84
	v_lshlrev_b32_e32 v74, 16, v57
	global_store_dword v4, v72, s[12:13]
	v_and_b32_e32 v86, 0xffff0000, v57
	s_add_u32 s12, s12, 0x80000
	s_addc_u32 s13, s13, 0
	v_mul_f32_e32 v83, s48, v83
	v_mul_f32_e32 v84, s48, v84
	v_fmac_f32_e32 v83, s49, v74
	v_fmac_f32_e32 v84, s49, v86
	v_readlane_b32 s46, v81, 54
	v_readlane_b32 s47, v82, 54
	s_waitcnt vmcnt(63)
	v_cvt_pk_bf16_f32 v72, v83, v84
	v_lshlrev_b32_e32 v74, 16, v58
	global_store_dword v4, v72, s[12:13]
	v_and_b32_e32 v86, 0xffff0000, v58
	s_add_u32 s12, s12, 0x80000
	s_addc_u32 s13, s13, 0
	v_mul_f32_e32 v83, s42, v83
	v_mul_f32_e32 v84, s42, v84
	v_fmac_f32_e32 v83, s43, v74
	v_fmac_f32_e32 v84, s43, v86
	v_readlane_b32 s48, v81, 55
	v_readlane_b32 s49, v82, 55
	s_waitcnt vmcnt(63)
	v_cvt_pk_bf16_f32 v72, v83, v84
	v_lshlrev_b32_e32 v74, 16, v59
	global_store_dword v4, v72, s[12:13]
	v_and_b32_e32 v86, 0xffff0000, v59
	s_add_u32 s12, s12, 0x80000
	s_addc_u32 s13, s13, 0
	v_mul_f32_e32 v83, s44, v83
	v_mul_f32_e32 v84, s44, v84
	v_fmac_f32_e32 v83, s45, v74
	v_fmac_f32_e32 v84, s45, v86
	v_readlane_b32 s42, v81, 56
	v_readlane_b32 s43, v82, 56
	s_waitcnt vmcnt(63)
	v_cvt_pk_bf16_f32 v72, v83, v84
	v_lshlrev_b32_e32 v74, 16, v60
	global_store_dword v4, v72, s[12:13]
	v_and_b32_e32 v86, 0xffff0000, v60
	s_add_u32 s12, s12, 0x80000
	s_addc_u32 s13, s13, 0
	v_mul_f32_e32 v83, s46, v83
	v_mul_f32_e32 v84, s46, v84
	v_fmac_f32_e32 v83, s47, v74
	v_fmac_f32_e32 v84, s47, v86
	v_readlane_b32 s44, v81, 57
	v_readlane_b32 s45, v82, 57
	s_waitcnt vmcnt(63)
	v_cvt_pk_bf16_f32 v72, v83, v84
	v_lshlrev_b32_e32 v74, 16, v61
	global_store_dword v4, v72, s[12:13]
	v_and_b32_e32 v86, 0xffff0000, v61
	s_add_u32 s12, s12, 0x80000
	s_addc_u32 s13, s13, 0
	v_mul_f32_e32 v83, s48, v83
	v_mul_f32_e32 v84, s48, v84
	v_fmac_f32_e32 v83, s49, v74
	v_fmac_f32_e32 v84, s49, v86
	v_readlane_b32 s46, v81, 58
	v_readlane_b32 s47, v82, 58
	s_waitcnt vmcnt(63)
	v_cvt_pk_bf16_f32 v72, v83, v84
	v_lshlrev_b32_e32 v74, 16, v62
	global_store_dword v4, v72, s[12:13]
	v_and_b32_e32 v86, 0xffff0000, v62
	s_add_u32 s12, s12, 0x80000
	s_addc_u32 s13, s13, 0
	v_mul_f32_e32 v83, s42, v83
	v_mul_f32_e32 v84, s42, v84
	v_fmac_f32_e32 v83, s43, v74
	v_fmac_f32_e32 v84, s43, v86
	v_readlane_b32 s48, v81, 59
	v_readlane_b32 s49, v82, 59
	s_waitcnt vmcnt(63)
	v_cvt_pk_bf16_f32 v72, v83, v84
	v_lshlrev_b32_e32 v74, 16, v63
	global_store_dword v4, v72, s[12:13]
	v_and_b32_e32 v86, 0xffff0000, v63
	s_add_u32 s12, s12, 0x80000
	s_addc_u32 s13, s13, 0
	v_mul_f32_e32 v83, s44, v83
	v_mul_f32_e32 v84, s44, v84
	v_fmac_f32_e32 v83, s45, v74
	v_fmac_f32_e32 v84, s45, v86
	v_readlane_b32 s42, v81, 60
	v_readlane_b32 s43, v82, 60
	s_waitcnt vmcnt(63)
	v_cvt_pk_bf16_f32 v72, v83, v84
	v_lshlrev_b32_e32 v74, 16, v64
	global_store_dword v4, v72, s[12:13]
	v_and_b32_e32 v86, 0xffff0000, v64
	s_add_u32 s12, s12, 0x80000
	s_addc_u32 s13, s13, 0
	v_mul_f32_e32 v83, s46, v83
	v_mul_f32_e32 v84, s46, v84
	v_fmac_f32_e32 v83, s47, v74
	v_fmac_f32_e32 v84, s47, v86
	v_readlane_b32 s44, v81, 61
	v_readlane_b32 s45, v82, 61
	s_waitcnt vmcnt(63)
	v_cvt_pk_bf16_f32 v72, v83, v84
	v_lshlrev_b32_e32 v74, 16, v65
	global_store_dword v4, v72, s[12:13]
	v_and_b32_e32 v86, 0xffff0000, v65
	s_add_u32 s12, s12, 0x80000
	s_addc_u32 s13, s13, 0
	v_mul_f32_e32 v83, s48, v83
	v_mul_f32_e32 v84, s48, v84
	v_fmac_f32_e32 v83, s49, v74
	v_fmac_f32_e32 v84, s49, v86
	v_readlane_b32 s46, v81, 62
	v_readlane_b32 s47, v82, 62
	s_waitcnt vmcnt(62)
	v_cvt_pk_bf16_f32 v72, v83, v84
	v_lshlrev_b32_e32 v74, 16, v66
	global_store_dword v4, v72, s[12:13]
	v_and_b32_e32 v86, 0xffff0000, v66
	s_add_u32 s12, s12, 0x80000
	s_addc_u32 s13, s13, 0
	v_mul_f32_e32 v83, s42, v83
	v_mul_f32_e32 v84, s42, v84
	v_fmac_f32_e32 v83, s43, v74
	v_fmac_f32_e32 v84, s43, v86
	v_readlane_b32 s48, v81, 63
	v_readlane_b32 s49, v82, 63
	s_waitcnt vmcnt(61)
	v_cvt_pk_bf16_f32 v72, v83, v84
	v_lshlrev_b32_e32 v74, 16, v67
	global_store_dword v4, v72, s[12:13]
	v_and_b32_e32 v86, 0xffff0000, v67
	s_add_u32 s12, s12, 0x80000
	s_addc_u32 s13, s13, 0
	v_mul_f32_e32 v83, s44, v83
	v_mul_f32_e32 v84, s44, v84
	v_fmac_f32_e32 v83, s45, v74
	v_fmac_f32_e32 v84, s45, v86
	s_waitcnt vmcnt(60)
	v_cvt_pk_bf16_f32 v72, v83, v84
	v_lshlrev_b32_e32 v74, 16, v68
	global_store_dword v4, v72, s[12:13]
	v_and_b32_e32 v86, 0xffff0000, v68
	s_add_u32 s12, s12, 0x80000
	s_addc_u32 s13, s13, 0
	v_mul_f32_e32 v83, s46, v83
	v_mul_f32_e32 v84, s46, v84
	v_fmac_f32_e32 v83, s47, v74
	v_fmac_f32_e32 v84, s47, v86
	s_waitcnt vmcnt(59)
	v_cvt_pk_bf16_f32 v72, v83, v84
	v_lshlrev_b32_e32 v74, 16, v69
	global_store_dword v4, v72, s[12:13]
	v_and_b32_e32 v86, 0xffff0000, v69
	s_add_u32 s12, s12, 0x80000
	s_addc_u32 s13, s13, 0
	v_mul_f32_e32 v83, s48, v83
	v_mul_f32_e32 v84, s48, v84
	v_fmac_f32_e32 v83, s49, v74
	v_fmac_f32_e32 v84, s49, v86
	s_cmp_lg_u32 s35, 0
	s_cbranch_scc1 .Lscan_nomst
	s_lshl_b32 s37, s34, 8
	s_add_u32 s40, s8, 0x61d00000
	s_addc_u32 s41, s9, 0
	s_add_u32 s40, s40, s37
	s_addc_u32 s41, s41, 0
	v_lshlrev_b32_e32 v72, 2, v2
	global_store_dword v72, v80, s[40:41]
.Lscan_nomst:
	s_cmp_gt_u32 s35, 3
	s_cbranch_scc1 .LBB0_1860
	s_waitcnt vmcnt(0)
	s_lshl_b32 s36, s35, 8
	s_lshl_b32 s37, s34, 10
	s_add_i32 s36, s36, s37
	v_lshl_add_u32 v4, v2, 2, s36
	s_add_u32 s10, s8, 0x61a00000
	s_addc_u32 s11, s9, 0
	s_add_u32 s12, s8, 0x61b00000
	s_addc_u32 s13, s9, 0
	global_load_dword v6, v4, s[10:11]
	s_add_u32 s10, s10, 0x1000
	s_addc_u32 s11, s11, 0
	global_load_dword v7, v4, s[10:11]
	s_add_u32 s10, s10, 0x1000
	s_addc_u32 s11, s11, 0
	global_load_dword v8, v4, s[10:11]
	s_add_u32 s10, s10, 0x1000
	s_addc_u32 s11, s11, 0
	global_load_dword v9, v4, s[10:11]
	s_add_u32 s10, s10, 0x1000
	s_addc_u32 s11, s11, 0
	global_load_dword v10, v4, s[10:11]
	s_add_u32 s10, s10, 0x1000
	s_addc_u32 s11, s11, 0
	global_load_dword v11, v4, s[10:11]
	s_add_u32 s10, s10, 0x1000
	s_addc_u32 s11, s11, 0
	global_load_dword v12, v4, s[10:11]
	s_add_u32 s10, s10, 0x1000
	s_addc_u32 s11, s11, 0
	global_load_dword v13, v4, s[10:11]
	s_add_u32 s10, s10, 0x1000
	s_addc_u32 s11, s11, 0
	global_load_dword v14, v4, s[10:11]
	s_add_u32 s10, s10, 0x1000
	s_addc_u32 s11, s11, 0
	global_load_dword v15, v4, s[10:11]
	s_add_u32 s10, s10, 0x1000
	s_addc_u32 s11, s11, 0
	global_load_dword v16, v4, s[10:11]
	s_add_u32 s10, s10, 0x1000
	s_addc_u32 s11, s11, 0
	global_load_dword v17, v4, s[10:11]
	s_add_u32 s10, s10, 0x1000
	s_addc_u32 s11, s11, 0
	global_load_dword v18, v4, s[10:11]
	s_add_u32 s10, s10, 0x1000
	s_addc_u32 s11, s11, 0
	global_load_dword v19, v4, s[10:11]
	s_add_u32 s10, s10, 0x1000
	s_addc_u32 s11, s11, 0
	global_load_dword v20, v4, s[10:11]
	s_add_u32 s10, s10, 0x1000
	s_addc_u32 s11, s11, 0
	global_load_dword v21, v4, s[10:11]
	s_add_u32 s10, s10, 0x1000
	s_addc_u32 s11, s11, 0
	global_load_dword v22, v4, s[10:11]
	s_add_u32 s10, s10, 0x1000
	s_addc_u32 s11, s11, 0
	global_load_dword v23, v4, s[10:11]
	s_add_u32 s10, s10, 0x1000
	s_addc_u32 s11, s11, 0
	global_load_dword v24, v4, s[10:11]
	s_add_u32 s10, s10, 0x1000
	s_addc_u32 s11, s11, 0
	global_load_dword v25, v4, s[10:11]
	s_add_u32 s10, s10, 0x1000
	s_addc_u32 s11, s11, 0
	global_load_dword v26, v4, s[10:11]
	s_add_u32 s10, s10, 0x1000
	s_addc_u32 s11, s11, 0
	global_load_dword v27, v4, s[10:11]
	s_add_u32 s10, s10, 0x1000
	s_addc_u32 s11, s11, 0
	global_load_dword v28, v4, s[10:11]
	s_add_u32 s10, s10, 0x1000
	s_addc_u32 s11, s11, 0
	global_load_dword v29, v4, s[10:11]
	s_add_u32 s10, s10, 0x1000
	s_addc_u32 s11, s11, 0
	global_load_dword v30, v4, s[10:11]
	s_add_u32 s10, s10, 0x1000
	s_addc_u32 s11, s11, 0
	global_load_dword v31, v4, s[10:11]
	s_add_u32 s10, s10, 0x1000
	s_addc_u32 s11, s11, 0
	global_load_dword v32, v4, s[10:11]
	s_add_u32 s10, s10, 0x1000
	s_addc_u32 s11, s11, 0
	global_load_dword v33, v4, s[10:11]
	s_add_u32 s10, s10, 0x1000
	s_addc_u32 s11, s11, 0
	global_load_dword v34, v4, s[10:11]
	s_add_u32 s10, s10, 0x1000
	s_addc_u32 s11, s11, 0
	global_load_dword v35, v4, s[10:11]
	s_add_u32 s10, s10, 0x1000
	s_addc_u32 s11, s11, 0
	global_load_dword v36, v4, s[10:11]
	s_add_u32 s10, s10, 0x1000
	s_addc_u32 s11, s11, 0
	global_load_dword v37, v4, s[10:11]
	s_add_u32 s10, s10, 0x1000
	s_addc_u32 s11, s11, 0
	global_load_dword v38, v4, s[10:11]
	s_add_u32 s10, s10, 0x1000
	s_addc_u32 s11, s11, 0
	global_load_dword v39, v4, s[10:11]
	s_add_u32 s10, s10, 0x1000
	s_addc_u32 s11, s11, 0
	global_load_dword v40, v4, s[10:11]
	s_add_u32 s10, s10, 0x1000
	s_addc_u32 s11, s11, 0
	global_load_dword v41, v4, s[10:11]
	s_add_u32 s10, s10, 0x1000
	s_addc_u32 s11, s11, 0
	global_load_dword v42, v4, s[10:11]
	s_add_u32 s10, s10, 0x1000
	s_addc_u32 s11, s11, 0
	global_load_dword v43, v4, s[10:11]
	s_add_u32 s10, s10, 0x1000
	s_addc_u32 s11, s11, 0
	global_load_dword v44, v4, s[10:11]
	s_add_u32 s10, s10, 0x1000
	s_addc_u32 s11, s11, 0
	global_load_dword v45, v4, s[10:11]
	s_add_u32 s10, s10, 0x1000
	s_addc_u32 s11, s11, 0
	global_load_dword v46, v4, s[10:11]
	s_add_u32 s10, s10, 0x1000
	s_addc_u32 s11, s11, 0
	global_load_dword v47, v4, s[10:11]
	s_add_u32 s10, s10, 0x1000
	s_addc_u32 s11, s11, 0
	global_load_dword v48, v4, s[10:11]
	s_add_u32 s10, s10, 0x1000
	s_addc_u32 s11, s11, 0
	global_load_dword v49, v4, s[10:11]
	s_add_u32 s10, s10, 0x1000
	s_addc_u32 s11, s11, 0
	global_load_dword v50, v4, s[10:11]
	s_add_u32 s10, s10, 0x1000
	s_addc_u32 s11, s11, 0
	global_load_dword v51, v4, s[10:11]
	s_add_u32 s10, s10, 0x1000
	s_addc_u32 s11, s11, 0
	global_load_dword v52, v4, s[10:11]
	s_add_u32 s10, s10, 0x1000
	s_addc_u32 s11, s11, 0
	global_load_dword v53, v4, s[10:11]
	s_add_u32 s10, s10, 0x1000
	s_addc_u32 s11, s11, 0
	global_load_dword v54, v4, s[10:11]
	s_add_u32 s10, s10, 0x1000
	s_addc_u32 s11, s11, 0
	global_load_dword v55, v4, s[10:11]
	s_add_u32 s10, s10, 0x1000
	s_addc_u32 s11, s11, 0
	global_load_dword v56, v4, s[10:11]
	s_add_u32 s10, s10, 0x1000
	s_addc_u32 s11, s11, 0
	global_load_dword v57, v4, s[10:11]
	s_add_u32 s10, s10, 0x1000
	s_addc_u32 s11, s11, 0
	global_load_dword v58, v4, s[10:11]
	s_add_u32 s10, s10, 0x1000
	s_addc_u32 s11, s11, 0
	global_load_dword v59, v4, s[10:11]
	s_add_u32 s10, s10, 0x1000
	s_addc_u32 s11, s11, 0
	global_load_dword v60, v4, s[10:11]
	s_add_u32 s10, s10, 0x1000
	s_addc_u32 s11, s11, 0
	global_load_dword v61, v4, s[10:11]
	s_add_u32 s10, s10, 0x1000
	s_addc_u32 s11, s11, 0
	global_load_dword v62, v4, s[10:11]
	s_add_u32 s10, s10, 0x1000
	s_addc_u32 s11, s11, 0
	global_load_dword v63, v4, s[10:11]
	s_add_u32 s10, s10, 0x1000
	s_addc_u32 s11, s11, 0
	global_load_dword v64, v4, s[10:11]
	s_add_u32 s10, s10, 0x1000
	s_addc_u32 s11, s11, 0
	global_load_dword v65, v4, s[10:11]
	s_add_u32 s10, s10, 0x1000
	s_addc_u32 s11, s11, 0
	v_mov_b32_e32 v83, 0
	v_readlane_b32 s42, v81, 0
	v_readlane_b32 s43, v82, 0
	v_readlane_b32 s44, v81, 1
	v_readlane_b32 s45, v82, 1
	v_readlane_b32 s46, v81, 2
	v_readlane_b32 s47, v82, 2
	s_waitcnt vmcnt(59)
	global_store_dword v4, v83, s[12:13]
	v_mul_f32_e32 v74, s43, v6
	s_add_u32 s12, s12, 0x1000
	s_addc_u32 s13, s13, 0
	v_mul_f32_e32 v86, s42, v83
	s_nop 0
	v_add_f32_e32 v83, v86, v74
	global_load_dword v66, v4, s[10:11]
	s_add_u32 s10, s10, 0x1000
	s_addc_u32 s11, s11, 0
	v_readlane_b32 s48, v81, 3
	v_readlane_b32 s49, v82, 3
	s_waitcnt vmcnt(60)
	global_store_dword v4, v83, s[12:13]
	v_mul_f32_e32 v74, s45, v7
	s_add_u32 s12, s12, 0x1000
	s_addc_u32 s13, s13, 0
	v_mul_f32_e32 v86, s44, v83
	s_nop 0
	v_add_f32_e32 v83, v86, v74
	global_load_dword v67, v4, s[10:11]
	s_add_u32 s10, s10, 0x1000
	s_addc_u32 s11, s11, 0
	v_readlane_b32 s42, v81, 4
	v_readlane_b32 s43, v82, 4
	s_waitcnt vmcnt(61)
	global_store_dword v4, v83, s[12:13]
	v_mul_f32_e32 v74, s47, v8
	s_add_u32 s12, s12, 0x1000
	s_addc_u32 s13, s13, 0
	v_mul_f32_e32 v86, s46, v83
	s_nop 0
	v_add_f32_e32 v83, v86, v74
	global_load_dword v68, v4, s[10:11]
	s_add_u32 s10, s10, 0x1000
	s_addc_u32 s11, s11, 0
	v_readlane_b32 s44, v81, 5
	v_readlane_b32 s45, v82, 5
	s_waitcnt vmcnt(62)
	global_store_dword v4, v83, s[12:13]
	v_mul_f32_e32 v74, s49, v9
	s_add_u32 s12, s12, 0x1000
	s_addc_u32 s13, s13, 0
	v_mul_f32_e32 v86, s48, v83
	s_nop 0
	v_add_f32_e32 v83, v86, v74
	global_load_dword v69, v4, s[10:11]
	s_add_u32 s10, s10, 0x1000
	s_addc_u32 s11, s11, 0
	v_readlane_b32 s46, v81, 6
	v_readlane_b32 s47, v82, 6
	s_waitcnt vmcnt(63)
	global_store_dword v4, v83, s[12:13]
	v_mul_f32_e32 v74, s43, v10
	s_add_u32 s12, s12, 0x1000
	s_addc_u32 s13, s13, 0
	v_mul_f32_e32 v86, s42, v83
	s_nop 0
	v_add_f32_e32 v83, v86, v74
	v_readlane_b32 s48, v81, 7
	v_readlane_b32 s49, v82, 7
	s_waitcnt vmcnt(63)
	global_store_dword v4, v83, s[12:13]
	v_mul_f32_e32 v74, s45, v11
	s_add_u32 s12, s12, 0x1000
	s_addc_u32 s13, s13, 0
	v_mul_f32_e32 v86, s44, v83
	s_nop 0
	v_add_f32_e32 v83, v86, v74
	v_readlane_b32 s42, v81, 8
	v_readlane_b32 s43, v82, 8
	s_waitcnt vmcnt(63)
	global_store_dword v4, v83, s[12:13]
	v_mul_f32_e32 v74, s47, v12
	s_add_u32 s12, s12, 0x1000
	s_addc_u32 s13, s13, 0
	v_mul_f32_e32 v86, s46, v83
	s_nop 0
	v_add_f32_e32 v83, v86, v74
	v_readlane_b32 s44, v81, 9
	v_readlane_b32 s45, v82, 9
	s_waitcnt vmcnt(63)
	global_store_dword v4, v83, s[12:13]
	v_mul_f32_e32 v74, s49, v13
	s_add_u32 s12, s12, 0x1000
	s_addc_u32 s13, s13, 0
	v_mul_f32_e32 v86, s48, v83
	s_nop 0
	v_add_f32_e32 v83, v86, v74
	v_readlane_b32 s46, v81, 10
	v_readlane_b32 s47, v82, 10
	s_waitcnt vmcnt(63)
	global_store_dword v4, v83, s[12:13]
	v_mul_f32_e32 v74, s43, v14
	s_add_u32 s12, s12, 0x1000
	s_addc_u32 s13, s13, 0
	v_mul_f32_e32 v86, s42, v83
	s_nop 0
	v_add_f32_e32 v83, v86, v74
	v_readlane_b32 s48, v81, 11
	v_readlane_b32 s49, v82, 11
	s_waitcnt vmcnt(63)
	global_store_dword v4, v83, s[12:13]
	v_mul_f32_e32 v74, s45, v15
	s_add_u32 s12, s12, 0x1000
	s_addc_u32 s13, s13, 0
	v_mul_f32_e32 v86, s44, v83
	s_nop 0
	v_add_f32_e32 v83, v86, v74
	v_readlane_b32 s42, v81, 12
	v_readlane_b32 s43, v82, 12
	s_waitcnt vmcnt(63)
	global_store_dword v4, v83, s[12:13]
	v_mul_f32_e32 v74, s47, v16
	s_add_u32 s12, s12, 0x1000
	s_addc_u32 s13, s13, 0
	v_mul_f32_e32 v86, s46, v83
	s_nop 0
	v_add_f32_e32 v83, v86, v74
	v_readlane_b32 s44, v81, 13
	v_readlane_b32 s45, v82, 13
	s_waitcnt vmcnt(63)
	global_store_dword v4, v83, s[12:13]
	v_mul_f32_e32 v74, s49, v17
	s_add_u32 s12, s12, 0x1000
	s_addc_u32 s13, s13, 0
	v_mul_f32_e32 v86, s48, v83
	s_nop 0
	v_add_f32_e32 v83, v86, v74
	v_readlane_b32 s46, v81, 14
	v_readlane_b32 s47, v82, 14
	s_waitcnt vmcnt(63)
	global_store_dword v4, v83, s[12:13]
	v_mul_f32_e32 v74, s43, v18
	s_add_u32 s12, s12, 0x1000
	s_addc_u32 s13, s13, 0
	v_mul_f32_e32 v86, s42, v83
	s_nop 0
	v_add_f32_e32 v83, v86, v74
	v_readlane_b32 s48, v81, 15
	v_readlane_b32 s49, v82, 15
	s_waitcnt vmcnt(63)
	global_store_dword v4, v83, s[12:13]
	v_mul_f32_e32 v74, s45, v19
	s_add_u32 s12, s12, 0x1000
	s_addc_u32 s13, s13, 0
	v_mul_f32_e32 v86, s44, v83
	s_nop 0
	v_add_f32_e32 v83, v86, v74
	v_readlane_b32 s42, v81, 16
	v_readlane_b32 s43, v82, 16
	s_waitcnt vmcnt(63)
	global_store_dword v4, v83, s[12:13]
	v_mul_f32_e32 v74, s47, v20
	s_add_u32 s12, s12, 0x1000
	s_addc_u32 s13, s13, 0
	v_mul_f32_e32 v86, s46, v83
	s_nop 0
	v_add_f32_e32 v83, v86, v74
	v_readlane_b32 s44, v81, 17
	v_readlane_b32 s45, v82, 17
	s_waitcnt vmcnt(63)
	global_store_dword v4, v83, s[12:13]
	v_mul_f32_e32 v74, s49, v21
	s_add_u32 s12, s12, 0x1000
	s_addc_u32 s13, s13, 0
	v_mul_f32_e32 v86, s48, v83
	s_nop 0
	v_add_f32_e32 v83, v86, v74
	v_readlane_b32 s46, v81, 18
	v_readlane_b32 s47, v82, 18
	s_waitcnt vmcnt(63)
	global_store_dword v4, v83, s[12:13]
	v_mul_f32_e32 v74, s43, v22
	s_add_u32 s12, s12, 0x1000
	s_addc_u32 s13, s13, 0
	v_mul_f32_e32 v86, s42, v83
	s_nop 0
	v_add_f32_e32 v83, v86, v74
	v_readlane_b32 s48, v81, 19
	v_readlane_b32 s49, v82, 19
	s_waitcnt vmcnt(63)
	global_store_dword v4, v83, s[12:13]
	v_mul_f32_e32 v74, s45, v23
	s_add_u32 s12, s12, 0x1000
	s_addc_u32 s13, s13, 0
	v_mul_f32_e32 v86, s44, v83
	s_nop 0
	v_add_f32_e32 v83, v86, v74
	v_readlane_b32 s42, v81, 20
	v_readlane_b32 s43, v82, 20
	s_waitcnt vmcnt(63)
	global_store_dword v4, v83, s[12:13]
	v_mul_f32_e32 v74, s47, v24
	s_add_u32 s12, s12, 0x1000
	s_addc_u32 s13, s13, 0
	v_mul_f32_e32 v86, s46, v83
	s_nop 0
	v_add_f32_e32 v83, v86, v74
	v_readlane_b32 s44, v81, 21
	v_readlane_b32 s45, v82, 21
	s_waitcnt vmcnt(63)
	global_store_dword v4, v83, s[12:13]
	v_mul_f32_e32 v74, s49, v25
	s_add_u32 s12, s12, 0x1000
	s_addc_u32 s13, s13, 0
	v_mul_f32_e32 v86, s48, v83
	s_nop 0
	v_add_f32_e32 v83, v86, v74
	v_readlane_b32 s46, v81, 22
	v_readlane_b32 s47, v82, 22
	s_waitcnt vmcnt(63)
	global_store_dword v4, v83, s[12:13]
	v_mul_f32_e32 v74, s43, v26
	s_add_u32 s12, s12, 0x1000
	s_addc_u32 s13, s13, 0
	v_mul_f32_e32 v86, s42, v83
	s_nop 0
	v_add_f32_e32 v83, v86, v74
	v_readlane_b32 s48, v81, 23
	v_readlane_b32 s49, v82, 23
	s_waitcnt vmcnt(63)
	global_store_dword v4, v83, s[12:13]
	v_mul_f32_e32 v74, s45, v27
	s_add_u32 s12, s12, 0x1000
	s_addc_u32 s13, s13, 0
	v_mul_f32_e32 v86, s44, v83
	s_nop 0
	v_add_f32_e32 v83, v86, v74
	v_readlane_b32 s42, v81, 24
	v_readlane_b32 s43, v82, 24
	s_waitcnt vmcnt(63)
	global_store_dword v4, v83, s[12:13]
	v_mul_f32_e32 v74, s47, v28
	s_add_u32 s12, s12, 0x1000
	s_addc_u32 s13, s13, 0
	v_mul_f32_e32 v86, s46, v83
	s_nop 0
	v_add_f32_e32 v83, v86, v74
	v_readlane_b32 s44, v81, 25
	v_readlane_b32 s45, v82, 25
	s_waitcnt vmcnt(63)
	global_store_dword v4, v83, s[12:13]
	v_mul_f32_e32 v74, s49, v29
	s_add_u32 s12, s12, 0x1000
	s_addc_u32 s13, s13, 0
	v_mul_f32_e32 v86, s48, v83
	s_nop 0
	v_add_f32_e32 v83, v86, v74
	v_readlane_b32 s46, v81, 26
	v_readlane_b32 s47, v82, 26
	s_waitcnt vmcnt(63)
	global_store_dword v4, v83, s[12:13]
	v_mul_f32_e32 v74, s43, v30
	s_add_u32 s12, s12, 0x1000
	s_addc_u32 s13, s13, 0
	v_mul_f32_e32 v86, s42, v83
	s_nop 0
	v_add_f32_e32 v83, v86, v74
	v_readlane_b32 s48, v81, 27
	v_readlane_b32 s49, v82, 27
	s_waitcnt vmcnt(63)
	global_store_dword v4, v83, s[12:13]
	v_mul_f32_e32 v74, s45, v31
	s_add_u32 s12, s12, 0x1000
	s_addc_u32 s13, s13, 0
	v_mul_f32_e32 v86, s44, v83
	s_nop 0
	v_add_f32_e32 v83, v86, v74
	v_readlane_b32 s42, v81, 28
	v_readlane_b32 s43, v82, 28
	s_waitcnt vmcnt(63)
	global_store_dword v4, v83, s[12:13]
	v_mul_f32_e32 v74, s47, v32
	s_add_u32 s12, s12, 0x1000
	s_addc_u32 s13, s13, 0
	v_mul_f32_e32 v86, s46, v83
	s_nop 0
	v_add_f32_e32 v83, v86, v74
	v_readlane_b32 s44, v81, 29
	v_readlane_b32 s45, v82, 29
	s_waitcnt vmcnt(63)
	global_store_dword v4, v83, s[12:13]
	v_mul_f32_e32 v74, s49, v33
	s_add_u32 s12, s12, 0x1000
	s_addc_u32 s13, s13, 0
	v_mul_f32_e32 v86, s48, v83
	s_nop 0
	v_add_f32_e32 v83, v86, v74
	v_readlane_b32 s46, v81, 30
	v_readlane_b32 s47, v82, 30
	s_waitcnt vmcnt(63)
	global_store_dword v4, v83, s[12:13]
	v_mul_f32_e32 v74, s43, v34
	s_add_u32 s12, s12, 0x1000
	s_addc_u32 s13, s13, 0
	v_mul_f32_e32 v86, s42, v83
	s_nop 0
	v_add_f32_e32 v83, v86, v74
	v_readlane_b32 s48, v81, 31
	v_readlane_b32 s49, v82, 31
	s_waitcnt vmcnt(63)
	global_store_dword v4, v83, s[12:13]
	v_mul_f32_e32 v74, s45, v35
	s_add_u32 s12, s12, 0x1000
	s_addc_u32 s13, s13, 0
	v_mul_f32_e32 v86, s44, v83
	s_nop 0
	v_add_f32_e32 v83, v86, v74
	v_readlane_b32 s42, v81, 32
	v_readlane_b32 s43, v82, 32
	s_waitcnt vmcnt(63)
	global_store_dword v4, v83, s[12:13]
	v_mul_f32_e32 v74, s47, v36
	s_add_u32 s12, s12, 0x1000
	s_addc_u32 s13, s13, 0
	v_mul_f32_e32 v86, s46, v83
	s_nop 0
	v_add_f32_e32 v83, v86, v74
	v_readlane_b32 s44, v81, 33
	v_readlane_b32 s45, v82, 33
	s_waitcnt vmcnt(63)
	global_store_dword v4, v83, s[12:13]
	v_mul_f32_e32 v74, s49, v37
	s_add_u32 s12, s12, 0x1000
	s_addc_u32 s13, s13, 0
	v_mul_f32_e32 v86, s48, v83
	s_nop 0
	v_add_f32_e32 v83, v86, v74
	v_readlane_b32 s46, v81, 34
	v_readlane_b32 s47, v82, 34
	s_waitcnt vmcnt(63)
	global_store_dword v4, v83, s[12:13]
	v_mul_f32_e32 v74, s43, v38
	s_add_u32 s12, s12, 0x1000
	s_addc_u32 s13, s13, 0
	v_mul_f32_e32 v86, s42, v83
	s_nop 0
	v_add_f32_e32 v83, v86, v74
	v_readlane_b32 s48, v81, 35
	v_readlane_b32 s49, v82, 35
	s_waitcnt vmcnt(63)
	global_store_dword v4, v83, s[12:13]
	v_mul_f32_e32 v74, s45, v39
	s_add_u32 s12, s12, 0x1000
	s_addc_u32 s13, s13, 0
	v_mul_f32_e32 v86, s44, v83
	s_nop 0
	v_add_f32_e32 v83, v86, v74
	v_readlane_b32 s42, v81, 36
	v_readlane_b32 s43, v82, 36
	s_waitcnt vmcnt(63)
	global_store_dword v4, v83, s[12:13]
	v_mul_f32_e32 v74, s47, v40
	s_add_u32 s12, s12, 0x1000
	s_addc_u32 s13, s13, 0
	v_mul_f32_e32 v86, s46, v83
	s_nop 0
	v_add_f32_e32 v83, v86, v74
	v_readlane_b32 s44, v81, 37
	v_readlane_b32 s45, v82, 37
	s_waitcnt vmcnt(63)
	global_store_dword v4, v83, s[12:13]
	v_mul_f32_e32 v74, s49, v41
	s_add_u32 s12, s12, 0x1000
	s_addc_u32 s13, s13, 0
	v_mul_f32_e32 v86, s48, v83
	s_nop 0
	v_add_f32_e32 v83, v86, v74
	v_readlane_b32 s46, v81, 38
	v_readlane_b32 s47, v82, 38
	s_waitcnt vmcnt(63)
	global_store_dword v4, v83, s[12:13]
	v_mul_f32_e32 v74, s43, v42
	s_add_u32 s12, s12, 0x1000
	s_addc_u32 s13, s13, 0
	v_mul_f32_e32 v86, s42, v83
	s_nop 0
	v_add_f32_e32 v83, v86, v74
	v_readlane_b32 s48, v81, 39
	v_readlane_b32 s49, v82, 39
	s_waitcnt vmcnt(63)
	global_store_dword v4, v83, s[12:13]
	v_mul_f32_e32 v74, s45, v43
	s_add_u32 s12, s12, 0x1000
	s_addc_u32 s13, s13, 0
	v_mul_f32_e32 v86, s44, v83
	s_nop 0
	v_add_f32_e32 v83, v86, v74
	v_readlane_b32 s42, v81, 40
	v_readlane_b32 s43, v82, 40
	s_waitcnt vmcnt(63)
	global_store_dword v4, v83, s[12:13]
	v_mul_f32_e32 v74, s47, v44
	s_add_u32 s12, s12, 0x1000
	s_addc_u32 s13, s13, 0
	v_mul_f32_e32 v86, s46, v83
	s_nop 0
	v_add_f32_e32 v83, v86, v74
	v_readlane_b32 s44, v81, 41
	v_readlane_b32 s45, v82, 41
	s_waitcnt vmcnt(63)
	global_store_dword v4, v83, s[12:13]
	v_mul_f32_e32 v74, s49, v45
	s_add_u32 s12, s12, 0x1000
	s_addc_u32 s13, s13, 0
	v_mul_f32_e32 v86, s48, v83
	s_nop 0
	v_add_f32_e32 v83, v86, v74
	v_readlane_b32 s46, v81, 42
	v_readlane_b32 s47, v82, 42
	s_waitcnt vmcnt(63)
	global_store_dword v4, v83, s[12:13]
	v_mul_f32_e32 v74, s43, v46
	s_add_u32 s12, s12, 0x1000
	s_addc_u32 s13, s13, 0
	v_mul_f32_e32 v86, s42, v83
	s_nop 0
	v_add_f32_e32 v83, v86, v74
	v_readlane_b32 s48, v81, 43
	v_readlane_b32 s49, v82, 43
	s_waitcnt vmcnt(63)
	global_store_dword v4, v83, s[12:13]
	v_mul_f32_e32 v74, s45, v47
	s_add_u32 s12, s12, 0x1000
	s_addc_u32 s13, s13, 0
	v_mul_f32_e32 v86, s44, v83
	s_nop 0
	v_add_f32_e32 v83, v86, v74
	v_readlane_b32 s42, v81, 44
	v_readlane_b32 s43, v82, 44
	s_waitcnt vmcnt(63)
	global_store_dword v4, v83, s[12:13]
	v_mul_f32_e32 v74, s47, v48
	s_add_u32 s12, s12, 0x1000
	s_addc_u32 s13, s13, 0
	v_mul_f32_e32 v86, s46, v83
	s_nop 0
	v_add_f32_e32 v83, v86, v74
	v_readlane_b32 s44, v81, 45
	v_readlane_b32 s45, v82, 45
	s_waitcnt vmcnt(63)
	global_store_dword v4, v83, s[12:13]
	v_mul_f32_e32 v74, s49, v49
	s_add_u32 s12, s12, 0x1000
	s_addc_u32 s13, s13, 0
	v_mul_f32_e32 v86, s48, v83
	s_nop 0
	v_add_f32_e32 v83, v86, v74
	v_readlane_b32 s46, v81, 46
	v_readlane_b32 s47, v82, 46
	s_waitcnt vmcnt(63)
	global_store_dword v4, v83, s[12:13]
	v_mul_f32_e32 v74, s43, v50
	s_add_u32 s12, s12, 0x1000
	s_addc_u32 s13, s13, 0
	v_mul_f32_e32 v86, s42, v83
	s_nop 0
	v_add_f32_e32 v83, v86, v74
	v_readlane_b32 s48, v81, 47
	v_readlane_b32 s49, v82, 47
	s_waitcnt vmcnt(63)
	global_store_dword v4, v83, s[12:13]
	v_mul_f32_e32 v74, s45, v51
	s_add_u32 s12, s12, 0x1000
	s_addc_u32 s13, s13, 0
	v_mul_f32_e32 v86, s44, v83
	s_nop 0
	v_add_f32_e32 v83, v86, v74
	v_readlane_b32 s42, v81, 48
	v_readlane_b32 s43, v82, 48
	s_waitcnt vmcnt(63)
	global_store_dword v4, v83, s[12:13]
	v_mul_f32_e32 v74, s47, v52
	s_add_u32 s12, s12, 0x1000
	s_addc_u32 s13, s13, 0
	v_mul_f32_e32 v86, s46, v83
	s_nop 0
	v_add_f32_e32 v83, v86, v74
	v_readlane_b32 s44, v81, 49
	v_readlane_b32 s45, v82, 49
	s_waitcnt vmcnt(63)
	global_store_dword v4, v83, s[12:13]
	v_mul_f32_e32 v74, s49, v53
	s_add_u32 s12, s12, 0x1000
	s_addc_u32 s13, s13, 0
	v_mul_f32_e32 v86, s48, v83
	s_nop 0
	v_add_f32_e32 v83, v86, v74
	v_readlane_b32 s46, v81, 50
	v_readlane_b32 s47, v82, 50
	s_waitcnt vmcnt(63)
	global_store_dword v4, v83, s[12:13]
	v_mul_f32_e32 v74, s43, v54
	s_add_u32 s12, s12, 0x1000
	s_addc_u32 s13, s13, 0
	v_mul_f32_e32 v86, s42, v83
	s_nop 0
	v_add_f32_e32 v83, v86, v74
	v_readlane_b32 s48, v81, 51
	v_readlane_b32 s49, v82, 51
	s_waitcnt vmcnt(63)
	global_store_dword v4, v83, s[12:13]
	v_mul_f32_e32 v74, s45, v55
	s_add_u32 s12, s12, 0x1000
	s_addc_u32 s13, s13, 0
	v_mul_f32_e32 v86, s44, v83
	s_nop 0
	v_add_f32_e32 v83, v86, v74
	v_readlane_b32 s42, v81, 52
	v_readlane_b32 s43, v82, 52
	s_waitcnt vmcnt(63)
	global_store_dword v4, v83, s[12:13]
	v_mul_f32_e32 v74, s47, v56
	s_add_u32 s12, s12, 0x1000
	s_addc_u32 s13, s13, 0
	v_mul_f32_e32 v86, s46, v83
	s_nop 0
	v_add_f32_e32 v83, v86, v74
	v_readlane_b32 s44, v81, 53
	v_readlane_b32 s45, v82, 53
	s_waitcnt vmcnt(63)
	global_store_dword v4, v83, s[12:13]
	v_mul_f32_e32 v74, s49, v57
	s_add_u32 s12, s12, 0x1000
	s_addc_u32 s13, s13, 0
	v_mul_f32_e32 v86, s48, v83
	s_nop 0
	v_add_f32_e32 v83, v86, v74
	v_readlane_b32 s46, v81, 54
	v_readlane_b32 s47, v82, 54
	s_waitcnt vmcnt(63)
	global_store_dword v4, v83, s[12:13]
	v_mul_f32_e32 v74, s43, v58
	s_add_u32 s12, s12, 0x1000
	s_addc_u32 s13, s13, 0
	v_mul_f32_e32 v86, s42, v83
	s_nop 0
	v_add_f32_e32 v83, v86, v74
	v_readlane_b32 s48, v81, 55
	v_readlane_b32 s49, v82, 55
	s_waitcnt vmcnt(63)
	global_store_dword v4, v83, s[12:13]
	v_mul_f32_e32 v74, s45, v59
	s_add_u32 s12, s12, 0x1000
	s_addc_u32 s13, s13, 0
	v_mul_f32_e32 v86, s44, v83
	s_nop 0
	v_add_f32_e32 v83, v86, v74
	v_readlane_b32 s42, v81, 56
	v_readlane_b32 s43, v82, 56
	s_waitcnt vmcnt(63)
	global_store_dword v4, v83, s[12:13]
	v_mul_f32_e32 v74, s47, v60
	s_add_u32 s12, s12, 0x1000
	s_addc_u32 s13, s13, 0
	v_mul_f32_e32 v86, s46, v83
	s_nop 0
	v_add_f32_e32 v83, v86, v74
	v_readlane_b32 s44, v81, 57
	v_readlane_b32 s45, v82, 57
	s_waitcnt vmcnt(63)
	global_store_dword v4, v83, s[12:13]
	v_mul_f32_e32 v74, s49, v61
	s_add_u32 s12, s12, 0x1000
	s_addc_u32 s13, s13, 0
	v_mul_f32_e32 v86, s48, v83
	s_nop 0
	v_add_f32_e32 v83, v86, v74
	v_readlane_b32 s46, v81, 58
	v_readlane_b32 s47, v82, 58
	s_waitcnt vmcnt(63)
	global_store_dword v4, v83, s[12:13]
	v_mul_f32_e32 v74, s43, v62
	s_add_u32 s12, s12, 0x1000
	s_addc_u32 s13, s13, 0
	v_mul_f32_e32 v86, s42, v83
	s_nop 0
	v_add_f32_e32 v83, v86, v74
	v_readlane_b32 s48, v81, 59
	v_readlane_b32 s49, v82, 59
	s_waitcnt vmcnt(63)
	global_store_dword v4, v83, s[12:13]
	v_mul_f32_e32 v74, s45, v63
	s_add_u32 s12, s12, 0x1000
	s_addc_u32 s13, s13, 0
	v_mul_f32_e32 v86, s44, v83
	s_nop 0
	v_add_f32_e32 v83, v86, v74
	v_readlane_b32 s42, v81, 60
	v_readlane_b32 s43, v82, 60
	s_waitcnt vmcnt(63)
	global_store_dword v4, v83, s[12:13]
	v_mul_f32_e32 v74, s47, v64
	s_add_u32 s12, s12, 0x1000
	s_addc_u32 s13, s13, 0
	v_mul_f32_e32 v86, s46, v83
	s_nop 0
	v_add_f32_e32 v83, v86, v74
	v_readlane_b32 s44, v81, 61
	v_readlane_b32 s45, v82, 61
	s_waitcnt vmcnt(63)
	global_store_dword v4, v83, s[12:13]
	v_mul_f32_e32 v74, s49, v65
	s_add_u32 s12, s12, 0x1000
	s_addc_u32 s13, s13, 0
	v_mul_f32_e32 v86, s48, v83
	s_nop 0
	v_add_f32_e32 v83, v86, v74
	v_readlane_b32 s46, v81, 62
	v_readlane_b32 s47, v82, 62
	s_waitcnt vmcnt(62)
	global_store_dword v4, v83, s[12:13]
	v_mul_f32_e32 v74, s43, v66
	s_add_u32 s12, s12, 0x1000
	s_addc_u32 s13, s13, 0
	v_mul_f32_e32 v86, s42, v83
	s_nop 0
	v_add_f32_e32 v83, v86, v74
	v_readlane_b32 s48, v81, 63
	v_readlane_b32 s49, v82, 63
	s_waitcnt vmcnt(61)
	global_store_dword v4, v83, s[12:13]
	v_mul_f32_e32 v74, s45, v67
	s_add_u32 s12, s12, 0x1000
	s_addc_u32 s13, s13, 0
	v_mul_f32_e32 v86, s44, v83
	s_nop 0
	v_add_f32_e32 v83, v86, v74
	s_waitcnt vmcnt(60)
	global_store_dword v4, v83, s[12:13]
	v_mul_f32_e32 v74, s47, v68
	s_add_u32 s12, s12, 0x1000
	s_addc_u32 s13, s13, 0
	v_mul_f32_e32 v86, s46, v83
	s_nop 0
	v_add_f32_e32 v83, v86, v74
	s_waitcnt vmcnt(59)
	global_store_dword v4, v83, s[12:13]
	v_mul_f32_e32 v74, s49, v69
	s_add_u32 s12, s12, 0x1000
	s_addc_u32 s13, s13, 0
	v_mul_f32_e32 v86, s48, v83
	s_nop 0
	v_add_f32_e32 v83, v86, v74

; #define PG8_STAGE(bufoff, gbase, voff) do { _Pragma("unroll") for (int _i = 0; _i < 2; ++_i) \
;         __builtin_amdgcn_global_load_lds((const unsigned*)((const char*)(gbase) + (voff)[_i]), (PG8_LAS unsigned*)(lds + (bufoff) + ldsw + _i * 8192), 16, 0, 0); } while (0)
; #define PG8_LDA(dst, b, h) do { _Pragma("unroll") for (int m = 0; m < 4; ++m) _Pragma("unroll") for (int k = 0; k < 2; ++k) dst[m][k] = *(const PG8_LAS bf16x8*)(lds + PG8_SA(b, h) + aoff + m * 2048 + k * 1024); } while (0)
; #define PG8_LDB(dst, b, h) do { _Pragma("unroll") for (int n = 0; n < 2; ++n) _Pragma("unroll") for (int k = 0; k < 2; ++k) dst[n][k] = *(const PG8_LAS bf16x8*)(lds + PG8_SB(b, h) + boff + n * 2048 + k * 1024); } while (0)
; #define PG8_MMA(ai, bj, At, Bt) do { __builtin_amdgcn_s_setprio(1); _Pragma("unroll") for (int m = 0; m < 4; ++m) _Pragma("unroll") for (int n = 0; n < 2; ++n) _Pragma("unroll") for (int k = 0; k < 2; ++k) \
;         acc[ai][bj][m][n] = __builtin_amdgcn_mfma_f32_16x16x32_bf16(Bt[n][k], At[m][k], acc[ai][bj][m][n], 0, 0, 0); __builtin_amdgcn_s_setprio(0); } while (0)
; #define PG8_WAIT_V(n) asm volatile("s_waitcnt vmcnt(" #n ")" ::: "memory")
; #define PG8_WAIT_L(n) asm volatile("s_waitcnt lgkmcnt(" #n ")" ::: "memory")
; #define PG8_BAR __builtin_amdgcn_s_barrier()
; #define PG8_SCHED __builtin_amdgcn_sched_barrier(0)
; template <class Epi, class Sched, bool ALIGN_EPI = false, bool SP2 = false>
; __device__ __forceinline__ void gemm_phase(PG8_LAS unsigned char* lds, const Gemm g, const Sched& S, const Epi& E) {
;     ...
;             PG8_LDB(B0, 0, 0); PG8_LDB(B1, 0, 1); PG8_SCHED; PG8_LDA(At, 0, 0); PG8_STAGE(PG8_SA(1, 1), a1 + hstep, voffA);
;             PG8_WAIT_V(8); PG8_WAIT_L(0); PG8_BAR; PG8_MMA(0, 0, At, B0); PG8_MMA(0, 1, At, B1); PG8_BAR; PG8_SCHED;
;             PG8_LDA(At, 0, 1); PG8_STAGE(PG8_SB(0, 0), b2, voffB); PG8_STAGE(PG8_SB(0, 1), b2 + hstep, voffB); PG8_STAGE(PG8_SA(0, 0), a2, voffA);
.LBB0_2095:
	s_add_u32 s40, s40, 0x40080
	s_addc_u32 s41, s41, 0
	s_add_u32 s11, s42, 0x100
	s_addc_u32 s13, s43, 0
	s_mov_b32 s26, -2
	.p2align 6
	s_nop 0
.LBB0_2096:
	s_add_u32 s27, s40, 0xfffc0080
	s_addc_u32 s29, s41, -1
	s_add_i32 s31, 0, 0x10000
	s_cmp_eq_u32 s26, 12
	s_cselect_b32 s45, s1, s29
	s_cselect_b32 s44, s0, s27
	v_add_u32_e32 v2, s31, v173
	s_cselect_b32 s43, s35, s13
	s_cselect_b32 s42, s34, s11
	s_add_i32 s27, 0, 0x14000
	ds_read_b128 v[134:137], v2
	ds_read_b128 v[138:141], v2 offset:1024
	ds_read_b128 v[154:157], v2 offset:2048
	ds_read_b128 v[158:161], v2 offset:3072
	v_add_u32_e32 v2, s27, v173
	ds_read_b128 v[178:181], v2
	ds_read_b128 v[204:207], v2 offset:1024
	ds_read_b128 v[208:211], v2 offset:2048
	ds_read_b128 v[212:215], v2 offset:3072
	s_add_i32 m0, s55, 0xc000
	ds_read_b128 v[216:219], v177
	ds_read_b128 v[220:223], v177 offset:1024
	ds_read_b128 v[224:227], v177 offset:2048
	ds_read_b128 v[228:231], v177 offset:3072
	ds_read_b128 v[232:235], v177 offset:4096
	ds_read_b128 v[236:239], v177 offset:5120
	ds_read_b128 v[240:243], v177 offset:6144
	ds_read_b128 v[244:247], v177 offset:7168
	global_load_lds_dwordx4 v150, s[40:41]
	s_add_i32 m0, s55, 0xe000
	s_nop 0
	global_load_lds_dwordx4 v152, s[40:41]
	s_waitcnt vmcnt(8)
	s_waitcnt lgkmcnt(0)
	s_barrier
	s_setprio 1
	s_waitcnt lgkmcnt(0)
	v_mfma_f32_16x16x32_bf16 v[130:133], v[134:137], v[216:219], v[130:133]
	v_mfma_f32_16x16x32_bf16 v[126:129], v[154:157], v[216:219], v[126:129]
	v_mfma_f32_16x16x32_bf16 v[122:125], v[134:137], v[224:227], v[122:125]
	v_mfma_f32_16x16x32_bf16 v[118:121], v[154:157], v[224:227], v[118:121]
	v_mfma_f32_16x16x32_bf16 v[114:117], v[134:137], v[232:235], v[114:117]
	v_mfma_f32_16x16x32_bf16 v[110:113], v[154:157], v[232:235], v[110:113]
	v_mfma_f32_16x16x32_bf16 v[106:109], v[134:137], v[240:243], v[106:109]
	v_mfma_f32_16x16x32_bf16 v[102:105], v[154:157], v[240:243], v[102:105]
	v_mfma_f32_16x16x32_bf16 v[130:133], v[138:141], v[220:223], v[130:133]
	v_mfma_f32_16x16x32_bf16 v[126:129], v[158:161], v[220:223], v[126:129]
	v_mfma_f32_16x16x32_bf16 v[122:125], v[138:141], v[228:231], v[122:125]
	v_mfma_f32_16x16x32_bf16 v[118:121], v[158:161], v[228:231], v[118:121]
	v_mfma_f32_16x16x32_bf16 v[114:117], v[138:141], v[236:239], v[114:117]
	v_mfma_f32_16x16x32_bf16 v[110:113], v[158:161], v[236:239], v[110:113]
	v_mfma_f32_16x16x32_bf16 v[106:109], v[138:141], v[244:247], v[106:109]
	v_mfma_f32_16x16x32_bf16 v[102:105], v[158:161], v[244:247], v[102:105]
	s_setprio 0
	s_setprio 1
	v_mfma_f32_16x16x32_bf16 v[98:101], v[178:181], v[216:219], v[98:101]
	v_mfma_f32_16x16x32_bf16 v[94:97], v[208:211], v[216:219], v[94:97]
	v_mfma_f32_16x16x32_bf16 v[90:93], v[178:181], v[224:227], v[90:93]
	v_mfma_f32_16x16x32_bf16 v[86:89], v[208:211], v[224:227], v[86:89]
	v_mfma_f32_16x16x32_bf16 v[82:85], v[178:181], v[232:235], v[82:85]
	v_mfma_f32_16x16x32_bf16 v[78:81], v[208:211], v[232:235], v[78:81]
	v_mfma_f32_16x16x32_bf16 v[74:77], v[178:181], v[240:243], v[74:77]
	v_mfma_f32_16x16x32_bf16 v[70:73], v[208:211], v[240:243], v[70:73]
	v_mfma_f32_16x16x32_bf16 v[98:101], v[204:207], v[220:223], v[98:101]
	v_mfma_f32_16x16x32_bf16 v[94:97], v[212:215], v[220:223], v[94:97]
	v_mfma_f32_16x16x32_bf16 v[90:93], v[204:207], v[228:231], v[90:93]
	v_mfma_f32_16x16x32_bf16 v[86:89], v[212:215], v[228:231], v[86:89]
	v_mfma_f32_16x16x32_bf16 v[82:85], v[204:207], v[236:239], v[82:85]
	v_mfma_f32_16x16x32_bf16 v[78:81], v[212:215], v[236:239], v[78:81]
	v_mfma_f32_16x16x32_bf16 v[74:77], v[204:207], v[244:247], v[74:77]
	v_mfma_f32_16x16x32_bf16 v[70:73], v[212:215], v[244:247], v[70:73]
	s_setprio 0
	s_barrier
	s_add_i32 s29, s31, s54
	s_mov_b32 m0, s29
	ds_read_b128 v[216:219], v177 offset:16384
	ds_read_b128 v[220:223], v177 offset:17408
	ds_read_b128 v[224:227], v177 offset:18432
	ds_read_b128 v[228:231], v177 offset:19456
	ds_read_b128 v[232:235], v177 offset:20480
	ds_read_b128 v[236:239], v177 offset:21504
	ds_read_b128 v[240:243], v177 offset:22528
	ds_read_b128 v[244:247], v177 offset:23552
	global_load_lds_dwordx4 v144, s[42:43]
	s_add_i32 m0, s29, 0x2000
	s_add_u32 s64, s42, 0x40000
	s_addc_u32 s65, s43, 0
	s_add_i32 s27, s27, s54
	global_load_lds_dwordx4 v148, s[42:43]
	s_mov_b32 m0, s27
	s_nop 0
	global_load_lds_dwordx4 v144, s[64:65]
	s_add_i32 m0, s27, 0x2000
	s_nop 0
	global_load_lds_dwordx4 v148, s[64:65]
	s_mov_b32 m0, s55
	s_nop 0
	global_load_lds_dwordx4 v142, s[44:45]
	s_mov_b32 m0, s56
	s_nop 0
	global_load_lds_dwordx4 v146, s[44:45]
	s_waitcnt vmcnt(8)
	s_waitcnt lgkmcnt(0)
	s_barrier
; #define PG8_STAGE(bufoff, gbase, voff) do { _Pragma("unroll") for (int _i = 0; _i < 2; ++_i) \
;         __builtin_amdgcn_global_load_lds((const unsigned*)((const char*)(gbase) + (voff)[_i]), (PG8_LAS unsigned*)(lds + (bufoff) + ldsw + _i * 8192), 16, 0, 0); } while (0)
; #define PG8_LDA(dst, b, h) do { _Pragma("unroll") for (int m = 0; m < 4; ++m) _Pragma("unroll") for (int k = 0; k < 2; ++k) dst[m][k] = *(const PG8_LAS bf16x8*)(lds + PG8_SA(b, h) + aoff + m * 2048 + k * 1024); } while (0)
; #define PG8_LDB(dst, b, h) do { _Pragma("unroll") for (int n = 0; n < 2; ++n) _Pragma("unroll") for (int k = 0; k < 2; ++k) dst[n][k] = *(const PG8_LAS bf16x8*)(lds + PG8_SB(b, h) + boff + n * 2048 + k * 1024); } while (0)
; #define PG8_MMA(ai, bj, At, Bt) do { __builtin_amdgcn_s_setprio(1); _Pragma("unroll") for (int m = 0; m < 4; ++m) _Pragma("unroll") for (int n = 0; n < 2; ++n) _Pragma("unroll") for (int k = 0; k < 2; ++k) \
;         acc[ai][bj][m][n] = __builtin_amdgcn_mfma_f32_16x16x32_bf16(Bt[n][k], At[m][k], acc[ai][bj][m][n], 0, 0, 0); __builtin_amdgcn_s_setprio(0); } while (0)
; #define PG8_WAIT_V(n) asm volatile("s_waitcnt vmcnt(" #n ")" ::: "memory")
; #define PG8_WAIT_L(n) asm volatile("s_waitcnt lgkmcnt(" #n ")" ::: "memory")
; #define PG8_BAR __builtin_amdgcn_s_barrier()
; #define PG8_SCHED __builtin_amdgcn_sched_barrier(0)
; template <class Epi, class Sched, bool ALIGN_EPI = false, bool SP2 = false>
; __device__ __forceinline__ void gemm_phase(PG8_LAS unsigned char* lds, const Gemm g, const Sched& S, const Epi& E) {
;     ...
;             PG8_WAIT_V(8); PG8_WAIT_L(0); PG8_BAR; PG8_MMA(1, 0, At, B0); PG8_MMA(1, 1, At, B1); PG8_BAR; PG8_SCHED;
;             PG8_LDB(B0, 1, 0); PG8_LDB(B1, 1, 1); PG8_SCHED; PG8_LDA(At, 1, 0); PG8_STAGE(PG8_SA(0, 1), a2 + hstep, voffA);
	s_setprio 1
	s_waitcnt lgkmcnt(0)
	v_mfma_f32_16x16x32_bf16 v[66:69], v[134:137], v[216:219], v[66:69]
	v_mfma_f32_16x16x32_bf16 v[62:65], v[154:157], v[216:219], v[62:65]
	v_mfma_f32_16x16x32_bf16 v[58:61], v[134:137], v[224:227], v[58:61]
	v_mfma_f32_16x16x32_bf16 v[54:57], v[154:157], v[224:227], v[54:57]
	v_mfma_f32_16x16x32_bf16 v[50:53], v[134:137], v[232:235], v[50:53]
	v_mfma_f32_16x16x32_bf16 v[46:49], v[154:157], v[232:235], v[46:49]
	v_mfma_f32_16x16x32_bf16 v[42:45], v[134:137], v[240:243], v[42:45]
	v_mfma_f32_16x16x32_bf16 v[38:41], v[154:157], v[240:243], v[38:41]
	v_mfma_f32_16x16x32_bf16 v[66:69], v[138:141], v[220:223], v[66:69]
	v_mfma_f32_16x16x32_bf16 v[62:65], v[158:161], v[220:223], v[62:65]
	v_mfma_f32_16x16x32_bf16 v[58:61], v[138:141], v[228:231], v[58:61]
	v_mfma_f32_16x16x32_bf16 v[54:57], v[158:161], v[228:231], v[54:57]
	v_mfma_f32_16x16x32_bf16 v[50:53], v[138:141], v[236:239], v[50:53]
	v_mfma_f32_16x16x32_bf16 v[46:49], v[158:161], v[236:239], v[46:49]
	v_mfma_f32_16x16x32_bf16 v[42:45], v[138:141], v[244:247], v[42:45]
	v_mfma_f32_16x16x32_bf16 v[38:41], v[158:161], v[244:247], v[38:41]
	s_setprio 0
	s_setprio 1
	v_mfma_f32_16x16x32_bf16 v[34:37], v[178:181], v[216:219], v[34:37]
	v_mfma_f32_16x16x32_bf16 v[30:33], v[208:211], v[216:219], v[30:33]
	v_mfma_f32_16x16x32_bf16 v[26:29], v[178:181], v[224:227], v[26:29]
	v_mfma_f32_16x16x32_bf16 v[22:25], v[208:211], v[224:227], v[22:25]
	v_mfma_f32_16x16x32_bf16 v[18:21], v[178:181], v[232:235], v[18:21]
	v_mfma_f32_16x16x32_bf16 v[14:17], v[208:211], v[232:235], v[14:17]
	v_mfma_f32_16x16x32_bf16 v[10:13], v[178:181], v[240:243], v[10:13]
	v_mfma_f32_16x16x32_bf16 v[4:7], v[208:211], v[240:243], v[6:9]
	v_mfma_f32_16x16x32_bf16 v[34:37], v[204:207], v[220:223], v[34:37]
	v_mfma_f32_16x16x32_bf16 v[30:33], v[212:215], v[220:223], v[30:33]
	v_mfma_f32_16x16x32_bf16 v[26:29], v[204:207], v[228:231], v[26:29]
	v_mfma_f32_16x16x32_bf16 v[22:25], v[212:215], v[228:231], v[22:25]
	v_mfma_f32_16x16x32_bf16 v[18:21], v[204:207], v[236:239], v[18:21]
	v_mfma_f32_16x16x32_bf16 v[14:17], v[212:215], v[236:239], v[14:17]
	v_mfma_f32_16x16x32_bf16 v[10:13], v[204:207], v[244:247], v[10:13]
	v_mfma_f32_16x16x32_bf16 v[4:7], v[212:215], v[244:247], v[4:7]
	s_setprio 0
	s_barrier
	s_add_i32 s27, 0, 0x18000
	v_add_u32_e32 v2, s27, v173
	s_add_i32 s29, 0, 0x1c000
	ds_read_b128 v[134:137], v2
	ds_read_b128 v[138:141], v2 offset:1024
	ds_read_b128 v[154:157], v2 offset:2048
	ds_read_b128 v[158:161], v2 offset:3072
	v_add_u32_e32 v2, s29, v173
	ds_read_b128 v[178:181], v2
	ds_read_b128 v[204:207], v2 offset:1024
	ds_read_b128 v[208:211], v2 offset:2048
	ds_read_b128 v[212:215], v2 offset:3072
	s_add_u32 s100, s44, 0x80
	s_addc_u32 s101, s45, 0
	s_add_u32 s44, s44, 0x40000
	s_addc_u32 s45, s45, 0
	s_mov_b32 m0, s57
	ds_read_b128 v[216:219], v177 offset:32768
	ds_read_b128 v[220:223], v177 offset:33792
	ds_read_b128 v[224:227], v177 offset:34816
	ds_read_b128 v[228:231], v177 offset:35840
	ds_read_b128 v[232:235], v177 offset:36864
	ds_read_b128 v[236:239], v177 offset:37888
	ds_read_b128 v[240:243], v177 offset:38912
	ds_read_b128 v[244:247], v177 offset:39936
	global_load_lds_dwordx4 v142, s[44:45]
	s_mov_b32 m0, s58
	s_nop 0
	global_load_lds_dwordx4 v146, s[44:45]
	s_waitcnt vmcnt(8)
	s_waitcnt lgkmcnt(0)
	s_barrier
	s_setprio 1
	s_waitcnt lgkmcnt(0)
	v_mfma_f32_16x16x32_bf16 v[130:133], v[134:137], v[216:219], v[130:133]
	v_mfma_f32_16x16x32_bf16 v[126:129], v[154:157], v[216:219], v[126:129]
	v_mfma_f32_16x16x32_bf16 v[122:125], v[134:137], v[224:227], v[122:125]
	v_mfma_f32_16x16x32_bf16 v[118:121], v[154:157], v[224:227], v[118:121]
	v_mfma_f32_16x16x32_bf16 v[114:117], v[134:137], v[232:235], v[114:117]
	v_mfma_f32_16x16x32_bf16 v[110:113], v[154:157], v[232:235], v[110:113]
	v_mfma_f32_16x16x32_bf16 v[106:109], v[134:137], v[240:243], v[106:109]
	v_mfma_f32_16x16x32_bf16 v[102:105], v[154:157], v[240:243], v[102:105]
	v_mfma_f32_16x16x32_bf16 v[130:133], v[138:141], v[220:223], v[130:133]
	v_mfma_f32_16x16x32_bf16 v[126:129], v[158:161], v[220:223], v[126:129]
	v_mfma_f32_16x16x32_bf16 v[122:125], v[138:141], v[228:231], v[122:125]
	v_mfma_f32_16x16x32_bf16 v[118:121], v[158:161], v[228:231], v[118:121]
	v_mfma_f32_16x16x32_bf16 v[114:117], v[138:141], v[236:239], v[114:117]
	v_mfma_f32_16x16x32_bf16 v[110:113], v[158:161], v[236:239], v[110:113]
	v_mfma_f32_16x16x32_bf16 v[106:109], v[138:141], v[244:247], v[106:109]
	v_mfma_f32_16x16x32_bf16 v[102:105], v[158:161], v[244:247], v[102:105]
	s_setprio 0
	s_setprio 1
	v_mfma_f32_16x16x32_bf16 v[98:101], v[178:181], v[216:219], v[98:101]
	v_mfma_f32_16x16x32_bf16 v[94:97], v[208:211], v[216:219], v[94:97]
	v_mfma_f32_16x16x32_bf16 v[90:93], v[178:181], v[224:227], v[90:93]
	v_mfma_f32_16x16x32_bf16 v[86:89], v[208:211], v[224:227], v[86:89]
	v_mfma_f32_16x16x32_bf16 v[82:85], v[178:181], v[232:235], v[82:85]
	v_mfma_f32_16x16x32_bf16 v[78:81], v[208:211], v[232:235], v[78:81]
	v_mfma_f32_16x16x32_bf16 v[74:77], v[178:181], v[240:243], v[74:77]
	v_mfma_f32_16x16x32_bf16 v[70:73], v[208:211], v[240:243], v[70:73]
	v_mfma_f32_16x16x32_bf16 v[98:101], v[204:207], v[220:223], v[98:101]
	v_mfma_f32_16x16x32_bf16 v[94:97], v[212:215], v[220:223], v[94:97]
	v_mfma_f32_16x16x32_bf16 v[90:93], v[204:207], v[228:231], v[90:93]
	v_mfma_f32_16x16x32_bf16 v[86:89], v[212:215], v[228:231], v[86:89]
	v_mfma_f32_16x16x32_bf16 v[82:85], v[204:207], v[236:239], v[82:85]
	v_mfma_f32_16x16x32_bf16 v[78:81], v[212:215], v[236:239], v[78:81]
	v_mfma_f32_16x16x32_bf16 v[74:77], v[204:207], v[244:247], v[74:77]
	v_mfma_f32_16x16x32_bf16 v[70:73], v[212:215], v[244:247], v[70:73]
	s_setprio 0
	s_barrier
; #define PG8_STAGE(bufoff, gbase, voff) do { _Pragma("unroll") for (int _i = 0; _i < 2; ++_i) \
;         __builtin_amdgcn_global_load_lds((const unsigned*)((const char*)(gbase) + (voff)[_i]), (PG8_LAS unsigned*)(lds + (bufoff) + ldsw + _i * 8192), 16, 0, 0); } while (0)
; #define PG8_LDA(dst, b, h) do { _Pragma("unroll") for (int m = 0; m < 4; ++m) _Pragma("unroll") for (int k = 0; k < 2; ++k) dst[m][k] = *(const PG8_LAS bf16x8*)(lds + PG8_SA(b, h) + aoff + m * 2048 + k * 1024); } while (0)
; #define PG8_MMA(ai, bj, At, Bt) do { __builtin_amdgcn_s_setprio(1); _Pragma("unroll") for (int m = 0; m < 4; ++m) _Pragma("unroll") for (int n = 0; n < 2; ++n) _Pragma("unroll") for (int k = 0; k < 2; ++k) \
;         acc[ai][bj][m][n] = __builtin_amdgcn_mfma_f32_16x16x32_bf16(Bt[n][k], At[m][k], acc[ai][bj][m][n], 0, 0, 0); __builtin_amdgcn_s_setprio(0); } while (0)
; #define PG8_WAIT_V(n) asm volatile("s_waitcnt vmcnt(" #n ")" ::: "memory")
; #define PG8_WAIT_L(n) asm volatile("s_waitcnt lgkmcnt(" #n ")" ::: "memory")
; #define PG8_BAR __builtin_amdgcn_s_barrier()
; #define PG8_SCHED __builtin_amdgcn_sched_barrier(0)
; template <class Epi, class Sched, bool ALIGN_EPI = false, bool SP2 = false>
; __device__ __forceinline__ void gemm_phase(PG8_LAS unsigned char* lds, const Gemm g, const Sched& S, const Epi& E) {
;     ...
;             PG8_LDA(At, 1, 1); PG8_STAGE(PG8_SB(1, 0), b3, voffB); PG8_STAGE(PG8_SB(1, 1), b3 + hstep, voffB); PG8_STAGE(PG8_SA(1, 0), a3, voffA);
;             PG8_WAIT_V(8); PG8_WAIT_L(0); PG8_BAR; PG8_MMA(1, 0, At, B0); PG8_MMA(1, 1, At, B1); PG8_BAR; PG8_SCHED;
	s_add_i32 s27, s27, s54
	s_add_i32 m0, s27, 0xffffff80
	ds_read_b128 v[216:219], v177 offset:49152
	ds_read_b128 v[220:223], v177 offset:50176
	ds_read_b128 v[224:227], v177 offset:51200
	ds_read_b128 v[228:231], v177 offset:52224
	ds_read_b128 v[232:235], v177 offset:53248
	ds_read_b128 v[236:239], v177 offset:54272
	ds_read_b128 v[240:243], v177 offset:55296
	ds_read_b128 v[244:247], v177 offset:56320
	global_load_lds_dwordx4 v144, s[42:43] offset:128
	s_add_i32 m0, s27, 0x1f80
	s_add_i32 s27, s29, s54
	global_load_lds_dwordx4 v148, s[42:43] offset:128
	s_add_u32 s42, s42, 0x40080
	s_addc_u32 s43, s43, 0
	s_mov_b32 m0, s27
	s_nop 0
	global_load_lds_dwordx4 v144, s[42:43]
	s_add_i32 m0, s27, 0x2000
	s_nop 0
	global_load_lds_dwordx4 v148, s[42:43]
	s_mov_b32 m0, s61
	s_nop 0
	global_load_lds_dwordx4 v142, s[100:101]
	s_mov_b32 m0, s62
	s_nop 0
	global_load_lds_dwordx4 v146, s[100:101]
	s_nop 0
	s_waitcnt vmcnt(8)
	s_waitcnt lgkmcnt(0)
	s_barrier
	s_setprio 1
	s_waitcnt lgkmcnt(0)
	v_mfma_f32_16x16x32_bf16 v[66:69], v[134:137], v[216:219], v[66:69]
	v_mfma_f32_16x16x32_bf16 v[62:65], v[154:157], v[216:219], v[62:65]
	v_mfma_f32_16x16x32_bf16 v[58:61], v[134:137], v[224:227], v[58:61]
	v_mfma_f32_16x16x32_bf16 v[54:57], v[154:157], v[224:227], v[54:57]
	v_mfma_f32_16x16x32_bf16 v[50:53], v[134:137], v[232:235], v[50:53]
	v_mfma_f32_16x16x32_bf16 v[46:49], v[154:157], v[232:235], v[46:49]
	v_mfma_f32_16x16x32_bf16 v[42:45], v[134:137], v[240:243], v[42:45]
	v_mfma_f32_16x16x32_bf16 v[38:41], v[154:157], v[240:243], v[38:41]
	v_mfma_f32_16x16x32_bf16 v[66:69], v[138:141], v[220:223], v[66:69]
	v_mfma_f32_16x16x32_bf16 v[62:65], v[158:161], v[220:223], v[62:65]
	v_mfma_f32_16x16x32_bf16 v[58:61], v[138:141], v[228:231], v[58:61]
	v_mfma_f32_16x16x32_bf16 v[54:57], v[158:161], v[228:231], v[54:57]
	v_mfma_f32_16x16x32_bf16 v[50:53], v[138:141], v[236:239], v[50:53]
	v_mfma_f32_16x16x32_bf16 v[46:49], v[158:161], v[236:239], v[46:49]
	v_mfma_f32_16x16x32_bf16 v[42:45], v[138:141], v[244:247], v[42:45]
	v_mfma_f32_16x16x32_bf16 v[38:41], v[158:161], v[244:247], v[38:41]
	s_setprio 0
	s_setprio 1
	v_mfma_f32_16x16x32_bf16 v[34:37], v[178:181], v[216:219], v[34:37]
	v_mfma_f32_16x16x32_bf16 v[30:33], v[208:211], v[216:219], v[30:33]
	v_mfma_f32_16x16x32_bf16 v[26:29], v[178:181], v[224:227], v[26:29]
	v_mfma_f32_16x16x32_bf16 v[22:25], v[208:211], v[224:227], v[22:25]
	v_mfma_f32_16x16x32_bf16 v[18:21], v[178:181], v[232:235], v[18:21]
	v_mfma_f32_16x16x32_bf16 v[14:17], v[208:211], v[232:235], v[14:17]
	v_mfma_f32_16x16x32_bf16 v[8:11], v[178:181], v[240:243], v[10:13]
	v_mfma_f32_16x16x32_bf16 v[4:7], v[208:211], v[240:243], v[4:7]
	v_mfma_f32_16x16x32_bf16 v[34:37], v[204:207], v[220:223], v[34:37]
	v_mfma_f32_16x16x32_bf16 v[30:33], v[212:215], v[220:223], v[30:33]
	v_mfma_f32_16x16x32_bf16 v[26:29], v[204:207], v[228:231], v[26:29]
	v_mfma_f32_16x16x32_bf16 v[22:25], v[212:215], v[228:231], v[22:25]
	v_mfma_f32_16x16x32_bf16 v[18:21], v[204:207], v[236:239], v[18:21]
	v_mfma_f32_16x16x32_bf16 v[14:17], v[212:215], v[236:239], v[14:17]
	v_mfma_f32_16x16x32_bf16 v[10:13], v[204:207], v[244:247], v[8:11]
	v_mfma_f32_16x16x32_bf16 v[6:9], v[212:215], v[244:247], v[4:7]
	s_setprio 0
	s_barrier
	s_add_i32 s26, s26, 2
	s_add_u32 s40, s40, 0x100
	s_addc_u32 s41, s41, 0
	s_add_u32 s11, s11, 0x100
	s_addc_u32 s13, s13, 0
	s_cmp_gt_u32 s26, 13
	s_cbranch_scc0 .LBB0_2096
	s_and_b64 vcc, exec, s[8:9]
	s_cbranch_vccz .LBB0_2099
	s_barrier

; #define PG8_STAGE(bufoff, gbase, voff) do { _Pragma("unroll") for (int _i = 0; _i < 2; ++_i) \
;         __builtin_amdgcn_global_load_lds((const unsigned*)((const char*)(gbase) + (voff)[_i]), (PG8_LAS unsigned*)(lds + (bufoff) + ldsw + _i * 8192), 16, 0, 0); } while (0)
; #define PG8_LDA(dst, b, h) do { _Pragma("unroll") for (int m = 0; m < 4; ++m) _Pragma("unroll") for (int k = 0; k < 2; ++k) dst[m][k] = *(const PG8_LAS bf16x8*)(lds + PG8_SA(b, h) + aoff + m * 2048 + k * 1024); } while (0)
; #define PG8_LDB(dst, b, h) do { _Pragma("unroll") for (int n = 0; n < 2; ++n) _Pragma("unroll") for (int k = 0; k < 2; ++k) dst[n][k] = *(const PG8_LAS bf16x8*)(lds + PG8_SB(b, h) + boff + n * 2048 + k * 1024); } while (0)
; #define PG8_MMA(ai, bj, At, Bt) do { __builtin_amdgcn_s_setprio(1); _Pragma("unroll") for (int m = 0; m < 4; ++m) _Pragma("unroll") for (int n = 0; n < 2; ++n) _Pragma("unroll") for (int k = 0; k < 2; ++k) \
;         acc[ai][bj][m][n] = __builtin_amdgcn_mfma_f32_16x16x32_bf16(Bt[n][k], At[m][k], acc[ai][bj][m][n], 0, 0, 0); __builtin_amdgcn_s_setprio(0); } while (0)
; #define PG8_WAIT_V(n) asm volatile("s_waitcnt vmcnt(" #n ")" ::: "memory")
; #define PG8_WAIT_L(n) asm volatile("s_waitcnt lgkmcnt(" #n ")" ::: "memory")
; #define PG8_BAR __builtin_amdgcn_s_barrier()
; #define PG8_SCHED __builtin_amdgcn_sched_barrier(0)
; template <class Epi, class Sched, bool ALIGN_EPI = false, bool SP2 = false>
; __device__ __forceinline__ void gemm_phase(PG8_LAS unsigned char* lds, const Gemm g, const Sched& S, const Epi& E) {
;     ...
;             PG8_LDB(B0, 0, 0); PG8_LDB(B1, 0, 1); PG8_SCHED; PG8_LDA(At, 0, 0); PG8_STAGE(PG8_SA(1, 1), a1 + hstep, voffA);
;             PG8_WAIT_V(8); PG8_WAIT_L(0); PG8_BAR; PG8_MMA(0, 0, At, B0); PG8_MMA(0, 1, At, B1); PG8_BAR; PG8_SCHED;
;     ...
;         bool zero_acc = true; if constexpr (Epi::KEEP_ACC) zero_acc = (cur.aux == 2);
;         if (zero_acc) {
; #pragma unroll
;         for (int a = 0; a < 2; ++a)
; #pragma unroll
;             for (int b = 0; b < 2; ++b)
; #pragma unroll
;                 for (int m = 0; m < 4; ++m)
; #pragma unroll
;                     for (int n = 0; n < 2; ++n) acc[a][b][m][n] = (f32x4){0.f, 0.f, 0.f, 0.f};
.LBB0_2184:
	s_add_u32 s2, s42, 0x100
	v_mov_b32_e32 v4, 0
	s_addc_u32 s29, s43, 0
	s_mov_b32 s31, -2
	s_waitcnt lgkmcnt(0)
	v_mov_b32_e32 v5, v4
	v_mov_b32_e32 v6, v4
	v_mov_b32_e32 v7, v4
	v_mov_b32_e32 v8, v4
	v_mov_b32_e32 v9, v4
	v_mov_b32_e32 v10, v4
	v_mov_b32_e32 v11, v4
	v_mov_b32_e32 v20, v4
	v_mov_b32_e32 v21, v4
	v_mov_b32_e32 v22, v4
	v_mov_b32_e32 v23, v4
	v_mov_b32_e32 v24, v4
	v_mov_b32_e32 v25, v4
	v_mov_b32_e32 v26, v4
	v_mov_b32_e32 v27, v4
	v_mov_b32_e32 v36, v4
	v_mov_b32_e32 v37, v4
	v_mov_b32_e32 v38, v4
	v_mov_b32_e32 v39, v4
	v_mov_b32_e32 v40, v4
	v_mov_b32_e32 v41, v4
	v_mov_b32_e32 v42, v4
	v_mov_b32_e32 v43, v4
	v_mov_b32_e32 v52, v4
	v_mov_b32_e32 v53, v4
	v_mov_b32_e32 v54, v4
	v_mov_b32_e32 v55, v4
	v_mov_b32_e32 v56, v4
	v_mov_b32_e32 v57, v4
	v_mov_b32_e32 v58, v4
	v_mov_b32_e32 v59, v4
	v_mov_b32_e32 v12, v4
	v_mov_b32_e32 v13, v4
	v_mov_b32_e32 v14, v4
	v_mov_b32_e32 v15, v4
	v_mov_b32_e32 v16, v4
	v_mov_b32_e32 v17, v4
	v_mov_b32_e32 v18, v4
	v_mov_b32_e32 v19, v4
	v_mov_b32_e32 v28, v4
	v_mov_b32_e32 v29, v4
	v_mov_b32_e32 v30, v4
	v_mov_b32_e32 v31, v4
	v_mov_b32_e32 v32, v4
	v_mov_b32_e32 v33, v4
	v_mov_b32_e32 v34, v4
	v_mov_b32_e32 v35, v4
	v_mov_b32_e32 v44, v4
	v_mov_b32_e32 v45, v4
	v_mov_b32_e32 v46, v4
	v_mov_b32_e32 v47, v4
	v_mov_b32_e32 v48, v4
	v_mov_b32_e32 v49, v4
	v_mov_b32_e32 v50, v4
	v_mov_b32_e32 v51, v4
	v_mov_b32_e32 v60, v4
	v_mov_b32_e32 v61, v4
	v_mov_b32_e32 v62, v4
	v_mov_b32_e32 v63, v4
	v_mov_b32_e32 v64, v4
	v_mov_b32_e32 v65, v4
	v_mov_b32_e32 v66, v4
	v_mov_b32_e32 v67, v4
	v_mov_b32_e32 v68, v4
	v_mov_b32_e32 v69, v4
	v_mov_b32_e32 v70, v4
	v_mov_b32_e32 v71, v4
	v_mov_b32_e32 v72, v4
	v_mov_b32_e32 v73, v4
	v_mov_b32_e32 v74, v4
	v_mov_b32_e32 v75, v4
	v_mov_b32_e32 v84, v4
	v_mov_b32_e32 v85, v4
	v_mov_b32_e32 v86, v4
	v_mov_b32_e32 v87, v4
	v_mov_b32_e32 v88, v4
	v_mov_b32_e32 v89, v4
	v_mov_b32_e32 v90, v4
	v_mov_b32_e32 v91, v4
	v_mov_b32_e32 v100, v4
	v_mov_b32_e32 v101, v4
	v_mov_b32_e32 v102, v4
	v_mov_b32_e32 v103, v4
	v_mov_b32_e32 v104, v4
	v_mov_b32_e32 v105, v4
	v_mov_b32_e32 v106, v4
	v_mov_b32_e32 v107, v4
	v_mov_b32_e32 v116, v4
	v_mov_b32_e32 v117, v4
	v_mov_b32_e32 v118, v4
	v_mov_b32_e32 v119, v4
	v_mov_b32_e32 v120, v4
	v_mov_b32_e32 v121, v4
	v_mov_b32_e32 v122, v4
	v_mov_b32_e32 v123, v4
	v_mov_b32_e32 v76, v4
	v_mov_b32_e32 v77, v4
	v_mov_b32_e32 v78, v4
	v_mov_b32_e32 v79, v4
	v_mov_b32_e32 v80, v4
	v_mov_b32_e32 v81, v4
	v_mov_b32_e32 v82, v4
	v_mov_b32_e32 v83, v4
	v_mov_b32_e32 v92, v4
	v_mov_b32_e32 v93, v4
	v_mov_b32_e32 v94, v4
	v_mov_b32_e32 v95, v4
	v_mov_b32_e32 v96, v4
	v_mov_b32_e32 v97, v4
	v_mov_b32_e32 v98, v4
	v_mov_b32_e32 v99, v4
	v_mov_b32_e32 v108, v4
	v_mov_b32_e32 v109, v4
	v_mov_b32_e32 v110, v4
	v_mov_b32_e32 v111, v4
	v_mov_b32_e32 v112, v4
	v_mov_b32_e32 v113, v4
	v_mov_b32_e32 v114, v4
	v_mov_b32_e32 v115, v4
	v_mov_b32_e32 v124, v4
	v_mov_b32_e32 v125, v4
	v_mov_b32_e32 v126, v4
	v_mov_b32_e32 v127, v4
	v_mov_b32_e32 v128, v4
	v_mov_b32_e32 v129, v4
	v_mov_b32_e32 v130, v4
	v_mov_b32_e32 v131, v4
	.p2align 6
	s_nop 0
.LBB0_2185:
	s_add_u32 s42, s40, 0x100
	s_addc_u32 s43, s41, 0
	s_add_i32 s37, 0, 0x10000
	s_cmp_eq_u32 s31, 28
	s_cselect_b32 s47, s5, s43
	s_cselect_b32 s46, s4, s42
	v_add_u32_e32 v135, s37, v173
	s_cselect_b32 s45, s35, s29
	s_cselect_b32 s44, s34, s2
	s_add_i32 s39, 0, 0x14000
	ds_read_b128 v[142:145], v135
	ds_read_b128 v[146:149], v135 offset:1024
	ds_read_b128 v[150:153], v135 offset:2048
	ds_read_b128 v[154:157], v135 offset:3072
	v_add_u32_e32 v135, s39, v173
	ds_read_b128 v[158:161], v135
	ds_read_b128 v[174:177], v135 offset:1024
	ds_read_b128 v[180:183], v135 offset:2048
	ds_read_b128 v[204:207], v135 offset:3072
	v_lshl_add_u64 v[162:163], s[40:41], 0, v[138:139]
	s_add_i32 m0, s55, 0xc000
	ds_read_b128 v[208:211], v179
	ds_read_b128 v[212:215], v179 offset:1024
	ds_read_b128 v[216:219], v179 offset:2048
	ds_read_b128 v[220:223], v179 offset:3072
	ds_read_b128 v[224:227], v179 offset:4096
	ds_read_b128 v[228:231], v179 offset:5120
	ds_read_b128 v[232:235], v179 offset:6144
	ds_read_b128 v[236:239], v179 offset:7168
	global_load_lds_dwordx4 v[162:163], off
	v_lshl_add_u64 v[162:163], s[40:41], 0, v[140:141]
	s_add_i32 m0, s55, 0xe000
	s_nop 0
	global_load_lds_dwordx4 v[162:163], off
	s_waitcnt vmcnt(8)
	s_waitcnt lgkmcnt(0)
	s_barrier
	s_setprio 1
	s_waitcnt lgkmcnt(0)
	v_mfma_f32_16x16x32_bf16 v[128:131], v[142:145], v[208:211], v[128:131]
	v_mfma_f32_16x16x32_bf16 v[124:127], v[150:153], v[208:211], v[124:127]
	v_mfma_f32_16x16x32_bf16 v[112:115], v[142:145], v[216:219], v[112:115]
	v_mfma_f32_16x16x32_bf16 v[108:111], v[150:153], v[216:219], v[108:111]
	v_mfma_f32_16x16x32_bf16 v[96:99], v[142:145], v[224:227], v[96:99]
	v_mfma_f32_16x16x32_bf16 v[92:95], v[150:153], v[224:227], v[92:95]
	v_mfma_f32_16x16x32_bf16 v[80:83], v[142:145], v[232:235], v[80:83]
	v_mfma_f32_16x16x32_bf16 v[76:79], v[150:153], v[232:235], v[76:79]
	v_mfma_f32_16x16x32_bf16 v[128:131], v[146:149], v[212:215], v[128:131]
	v_mfma_f32_16x16x32_bf16 v[124:127], v[154:157], v[212:215], v[124:127]
	v_mfma_f32_16x16x32_bf16 v[112:115], v[146:149], v[220:223], v[112:115]
	v_mfma_f32_16x16x32_bf16 v[108:111], v[154:157], v[220:223], v[108:111]
	v_mfma_f32_16x16x32_bf16 v[96:99], v[146:149], v[228:231], v[96:99]
	v_mfma_f32_16x16x32_bf16 v[92:95], v[154:157], v[228:231], v[92:95]
	v_mfma_f32_16x16x32_bf16 v[80:83], v[146:149], v[236:239], v[80:83]
	v_mfma_f32_16x16x32_bf16 v[76:79], v[154:157], v[236:239], v[76:79]
	s_setprio 0
	s_setprio 1
	v_mfma_f32_16x16x32_bf16 v[120:123], v[158:161], v[208:211], v[120:123]
	v_mfma_f32_16x16x32_bf16 v[116:119], v[180:183], v[208:211], v[116:119]
	v_mfma_f32_16x16x32_bf16 v[104:107], v[158:161], v[216:219], v[104:107]
	v_mfma_f32_16x16x32_bf16 v[100:103], v[180:183], v[216:219], v[100:103]
	v_mfma_f32_16x16x32_bf16 v[88:91], v[158:161], v[224:227], v[88:91]
	v_mfma_f32_16x16x32_bf16 v[84:87], v[180:183], v[224:227], v[84:87]
	v_mfma_f32_16x16x32_bf16 v[72:75], v[158:161], v[232:235], v[72:75]
	v_mfma_f32_16x16x32_bf16 v[68:71], v[180:183], v[232:235], v[68:71]
	v_mfma_f32_16x16x32_bf16 v[120:123], v[174:177], v[212:215], v[120:123]
	v_mfma_f32_16x16x32_bf16 v[116:119], v[204:207], v[212:215], v[116:119]
	v_mfma_f32_16x16x32_bf16 v[104:107], v[174:177], v[220:223], v[104:107]
	v_mfma_f32_16x16x32_bf16 v[100:103], v[204:207], v[220:223], v[100:103]
	v_mfma_f32_16x16x32_bf16 v[88:91], v[174:177], v[228:231], v[88:91]
	v_mfma_f32_16x16x32_bf16 v[84:87], v[204:207], v[228:231], v[84:87]
	v_mfma_f32_16x16x32_bf16 v[72:75], v[174:177], v[236:239], v[72:75]
	v_mfma_f32_16x16x32_bf16 v[68:71], v[204:207], v[236:239], v[68:71]
	s_setprio 0
	s_barrier
; #define PG8_STAGE(bufoff, gbase, voff) do { _Pragma("unroll") for (int _i = 0; _i < 2; ++_i) \
;         __builtin_amdgcn_global_load_lds((const unsigned*)((const char*)(gbase) + (voff)[_i]), (PG8_LAS unsigned*)(lds + (bufoff) + ldsw + _i * 8192), 16, 0, 0); } while (0)
; #define PG8_LDA(dst, b, h) do { _Pragma("unroll") for (int m = 0; m < 4; ++m) _Pragma("unroll") for (int k = 0; k < 2; ++k) dst[m][k] = *(const PG8_LAS bf16x8*)(lds + PG8_SA(b, h) + aoff + m * 2048 + k * 1024); } while (0)
; #define PG8_LDB(dst, b, h) do { _Pragma("unroll") for (int n = 0; n < 2; ++n) _Pragma("unroll") for (int k = 0; k < 2; ++k) dst[n][k] = *(const PG8_LAS bf16x8*)(lds + PG8_SB(b, h) + boff + n * 2048 + k * 1024); } while (0)
; #define PG8_MMA(ai, bj, At, Bt) do { __builtin_amdgcn_s_setprio(1); _Pragma("unroll") for (int m = 0; m < 4; ++m) _Pragma("unroll") for (int n = 0; n < 2; ++n) _Pragma("unroll") for (int k = 0; k < 2; ++k) \
;         acc[ai][bj][m][n] = __builtin_amdgcn_mfma_f32_16x16x32_bf16(Bt[n][k], At[m][k], acc[ai][bj][m][n], 0, 0, 0); __builtin_amdgcn_s_setprio(0); } while (0)
; #define PG8_WAIT_V(n) asm volatile("s_waitcnt vmcnt(" #n ")" ::: "memory")
; #define PG8_WAIT_L(n) asm volatile("s_waitcnt lgkmcnt(" #n ")" ::: "memory")
; #define PG8_BAR __builtin_amdgcn_s_barrier()
; #define PG8_SCHED __builtin_amdgcn_sched_barrier(0)
; template <class Epi, class Sched, bool ALIGN_EPI = false, bool SP2 = false>
; __device__ __forceinline__ void gemm_phase(PG8_LAS unsigned char* lds, const Gemm g, const Sched& S, const Epi& E) {
;     ...
;             PG8_LDA(At, 0, 1); PG8_STAGE(PG8_SB(0, 0), b2, voffB); PG8_STAGE(PG8_SB(0, 1), b2 + hstep, voffB); PG8_STAGE(PG8_SA(0, 0), a2, voffA);
;             PG8_WAIT_V(8); PG8_WAIT_L(0); PG8_BAR; PG8_MMA(1, 0, At, B0); PG8_MMA(1, 1, At, B1); PG8_BAR; PG8_SCHED;
;             PG8_LDB(B0, 1, 0); PG8_LDB(B1, 1, 1); PG8_SCHED; PG8_LDA(At, 1, 0); PG8_STAGE(PG8_SA(0, 1), a2 + hstep, voffA);
	s_add_i32 s37, s37, s54
	s_mov_b32 m0, s37
	ds_read_b128 v[208:211], v179 offset:16384
	ds_read_b128 v[212:215], v179 offset:17408
	ds_read_b128 v[216:219], v179 offset:18432
	ds_read_b128 v[220:223], v179 offset:19456
	ds_read_b128 v[224:227], v179 offset:20480
	ds_read_b128 v[228:231], v179 offset:21504
	ds_read_b128 v[232:235], v179 offset:22528
	ds_read_b128 v[236:239], v179 offset:23552
	global_load_lds_dwordx4 v2, s[44:45]
	s_add_i32 m0, s37, 0x2000
	s_add_u32 s40, s44, 0x80000
	s_addc_u32 s41, s45, 0
	s_add_i32 s37, s39, s54
	global_load_lds_dwordx4 v132, s[44:45]
	s_mov_b32 m0, s37
	s_nop 0
	global_load_lds_dwordx4 v2, s[40:41]
	s_add_i32 m0, s37, 0x2000
	s_nop 0
	global_load_lds_dwordx4 v132, s[40:41]
	s_mov_b32 m0, s55
	s_nop 0
	global_load_lds_dwordx4 v2, s[46:47]
	s_mov_b32 m0, s56
	s_nop 0
	global_load_lds_dwordx4 v132, s[46:47]
	s_waitcnt vmcnt(8)
	s_waitcnt lgkmcnt(0)
	s_barrier
	s_setprio 1
	s_waitcnt lgkmcnt(0)
	v_mfma_f32_16x16x32_bf16 v[64:67], v[142:145], v[208:211], v[64:67]
	v_mfma_f32_16x16x32_bf16 v[60:63], v[150:153], v[208:211], v[60:63]
	v_mfma_f32_16x16x32_bf16 v[48:51], v[142:145], v[216:219], v[48:51]
	v_mfma_f32_16x16x32_bf16 v[44:47], v[150:153], v[216:219], v[44:47]
	v_mfma_f32_16x16x32_bf16 v[32:35], v[142:145], v[224:227], v[32:35]
	v_mfma_f32_16x16x32_bf16 v[28:31], v[150:153], v[224:227], v[28:31]
	v_mfma_f32_16x16x32_bf16 v[16:19], v[142:145], v[232:235], v[16:19]
	v_mfma_f32_16x16x32_bf16 v[12:15], v[150:153], v[232:235], v[12:15]
	v_mfma_f32_16x16x32_bf16 v[64:67], v[146:149], v[212:215], v[64:67]
	v_mfma_f32_16x16x32_bf16 v[60:63], v[154:157], v[212:215], v[60:63]
	v_mfma_f32_16x16x32_bf16 v[48:51], v[146:149], v[220:223], v[48:51]
	v_mfma_f32_16x16x32_bf16 v[44:47], v[154:157], v[220:223], v[44:47]
	v_mfma_f32_16x16x32_bf16 v[32:35], v[146:149], v[228:231], v[32:35]
	v_mfma_f32_16x16x32_bf16 v[28:31], v[154:157], v[228:231], v[28:31]
	v_mfma_f32_16x16x32_bf16 v[16:19], v[146:149], v[236:239], v[16:19]
	v_mfma_f32_16x16x32_bf16 v[12:15], v[154:157], v[236:239], v[12:15]
	s_setprio 0
	s_setprio 1
	v_mfma_f32_16x16x32_bf16 v[56:59], v[158:161], v[208:211], v[56:59]
	v_mfma_f32_16x16x32_bf16 v[52:55], v[180:183], v[208:211], v[52:55]
	v_mfma_f32_16x16x32_bf16 v[40:43], v[158:161], v[216:219], v[40:43]
	v_mfma_f32_16x16x32_bf16 v[36:39], v[180:183], v[216:219], v[36:39]
	v_mfma_f32_16x16x32_bf16 v[24:27], v[158:161], v[224:227], v[24:27]
	v_mfma_f32_16x16x32_bf16 v[20:23], v[180:183], v[224:227], v[20:23]
	v_mfma_f32_16x16x32_bf16 v[8:11], v[158:161], v[232:235], v[8:11]
	v_mfma_f32_16x16x32_bf16 v[4:7], v[180:183], v[232:235], v[4:7]
	v_mfma_f32_16x16x32_bf16 v[56:59], v[174:177], v[212:215], v[56:59]
	v_mfma_f32_16x16x32_bf16 v[52:55], v[204:207], v[212:215], v[52:55]
	v_mfma_f32_16x16x32_bf16 v[40:43], v[174:177], v[220:223], v[40:43]
	v_mfma_f32_16x16x32_bf16 v[36:39], v[204:207], v[220:223], v[36:39]
	v_mfma_f32_16x16x32_bf16 v[24:27], v[174:177], v[228:231], v[24:27]
	v_mfma_f32_16x16x32_bf16 v[20:23], v[204:207], v[228:231], v[20:23]
	v_mfma_f32_16x16x32_bf16 v[8:11], v[174:177], v[236:239], v[8:11]
	v_mfma_f32_16x16x32_bf16 v[4:7], v[204:207], v[236:239], v[4:7]
	s_setprio 0
	s_barrier
	s_add_i32 s37, 0, 0x18000
	v_add_u32_e32 v135, s37, v173
	s_add_i32 s39, 0, 0x1c000
	ds_read_b128 v[142:145], v135
	ds_read_b128 v[146:149], v135 offset:1024
	ds_read_b128 v[150:153], v135 offset:2048
	ds_read_b128 v[154:157], v135 offset:3072
	v_add_u32_e32 v135, s39, v173
	ds_read_b128 v[158:161], v135
	ds_read_b128 v[174:177], v135 offset:1024
	ds_read_b128 v[180:183], v135 offset:2048
	ds_read_b128 v[204:207], v135 offset:3072
	s_add_u32 s40, s46, 0x80000
	s_addc_u32 s41, s47, 0
	s_mov_b32 m0, s57
	ds_read_b128 v[208:211], v179 offset:32768
	ds_read_b128 v[212:215], v179 offset:33792
	ds_read_b128 v[216:219], v179 offset:34816
	ds_read_b128 v[220:223], v179 offset:35840
	ds_read_b128 v[224:227], v179 offset:36864
	ds_read_b128 v[228:231], v179 offset:37888
	ds_read_b128 v[232:235], v179 offset:38912
	ds_read_b128 v[236:239], v179 offset:39936
	global_load_lds_dwordx4 v2, s[40:41]
	s_mov_b32 m0, s58
	s_nop 0
	global_load_lds_dwordx4 v132, s[40:41]
	s_nop 0
	s_waitcnt vmcnt(8)
	s_waitcnt lgkmcnt(0)
	s_barrier
; #define PG8_STAGE(bufoff, gbase, voff) do { _Pragma("unroll") for (int _i = 0; _i < 2; ++_i) \
;         __builtin_amdgcn_global_load_lds((const unsigned*)((const char*)(gbase) + (voff)[_i]), (PG8_LAS unsigned*)(lds + (bufoff) + ldsw + _i * 8192), 16, 0, 0); } while (0)
; #define PG8_LDA(dst, b, h) do { _Pragma("unroll") for (int m = 0; m < 4; ++m) _Pragma("unroll") for (int k = 0; k < 2; ++k) dst[m][k] = *(const PG8_LAS bf16x8*)(lds + PG8_SA(b, h) + aoff + m * 2048 + k * 1024); } while (0)
; #define PG8_MMA(ai, bj, At, Bt) do { __builtin_amdgcn_s_setprio(1); _Pragma("unroll") for (int m = 0; m < 4; ++m) _Pragma("unroll") for (int n = 0; n < 2; ++n) _Pragma("unroll") for (int k = 0; k < 2; ++k) \
;         acc[ai][bj][m][n] = __builtin_amdgcn_mfma_f32_16x16x32_bf16(Bt[n][k], At[m][k], acc[ai][bj][m][n], 0, 0, 0); __builtin_amdgcn_s_setprio(0); } while (0)
; #define PG8_WAIT_V(n) asm volatile("s_waitcnt vmcnt(" #n ")" ::: "memory")
; #define PG8_WAIT_L(n) asm volatile("s_waitcnt lgkmcnt(" #n ")" ::: "memory")
; #define PG8_BAR __builtin_amdgcn_s_barrier()
; #define PG8_SCHED __builtin_amdgcn_sched_barrier(0)
; template <class Epi, class Sched, bool ALIGN_EPI = false, bool SP2 = false>
; __device__ __forceinline__ void gemm_phase(PG8_LAS unsigned char* lds, const Gemm g, const Sched& S, const Epi& E) {
;     ...
;             PG8_WAIT_V(8); PG8_WAIT_L(0); PG8_BAR; PG8_MMA(0, 0, At, B0); PG8_MMA(0, 1, At, B1); PG8_BAR; PG8_SCHED;
;             PG8_LDA(At, 1, 1); PG8_STAGE(PG8_SB(1, 0), b3, voffB); PG8_STAGE(PG8_SB(1, 1), b3 + hstep, voffB); PG8_STAGE(PG8_SA(1, 0), a3, voffA);
;             PG8_WAIT_V(8); PG8_WAIT_L(0); PG8_BAR; PG8_MMA(1, 0, At, B0); PG8_MMA(1, 1, At, B1); PG8_BAR; PG8_SCHED;
	s_setprio 1
	s_waitcnt lgkmcnt(0)
	v_mfma_f32_16x16x32_bf16 v[128:131], v[142:145], v[208:211], v[128:131]
	v_mfma_f32_16x16x32_bf16 v[124:127], v[150:153], v[208:211], v[124:127]
	v_mfma_f32_16x16x32_bf16 v[112:115], v[142:145], v[216:219], v[112:115]
	v_mfma_f32_16x16x32_bf16 v[108:111], v[150:153], v[216:219], v[108:111]
	v_mfma_f32_16x16x32_bf16 v[96:99], v[142:145], v[224:227], v[96:99]
	v_mfma_f32_16x16x32_bf16 v[92:95], v[150:153], v[224:227], v[92:95]
	v_mfma_f32_16x16x32_bf16 v[80:83], v[142:145], v[232:235], v[80:83]
	v_mfma_f32_16x16x32_bf16 v[76:79], v[150:153], v[232:235], v[76:79]
	v_mfma_f32_16x16x32_bf16 v[128:131], v[146:149], v[212:215], v[128:131]
	v_mfma_f32_16x16x32_bf16 v[124:127], v[154:157], v[212:215], v[124:127]
	v_mfma_f32_16x16x32_bf16 v[112:115], v[146:149], v[220:223], v[112:115]
	v_mfma_f32_16x16x32_bf16 v[108:111], v[154:157], v[220:223], v[108:111]
	v_mfma_f32_16x16x32_bf16 v[96:99], v[146:149], v[228:231], v[96:99]
	v_mfma_f32_16x16x32_bf16 v[92:95], v[154:157], v[228:231], v[92:95]
	v_mfma_f32_16x16x32_bf16 v[80:83], v[146:149], v[236:239], v[80:83]
	v_mfma_f32_16x16x32_bf16 v[76:79], v[154:157], v[236:239], v[76:79]
	s_setprio 0
	s_setprio 1
	v_mfma_f32_16x16x32_bf16 v[120:123], v[158:161], v[208:211], v[120:123]
	v_mfma_f32_16x16x32_bf16 v[116:119], v[180:183], v[208:211], v[116:119]
	v_mfma_f32_16x16x32_bf16 v[104:107], v[158:161], v[216:219], v[104:107]
	v_mfma_f32_16x16x32_bf16 v[100:103], v[180:183], v[216:219], v[100:103]
	v_mfma_f32_16x16x32_bf16 v[88:91], v[158:161], v[224:227], v[88:91]
	v_mfma_f32_16x16x32_bf16 v[84:87], v[180:183], v[224:227], v[84:87]
	v_mfma_f32_16x16x32_bf16 v[72:75], v[158:161], v[232:235], v[72:75]
	v_mfma_f32_16x16x32_bf16 v[68:71], v[180:183], v[232:235], v[68:71]
	v_mfma_f32_16x16x32_bf16 v[120:123], v[174:177], v[212:215], v[120:123]
	v_mfma_f32_16x16x32_bf16 v[116:119], v[204:207], v[212:215], v[116:119]
	v_mfma_f32_16x16x32_bf16 v[104:107], v[174:177], v[220:223], v[104:107]
	v_mfma_f32_16x16x32_bf16 v[100:103], v[204:207], v[220:223], v[100:103]
	v_mfma_f32_16x16x32_bf16 v[88:91], v[174:177], v[228:231], v[88:91]
	v_mfma_f32_16x16x32_bf16 v[84:87], v[204:207], v[228:231], v[84:87]
	v_mfma_f32_16x16x32_bf16 v[72:75], v[174:177], v[236:239], v[72:75]
	v_mfma_f32_16x16x32_bf16 v[68:71], v[204:207], v[236:239], v[68:71]
	s_setprio 0
	s_barrier
	s_add_i32 s37, s37, s54
	s_add_i32 m0, s37, 0xffffff80
	ds_read_b128 v[208:211], v179 offset:49152
	ds_read_b128 v[212:215], v179 offset:50176
	ds_read_b128 v[216:219], v179 offset:51200
	ds_read_b128 v[220:223], v179 offset:52224
	ds_read_b128 v[224:227], v179 offset:53248
	ds_read_b128 v[228:231], v179 offset:54272
	ds_read_b128 v[232:235], v179 offset:55296
	ds_read_b128 v[236:239], v179 offset:56320
	global_load_lds_dwordx4 v2, s[44:45] offset:128
	s_add_i32 m0, s37, 0x1f80
	s_add_u32 s40, s44, 0x80080
	s_addc_u32 s41, s45, 0
	s_add_i32 s37, s39, s54
	global_load_lds_dwordx4 v132, s[44:45] offset:128
	s_mov_b32 m0, s37
	s_nop 0
	global_load_lds_dwordx4 v2, s[40:41]
	s_add_i32 m0, s37, 0x2000
	s_nop 0
	global_load_lds_dwordx4 v132, s[40:41]
	s_add_i32 m0, s60, 0xffffff80
	s_nop 0
	global_load_lds_dwordx4 v2, s[46:47] offset:128
	s_add_i32 m0, s61, 0xffffff80
	s_nop 0
	global_load_lds_dwordx4 v132, s[46:47] offset:128
	s_nop 0
	s_waitcnt vmcnt(8)
	s_waitcnt lgkmcnt(0)
	s_barrier
	s_setprio 1
	s_waitcnt lgkmcnt(0)
	v_mfma_f32_16x16x32_bf16 v[64:67], v[142:145], v[208:211], v[64:67]
	v_mfma_f32_16x16x32_bf16 v[60:63], v[150:153], v[208:211], v[60:63]
	v_mfma_f32_16x16x32_bf16 v[48:51], v[142:145], v[216:219], v[48:51]
	v_mfma_f32_16x16x32_bf16 v[44:47], v[150:153], v[216:219], v[44:47]
	v_mfma_f32_16x16x32_bf16 v[32:35], v[142:145], v[224:227], v[32:35]
	v_mfma_f32_16x16x32_bf16 v[28:31], v[150:153], v[224:227], v[28:31]
	v_mfma_f32_16x16x32_bf16 v[16:19], v[142:145], v[232:235], v[16:19]
	v_mfma_f32_16x16x32_bf16 v[12:15], v[150:153], v[232:235], v[12:15]
	v_mfma_f32_16x16x32_bf16 v[64:67], v[146:149], v[212:215], v[64:67]
	v_mfma_f32_16x16x32_bf16 v[60:63], v[154:157], v[212:215], v[60:63]
	v_mfma_f32_16x16x32_bf16 v[48:51], v[146:149], v[220:223], v[48:51]
	v_mfma_f32_16x16x32_bf16 v[44:47], v[154:157], v[220:223], v[44:47]
	v_mfma_f32_16x16x32_bf16 v[32:35], v[146:149], v[228:231], v[32:35]
	v_mfma_f32_16x16x32_bf16 v[28:31], v[154:157], v[228:231], v[28:31]
	v_mfma_f32_16x16x32_bf16 v[16:19], v[146:149], v[236:239], v[16:19]
	v_mfma_f32_16x16x32_bf16 v[12:15], v[154:157], v[236:239], v[12:15]
	s_setprio 0
	s_setprio 1
	v_mfma_f32_16x16x32_bf16 v[56:59], v[158:161], v[208:211], v[56:59]
	v_mfma_f32_16x16x32_bf16 v[52:55], v[180:183], v[208:211], v[52:55]
	v_mfma_f32_16x16x32_bf16 v[40:43], v[158:161], v[216:219], v[40:43]
	v_mfma_f32_16x16x32_bf16 v[36:39], v[180:183], v[216:219], v[36:39]
	v_mfma_f32_16x16x32_bf16 v[24:27], v[158:161], v[224:227], v[24:27]
	v_mfma_f32_16x16x32_bf16 v[20:23], v[180:183], v[224:227], v[20:23]
	v_mfma_f32_16x16x32_bf16 v[8:11], v[158:161], v[232:235], v[8:11]
	v_mfma_f32_16x16x32_bf16 v[4:7], v[180:183], v[232:235], v[4:7]
	v_mfma_f32_16x16x32_bf16 v[56:59], v[174:177], v[212:215], v[56:59]
	v_mfma_f32_16x16x32_bf16 v[52:55], v[204:207], v[212:215], v[52:55]
	v_mfma_f32_16x16x32_bf16 v[40:43], v[174:177], v[220:223], v[40:43]
	v_mfma_f32_16x16x32_bf16 v[36:39], v[204:207], v[220:223], v[36:39]
	v_mfma_f32_16x16x32_bf16 v[24:27], v[174:177], v[228:231], v[24:27]
	v_mfma_f32_16x16x32_bf16 v[20:23], v[204:207], v[228:231], v[20:23]
	v_mfma_f32_16x16x32_bf16 v[8:11], v[174:177], v[236:239], v[8:11]
	v_mfma_f32_16x16x32_bf16 v[4:7], v[204:207], v[236:239], v[4:7]
	s_setprio 0
	s_barrier
	s_add_i32 s31, s31, 2
	s_add_u32 s2, s2, 0x100
	s_addc_u32 s29, s29, 0
	s_cmp_gt_u32 s31, 29
	s_mov_b64 s[40:41], s[42:43]
	s_cbranch_scc0 .LBB0_2185
	s_and_b64 vcc, exec, s[26:27]
	s_cbranch_vccz .LBB0_2188
	s_barrier

; __global__ void __launch_bounds__(512, 2) mega(MegaArgs a) {
	.amdhsa_kernel _Z4mega8MegaArgs
		.amdhsa_group_segment_fixed_size 0
		.amdhsa_private_segment_fixed_size 0
		.amdhsa_kernarg_size 1264
		.amdhsa_user_sgpr_count 2
		.amdhsa_user_sgpr_dispatch_ptr 0
		.amdhsa_user_sgpr_queue_ptr 0
		.amdhsa_user_sgpr_kernarg_segment_ptr 1
		.amdhsa_user_sgpr_dispatch_id 0
		.amdhsa_user_sgpr_kernarg_preload_length 0
		.amdhsa_user_sgpr_kernarg_preload_offset 0
		.amdhsa_user_sgpr_private_segment_size 0
		.amdhsa_uses_dynamic_stack 0
		.amdhsa_enable_private_segment 0
		.amdhsa_system_sgpr_workgroup_id_x 1
		.amdhsa_system_sgpr_workgroup_id_y 0
		.amdhsa_system_sgpr_workgroup_id_z 0
		.amdhsa_system_sgpr_workgroup_info 0
		.amdhsa_system_vgpr_workitem_id 0
		.amdhsa_next_free_vgpr 256
		.amdhsa_next_free_sgpr 102
		.amdhsa_accum_offset 256
		.amdhsa_reserve_vcc 1
		.amdhsa_float_round_mode_32 0
		.amdhsa_float_round_mode_16_64 0
		.amdhsa_float_denorm_mode_32 3
		.amdhsa_float_denorm_mode_16_64 3
		.amdhsa_dx10_clamp 1
		.amdhsa_ieee_mode 1
		.amdhsa_fp16_overflow 0
		.amdhsa_tg_split 0
		.amdhsa_exception_fp_ieee_invalid_op 0
		.amdhsa_exception_fp_denorm_src 0
		.amdhsa_exception_fp_ieee_div_zero 0
		.amdhsa_exception_fp_ieee_overflow 0
		.amdhsa_exception_fp_ieee_underflow 0
		.amdhsa_exception_fp_ieee_inexact 0
		.amdhsa_exception_int_div_zero 0
	.end_amdhsa_kernel

; __global__ void __launch_bounds__(512, 2) mega(MegaArgs a) {
amdhsa.kernels:
  - .agpr_count:     0
    .args:
      - .offset:         0
        .size:           1008
        .value_kind:     by_value
      - .offset:         1008
        .size:           4
        .value_kind:     hidden_block_count_x
      - .offset:         1012
        .size:           4
        .value_kind:     hidden_block_count_y
      - .offset:         1016
        .size:           4
        .value_kind:     hidden_block_count_z
      - .offset:         1020
        .size:           2
        .value_kind:     hidden_group_size_x
      - .offset:         1022
        .size:           2
        .value_kind:     hidden_group_size_y
      - .offset:         1024
        .size:           2
        .value_kind:     hidden_group_size_z
      - .offset:         1026
        .size:           2
        .value_kind:     hidden_remainder_x
      - .offset:         1028
        .size:           2
        .value_kind:     hidden_remainder_y
      - .offset:         1030
        .size:           2
        .value_kind:     hidden_remainder_z
      - .offset:         1048
        .size:           8
        .value_kind:     hidden_global_offset_x
      - .offset:         1056
        .size:           8
        .value_kind:     hidden_global_offset_y
      - .offset:         1064
        .size:           8
        .value_kind:     hidden_global_offset_z
      - .offset:         1072
        .size:           2
        .value_kind:     hidden_grid_dims
      - .offset:         1128
        .size:           4
        .value_kind:     hidden_dynamic_lds_size
    .group_segment_fixed_size: 0
    .kernarg_segment_align: 8
    .kernarg_segment_size: 1264
    .language:       OpenCL C
    .language_version:
      - 2
      - 0
    .max_flat_workgroup_size: 512
    .name:           _Z4mega8MegaArgs
    .private_segment_fixed_size: 0
    .sgpr_count:     108
    .sgpr_spill_count: 441
    .symbol:         _Z4mega8MegaArgs.kd
    .uniform_work_group_size: 1
    .uses_dynamic_stack: false
    .vgpr_count:     256
    .vgpr_spill_count: 0
    .wavefront_size: 64
